# stack: all validated neutral edits (token-loop hoists, vt pipeline, attention LDS deepen, cvt batching, DPP reductions) plus merged GEMM phases 2+3/6+7, on static-prio base
# speedup vs baseline: 1.0064x; 1.0064x over previous
; #define PG8_STAGE(bufoff, gbase, voff) do { _Pragma("unroll") for (int _i = 0; _i < 2; ++_i) \
;         __builtin_amdgcn_global_load_lds((const unsigned*)((const char*)(gbase) + (voff)[_i]), (LAS unsigned*)(lds + (bufoff) + ldsw + _i * 8192), 16, 0, 0); } while (0)
; #define PG8_LDA(dst, b, h) do { _Pragma("unroll") for (int m = 0; m < 4; ++m) _Pragma("unroll") for (int k = 0; k < 2; ++k) dst[m][k] = *(const LAS bf16x8*)(lds + PG8_SA(b, h) + aoff + m * 2048 + k * 1024); } while (0)
; #define PG8_LDB(dst, b, h) do { _Pragma("unroll") for (int n = 0; n < 2; ++n) _Pragma("unroll") for (int k = 0; k < 2; ++k) dst[n][k] = *(const LAS bf16x8*)(lds + PG8_SB(b, h) + boff + n * 2048 + k * 1024); } while (0)
; #define PG8_MMA(ai, bj, At, Bt) do { __builtin_amdgcn_s_setprio(1); _Pragma("unroll") for (int m = 0; m < 4; ++m) _Pragma("unroll") for (int n = 0; n < 2; ++n) _Pragma("unroll") for (int k = 0; k < 2; ++k) \
;         acc[ai][bj][m][n] = __builtin_amdgcn_mfma_f32_16x16x32_bf16(Bt[n][k], At[m][k], acc[ai][bj][m][n], 0, 0, 0); __builtin_amdgcn_s_setprio(0); } while (0)
; #define PG8_WAIT_V(n) asm volatile("s_waitcnt vmcnt(" #n ")" ::: "memory")
; #define PG8_WAIT_L(n) asm volatile("s_waitcnt lgkmcnt(" #n ")" ::: "memory")
; #define PG8_BAR __builtin_amdgcn_s_barrier()
; #define PG8_SCHED __builtin_amdgcn_sched_barrier(0)
; template <class Epi>
; __device__ __forceinline__ void gemm_phase(LAS unsigned char* lds, const Gemm g, const StaticOrder& S, const Epi& E) {
;     ...
;             PG8_LDB(B0, 0, 0); PG8_SCHED; PG8_LDA(At, 0, 0); PG8_STAGE(PG8_SA(1, 1), a1 + hstep, voffA);
;             PG8_WAIT_L(8); PG8_BAR; PG8_WAIT_L(0); PG8_MMA(0, 0, At, B0); PG8_BAR; PG8_SCHED;
;             PG8_LDB(B1, 0, 1); PG8_STAGE(PG8_SB(0, 0), b2, voffB0);
;             PG8_BAR; PG8_WAIT_L(0); PG8_MMA(0, 1, At, B1); PG8_BAR;
;             PG8_LDA(At, 0, 1); PG8_STAGE(PG8_SA(0, 0), a2, voffA);
;             PG8_BAR; PG8_WAIT_L(0); PG8_MMA(1, 0, At, B0); PG8_BAR; PG8_SCHED;
;             PG8_STAGE(PG8_SB(0, 1), b2, voffB1);
;             PG8_WAIT_V(6); PG8_BAR; PG8_MMA(1, 1, At, B1); PG8_BAR;
.LBB0_613:
	ds_read_b128 v[146:149], v155
	ds_read_b128 v[158:161], v155 offset:1024
	ds_read_b128 v[162:165], v155 offset:2048
	ds_read_b128 v[166:169], v155 offset:3072
	s_add_u32 s33, s54, 0xfff80080
	s_addc_u32 s56, s55, -1
	s_cmp_eq_u32 s88, 28
	s_cselect_b32 s57, s43, s56
	s_cselect_b32 s56, s51, s33
	s_cselect_b32 s59, s41, s87
	s_cselect_b32 s58, s85, s86
	v_lshl_add_u64 v[204:205], s[54:55], 0, v[140:141]
	s_add_i32 m0, s53, 0xc000
	ds_read_b128 v[170:173], v156
	ds_read_b128 v[174:177], v156 offset:1024
	ds_read_b128 v[178:181], v156 offset:2048
	ds_read_b128 v[182:185], v156 offset:3072
	ds_read_b128 v[186:189], v156 offset:4096
	ds_read_b128 v[190:193], v156 offset:5120
	ds_read_b128 v[194:197], v156 offset:6144
	ds_read_b128 v[198:201], v156 offset:7168
	global_load_lds_dwordx4 v[204:205], off
	v_lshl_add_u64 v[204:205], s[54:55], 0, v[142:143]
	s_add_i32 m0, s53, 0xe000
	s_nop 0
	global_load_lds_dwordx4 v[204:205], off
	s_waitcnt lgkmcnt(8)
	s_barrier
	s_waitcnt lgkmcnt(0)
	v_mfma_f32_16x16x32_bf16 v[124:127], v[146:149], v[170:173], v[124:127]
	v_mfma_f32_16x16x32_bf16 v[120:123], v[162:165], v[170:173], v[120:123]
	v_mfma_f32_16x16x32_bf16 v[108:111], v[146:149], v[178:181], v[108:111]
	v_mfma_f32_16x16x32_bf16 v[104:107], v[162:165], v[178:181], v[104:107]
	v_mfma_f32_16x16x32_bf16 v[92:95], v[146:149], v[186:189], v[92:95]
	v_mfma_f32_16x16x32_bf16 v[88:91], v[162:165], v[186:189], v[88:91]
	v_mfma_f32_16x16x32_bf16 v[76:79], v[146:149], v[194:197], v[76:79]
	v_mfma_f32_16x16x32_bf16 v[72:75], v[162:165], v[194:197], v[72:75]
	v_mfma_f32_16x16x32_bf16 v[124:127], v[158:161], v[174:177], v[124:127]
	v_mfma_f32_16x16x32_bf16 v[120:123], v[166:169], v[174:177], v[120:123]
	v_mfma_f32_16x16x32_bf16 v[108:111], v[158:161], v[182:185], v[108:111]
	v_mfma_f32_16x16x32_bf16 v[104:107], v[166:169], v[182:185], v[104:107]
	v_mfma_f32_16x16x32_bf16 v[92:95], v[158:161], v[190:193], v[92:95]
	v_mfma_f32_16x16x32_bf16 v[88:91], v[166:169], v[190:193], v[88:91]
	v_mfma_f32_16x16x32_bf16 v[76:79], v[158:161], v[198:201], v[76:79]
	v_mfma_f32_16x16x32_bf16 v[72:75], v[166:169], v[198:201], v[72:75]
	s_barrier
	s_add_i32 s33, s79, s65
	v_lshl_add_u64 v[220:221], s[58:59], 0, v[130:131]
	s_mov_b32 m0, s33
	ds_read_b128 v[204:207], v157
	ds_read_b128 v[208:211], v157 offset:1024
	ds_read_b128 v[212:215], v157 offset:2048
	ds_read_b128 v[216:219], v157 offset:3072
	global_load_lds_dwordx4 v[220:221], off
	v_lshl_add_u64 v[222:223], s[58:59], 0, v[136:137]
	s_add_i32 m0, s33, 0x2000
	s_nop 0
	global_load_lds_dwordx4 v[222:223], off
	s_waitcnt lgkmcnt(0)
	s_barrier
	s_waitcnt lgkmcnt(0)
	v_mfma_f32_16x16x32_bf16 v[116:119], v[204:207], v[170:173], v[116:119]
	v_mfma_f32_16x16x32_bf16 v[112:115], v[212:215], v[170:173], v[112:115]
	v_mfma_f32_16x16x32_bf16 v[100:103], v[204:207], v[178:181], v[100:103]
	v_mfma_f32_16x16x32_bf16 v[96:99], v[212:215], v[178:181], v[96:99]
	v_mfma_f32_16x16x32_bf16 v[84:87], v[204:207], v[186:189], v[84:87]
	v_mfma_f32_16x16x32_bf16 v[80:83], v[212:215], v[186:189], v[80:83]
	v_mfma_f32_16x16x32_bf16 v[68:71], v[204:207], v[194:197], v[68:71]
	v_mfma_f32_16x16x32_bf16 v[64:67], v[212:215], v[194:197], v[64:67]
	v_mfma_f32_16x16x32_bf16 v[116:119], v[208:211], v[174:177], v[116:119]
	v_mfma_f32_16x16x32_bf16 v[112:115], v[216:219], v[174:177], v[112:115]
	v_mfma_f32_16x16x32_bf16 v[100:103], v[208:211], v[182:185], v[100:103]
	v_mfma_f32_16x16x32_bf16 v[96:99], v[216:219], v[182:185], v[96:99]
	v_mfma_f32_16x16x32_bf16 v[84:87], v[208:211], v[190:193], v[84:87]
	v_mfma_f32_16x16x32_bf16 v[80:83], v[216:219], v[190:193], v[80:83]
	v_mfma_f32_16x16x32_bf16 v[68:71], v[208:211], v[198:201], v[68:71]
	v_mfma_f32_16x16x32_bf16 v[64:67], v[216:219], v[198:201], v[64:67]
	s_mov_b32 m0, s53
	v_lshl_add_u64 v[224:225], s[56:57], 0, v[128:129]
	s_barrier
	ds_read_b128 v[170:173], v156 offset:16384
	ds_read_b128 v[174:177], v156 offset:17408
	ds_read_b128 v[178:181], v156 offset:18432
	ds_read_b128 v[182:185], v156 offset:19456
	ds_read_b128 v[186:189], v156 offset:20480
	ds_read_b128 v[190:193], v156 offset:21504
	ds_read_b128 v[194:197], v156 offset:22528
	ds_read_b128 v[198:201], v156 offset:23552
	global_load_lds_dwordx4 v[224:225], off
	v_lshl_add_u64 v[226:227], s[56:57], 0, v[134:135]
	s_mov_b32 m0, s66
	s_nop 0
	global_load_lds_dwordx4 v[226:227], off
	s_add_i32 s33, s80, s65
	v_lshl_add_u64 v[228:229], s[58:59], 0, v[132:133]
	s_mov_b32 m0, s33
	v_lshl_add_u64 v[230:231], s[58:59], 0, v[138:139]
	global_load_lds_dwordx4 v[228:229], off
	s_add_i32 m0, s33, 0x2000
	s_nop 0
	global_load_lds_dwordx4 v[230:231], off
	s_waitcnt vmcnt(6)
	s_barrier
; #define PG8_STAGE(bufoff, gbase, voff) do { _Pragma("unroll") for (int _i = 0; _i < 2; ++_i) \
;         __builtin_amdgcn_global_load_lds((const unsigned*)((const char*)(gbase) + (voff)[_i]), (LAS unsigned*)(lds + (bufoff) + ldsw + _i * 8192), 16, 0, 0); } while (0)
; #define PG8_LDA(dst, b, h) do { _Pragma("unroll") for (int m = 0; m < 4; ++m) _Pragma("unroll") for (int k = 0; k < 2; ++k) dst[m][k] = *(const LAS bf16x8*)(lds + PG8_SA(b, h) + aoff + m * 2048 + k * 1024); } while (0)
; #define PG8_LDB(dst, b, h) do { _Pragma("unroll") for (int n = 0; n < 2; ++n) _Pragma("unroll") for (int k = 0; k < 2; ++k) dst[n][k] = *(const LAS bf16x8*)(lds + PG8_SB(b, h) + boff + n * 2048 + k * 1024); } while (0)
; #define PG8_MMA(ai, bj, At, Bt) do { __builtin_amdgcn_s_setprio(1); _Pragma("unroll") for (int m = 0; m < 4; ++m) _Pragma("unroll") for (int n = 0; n < 2; ++n) _Pragma("unroll") for (int k = 0; k < 2; ++k) \
;         acc[ai][bj][m][n] = __builtin_amdgcn_mfma_f32_16x16x32_bf16(Bt[n][k], At[m][k], acc[ai][bj][m][n], 0, 0, 0); __builtin_amdgcn_s_setprio(0); } while (0)
; #define PG8_WAIT_V(n) asm volatile("s_waitcnt vmcnt(" #n ")" ::: "memory")
; #define PG8_WAIT_L(n) asm volatile("s_waitcnt lgkmcnt(" #n ")" ::: "memory")
; #define PG8_BAR __builtin_amdgcn_s_barrier()
; #define PG8_SCHED __builtin_amdgcn_sched_barrier(0)
; template <class Epi>
; __device__ __forceinline__ void gemm_phase(LAS unsigned char* lds, const Gemm g, const StaticOrder& S, const Epi& E) {
;     ...
;             PG8_BAR; PG8_WAIT_L(0); PG8_MMA(1, 0, At, B0); PG8_BAR; PG8_SCHED;
;             PG8_STAGE(PG8_SB(0, 1), b2, voffB1);
;             PG8_WAIT_V(6); PG8_BAR; PG8_MMA(1, 1, At, B1); PG8_BAR;
;             PG8_LDB(B0, 1, 0); PG8_SCHED; PG8_LDA(At, 1, 0); PG8_STAGE(PG8_SA(0, 1), a2 + hstep, voffA);
;             PG8_WAIT_L(8); PG8_BAR; PG8_WAIT_L(0); PG8_MMA(0, 0, At, B0); PG8_BAR; PG8_SCHED;
;             PG8_LDB(B1, 1, 1); PG8_STAGE(PG8_SB(1, 0), b3, voffB0);
;             PG8_BAR; PG8_WAIT_L(0); PG8_MMA(0, 1, At, B1); PG8_BAR;
	s_waitcnt lgkmcnt(0)
	v_mfma_f32_16x16x32_bf16 v[60:63], v[146:149], v[170:173], v[60:63]
	v_mfma_f32_16x16x32_bf16 v[56:59], v[162:165], v[170:173], v[56:59]
	v_mfma_f32_16x16x32_bf16 v[44:47], v[146:149], v[178:181], v[44:47]
	v_mfma_f32_16x16x32_bf16 v[40:43], v[162:165], v[178:181], v[40:43]
	v_mfma_f32_16x16x32_bf16 v[28:31], v[146:149], v[186:189], v[28:31]
	v_mfma_f32_16x16x32_bf16 v[24:27], v[162:165], v[186:189], v[24:27]
	v_mfma_f32_16x16x32_bf16 v[12:15], v[146:149], v[194:197], v[12:15]
	v_mfma_f32_16x16x32_bf16 v[8:11], v[162:165], v[194:197], v[8:11]
	v_mfma_f32_16x16x32_bf16 v[60:63], v[158:161], v[174:177], v[60:63]
	v_mfma_f32_16x16x32_bf16 v[56:59], v[166:169], v[174:177], v[56:59]
	v_mfma_f32_16x16x32_bf16 v[44:47], v[158:161], v[182:185], v[44:47]
	v_mfma_f32_16x16x32_bf16 v[40:43], v[166:169], v[182:185], v[40:43]
	v_mfma_f32_16x16x32_bf16 v[28:31], v[158:161], v[190:193], v[28:31]
	v_mfma_f32_16x16x32_bf16 v[24:27], v[166:169], v[190:193], v[24:27]
	v_mfma_f32_16x16x32_bf16 v[12:15], v[158:161], v[198:201], v[12:15]
	v_mfma_f32_16x16x32_bf16 v[8:11], v[166:169], v[198:201], v[8:11]
	v_mfma_f32_16x16x32_bf16 v[52:55], v[204:207], v[170:173], v[52:55]
	v_mfma_f32_16x16x32_bf16 v[48:51], v[212:215], v[170:173], v[48:51]
	v_mfma_f32_16x16x32_bf16 v[36:39], v[204:207], v[178:181], v[36:39]
	v_mfma_f32_16x16x32_bf16 v[32:35], v[212:215], v[178:181], v[32:35]
	v_mfma_f32_16x16x32_bf16 v[20:23], v[204:207], v[186:189], v[20:23]
	v_mfma_f32_16x16x32_bf16 v[16:19], v[212:215], v[186:189], v[16:19]
	v_mfma_f32_16x16x32_bf16 v[4:7], v[204:207], v[194:197], v[4:7]
	v_mfma_f32_16x16x32_bf16 v[0:3], v[212:215], v[194:197], v[0:3]
	v_mfma_f32_16x16x32_bf16 v[52:55], v[208:211], v[174:177], v[52:55]
	v_mfma_f32_16x16x32_bf16 v[48:51], v[216:219], v[174:177], v[48:51]
	v_mfma_f32_16x16x32_bf16 v[36:39], v[208:211], v[182:185], v[36:39]
	v_mfma_f32_16x16x32_bf16 v[32:35], v[216:219], v[182:185], v[32:35]
	v_mfma_f32_16x16x32_bf16 v[20:23], v[208:211], v[190:193], v[20:23]
	v_mfma_f32_16x16x32_bf16 v[16:19], v[216:219], v[190:193], v[16:19]
	v_mfma_f32_16x16x32_bf16 v[4:7], v[208:211], v[198:201], v[4:7]
	v_mfma_f32_16x16x32_bf16 v[0:3], v[216:219], v[198:201], v[0:3]
	s_add_i32 s33, 0, 0x18000
	v_add_u32_e32 v166, s33, v151
	s_barrier
	ds_read_b128 v[146:149], v166
	ds_read_b128 v[158:161], v166 offset:1024
	ds_read_b128 v[162:165], v166 offset:2048
	ds_read_b128 v[166:169], v166 offset:3072
	s_add_u32 s56, s56, 0x80000
	s_addc_u32 s57, s57, 0
	s_mov_b32 m0, s67
	v_lshl_add_u64 v[204:205], s[56:57], 0, v[128:129]
	ds_read_b128 v[170:173], v156 offset:32768
	ds_read_b128 v[174:177], v156 offset:33792
	ds_read_b128 v[178:181], v156 offset:34816
	ds_read_b128 v[182:185], v156 offset:35840
	ds_read_b128 v[186:189], v156 offset:36864
	ds_read_b128 v[190:193], v156 offset:37888
	ds_read_b128 v[194:197], v156 offset:38912
	ds_read_b128 v[198:201], v156 offset:39936
	global_load_lds_dwordx4 v[204:205], off
	v_lshl_add_u64 v[204:205], s[56:57], 0, v[134:135]
	s_mov_b32 m0, s68
	s_nop 0
	global_load_lds_dwordx4 v[204:205], off
	s_waitcnt lgkmcnt(8)
	s_barrier
	s_waitcnt lgkmcnt(0)
	v_mfma_f32_16x16x32_bf16 v[124:127], v[146:149], v[170:173], v[124:127]
	v_mfma_f32_16x16x32_bf16 v[120:123], v[162:165], v[170:173], v[120:123]
	v_mfma_f32_16x16x32_bf16 v[108:111], v[146:149], v[178:181], v[108:111]
	v_mfma_f32_16x16x32_bf16 v[104:107], v[162:165], v[178:181], v[104:107]
	v_mfma_f32_16x16x32_bf16 v[92:95], v[146:149], v[186:189], v[92:95]
	v_mfma_f32_16x16x32_bf16 v[88:91], v[162:165], v[186:189], v[88:91]
	v_mfma_f32_16x16x32_bf16 v[76:79], v[146:149], v[194:197], v[76:79]
	v_mfma_f32_16x16x32_bf16 v[72:75], v[162:165], v[194:197], v[72:75]
	v_mfma_f32_16x16x32_bf16 v[124:127], v[158:161], v[174:177], v[124:127]
	v_mfma_f32_16x16x32_bf16 v[120:123], v[166:169], v[174:177], v[120:123]
	v_mfma_f32_16x16x32_bf16 v[108:111], v[158:161], v[182:185], v[108:111]
	v_mfma_f32_16x16x32_bf16 v[104:107], v[166:169], v[182:185], v[104:107]
	v_mfma_f32_16x16x32_bf16 v[92:95], v[158:161], v[190:193], v[92:95]
	v_mfma_f32_16x16x32_bf16 v[88:91], v[166:169], v[190:193], v[88:91]
	v_mfma_f32_16x16x32_bf16 v[76:79], v[158:161], v[198:201], v[76:79]
	v_mfma_f32_16x16x32_bf16 v[72:75], v[166:169], v[198:201], v[72:75]
	s_barrier
	s_add_i32 s56, 0, 0x1c000
	s_add_i32 s33, s33, s65
	v_add_u32_e32 v216, s56, v151
	v_lshl_add_u64 v[220:221], v[220:221], 0, s[36:37]
	s_mov_b32 m0, s33
	ds_read_b128 v[204:207], v216
	ds_read_b128 v[208:211], v216 offset:1024
	ds_read_b128 v[212:215], v216 offset:2048
	ds_read_b128 v[216:219], v216 offset:3072
	global_load_lds_dwordx4 v[220:221], off
	v_lshl_add_u64 v[220:221], v[222:223], 0, s[36:37]
	s_add_i32 m0, s33, 0x2000
	s_nop 0
	global_load_lds_dwordx4 v[220:221], off
	s_waitcnt lgkmcnt(0)
	s_barrier
	s_waitcnt lgkmcnt(0)
	v_mfma_f32_16x16x32_bf16 v[116:119], v[204:207], v[170:173], v[116:119]
	v_mfma_f32_16x16x32_bf16 v[112:115], v[212:215], v[170:173], v[112:115]
	v_mfma_f32_16x16x32_bf16 v[100:103], v[204:207], v[178:181], v[100:103]
	v_mfma_f32_16x16x32_bf16 v[96:99], v[212:215], v[178:181], v[96:99]
	v_mfma_f32_16x16x32_bf16 v[84:87], v[204:207], v[186:189], v[84:87]
	v_mfma_f32_16x16x32_bf16 v[80:83], v[212:215], v[186:189], v[80:83]
	v_mfma_f32_16x16x32_bf16 v[68:71], v[204:207], v[194:197], v[68:71]
	v_mfma_f32_16x16x32_bf16 v[64:67], v[212:215], v[194:197], v[64:67]
	v_mfma_f32_16x16x32_bf16 v[116:119], v[208:211], v[174:177], v[116:119]
	v_mfma_f32_16x16x32_bf16 v[112:115], v[216:219], v[174:177], v[112:115]
	v_mfma_f32_16x16x32_bf16 v[100:103], v[208:211], v[182:185], v[100:103]
	v_mfma_f32_16x16x32_bf16 v[96:99], v[216:219], v[182:185], v[96:99]
	v_mfma_f32_16x16x32_bf16 v[84:87], v[208:211], v[190:193], v[84:87]
	v_mfma_f32_16x16x32_bf16 v[80:83], v[216:219], v[190:193], v[80:83]
	v_mfma_f32_16x16x32_bf16 v[68:71], v[208:211], v[198:201], v[68:71]
	v_mfma_f32_16x16x32_bf16 v[64:67], v[216:219], v[198:201], v[64:67]
	s_mov_b32 m0, s72
	v_lshl_add_u64 v[220:221], v[224:225], 0, s[36:37]
	s_barrier
; #define PG8_STAGE(bufoff, gbase, voff) do { _Pragma("unroll") for (int _i = 0; _i < 2; ++_i) \
;         __builtin_amdgcn_global_load_lds((const unsigned*)((const char*)(gbase) + (voff)[_i]), (LAS unsigned*)(lds + (bufoff) + ldsw + _i * 8192), 16, 0, 0); } while (0)
; #define PG8_LDA(dst, b, h) do { _Pragma("unroll") for (int m = 0; m < 4; ++m) _Pragma("unroll") for (int k = 0; k < 2; ++k) dst[m][k] = *(const LAS bf16x8*)(lds + PG8_SA(b, h) + aoff + m * 2048 + k * 1024); } while (0)
; #define PG8_MMA(ai, bj, At, Bt) do { __builtin_amdgcn_s_setprio(1); _Pragma("unroll") for (int m = 0; m < 4; ++m) _Pragma("unroll") for (int n = 0; n < 2; ++n) _Pragma("unroll") for (int k = 0; k < 2; ++k) \
;         acc[ai][bj][m][n] = __builtin_amdgcn_mfma_f32_16x16x32_bf16(Bt[n][k], At[m][k], acc[ai][bj][m][n], 0, 0, 0); __builtin_amdgcn_s_setprio(0); } while (0)
; #define PG8_WAIT_V(n) asm volatile("s_waitcnt vmcnt(" #n ")" ::: "memory")
; #define PG8_WAIT_L(n) asm volatile("s_waitcnt lgkmcnt(" #n ")" ::: "memory")
; #define PG8_BAR __builtin_amdgcn_s_barrier()
; #define PG8_SCHED __builtin_amdgcn_sched_barrier(0)
; template <class Epi>
; __device__ __forceinline__ void gemm_phase(LAS unsigned char* lds, const Gemm g, const StaticOrder& S, const Epi& E) {
;     ...
;             PG8_LDA(At, 1, 1); PG8_STAGE(PG8_SA(1, 0), a3, voffA);
;             PG8_BAR; PG8_WAIT_L(0); PG8_MMA(1, 0, At, B0); PG8_BAR; PG8_SCHED;
;             PG8_STAGE(PG8_SB(1, 1), b3, voffB1);
;             PG8_WAIT_V(6); PG8_BAR; PG8_MMA(1, 1, At, B1); PG8_BAR;
;         }
	ds_read_b128 v[170:173], v156 offset:49152
	ds_read_b128 v[174:177], v156 offset:50176
	ds_read_b128 v[178:181], v156 offset:51200
	ds_read_b128 v[182:185], v156 offset:52224
	ds_read_b128 v[186:189], v156 offset:53248
	ds_read_b128 v[190:193], v156 offset:54272
	ds_read_b128 v[194:197], v156 offset:55296
	ds_read_b128 v[198:201], v156 offset:56320
	global_load_lds_dwordx4 v[220:221], off
	v_lshl_add_u64 v[220:221], v[226:227], 0, s[36:37]
	s_mov_b32 m0, s73
	s_nop 0
	global_load_lds_dwordx4 v[220:221], off
	s_add_i32 s33, s56, s65
	v_lshl_add_u64 v[250:251], v[228:229], 0, s[36:37]
	s_mov_b32 m0, s33
	s_nop 0
	global_load_lds_dwordx4 v[250:251], off
	v_lshl_add_u64 v[250:251], v[230:231], 0, s[36:37]
	s_add_i32 m0, s33, 0x2000
	s_nop 0
	global_load_lds_dwordx4 v[250:251], off
	s_waitcnt vmcnt(6)
	s_barrier
	s_waitcnt lgkmcnt(0)
	v_mfma_f32_16x16x32_bf16 v[60:63], v[146:149], v[170:173], v[60:63]
	v_mfma_f32_16x16x32_bf16 v[56:59], v[162:165], v[170:173], v[56:59]
	v_mfma_f32_16x16x32_bf16 v[44:47], v[146:149], v[178:181], v[44:47]
	v_mfma_f32_16x16x32_bf16 v[40:43], v[162:165], v[178:181], v[40:43]
	v_mfma_f32_16x16x32_bf16 v[28:31], v[146:149], v[186:189], v[28:31]
	v_mfma_f32_16x16x32_bf16 v[24:27], v[162:165], v[186:189], v[24:27]
	v_mfma_f32_16x16x32_bf16 v[12:15], v[146:149], v[194:197], v[12:15]
	v_mfma_f32_16x16x32_bf16 v[8:11], v[162:165], v[194:197], v[8:11]
	v_mfma_f32_16x16x32_bf16 v[60:63], v[158:161], v[174:177], v[60:63]
	v_mfma_f32_16x16x32_bf16 v[56:59], v[166:169], v[174:177], v[56:59]
	v_mfma_f32_16x16x32_bf16 v[44:47], v[158:161], v[182:185], v[44:47]
	v_mfma_f32_16x16x32_bf16 v[40:43], v[166:169], v[182:185], v[40:43]
	v_mfma_f32_16x16x32_bf16 v[28:31], v[158:161], v[190:193], v[28:31]
	v_mfma_f32_16x16x32_bf16 v[24:27], v[166:169], v[190:193], v[24:27]
	v_mfma_f32_16x16x32_bf16 v[12:15], v[158:161], v[198:201], v[12:15]
	v_mfma_f32_16x16x32_bf16 v[8:11], v[166:169], v[198:201], v[8:11]
	v_mfma_f32_16x16x32_bf16 v[52:55], v[204:207], v[170:173], v[52:55]
	v_mfma_f32_16x16x32_bf16 v[48:51], v[212:215], v[170:173], v[48:51]
	v_mfma_f32_16x16x32_bf16 v[36:39], v[204:207], v[178:181], v[36:39]
	v_mfma_f32_16x16x32_bf16 v[32:35], v[212:215], v[178:181], v[32:35]
	v_mfma_f32_16x16x32_bf16 v[20:23], v[204:207], v[186:189], v[20:23]
	v_mfma_f32_16x16x32_bf16 v[16:19], v[212:215], v[186:189], v[16:19]
	v_mfma_f32_16x16x32_bf16 v[4:7], v[204:207], v[194:197], v[4:7]
	v_mfma_f32_16x16x32_bf16 v[0:3], v[212:215], v[194:197], v[0:3]
	v_mfma_f32_16x16x32_bf16 v[52:55], v[208:211], v[174:177], v[52:55]
	v_mfma_f32_16x16x32_bf16 v[48:51], v[216:219], v[174:177], v[48:51]
	v_mfma_f32_16x16x32_bf16 v[36:39], v[208:211], v[182:185], v[36:39]
	v_mfma_f32_16x16x32_bf16 v[32:35], v[216:219], v[182:185], v[32:35]
	v_mfma_f32_16x16x32_bf16 v[20:23], v[208:211], v[190:193], v[20:23]
	v_mfma_f32_16x16x32_bf16 v[16:19], v[216:219], v[190:193], v[16:19]
	v_mfma_f32_16x16x32_bf16 v[4:7], v[208:211], v[198:201], v[4:7]
	v_mfma_f32_16x16x32_bf16 v[0:3], v[216:219], v[198:201], v[0:3]
	s_add_i32 s88, s88, 2
	s_add_u32 s54, s54, 0x100
	s_addc_u32 s55, s55, 0
	s_add_u32 s86, s86, 0x100
	s_addc_u32 s87, s87, 0
	s_cmp_gt_u32 s88, 29
	s_barrier
	s_cbranch_scc0 .LBB0_613
; __device__ __forceinline__ float bflo(unsigned w) { return __uint_as_float(w << 16); }
; __device__ __forceinline__ void store_pair_lines(bf16_t* O, int ldc, int row, int fr, int col0, u32x4 wA, u32x4 wB) {
;     const u32x4 sA = {dpp_ror8(wA.x), dpp_ror8(wA.y), dpp_ror8(wA.z), dpp_ror8(wA.w)}, sB = {dpp_ror8(wB.x), dpp_ror8(wB.y), dpp_ror8(wB.z), dpp_ror8(wB.w)};
;     const bool lo = fr < 8;
;     const u32x4 o1 = lo ? wA : sB, o2 = lo ? sA : wB;
;     const int r1 = row - fr + (fr & 7), cb = col0 + (lo ? 0 : 8);
;     *(u32x4*)(O + (size_t)r1 * ldc + cb) = o1;
;     *(u32x4*)(O + (size_t)(r1 + 8) * ldc + cb) = o2;
; }
;     __device__ __forceinline__ void operator()(const f32x4 (&acc)[2][2][4][2], const Unit& u, int wr, int wc, int fr, int fq) const {
;         const int row0 = u.pm * BM + wr * 64 + fr, col0 = u.pn * BM + wc * 64 + 16 * fq;
; #pragma unroll
;         for (int ai = 0; ai < 2; ++ai)
; #pragma unroll
;             for (int m = 0; m < 4; ++m) { const int row = row0 + ai * HALF + m * 16; const size_t off = (size_t)row * D + col0; float sq = 0.f; u32x4 w[2];
;                 const float sc = rsin ? __builtin_amdgcn_rcpf(rsin[row] * (1.f / D) + EPS) : 1.0f;
;                 u32x4 rr[2]; if (R) load_pair_lines(R, D, row, fr, col0, rr[0], rr[1]);
; #pragma unroll
;                 for (int bj = 0; bj < 2; ++bj) { f32x4 r0, r1;
;                     if (R) { const u32x4 rw = rr[bj]; r0 = (f32x4){bflo(rw.x), bfhi(rw.x), bflo(rw.y), bfhi(rw.y)}; r1 = (f32x4){bflo(rw.z), bfhi(rw.z), bflo(rw.w), bfhi(rw.w)}; }
;                     else { const float* rp = (row < 8192 ? src_p + off : src_s + (off - (size_t)8192 * D)) + 8 * bj; r0 = *(const f32x4*)rp; r1 = *(const f32x4*)(rp + 4); }
;                     const f32x4 o0 = r0 + acc[ai][bj][m][0] * sc, o1 = r1 + acc[ai][bj][m][1] * sc;
;                     sq += (o0[0] * o0[0] + o0[1] * o0[1]) + (o0[2] * o0[2] + o0[3] * o0[3]) + (o1[0] * o1[0] + o1[1] * o1[1]) + (o1[2] * o1[2] + o1[3] * o1[3]);
;                     w[bj].x = cvt_pk_bf16(o0[0], o0[1]); w[bj].y = cvt_pk_bf16(o0[2], o0[3]); w[bj].z = cvt_pk_bf16(o1[0], o1[1]); w[bj].w = cvt_pk_bf16(o1[2], o1[3]); }
;                 store_pair_lines(O, D, row, fr, col0, w[0], w[1]);
;                 if (ssout) { sq += __shfl_xor(sq, 16); sq += __shfl_xor(sq, 32); if (fq == 0) unsafeAtomicAdd(ssout + row, sq); } }
	s_lshl_b32 s33, s52, 8
	s_add_i32 s33, s33, s74
	v_or_b32_e32 v146, s33, v150
	v_lshl_or_b32 v148, s50, 8, v154
	v_ashrrev_i32_e32 v147, 31, v146
	v_ashrrev_i32_e32 v149, 31, v148
	v_lshlrev_b64 v[158:159], 11, v[146:147]
	v_lshl_add_u64 v[158:159], v[158:159], 0, v[148:149]
	v_lshlrev_b64 v[158:159], 2, v[158:159]
	v_lshl_add_u64 v[160:161], s[16:17], 0, v[158:159]
	v_lshl_add_u64 v[158:159], s[18:19], 0, v[158:159]
	v_lshl_add_u64 v[158:159], v[158:159], 0, s[38:39]
	v_cmp_gt_i32_e32 vcc, s70, v146
	v_mov_b32_e32 v183, 0
	v_mov_b32_e32 v184, 0
	v_cndmask_b32_e32 v167, v159, v161, vcc
	v_cndmask_b32_e32 v166, v158, v160, vcc
	global_load_dwordx4 v[158:161], v[166:167], off
	global_load_dwordx4 v[162:165], v[166:167], off offset:16
	v_or_b32_e32 v188, 16, v146
	v_ashrrev_i32_e32 v189, 31, v188
	v_lshlrev_b64 v[190:191], 11, v[188:189]
	v_lshl_add_u64 v[190:191], v[190:191], 0, v[148:149]
	v_lshlrev_b64 v[190:191], 2, v[190:191]
	v_lshl_add_u64 v[192:193], s[16:17], 0, v[190:191]
	v_lshl_add_u64 v[190:191], s[18:19], 0, v[190:191]
	v_lshl_add_u64 v[190:191], v[190:191], 0, s[38:39]
	v_cmp_gt_i32_e32 vcc, s70, v188
	s_nop 1
	v_cndmask_b32_e32 v195, v191, v193, vcc
	v_cndmask_b32_e32 v194, v190, v192, vcc
	global_load_dwordx4 v[196:199], v[194:195], off
	global_load_dwordx4 v[204:207], v[194:195], off offset:16
	global_load_dwordx4 v[208:211], v[194:195], off offset:32
	global_load_dwordx4 v[212:215], v[194:195], off offset:48
	v_or_b32_e32 v188, 32, v146
	v_ashrrev_i32_e32 v189, 31, v188
	v_lshlrev_b64 v[190:191], 11, v[188:189]
	v_lshl_add_u64 v[190:191], v[190:191], 0, v[148:149]
	v_lshlrev_b64 v[190:191], 2, v[190:191]
	v_lshl_add_u64 v[192:193], s[16:17], 0, v[190:191]
	v_lshl_add_u64 v[190:191], s[18:19], 0, v[190:191]
	v_lshl_add_u64 v[190:191], v[190:191], 0, s[38:39]
	v_cmp_gt_i32_e32 vcc, s70, v188
	s_nop 1
	v_cndmask_b32_e32 v195, v191, v193, vcc
	v_cndmask_b32_e32 v194, v190, v192, vcc
	global_load_dwordx4 v[216:219], v[194:195], off
	global_load_dwordx4 v[220:223], v[194:195], off offset:16
	global_load_dwordx4 v[224:227], v[194:195], off offset:32
	global_load_dwordx4 v[228:231], v[194:195], off offset:48
	v_or_b32_e32 v188, 48, v146
	v_ashrrev_i32_e32 v189, 31, v188
	v_lshlrev_b64 v[190:191], 11, v[188:189]
	v_lshl_add_u64 v[190:191], v[190:191], 0, v[148:149]
	v_lshlrev_b64 v[190:191], 2, v[190:191]
	v_lshl_add_u64 v[192:193], s[16:17], 0, v[190:191]
	v_lshl_add_u64 v[190:191], s[18:19], 0, v[190:191]
	v_lshl_add_u64 v[190:191], v[190:191], 0, s[38:39]
	v_cmp_gt_i32_e32 vcc, s70, v188
	s_nop 1
	v_cndmask_b32_e32 v195, v191, v193, vcc
	v_cndmask_b32_e32 v194, v190, v192, vcc
	global_load_dwordx4 v[232:235], v[194:195], off
	global_load_dwordx4 v[236:239], v[194:195], off offset:16
	global_load_dwordx4 v[240:243], v[194:195], off offset:32
	global_load_dwordx4 v[244:247], v[194:195], off offset:48
	s_waitcnt vmcnt(12)
	v_pk_add_f32 v[168:169], v[126:127], v[160:161]
	v_pk_add_f32 v[170:171], v[124:125], v[158:159]
	v_pk_add_f32 v[164:165], v[122:123], v[164:165]
	v_pk_add_f32 v[162:163], v[120:121], v[162:163]
	v_cvt_pk_bf16_f32 v123, v170, v171
	v_cvt_pk_bf16_f32 v176, v168, v169
	v_mul_f32_e32 v171, v171, v171
	v_cvt_pk_bf16_f32 v177, v162, v163
	v_cvt_pk_bf16_f32 v178, v164, v165
	global_load_dwordx4 v[124:127], v[166:167], off offset:32
	global_load_dwordx4 v[158:161], v[166:167], off offset:48
	v_mul_f32_e32 v169, v169, v169
	v_and_b32_e32 v121, 64, v203
	v_mul_f32_e32 v163, v163, v163
	v_fmac_f32_e32 v171, v170, v170
	v_fmac_f32_e32 v169, v168, v168
	v_xor_b32_e32 v122, 16, v203
	v_add_u32_e32 v172, 64, v121
	v_mul_f32_e32 v165, v165, v165
	v_fmac_f32_e32 v163, v162, v162
	v_add_f32_e32 v162, v171, v169
	v_cmp_lt_i32_e32 vcc, v122, v172
	v_fmac_f32_e32 v165, v164, v164
	v_add_f32_e32 v162, v163, v162
	v_cndmask_b32_e32 v122, v203, v122, vcc
	v_add_f32_e32 v162, v165, v162
	v_xor_b32_e32 v167, 32, v203
	v_lshlrev_b32_e32 v122, 2, v122
	v_or_b32_e32 v166, s33, v152
	v_cmp_lt_i32_e32 vcc, v167, v172
	v_or_b32_e32 v120, v148, v153
	v_ashrrev_i32_e32 v121, 31, v120
	v_cndmask_b32_e32 v187, v203, v167, vcc
	v_ashrrev_i32_e32 v167, 31, v166
	v_or_b32_e32 v174, 8, v166
	v_lshlrev_b64 v[166:167], 12, v[166:167]
	v_lshlrev_b64 v[172:173], 1, v[120:121]
	v_lshl_add_u64 v[166:167], s[10:11], 0, v[166:167]
	v_lshl_add_u64 v[166:167], v[166:167], 0, v[172:173]
	v_ashrrev_i32_e32 v175, 31, v174
	v_mov_b32_dpp v179, v123 row_ror:8 row_mask:0xf bank_mask:0xf
	v_mov_b32_dpp v180, v176 row_ror:8 row_mask:0xf bank_mask:0xf
	v_mov_b32_dpp v181, v177 row_ror:8 row_mask:0xf bank_mask:0xf
	v_mov_b32_dpp v182, v178 row_ror:8 row_mask:0xf bank_mask:0xf
	s_waitcnt vmcnt(0)
	v_pk_add_f32 v[126:127], v[118:119], v[126:127]
	v_pk_add_f32 v[124:125], v[116:117], v[124:125]
	v_pk_add_f32 v[112:113], v[112:113], v[158:159]
	v_cvt_pk_bf16_f32 v116, v124, v125
	v_cvt_pk_bf16_f32 v117, v126, v127
	v_mul_f32_e32 v125, v125, v125
	v_mul_f32_e32 v127, v127, v127
	v_pk_add_f32 v[114:115], v[114:115], v[160:161]
	v_mul_f32_e32 v158, v113, v113
	v_fmac_f32_e32 v125, v124, v124
	v_fmac_f32_e32 v127, v126, v126
	v_cvt_pk_bf16_f32 v118, v112, v113
	v_cvt_pk_bf16_f32 v119, v114, v115
	v_mul_f32_e32 v115, v115, v115
	v_fmac_f32_e32 v158, v112, v112
	v_add_f32_e32 v112, v125, v127
	v_fmac_f32_e32 v115, v114, v114
	v_add_f32_e32 v112, v158, v112
	v_add_f32_e32 v112, v115, v112
	v_add_f32_e32 v124, v162, v112
	v_mov_b32_e32 v125, v124
	s_nop 1
	v_permlane16_swap_b32_e32 v125, v124
	v_mov_b32_dpp v183, v116 row_ror:8 row_mask:0xf bank_mask:0xf
	v_mov_b32_dpp v184, v117 row_ror:8 row_mask:0xf bank_mask:0xf
	v_mov_b32_dpp v185, v118 row_ror:8 row_mask:0xf bank_mask:0xf
	v_mov_b32_dpp v186, v119 row_ror:8 row_mask:0xf bank_mask:0xf
	v_cndmask_b32_e64 v113, v184, v176, s[6:7]
	v_cndmask_b32_e64 v115, v186, v178, s[6:7]
	v_cndmask_b32_e64 v112, v183, v123, s[6:7]
	v_cndmask_b32_e64 v114, v185, v177, s[6:7]
	global_store_dwordx4 v[166:167], v[112:115], off
	v_cndmask_b32_e64 v117, v117, v180, s[6:7]
	v_cndmask_b32_e64 v119, v119, v182, s[6:7]
	s_waitcnt lgkmcnt(0)
	v_add_f32_e32 v112, v124, v125
	v_lshlrev_b32_e32 v114, 2, v187
	v_mov_b32_e32 v113, v112
	s_nop 1
	v_permlane32_swap_b32_e32 v113, v112
	v_lshlrev_b64 v[124:125], 12, v[174:175]
	v_lshl_add_u64 v[124:125], s[10:11], 0, v[124:125]
	v_cndmask_b32_e64 v116, v116, v179, s[6:7]
	v_cndmask_b32_e64 v118, v118, v181, s[6:7]
	v_lshl_add_u64 v[124:125], v[124:125], 0, v[172:173]
	global_store_dwordx4 v[124:125], v[116:119], off
	s_and_saveexec_b64 s[50:51], s[8:9]
	s_cbranch_execz .LBB0_616
	s_waitcnt lgkmcnt(0)
	v_add_f32_e32 v115, v112, v113
	v_lshl_add_u64 v[112:113], v[146:147], 2, s[12:13]
	global_atomic_add_f32 v[112:113], v115, off

; #define PG8_STAGE(bufoff, gbase, voff) do { _Pragma("unroll") for (int _i = 0; _i < 2; ++_i) \
;         __builtin_amdgcn_global_load_lds((const unsigned*)((const char*)(gbase) + (voff)[_i]), (LAS unsigned*)(lds + (bufoff) + ldsw + _i * 8192), 16, 0, 0); } while (0)
; #define PG8_LDA(dst, b, h) do { _Pragma("unroll") for (int m = 0; m < 4; ++m) _Pragma("unroll") for (int k = 0; k < 2; ++k) dst[m][k] = *(const LAS bf16x8*)(lds + PG8_SA(b, h) + aoff + m * 2048 + k * 1024); } while (0)
; #define PG8_LDB(dst, b, h) do { _Pragma("unroll") for (int n = 0; n < 2; ++n) _Pragma("unroll") for (int k = 0; k < 2; ++k) dst[n][k] = *(const LAS bf16x8*)(lds + PG8_SB(b, h) + boff + n * 2048 + k * 1024); } while (0)
; #define PG8_MMA(ai, bj, At, Bt) do { __builtin_amdgcn_s_setprio(1); _Pragma("unroll") for (int m = 0; m < 4; ++m) _Pragma("unroll") for (int n = 0; n < 2; ++n) _Pragma("unroll") for (int k = 0; k < 2; ++k) \
;         acc[ai][bj][m][n] = __builtin_amdgcn_mfma_f32_16x16x32_bf16(Bt[n][k], At[m][k], acc[ai][bj][m][n], 0, 0, 0); __builtin_amdgcn_s_setprio(0); } while (0)
; #define PG8_WAIT_V(n) asm volatile("s_waitcnt vmcnt(" #n ")" ::: "memory")
; #define PG8_WAIT_L(n) asm volatile("s_waitcnt lgkmcnt(" #n ")" ::: "memory")
; #define PG8_BAR __builtin_amdgcn_s_barrier()
; #define PG8_SCHED __builtin_amdgcn_sched_barrier(0)
; template <class Epi>
; __device__ __forceinline__ void gemm_phase(LAS unsigned char* lds, const Gemm g, const StaticOrder& S, const Epi& E) {
;     ...
;             PG8_LDB(B0, 0, 0); PG8_SCHED; PG8_LDA(At, 0, 0); PG8_STAGE(PG8_SA(1, 1), a1 + hstep, voffA);
;             PG8_WAIT_L(8); PG8_BAR; PG8_WAIT_L(0); PG8_MMA(0, 0, At, B0); PG8_BAR; PG8_SCHED;
;             PG8_LDB(B1, 0, 1); PG8_STAGE(PG8_SB(0, 0), b2, voffB0);
;             PG8_BAR; PG8_WAIT_L(0); PG8_MMA(0, 1, At, B1); PG8_BAR;
;             PG8_LDA(At, 0, 1); PG8_STAGE(PG8_SA(0, 0), a2, voffA);
;             PG8_BAR; PG8_WAIT_L(0); PG8_MMA(1, 0, At, B0); PG8_BAR; PG8_SCHED;
;             PG8_STAGE(PG8_SB(0, 1), b2, voffB1);
;             PG8_WAIT_V(6); PG8_BAR; PG8_MMA(1, 1, At, B1); PG8_BAR;
.LBB0_806:
	ds_read_b128 v[146:149], v156
	ds_read_b128 v[160:163], v156 offset:1024
	ds_read_b128 v[164:167], v156 offset:2048
	ds_read_b128 v[168:171], v156 offset:3072
	s_add_u32 s33, s50, 0xffe00080
	s_addc_u32 s52, s51, -1
	s_cmpk_eq_i32 s80, 0x7c
	s_cselect_b32 s53, s41, s52
	s_cselect_b32 s52, s75, s33
	s_cselect_b32 s55, s39, s79
	s_cselect_b32 s54, s77, s78
	v_lshl_add_u64 v[150:151], s[50:51], 0, v[140:141]
	s_add_i32 m0, s49, 0xc000
	ds_read_b128 v[172:175], v157
	ds_read_b128 v[176:179], v157 offset:1024
	ds_read_b128 v[180:183], v157 offset:2048
	ds_read_b128 v[184:187], v157 offset:3072
	ds_read_b128 v[188:191], v157 offset:4096
	ds_read_b128 v[192:195], v157 offset:5120
	ds_read_b128 v[196:199], v157 offset:6144
	ds_read_b128 v[204:207], v157 offset:7168
	global_load_lds_dwordx4 v[150:151], off
	v_lshl_add_u64 v[150:151], s[50:51], 0, v[142:143]
	s_add_i32 m0, s49, 0xe000
	s_nop 0
	global_load_lds_dwordx4 v[150:151], off
	s_waitcnt lgkmcnt(8)
	s_barrier
	s_waitcnt lgkmcnt(0)
	v_mfma_f32_16x16x32_bf16 v[124:127], v[146:149], v[172:175], v[124:127]
	v_mfma_f32_16x16x32_bf16 v[120:123], v[164:167], v[172:175], v[120:123]
	v_mfma_f32_16x16x32_bf16 v[108:111], v[146:149], v[180:183], v[108:111]
	v_mfma_f32_16x16x32_bf16 v[104:107], v[164:167], v[180:183], v[104:107]
	v_mfma_f32_16x16x32_bf16 v[92:95], v[146:149], v[188:191], v[92:95]
	v_mfma_f32_16x16x32_bf16 v[88:91], v[164:167], v[188:191], v[88:91]
	v_mfma_f32_16x16x32_bf16 v[76:79], v[146:149], v[196:199], v[76:79]
	v_mfma_f32_16x16x32_bf16 v[72:75], v[164:167], v[196:199], v[72:75]
	v_mfma_f32_16x16x32_bf16 v[124:127], v[160:163], v[176:179], v[124:127]
	v_mfma_f32_16x16x32_bf16 v[120:123], v[168:171], v[176:179], v[120:123]
	v_mfma_f32_16x16x32_bf16 v[108:111], v[160:163], v[184:187], v[108:111]
	v_mfma_f32_16x16x32_bf16 v[104:107], v[168:171], v[184:187], v[104:107]
	v_mfma_f32_16x16x32_bf16 v[92:95], v[160:163], v[192:195], v[92:95]
	v_mfma_f32_16x16x32_bf16 v[88:91], v[168:171], v[192:195], v[88:91]
	v_mfma_f32_16x16x32_bf16 v[76:79], v[160:163], v[204:207], v[76:79]
	v_mfma_f32_16x16x32_bf16 v[72:75], v[168:171], v[204:207], v[72:75]
	s_barrier
	s_add_i32 s33, s72, s62
	v_lshl_add_u64 v[150:151], s[54:55], 0, v[130:131]
	s_mov_b32 m0, s33
	ds_read_b128 v[208:211], v158
	ds_read_b128 v[212:215], v158 offset:1024
	ds_read_b128 v[216:219], v158 offset:2048
	ds_read_b128 v[220:223], v158 offset:3072
	global_load_lds_dwordx4 v[150:151], off
	v_lshl_add_u64 v[200:201], s[54:55], 0, v[136:137]
	s_add_i32 m0, s33, 0x2000
	s_nop 0
	global_load_lds_dwordx4 v[200:201], off
	s_waitcnt lgkmcnt(0)
	s_barrier
	s_waitcnt lgkmcnt(0)
	v_mfma_f32_16x16x32_bf16 v[116:119], v[208:211], v[172:175], v[116:119]
	v_mfma_f32_16x16x32_bf16 v[112:115], v[216:219], v[172:175], v[112:115]
	v_mfma_f32_16x16x32_bf16 v[100:103], v[208:211], v[180:183], v[100:103]
	v_mfma_f32_16x16x32_bf16 v[96:99], v[216:219], v[180:183], v[96:99]
	v_mfma_f32_16x16x32_bf16 v[84:87], v[208:211], v[188:191], v[84:87]
	v_mfma_f32_16x16x32_bf16 v[80:83], v[216:219], v[188:191], v[80:83]
	v_mfma_f32_16x16x32_bf16 v[68:71], v[208:211], v[196:199], v[68:71]
	v_mfma_f32_16x16x32_bf16 v[64:67], v[216:219], v[196:199], v[64:67]
	v_mfma_f32_16x16x32_bf16 v[116:119], v[212:215], v[176:179], v[116:119]
	v_mfma_f32_16x16x32_bf16 v[112:115], v[220:223], v[176:179], v[112:115]
	v_mfma_f32_16x16x32_bf16 v[100:103], v[212:215], v[184:187], v[100:103]
	v_mfma_f32_16x16x32_bf16 v[96:99], v[220:223], v[184:187], v[96:99]
	v_mfma_f32_16x16x32_bf16 v[84:87], v[212:215], v[192:195], v[84:87]
	v_mfma_f32_16x16x32_bf16 v[80:83], v[220:223], v[192:195], v[80:83]
	v_mfma_f32_16x16x32_bf16 v[68:71], v[212:215], v[204:207], v[68:71]
	v_mfma_f32_16x16x32_bf16 v[64:67], v[220:223], v[204:207], v[64:67]
	s_mov_b32 m0, s49
	v_lshl_add_u64 v[224:225], s[52:53], 0, v[128:129]
	s_barrier
	ds_read_b128 v[172:175], v157 offset:16384
	ds_read_b128 v[176:179], v157 offset:17408
	ds_read_b128 v[180:183], v157 offset:18432
	ds_read_b128 v[184:187], v157 offset:19456
	ds_read_b128 v[188:191], v157 offset:20480
	ds_read_b128 v[192:195], v157 offset:21504
	ds_read_b128 v[196:199], v157 offset:22528
	ds_read_b128 v[204:207], v157 offset:23552
	global_load_lds_dwordx4 v[224:225], off
	v_lshl_add_u64 v[226:227], s[52:53], 0, v[134:135]
	s_mov_b32 m0, s63
	s_nop 0
	global_load_lds_dwordx4 v[226:227], off
	s_add_i32 s33, s73, s62
	v_lshl_add_u64 v[228:229], s[54:55], 0, v[132:133]
	s_mov_b32 m0, s33
	v_lshl_add_u64 v[230:231], s[54:55], 0, v[138:139]
	global_load_lds_dwordx4 v[228:229], off
	s_add_i32 m0, s33, 0x2000
	s_nop 0
	global_load_lds_dwordx4 v[230:231], off
	s_waitcnt vmcnt(6)
	s_barrier
; #define PG8_STAGE(bufoff, gbase, voff) do { _Pragma("unroll") for (int _i = 0; _i < 2; ++_i) \
;         __builtin_amdgcn_global_load_lds((const unsigned*)((const char*)(gbase) + (voff)[_i]), (LAS unsigned*)(lds + (bufoff) + ldsw + _i * 8192), 16, 0, 0); } while (0)
; #define PG8_LDA(dst, b, h) do { _Pragma("unroll") for (int m = 0; m < 4; ++m) _Pragma("unroll") for (int k = 0; k < 2; ++k) dst[m][k] = *(const LAS bf16x8*)(lds + PG8_SA(b, h) + aoff + m * 2048 + k * 1024); } while (0)
; #define PG8_LDB(dst, b, h) do { _Pragma("unroll") for (int n = 0; n < 2; ++n) _Pragma("unroll") for (int k = 0; k < 2; ++k) dst[n][k] = *(const LAS bf16x8*)(lds + PG8_SB(b, h) + boff + n * 2048 + k * 1024); } while (0)
; #define PG8_MMA(ai, bj, At, Bt) do { __builtin_amdgcn_s_setprio(1); _Pragma("unroll") for (int m = 0; m < 4; ++m) _Pragma("unroll") for (int n = 0; n < 2; ++n) _Pragma("unroll") for (int k = 0; k < 2; ++k) \
;         acc[ai][bj][m][n] = __builtin_amdgcn_mfma_f32_16x16x32_bf16(Bt[n][k], At[m][k], acc[ai][bj][m][n], 0, 0, 0); __builtin_amdgcn_s_setprio(0); } while (0)
; #define PG8_WAIT_V(n) asm volatile("s_waitcnt vmcnt(" #n ")" ::: "memory")
; #define PG8_WAIT_L(n) asm volatile("s_waitcnt lgkmcnt(" #n ")" ::: "memory")
; #define PG8_BAR __builtin_amdgcn_s_barrier()
; #define PG8_SCHED __builtin_amdgcn_sched_barrier(0)
; template <class Epi>
; __device__ __forceinline__ void gemm_phase(LAS unsigned char* lds, const Gemm g, const StaticOrder& S, const Epi& E) {
;     ...
;             PG8_BAR; PG8_WAIT_L(0); PG8_MMA(1, 0, At, B0); PG8_BAR; PG8_SCHED;
;             PG8_STAGE(PG8_SB(0, 1), b2, voffB1);
;             PG8_WAIT_V(6); PG8_BAR; PG8_MMA(1, 1, At, B1); PG8_BAR;
;             PG8_LDB(B0, 1, 0); PG8_SCHED; PG8_LDA(At, 1, 0); PG8_STAGE(PG8_SA(0, 1), a2 + hstep, voffA);
;             PG8_WAIT_L(8); PG8_BAR; PG8_WAIT_L(0); PG8_MMA(0, 0, At, B0); PG8_BAR; PG8_SCHED;
;             PG8_LDB(B1, 1, 1); PG8_STAGE(PG8_SB(1, 0), b3, voffB0);
;             PG8_BAR; PG8_WAIT_L(0); PG8_MMA(0, 1, At, B1); PG8_BAR;
	s_waitcnt lgkmcnt(0)
	v_mfma_f32_16x16x32_bf16 v[60:63], v[146:149], v[172:175], v[60:63]
	v_mfma_f32_16x16x32_bf16 v[56:59], v[164:167], v[172:175], v[56:59]
	v_mfma_f32_16x16x32_bf16 v[44:47], v[146:149], v[180:183], v[44:47]
	v_mfma_f32_16x16x32_bf16 v[40:43], v[164:167], v[180:183], v[40:43]
	v_mfma_f32_16x16x32_bf16 v[28:31], v[146:149], v[188:191], v[28:31]
	v_mfma_f32_16x16x32_bf16 v[24:27], v[164:167], v[188:191], v[24:27]
	v_mfma_f32_16x16x32_bf16 v[12:15], v[146:149], v[196:199], v[12:15]
	v_mfma_f32_16x16x32_bf16 v[8:11], v[164:167], v[196:199], v[8:11]
	v_mfma_f32_16x16x32_bf16 v[60:63], v[160:163], v[176:179], v[60:63]
	v_mfma_f32_16x16x32_bf16 v[56:59], v[168:171], v[176:179], v[56:59]
	v_mfma_f32_16x16x32_bf16 v[44:47], v[160:163], v[184:187], v[44:47]
	v_mfma_f32_16x16x32_bf16 v[40:43], v[168:171], v[184:187], v[40:43]
	v_mfma_f32_16x16x32_bf16 v[28:31], v[160:163], v[192:195], v[28:31]
	v_mfma_f32_16x16x32_bf16 v[24:27], v[168:171], v[192:195], v[24:27]
	v_mfma_f32_16x16x32_bf16 v[12:15], v[160:163], v[204:207], v[12:15]
	v_mfma_f32_16x16x32_bf16 v[8:11], v[168:171], v[204:207], v[8:11]
	v_mfma_f32_16x16x32_bf16 v[52:55], v[208:211], v[172:175], v[52:55]
	v_mfma_f32_16x16x32_bf16 v[48:51], v[216:219], v[172:175], v[48:51]
	v_mfma_f32_16x16x32_bf16 v[36:39], v[208:211], v[180:183], v[36:39]
	v_mfma_f32_16x16x32_bf16 v[32:35], v[216:219], v[180:183], v[32:35]
	v_mfma_f32_16x16x32_bf16 v[20:23], v[208:211], v[188:191], v[20:23]
	v_mfma_f32_16x16x32_bf16 v[16:19], v[216:219], v[188:191], v[16:19]
	v_mfma_f32_16x16x32_bf16 v[4:7], v[208:211], v[196:199], v[4:7]
	v_mfma_f32_16x16x32_bf16 v[0:3], v[216:219], v[196:199], v[0:3]
	v_mfma_f32_16x16x32_bf16 v[52:55], v[212:215], v[176:179], v[52:55]
	v_mfma_f32_16x16x32_bf16 v[48:51], v[220:223], v[176:179], v[48:51]
	v_mfma_f32_16x16x32_bf16 v[36:39], v[212:215], v[184:187], v[36:39]
	v_mfma_f32_16x16x32_bf16 v[32:35], v[220:223], v[184:187], v[32:35]
	v_mfma_f32_16x16x32_bf16 v[20:23], v[212:215], v[192:195], v[20:23]
	v_mfma_f32_16x16x32_bf16 v[16:19], v[220:223], v[192:195], v[16:19]
	v_mfma_f32_16x16x32_bf16 v[4:7], v[212:215], v[204:207], v[4:7]
	v_mfma_f32_16x16x32_bf16 v[0:3], v[220:223], v[204:207], v[0:3]
	s_add_i32 s33, 0, 0x18000
	v_add_u32_e32 v168, s33, v153
	s_barrier
	ds_read_b128 v[146:149], v168
	ds_read_b128 v[160:163], v168 offset:1024
	ds_read_b128 v[164:167], v168 offset:2048
	ds_read_b128 v[168:171], v168 offset:3072
	s_add_u32 s52, s52, 0x200000
	s_addc_u32 s53, s53, 0
	s_mov_b32 m0, s64
	v_lshl_add_u64 v[208:209], s[52:53], 0, v[128:129]
	ds_read_b128 v[172:175], v157 offset:32768
	ds_read_b128 v[176:179], v157 offset:33792
	ds_read_b128 v[180:183], v157 offset:34816
	ds_read_b128 v[184:187], v157 offset:35840
	ds_read_b128 v[188:191], v157 offset:36864
	ds_read_b128 v[192:195], v157 offset:37888
	ds_read_b128 v[196:199], v157 offset:38912
	ds_read_b128 v[204:207], v157 offset:39936
	global_load_lds_dwordx4 v[208:209], off
	v_lshl_add_u64 v[208:209], s[52:53], 0, v[134:135]
	s_mov_b32 m0, s65
	s_nop 0
	global_load_lds_dwordx4 v[208:209], off
	s_waitcnt lgkmcnt(8)
	s_barrier
	s_waitcnt lgkmcnt(0)
	v_mfma_f32_16x16x32_bf16 v[124:127], v[146:149], v[172:175], v[124:127]
	v_mfma_f32_16x16x32_bf16 v[120:123], v[164:167], v[172:175], v[120:123]
	v_mfma_f32_16x16x32_bf16 v[108:111], v[146:149], v[180:183], v[108:111]
	v_mfma_f32_16x16x32_bf16 v[104:107], v[164:167], v[180:183], v[104:107]
	v_mfma_f32_16x16x32_bf16 v[92:95], v[146:149], v[188:191], v[92:95]
	v_mfma_f32_16x16x32_bf16 v[88:91], v[164:167], v[188:191], v[88:91]
	v_mfma_f32_16x16x32_bf16 v[76:79], v[146:149], v[196:199], v[76:79]
	v_mfma_f32_16x16x32_bf16 v[72:75], v[164:167], v[196:199], v[72:75]
	v_mfma_f32_16x16x32_bf16 v[124:127], v[160:163], v[176:179], v[124:127]
	v_mfma_f32_16x16x32_bf16 v[120:123], v[168:171], v[176:179], v[120:123]
	v_mfma_f32_16x16x32_bf16 v[108:111], v[160:163], v[184:187], v[108:111]
	v_mfma_f32_16x16x32_bf16 v[104:107], v[168:171], v[184:187], v[104:107]
	v_mfma_f32_16x16x32_bf16 v[92:95], v[160:163], v[192:195], v[92:95]
	v_mfma_f32_16x16x32_bf16 v[88:91], v[168:171], v[192:195], v[88:91]
	v_mfma_f32_16x16x32_bf16 v[76:79], v[160:163], v[204:207], v[76:79]
	v_mfma_f32_16x16x32_bf16 v[72:75], v[168:171], v[204:207], v[72:75]
	s_barrier
	s_add_i32 s52, 0, 0x1c000
	s_add_i32 s33, s33, s62
	v_add_u32_e32 v220, s52, v153
	v_lshl_add_u64 v[150:151], v[150:151], 0, s[18:19]
	s_mov_b32 m0, s33
	ds_read_b128 v[208:211], v220
	ds_read_b128 v[212:215], v220 offset:1024
	ds_read_b128 v[216:219], v220 offset:2048
	ds_read_b128 v[220:223], v220 offset:3072
	global_load_lds_dwordx4 v[150:151], off
	v_lshl_add_u64 v[150:151], v[200:201], 0, s[18:19]
	s_add_i32 m0, s33, 0x2000
	s_nop 0
	global_load_lds_dwordx4 v[150:151], off
	s_waitcnt lgkmcnt(0)
	s_barrier
	s_waitcnt lgkmcnt(0)
	v_mfma_f32_16x16x32_bf16 v[116:119], v[208:211], v[172:175], v[116:119]
	v_mfma_f32_16x16x32_bf16 v[112:115], v[216:219], v[172:175], v[112:115]
	v_mfma_f32_16x16x32_bf16 v[100:103], v[208:211], v[180:183], v[100:103]
	v_mfma_f32_16x16x32_bf16 v[96:99], v[216:219], v[180:183], v[96:99]
	v_mfma_f32_16x16x32_bf16 v[84:87], v[208:211], v[188:191], v[84:87]
	v_mfma_f32_16x16x32_bf16 v[80:83], v[216:219], v[188:191], v[80:83]
	v_mfma_f32_16x16x32_bf16 v[68:71], v[208:211], v[196:199], v[68:71]
	v_mfma_f32_16x16x32_bf16 v[64:67], v[216:219], v[196:199], v[64:67]
	v_mfma_f32_16x16x32_bf16 v[116:119], v[212:215], v[176:179], v[116:119]
	v_mfma_f32_16x16x32_bf16 v[112:115], v[220:223], v[176:179], v[112:115]
	v_mfma_f32_16x16x32_bf16 v[100:103], v[212:215], v[184:187], v[100:103]
	v_mfma_f32_16x16x32_bf16 v[96:99], v[220:223], v[184:187], v[96:99]
	v_mfma_f32_16x16x32_bf16 v[84:87], v[212:215], v[192:195], v[84:87]
	v_mfma_f32_16x16x32_bf16 v[80:83], v[220:223], v[192:195], v[80:83]
	v_mfma_f32_16x16x32_bf16 v[68:71], v[212:215], v[204:207], v[68:71]
	v_mfma_f32_16x16x32_bf16 v[64:67], v[220:223], v[204:207], v[64:67]
	s_mov_b32 m0, s67
	v_lshl_add_u64 v[150:151], v[224:225], 0, s[18:19]
	s_barrier
; #define PG8_STAGE(bufoff, gbase, voff) do { _Pragma("unroll") for (int _i = 0; _i < 2; ++_i) \
;         __builtin_amdgcn_global_load_lds((const unsigned*)((const char*)(gbase) + (voff)[_i]), (LAS unsigned*)(lds + (bufoff) + ldsw + _i * 8192), 16, 0, 0); } while (0)
; #define PG8_LDA(dst, b, h) do { _Pragma("unroll") for (int m = 0; m < 4; ++m) _Pragma("unroll") for (int k = 0; k < 2; ++k) dst[m][k] = *(const LAS bf16x8*)(lds + PG8_SA(b, h) + aoff + m * 2048 + k * 1024); } while (0)
; #define PG8_MMA(ai, bj, At, Bt) do { __builtin_amdgcn_s_setprio(1); _Pragma("unroll") for (int m = 0; m < 4; ++m) _Pragma("unroll") for (int n = 0; n < 2; ++n) _Pragma("unroll") for (int k = 0; k < 2; ++k) \
;         acc[ai][bj][m][n] = __builtin_amdgcn_mfma_f32_16x16x32_bf16(Bt[n][k], At[m][k], acc[ai][bj][m][n], 0, 0, 0); __builtin_amdgcn_s_setprio(0); } while (0)
; #define PG8_WAIT_V(n) asm volatile("s_waitcnt vmcnt(" #n ")" ::: "memory")
; #define PG8_WAIT_L(n) asm volatile("s_waitcnt lgkmcnt(" #n ")" ::: "memory")
; #define PG8_BAR __builtin_amdgcn_s_barrier()
; #define PG8_SCHED __builtin_amdgcn_sched_barrier(0)
;     __device__ __forceinline__ void operator()(const f32x4 (&acc)[2][2][4][2], const Unit& u, int wr, int wc, int fr, int fq) const {
;         const int row0 = u.pm * BM + wr * 64 + fr, col0 = u.pn * BM + wc * 64 + 16 * fq;
; #pragma unroll
;         for (int ai = 0; ai < 2; ++ai)
; #pragma unroll
;             for (int m = 0; m < 4; ++m) { const int row = row0 + ai * HALF + m * 16; const size_t off = (size_t)row * D + col0; float sq = 0.f; u32x4 w[2];
;                 const float sc = rsin ? __builtin_amdgcn_rcpf(rsin[row] * (1.f / D) + EPS) : 1.0f;
;                 u32x4 rr[2]; if (R) load_pair_lines(R, D, row, fr, col0, rr[0], rr[1]);
; template <class Epi>
; __device__ __forceinline__ void gemm_phase(LAS unsigned char* lds, const Gemm g, const StaticOrder& S, const Epi& E) {
;     ...
;             PG8_LDA(At, 1, 1); PG8_STAGE(PG8_SA(1, 0), a3, voffA);
;             PG8_BAR; PG8_WAIT_L(0); PG8_MMA(1, 0, At, B0); PG8_BAR; PG8_SCHED;
;             PG8_STAGE(PG8_SB(1, 1), b3, voffB1);
;             PG8_WAIT_V(6); PG8_BAR; PG8_MMA(1, 1, At, B1); PG8_BAR;
	ds_read_b128 v[172:175], v157 offset:49152
	ds_read_b128 v[176:179], v157 offset:50176
	ds_read_b128 v[180:183], v157 offset:51200
	ds_read_b128 v[184:187], v157 offset:52224
	ds_read_b128 v[188:191], v157 offset:53248
	ds_read_b128 v[192:195], v157 offset:54272
	ds_read_b128 v[196:199], v157 offset:55296
	ds_read_b128 v[204:207], v157 offset:56320
	global_load_lds_dwordx4 v[150:151], off
	v_lshl_add_u64 v[150:151], v[226:227], 0, s[18:19]
	s_mov_b32 m0, s68
	s_nop 0
	global_load_lds_dwordx4 v[150:151], off
	s_add_i32 s33, s52, s62
	v_lshl_add_u64 v[250:251], v[228:229], 0, s[18:19]
	s_mov_b32 m0, s33
	s_nop 0
	global_load_lds_dwordx4 v[250:251], off
	v_lshl_add_u64 v[250:251], v[230:231], 0, s[18:19]
	s_add_i32 m0, s33, 0x2000
	s_nop 0
	global_load_lds_dwordx4 v[250:251], off
	s_waitcnt vmcnt(6)
	s_barrier
	s_waitcnt lgkmcnt(0)
	v_mfma_f32_16x16x32_bf16 v[60:63], v[146:149], v[172:175], v[60:63]
	v_mfma_f32_16x16x32_bf16 v[56:59], v[164:167], v[172:175], v[56:59]
	v_mfma_f32_16x16x32_bf16 v[44:47], v[146:149], v[180:183], v[44:47]
	v_mfma_f32_16x16x32_bf16 v[40:43], v[164:167], v[180:183], v[40:43]
	v_mfma_f32_16x16x32_bf16 v[28:31], v[146:149], v[188:191], v[28:31]
	v_mfma_f32_16x16x32_bf16 v[24:27], v[164:167], v[188:191], v[24:27]
	v_mfma_f32_16x16x32_bf16 v[12:15], v[146:149], v[196:199], v[12:15]
	v_mfma_f32_16x16x32_bf16 v[8:11], v[164:167], v[196:199], v[8:11]
	v_mfma_f32_16x16x32_bf16 v[60:63], v[160:163], v[176:179], v[60:63]
	v_mfma_f32_16x16x32_bf16 v[56:59], v[168:171], v[176:179], v[56:59]
	v_mfma_f32_16x16x32_bf16 v[44:47], v[160:163], v[184:187], v[44:47]
	v_mfma_f32_16x16x32_bf16 v[40:43], v[168:171], v[184:187], v[40:43]
	v_mfma_f32_16x16x32_bf16 v[28:31], v[160:163], v[192:195], v[28:31]
	v_mfma_f32_16x16x32_bf16 v[24:27], v[168:171], v[192:195], v[24:27]
	v_mfma_f32_16x16x32_bf16 v[12:15], v[160:163], v[204:207], v[12:15]
	v_mfma_f32_16x16x32_bf16 v[8:11], v[168:171], v[204:207], v[8:11]
	v_mfma_f32_16x16x32_bf16 v[52:55], v[208:211], v[172:175], v[52:55]
	v_mfma_f32_16x16x32_bf16 v[48:51], v[216:219], v[172:175], v[48:51]
	v_mfma_f32_16x16x32_bf16 v[36:39], v[208:211], v[180:183], v[36:39]
	v_mfma_f32_16x16x32_bf16 v[32:35], v[216:219], v[180:183], v[32:35]
	v_mfma_f32_16x16x32_bf16 v[20:23], v[208:211], v[188:191], v[20:23]
	v_mfma_f32_16x16x32_bf16 v[16:19], v[216:219], v[188:191], v[16:19]
	v_mfma_f32_16x16x32_bf16 v[4:7], v[208:211], v[196:199], v[4:7]
	v_mfma_f32_16x16x32_bf16 v[0:3], v[216:219], v[196:199], v[0:3]
	v_mfma_f32_16x16x32_bf16 v[52:55], v[212:215], v[176:179], v[52:55]
	v_mfma_f32_16x16x32_bf16 v[48:51], v[220:223], v[176:179], v[48:51]
	v_mfma_f32_16x16x32_bf16 v[36:39], v[212:215], v[184:187], v[36:39]
	v_mfma_f32_16x16x32_bf16 v[32:35], v[220:223], v[184:187], v[32:35]
	v_mfma_f32_16x16x32_bf16 v[20:23], v[212:215], v[192:195], v[20:23]
	v_mfma_f32_16x16x32_bf16 v[16:19], v[220:223], v[192:195], v[16:19]
	v_mfma_f32_16x16x32_bf16 v[4:7], v[212:215], v[204:207], v[4:7]
	v_mfma_f32_16x16x32_bf16 v[0:3], v[220:223], v[204:207], v[0:3]
	s_add_i32 s80, s80, 2
	s_add_u32 s50, s50, 0x100
	s_addc_u32 s51, s51, 0
	s_add_u32 s78, s78, 0x100
	s_addc_u32 s79, s79, 0
	s_cmpk_gt_u32 s80, 0x7d
	s_barrier
	s_cbranch_scc0 .LBB0_806
	s_lshl_b32 s33, s48, 8
	s_add_i32 s33, s33, s69
	v_or_b32_e32 v164, s33, v154
	v_ashrrev_i32_e32 v165, 31, v164
	v_lshl_or_b32 v146, s74, 8, v155
	v_lshlrev_b64 v[168:169], 12, v[164:165]
	v_or_b32_e32 v164, 8, v164
	v_or_b32_e32 v150, s33, v152
	v_ashrrev_i32_e32 v147, 31, v146
	v_ashrrev_i32_e32 v165, 31, v164
	v_ashrrev_i32_e32 v151, 31, v150
	v_lshl_add_u64 v[160:161], s[16:17], 0, v[168:169]
	v_lshlrev_b64 v[146:147], 1, v[146:147]
	v_lshlrev_b64 v[170:171], 12, v[164:165]
	v_lshl_add_u64 v[148:149], v[150:151], 2, s[10:11]
	v_lshl_add_u64 v[160:161], v[160:161], 0, v[146:147]
	v_lshl_add_u64 v[164:165], s[16:17], 0, v[170:171]
	global_load_dword v151, v[148:149], off
	s_nop 0
	global_load_dwordx4 v[160:163], v[160:161], off
	v_lshl_add_u64 v[164:165], v[164:165], 0, v[146:147]
	global_load_dwordx4 v[164:167], v[164:165], off
	v_or_b32_e32 v190, 16, v150
	v_ashrrev_i32_e32 v191, 31, v190
	v_lshl_add_u64 v[192:193], v[190:191], 2, s[10:11]
	v_sub_u32_e32 v190, v190, v152
	v_add_u32_e32 v190, v190, v154
	v_ashrrev_i32_e32 v191, 31, v190
	v_lshlrev_b64 v[196:197], 12, v[190:191]
	v_lshl_add_u64 v[190:191], s[16:17], 0, v[196:197]
	v_lshl_add_u64 v[198:199], v[196:197], 0, s[36:37]
	v_lshl_add_u64 v[190:191], v[190:191], 0, v[146:147]
	v_lshl_add_u64 v[194:195], s[16:17], 0, v[198:199]
	global_load_dword v204, v[192:193], off
	global_load_dwordx4 v[208:211], v[190:191], off
	v_lshl_add_u64 v[194:195], v[194:195], 0, v[146:147]
	global_load_dwordx4 v[212:215], v[194:195], off
	v_or_b32_e32 v190, 32, v150
	v_ashrrev_i32_e32 v191, 31, v190
	v_lshl_add_u64 v[192:193], v[190:191], 2, s[10:11]
	v_sub_u32_e32 v190, v190, v152
	v_add_u32_e32 v190, v190, v154
	v_ashrrev_i32_e32 v191, 31, v190
	v_lshlrev_b64 v[196:197], 12, v[190:191]
	v_lshl_add_u64 v[190:191], s[16:17], 0, v[196:197]
	v_lshl_add_u64 v[198:199], v[196:197], 0, s[36:37]
	v_lshl_add_u64 v[190:191], v[190:191], 0, v[146:147]
	v_lshl_add_u64 v[194:195], s[16:17], 0, v[198:199]
	global_load_dword v205, v[192:193], off
	global_load_dwordx4 v[216:219], v[190:191], off
	v_lshl_add_u64 v[194:195], v[194:195], 0, v[146:147]
	global_load_dwordx4 v[220:223], v[194:195], off
	v_or_b32_e32 v190, 48, v150
	v_ashrrev_i32_e32 v191, 31, v190
	v_lshl_add_u64 v[192:193], v[190:191], 2, s[10:11]
	v_sub_u32_e32 v190, v190, v152
	v_add_u32_e32 v190, v190, v154
	v_ashrrev_i32_e32 v191, 31, v190
	v_lshlrev_b64 v[196:197], 12, v[190:191]
; __device__ __forceinline__ void store_pair_lines(bf16_t* O, int ldc, int row, int fr, int col0, u32x4 wA, u32x4 wB) {
;     const u32x4 sA = {dpp_ror8(wA.x), dpp_ror8(wA.y), dpp_ror8(wA.z), dpp_ror8(wA.w)}, sB = {dpp_ror8(wB.x), dpp_ror8(wB.y), dpp_ror8(wB.z), dpp_ror8(wB.w)};
;     const bool lo = fr < 8;
;     const u32x4 o1 = lo ? wA : sB, o2 = lo ? sA : wB;
;     const int r1 = row - fr + (fr & 7), cb = col0 + (lo ? 0 : 8);
;     *(u32x4*)(O + (size_t)r1 * ldc + cb) = o1;
;     *(u32x4*)(O + (size_t)(r1 + 8) * ldc + cb) = o2;
; }
;     const bool lo = fr < 8;
;     const int r1 = row - fr + (fr & 7), cb = col0 + (lo ? 0 : boff);
;     const u32x4 l1 = *(const u32x4*)(P + (size_t)r1 * ld + cb), l2 = *(const u32x4*)(P + (size_t)(r1 + 8) * ld + cb);
;     const u32x4 s1 = {dpp_ror8(l1.x), dpp_ror8(l1.y), dpp_ror8(l1.z), dpp_ror8(l1.w)}, s2 = {dpp_ror8(l2.x), dpp_ror8(l2.y), dpp_ror8(l2.z), dpp_ror8(l2.w)};
;     wA = lo ? l1 : s2; wB = lo ? s1 : l2;
;     __device__ __forceinline__ void operator()(const f32x4 (&acc)[2][2][4][2], const Unit& u, int wr, int wc, int fr, int fq) const {
;     ...
;             for (int m = 0; m < 4; ++m) { const int row = row0 + ai * HALF + m * 16; const size_t off = (size_t)row * D + col0; float sq = 0.f; u32x4 w[2];
;                 const float sc = rsin ? __builtin_amdgcn_rcpf(rsin[row] * (1.f / D) + EPS) : 1.0f;
;                 u32x4 rr[2]; if (R) load_pair_lines(R, D, row, fr, col0, rr[0], rr[1]);
; #pragma unroll
;                 for (int bj = 0; bj < 2; ++bj) { f32x4 r0, r1;
;                     if (R) { const u32x4 rw = rr[bj]; r0 = (f32x4){bflo(rw.x), bfhi(rw.x), bflo(rw.y), bfhi(rw.y)}; r1 = (f32x4){bflo(rw.z), bfhi(rw.z), bflo(rw.w), bfhi(rw.w)}; }
;                     else { const float* rp = (row < 8192 ? src_p + off : src_s + (off - (size_t)8192 * D)) + 8 * bj; r0 = *(const f32x4*)rp; r1 = *(const f32x4*)(rp + 4); }
;                     const f32x4 o0 = r0 + acc[ai][bj][m][0] * sc, o1 = r1 + acc[ai][bj][m][1] * sc;
;                     sq += (o0[0] * o0[0] + o0[1] * o0[1]) + (o0[2] * o0[2] + o0[3] * o0[3]) + (o1[0] * o1[0] + o1[1] * o1[1]) + (o1[2] * o1[2] + o1[3] * o1[3]);
;                     w[bj].x = cvt_pk_bf16(o0[0], o0[1]); w[bj].y = cvt_pk_bf16(o0[2], o0[3]); w[bj].z = cvt_pk_bf16(o1[0], o1[1]); w[bj].w = cvt_pk_bf16(o1[2], o1[3]); }
;                 store_pair_lines(O, D, row, fr, col0, w[0], w[1]);
	v_lshl_add_u64 v[190:191], s[16:17], 0, v[196:197]
	v_lshl_add_u64 v[198:199], v[196:197], 0, s[36:37]
	v_lshl_add_u64 v[190:191], v[190:191], 0, v[146:147]
	v_lshl_add_u64 v[194:195], s[16:17], 0, v[198:199]
	global_load_dword v206, v[192:193], off
	global_load_dwordx4 v[224:227], v[190:191], off
	v_lshl_add_u64 v[194:195], v[194:195], 0, v[146:147]
	global_load_dwordx4 v[228:231], v[194:195], off
	v_sub_u32_e32 v190, v150, v152
	v_add_u32_e32 v199, v190, v154
	v_add_u32_e32 v190, 0x80, v199
	v_ashrrev_i32_e32 v191, 31, v190
	v_lshlrev_b64 v[194:195], 12, v[190:191]
	v_lshl_add_u64 v[190:191], s[16:17], 0, v[194:195]
	v_lshl_add_u64 v[196:197], v[194:195], 0, s[36:37]
	v_lshl_add_u64 v[190:191], v[190:191], 0, v[146:147]
	v_lshl_add_u64 v[192:193], s[16:17], 0, v[196:197]
	global_load_dword v207, v[148:149], off offset:512
	global_load_dwordx4 v[232:235], v[190:191], off
	v_lshl_add_u64 v[192:193], v[192:193], 0, v[146:147]
	global_load_dwordx4 v[236:239], v[192:193], off
	v_sub_u32_e32 v198, v150, v152
	v_add_u32_e32 v201, v198, v154
	v_add_u32_e32 v190, 0x90, v201
	v_ashrrev_i32_e32 v191, 31, v190
	v_lshlrev_b64 v[194:195], 12, v[190:191]
	v_lshl_add_u64 v[190:191], s[16:17], 0, v[194:195]
	v_lshl_add_u64 v[196:197], v[194:195], 0, s[36:37]
	v_lshl_add_u64 v[190:191], v[190:191], 0, v[146:147]
	v_lshl_add_u64 v[192:193], s[16:17], 0, v[196:197]
	global_load_dword v240, v[148:149], off offset:576
	global_load_dwordx4 v[244:247], v[190:191], off
	v_lshl_add_u64 v[192:193], v[192:193], 0, v[146:147]
	global_load_dwordx4 v[248:251], v[192:193], off
	s_and_b64 vcc, exec, s[44:45]
	s_mov_b32 s74, s38
	s_mov_b32 s48, s40
	s_mov_b64 s[52:53], s[46:47]
	s_mov_b64 s[50:51], s[42:43]
	s_waitcnt vmcnt(15)
	v_fmamk_f32 v151, v151, 0x3a000000, v159
	v_rcp_f32_e32 v172, v151
	v_mov_b32_dpp v173, v160 row_ror:8 row_mask:0xf bank_mask:0xf
	v_mov_b32_dpp v174, v161 row_ror:8 row_mask:0xf bank_mask:0xf
	v_mov_b32_dpp v175, v162 row_ror:8 row_mask:0xf bank_mask:0xf
	v_mov_b32_dpp v177, v164 row_ror:8 row_mask:0xf bank_mask:0xf
	v_mov_b32_dpp v178, v165 row_ror:8 row_mask:0xf bank_mask:0xf
	v_mov_b32_dpp v179, v166 row_ror:8 row_mask:0xf bank_mask:0xf
	v_mov_b32_dpp v176, v163 row_ror:8 row_mask:0xf bank_mask:0xf
	v_mov_b32_dpp v180, v167 row_ror:8 row_mask:0xf bank_mask:0xf
	v_cndmask_b32_e64 v166, v166, v175, s[6:7]
	v_cndmask_b32_e64 v165, v165, v174, s[6:7]
	v_cndmask_b32_e64 v164, v164, v173, s[6:7]
	v_cndmask_b32_e64 v179, v179, v162, s[6:7]
	v_cndmask_b32_e64 v178, v178, v161, s[6:7]
	v_cndmask_b32_e64 v175, v177, v160, s[6:7]
	v_cndmask_b32_e64 v151, v167, v176, s[6:7]
	v_cndmask_b32_e64 v173, v180, v163, s[6:7]
	v_lshlrev_b32_e32 v160, 16, v164
	v_and_b32_e32 v161, 0xffff0000, v164
	v_lshlrev_b32_e32 v162, 16, v165
	v_and_b32_e32 v163, 0xffff0000, v165
	v_lshlrev_b32_e32 v174, 16, v175
	v_and_b32_e32 v175, 0xffff0000, v175
	v_lshlrev_b32_e32 v176, 16, v178
	v_and_b32_e32 v177, 0xffff0000, v178
	v_lshlrev_b32_e32 v178, 16, v179
	v_and_b32_e32 v179, 0xffff0000, v179
	v_lshlrev_b32_e32 v164, 16, v166
	v_and_b32_e32 v165, 0xffff0000, v166
	v_lshlrev_b32_e32 v166, 16, v151
	v_and_b32_e32 v167, 0xffff0000, v151
	v_lshlrev_b32_e32 v180, 16, v173
	v_and_b32_e32 v181, 0xffff0000, v173
	v_pk_fma_f32 v[118:119], v[118:119], v[172:173], v[162:163] op_sel_hi:[1,0,1]
	v_pk_fma_f32 v[116:117], v[116:117], v[172:173], v[160:161] op_sel_hi:[1,0,1]
	v_pk_fma_f32 v[124:125], v[124:125], v[172:173], v[174:175] op_sel_hi:[1,0,1]
	v_pk_fma_f32 v[120:121], v[120:121], v[172:173], v[178:179] op_sel_hi:[1,0,1]
	v_pk_fma_f32 v[114:115], v[114:115], v[172:173], v[166:167] op_sel_hi:[1,0,1]
	v_pk_fma_f32 v[112:113], v[112:113], v[172:173], v[164:165] op_sel_hi:[1,0,1]
	v_pk_fma_f32 v[126:127], v[126:127], v[172:173], v[176:177] op_sel_hi:[1,0,1]
	v_pk_fma_f32 v[122:123], v[122:123], v[172:173], v[180:181] op_sel_hi:[1,0,1]
	v_cvt_pk_bf16_f32 v124, v124, v125
	v_cvt_pk_bf16_f32 v125, v126, v127
	v_cvt_pk_bf16_f32 v120, v120, v121
	v_cvt_pk_bf16_f32 v121, v122, v123
	v_cvt_pk_bf16_f32 v116, v116, v117
	v_cvt_pk_bf16_f32 v117, v118, v119
	v_cvt_pk_bf16_f32 v118, v112, v113
	v_cvt_pk_bf16_f32 v119, v114, v115
	s_nop 0
	v_mov_b32_dpp v184, v120 row_ror:8 row_mask:0xf bank_mask:0xf
	v_mov_b32_dpp v185, v121 row_ror:8 row_mask:0xf bank_mask:0xf
	v_mov_b32_dpp v188, v118 row_ror:8 row_mask:0xf bank_mask:0xf
	v_mov_b32_dpp v189, v119 row_ror:8 row_mask:0xf bank_mask:0xf
	v_mov_b32_dpp v186, v116 row_ror:8 row_mask:0xf bank_mask:0xf
	v_mov_b32_dpp v187, v117 row_ror:8 row_mask:0xf bank_mask:0xf
	v_cndmask_b32_e64 v114, v188, v120, s[6:7]
	v_cndmask_b32_e64 v115, v189, v121, s[6:7]
	v_lshl_add_u64 v[120:121], s[8:9], 0, v[168:169]
	v_cndmask_b32_e64 v112, v186, v124, s[6:7]
	v_cndmask_b32_e64 v113, v187, v125, s[6:7]
	v_lshl_add_u64 v[120:121], v[120:121], 0, v[146:147]
	v_mov_b32_dpp v182, v124 row_ror:8 row_mask:0xf bank_mask:0xf
	v_mov_b32_dpp v183, v125 row_ror:8 row_mask:0xf bank_mask:0xf
	global_store_dwordx4 v[120:121], v[112:115], off
	v_cndmask_b32_e64 v116, v116, v182, s[6:7]
	v_cndmask_b32_e64 v117, v117, v183, s[6:7]
	v_lshl_add_u64 v[112:113], s[8:9], 0, v[170:171]
	v_cndmask_b32_e64 v118, v118, v184, s[6:7]
	v_cndmask_b32_e64 v119, v119, v185, s[6:7]
	v_lshl_add_u64 v[112:113], v[112:113], 0, v[146:147]
	global_store_dwordx4 v[112:113], v[116:119], off
	v_or_b32_e32 v112, 16, v150
	v_ashrrev_i32_e32 v113, 31, v112
	v_lshl_add_u64 v[114:115], v[112:113], 2, s[10:11]
	v_sub_u32_e32 v112, v112, v152
	v_add_u32_e32 v112, v112, v154
	v_ashrrev_i32_e32 v113, 31, v112
	v_lshlrev_b64 v[120:121], 12, v[112:113]
	v_lshl_add_u64 v[112:113], s[16:17], 0, v[120:121]
	v_lshl_add_u64 v[122:123], v[120:121], 0, s[36:37]
	v_lshl_add_u64 v[112:113], v[112:113], 0, v[146:147]
	v_lshl_add_u64 v[116:117], s[16:17], 0, v[122:123]
	s_waitcnt vmcnt(14)
; __device__ __forceinline__ void store_pair_lines(bf16_t* O, int ldc, int row, int fr, int col0, u32x4 wA, u32x4 wB) {
;     const u32x4 sA = {dpp_ror8(wA.x), dpp_ror8(wA.y), dpp_ror8(wA.z), dpp_ror8(wA.w)}, sB = {dpp_ror8(wB.x), dpp_ror8(wB.y), dpp_ror8(wB.z), dpp_ror8(wB.w)};
;     const bool lo = fr < 8;
;     const u32x4 o1 = lo ? wA : sB, o2 = lo ? sA : wB;
;     const int r1 = row - fr + (fr & 7), cb = col0 + (lo ? 0 : 8);
;     *(u32x4*)(O + (size_t)r1 * ldc + cb) = o1;
;     *(u32x4*)(O + (size_t)(r1 + 8) * ldc + cb) = o2;
; }
;     const bool lo = fr < 8;
;     const int r1 = row - fr + (fr & 7), cb = col0 + (lo ? 0 : boff);
;     const u32x4 l1 = *(const u32x4*)(P + (size_t)r1 * ld + cb), l2 = *(const u32x4*)(P + (size_t)(r1 + 8) * ld + cb);
;     const u32x4 s1 = {dpp_ror8(l1.x), dpp_ror8(l1.y), dpp_ror8(l1.z), dpp_ror8(l1.w)}, s2 = {dpp_ror8(l2.x), dpp_ror8(l2.y), dpp_ror8(l2.z), dpp_ror8(l2.w)};
;     wA = lo ? l1 : s2; wB = lo ? s1 : l2;
;     __device__ __forceinline__ void operator()(const f32x4 (&acc)[2][2][4][2], const Unit& u, int wr, int wc, int fr, int fq) const {
;     ...
;             for (int m = 0; m < 4; ++m) { const int row = row0 + ai * HALF + m * 16; const size_t off = (size_t)row * D + col0; float sq = 0.f; u32x4 w[2];
;                 const float sc = rsin ? __builtin_amdgcn_rcpf(rsin[row] * (1.f / D) + EPS) : 1.0f;
;                 u32x4 rr[2]; if (R) load_pair_lines(R, D, row, fr, col0, rr[0], rr[1]);
; #pragma unroll
;                 for (int bj = 0; bj < 2; ++bj) { f32x4 r0, r1;
;                     if (R) { const u32x4 rw = rr[bj]; r0 = (f32x4){bflo(rw.x), bfhi(rw.x), bflo(rw.y), bfhi(rw.y)}; r1 = (f32x4){bflo(rw.z), bfhi(rw.z), bflo(rw.w), bfhi(rw.w)}; }
;                     else { const float* rp = (row < 8192 ? src_p + off : src_s + (off - (size_t)8192 * D)) + 8 * bj; r0 = *(const f32x4*)rp; r1 = *(const f32x4*)(rp + 4); }
;                     const f32x4 o0 = r0 + acc[ai][bj][m][0] * sc, o1 = r1 + acc[ai][bj][m][1] * sc;
;                     sq += (o0[0] * o0[0] + o0[1] * o0[1]) + (o0[2] * o0[2] + o0[3] * o0[3]) + (o1[0] * o1[0] + o1[1] * o1[1]) + (o1[2] * o1[2] + o1[3] * o1[3]);
;                     w[bj].x = cvt_pk_bf16(o0[0], o0[1]); w[bj].y = cvt_pk_bf16(o0[2], o0[3]); w[bj].z = cvt_pk_bf16(o1[0], o1[1]); w[bj].w = cvt_pk_bf16(o1[2], o1[3]); }
;                 store_pair_lines(O, D, row, fr, col0, w[0], w[1]);
	s_nop 0
	v_mov_b32_e32 v124, v204
	s_nop 0
	v_mov_b64_e32 v[112:113], v[208:209]
	v_mov_b64_e32 v[114:115], v[210:211]
	v_lshl_add_u64 v[116:117], v[116:117], 0, v[146:147]
	v_mov_b64_e32 v[116:117], v[212:213]
	v_mov_b64_e32 v[118:119], v[214:215]
	s_nop 1
	v_sub_u32_e32 v198, v150, v152
	v_add_u32_e32 v201, v198, v154
	v_add_u32_e32 v190, 0xa0, v201
	v_ashrrev_i32_e32 v191, 31, v190
	v_lshlrev_b64 v[194:195], 12, v[190:191]
	v_lshl_add_u64 v[196:197], v[194:195], 0, s[36:37]
	global_load_dword v204, v[148:149], off offset:640
	v_lshl_add_u64 v[190:191], s[16:17], 0, v[194:195]
	v_lshl_add_u64 v[192:193], s[16:17], 0, v[196:197]
	v_lshl_add_u64 v[190:191], v[190:191], 0, v[146:147]
	v_lshl_add_u64 v[192:193], v[192:193], 0, v[146:147]
	global_load_dwordx4 v[208:211], v[190:191], off
	global_load_dwordx4 v[212:215], v[192:193], off
	s_waitcnt vmcnt(20)
	v_fmamk_f32 v124, v124, 0x3a000000, v159
	v_rcp_f32_e32 v124, v124
	v_mov_b32_dpp v125, v112 row_ror:8 row_mask:0xf bank_mask:0xf
	v_mov_b32_dpp v126, v113 row_ror:8 row_mask:0xf bank_mask:0xf
	v_mov_b32_dpp v127, v114 row_ror:8 row_mask:0xf bank_mask:0xf
	v_mov_b32_dpp v151, v115 row_ror:8 row_mask:0xf bank_mask:0xf
	v_mov_b32_dpp v160, v116 row_ror:8 row_mask:0xf bank_mask:0xf
	v_mov_b32_dpp v161, v117 row_ror:8 row_mask:0xf bank_mask:0xf
	v_mov_b32_dpp v162, v118 row_ror:8 row_mask:0xf bank_mask:0xf
	v_mov_b32_dpp v163, v119 row_ror:8 row_mask:0xf bank_mask:0xf
	v_cndmask_b32_e64 v163, v163, v115, s[6:7]
	v_cndmask_b32_e64 v162, v162, v114, s[6:7]
	v_cndmask_b32_e64 v115, v161, v113, s[6:7]
	v_cndmask_b32_e64 v113, v160, v112, s[6:7]
	v_cndmask_b32_e64 v151, v119, v151, s[6:7]
	v_cndmask_b32_e64 v164, v118, v127, s[6:7]
	v_cndmask_b32_e64 v161, v117, v126, s[6:7]
	v_cndmask_b32_e64 v125, v116, v125, s[6:7]
	v_lshlrev_b32_e32 v112, 16, v113
	v_and_b32_e32 v113, 0xffff0000, v113
	v_lshlrev_b32_e32 v116, 16, v162
	v_and_b32_e32 v117, 0xffff0000, v162
	v_lshlrev_b32_e32 v118, 16, v163
	v_and_b32_e32 v119, 0xffff0000, v163
	v_lshlrev_b32_e32 v126, 16, v125
	v_and_b32_e32 v127, 0xffff0000, v125
	v_lshlrev_b32_e32 v160, 16, v161
	v_and_b32_e32 v161, 0xffff0000, v161
	v_lshlrev_b32_e32 v162, 16, v164
	v_and_b32_e32 v163, 0xffff0000, v164
	v_lshlrev_b32_e32 v164, 16, v151
	v_and_b32_e32 v165, 0xffff0000, v151
	v_lshlrev_b32_e32 v114, 16, v115
	v_and_b32_e32 v115, 0xffff0000, v115
	v_pk_fma_f32 v[108:109], v[108:109], v[124:125], v[112:113] op_sel_hi:[1,0,1]
	v_pk_fma_f32 v[104:105], v[104:105], v[124:125], v[116:117] op_sel_hi:[1,0,1]
	v_pk_fma_f32 v[102:103], v[102:103], v[124:125], v[160:161] op_sel_hi:[1,0,1]
	v_pk_fma_f32 v[100:101], v[100:101], v[124:125], v[126:127] op_sel_hi:[1,0,1]
	v_pk_fma_f32 v[98:99], v[98:99], v[124:125], v[164:165] op_sel_hi:[1,0,1]
	v_pk_fma_f32 v[110:111], v[110:111], v[124:125], v[114:115] op_sel_hi:[1,0,1]
	v_pk_fma_f32 v[106:107], v[106:107], v[124:125], v[118:119] op_sel_hi:[1,0,1]
	v_pk_fma_f32 v[96:97], v[96:97], v[124:125], v[162:163] op_sel_hi:[1,0,1]
	v_cvt_pk_bf16_f32 v108, v108, v109
	v_cvt_pk_bf16_f32 v109, v110, v111
	v_cvt_pk_bf16_f32 v104, v104, v105
	v_cvt_pk_bf16_f32 v105, v106, v107
	v_cvt_pk_bf16_f32 v100, v100, v101
	v_cvt_pk_bf16_f32 v101, v102, v103
	s_nop 0
	v_cvt_pk_bf16_f32 v102, v96, v97
	v_cvt_pk_bf16_f32 v103, v98, v99
	v_mov_b32_e32 v98, 0
	v_mov_b32_dpp v98, v102 row_ror:8 row_mask:0xf bank_mask:0xf
	v_mov_b32_dpp v99, v103 row_ror:8 row_mask:0xf bank_mask:0xf
	v_mov_b32_dpp v107, v104 row_ror:8 row_mask:0xf bank_mask:0xf
	v_mov_b32_dpp v110, v105 row_ror:8 row_mask:0xf bank_mask:0xf
	v_mov_b32_dpp v96, v100 row_ror:8 row_mask:0xf bank_mask:0xf
	v_mov_b32_dpp v97, v101 row_ror:8 row_mask:0xf bank_mask:0xf
	v_cndmask_b32_e64 v98, v98, v104, s[6:7]
	v_cndmask_b32_e64 v99, v99, v105, s[6:7]
	v_lshl_add_u64 v[104:105], s[8:9], 0, v[120:121]
	v_cndmask_b32_e64 v96, v96, v108, s[6:7]
	v_cndmask_b32_e64 v97, v97, v109, s[6:7]
	v_lshl_add_u64 v[104:105], v[104:105], 0, v[146:147]
	v_mov_b32_dpp v166, v108 row_ror:8 row_mask:0xf bank_mask:0xf
	v_mov_b32_dpp v106, v109 row_ror:8 row_mask:0xf bank_mask:0xf
	global_store_dwordx4 v[104:105], v[96:99], off
	v_cndmask_b32_e64 v100, v100, v166, s[6:7]
	v_cndmask_b32_e64 v101, v101, v106, s[6:7]
	v_lshl_add_u64 v[96:97], s[8:9], 0, v[122:123]
	v_cndmask_b32_e64 v102, v102, v107, s[6:7]
	v_cndmask_b32_e64 v103, v103, v110, s[6:7]
	v_lshl_add_u64 v[96:97], v[96:97], 0, v[146:147]
	global_store_dwordx4 v[96:97], v[100:103], off
	v_or_b32_e32 v96, 32, v150
	v_ashrrev_i32_e32 v97, 31, v96
	v_lshl_add_u64 v[98:99], v[96:97], 2, s[10:11]
	v_sub_u32_e32 v96, v96, v152
	v_add_u32_e32 v96, v96, v154
	v_ashrrev_i32_e32 v97, 31, v96
	v_lshlrev_b64 v[104:105], 12, v[96:97]
	v_lshl_add_u64 v[96:97], s[16:17], 0, v[104:105]
	v_lshl_add_u64 v[106:107], v[104:105], 0, s[36:37]
	v_lshl_add_u64 v[96:97], v[96:97], 0, v[146:147]
	v_lshl_add_u64 v[100:101], s[16:17], 0, v[106:107]
	s_waitcnt vmcnt(16)
	s_nop 0
	v_mov_b32_e32 v108, v205
	s_nop 0
	v_mov_b64_e32 v[96:97], v[216:217]
	v_mov_b64_e32 v[98:99], v[218:219]
	v_lshl_add_u64 v[100:101], v[100:101], 0, v[146:147]
	v_mov_b64_e32 v[100:101], v[220:221]
	v_mov_b64_e32 v[102:103], v[222:223]
	s_nop 1
	v_sub_u32_e32 v198, v150, v152
	v_add_u32_e32 v201, v198, v154
	v_add_u32_e32 v190, 0xb0, v201
	v_ashrrev_i32_e32 v191, 31, v190
	v_lshlrev_b64 v[194:195], 12, v[190:191]
	v_lshl_add_u64 v[196:197], v[194:195], 0, s[36:37]
	global_load_dword v205, v[148:149], off offset:704
	v_lshl_add_u64 v[190:191], s[16:17], 0, v[194:195]
	v_lshl_add_u64 v[192:193], s[16:17], 0, v[196:197]
	v_lshl_add_u64 v[190:191], v[190:191], 0, v[146:147]
	v_lshl_add_u64 v[192:193], v[192:193], 0, v[146:147]
	global_load_dwordx4 v[216:219], v[190:191], off
	global_load_dwordx4 v[220:223], v[192:193], off
	s_waitcnt vmcnt(25)
; __device__ __forceinline__ void store_pair_lines(bf16_t* O, int ldc, int row, int fr, int col0, u32x4 wA, u32x4 wB) {
;     const u32x4 sA = {dpp_ror8(wA.x), dpp_ror8(wA.y), dpp_ror8(wA.z), dpp_ror8(wA.w)}, sB = {dpp_ror8(wB.x), dpp_ror8(wB.y), dpp_ror8(wB.z), dpp_ror8(wB.w)};
;     const bool lo = fr < 8;
;     const u32x4 o1 = lo ? wA : sB, o2 = lo ? sA : wB;
;     const int r1 = row - fr + (fr & 7), cb = col0 + (lo ? 0 : 8);
;     *(u32x4*)(O + (size_t)r1 * ldc + cb) = o1;
;     *(u32x4*)(O + (size_t)(r1 + 8) * ldc + cb) = o2;
; }
;     const bool lo = fr < 8;
;     const int r1 = row - fr + (fr & 7), cb = col0 + (lo ? 0 : boff);
;     const u32x4 l1 = *(const u32x4*)(P + (size_t)r1 * ld + cb), l2 = *(const u32x4*)(P + (size_t)(r1 + 8) * ld + cb);
;     const u32x4 s1 = {dpp_ror8(l1.x), dpp_ror8(l1.y), dpp_ror8(l1.z), dpp_ror8(l1.w)}, s2 = {dpp_ror8(l2.x), dpp_ror8(l2.y), dpp_ror8(l2.z), dpp_ror8(l2.w)};
;     wA = lo ? l1 : s2; wB = lo ? s1 : l2;
;     __device__ __forceinline__ void operator()(const f32x4 (&acc)[2][2][4][2], const Unit& u, int wr, int wc, int fr, int fq) const {
;     ...
;             for (int m = 0; m < 4; ++m) { const int row = row0 + ai * HALF + m * 16; const size_t off = (size_t)row * D + col0; float sq = 0.f; u32x4 w[2];
;                 const float sc = rsin ? __builtin_amdgcn_rcpf(rsin[row] * (1.f / D) + EPS) : 1.0f;
;                 u32x4 rr[2]; if (R) load_pair_lines(R, D, row, fr, col0, rr[0], rr[1]);
; #pragma unroll
;                 for (int bj = 0; bj < 2; ++bj) { f32x4 r0, r1;
;                     if (R) { const u32x4 rw = rr[bj]; r0 = (f32x4){bflo(rw.x), bfhi(rw.x), bflo(rw.y), bfhi(rw.y)}; r1 = (f32x4){bflo(rw.z), bfhi(rw.z), bflo(rw.w), bfhi(rw.w)}; }
;                     else { const float* rp = (row < 8192 ? src_p + off : src_s + (off - (size_t)8192 * D)) + 8 * bj; r0 = *(const f32x4*)rp; r1 = *(const f32x4*)(rp + 4); }
;                     const f32x4 o0 = r0 + acc[ai][bj][m][0] * sc, o1 = r1 + acc[ai][bj][m][1] * sc;
;                     sq += (o0[0] * o0[0] + o0[1] * o0[1]) + (o0[2] * o0[2] + o0[3] * o0[3]) + (o1[0] * o1[0] + o1[1] * o1[1]) + (o1[2] * o1[2] + o1[3] * o1[3]);
;                     w[bj].x = cvt_pk_bf16(o0[0], o0[1]); w[bj].y = cvt_pk_bf16(o0[2], o0[3]); w[bj].z = cvt_pk_bf16(o1[0], o1[1]); w[bj].w = cvt_pk_bf16(o1[2], o1[3]); }
;                 store_pair_lines(O, D, row, fr, col0, w[0], w[1]);
	v_fmamk_f32 v108, v108, 0x3a000000, v159
	v_rcp_f32_e32 v108, v108
	v_mov_b32_dpp v109, v96 row_ror:8 row_mask:0xf bank_mask:0xf
	v_mov_b32_dpp v113, v100 row_ror:8 row_mask:0xf bank_mask:0xf
	v_mov_b32_dpp v114, v101 row_ror:8 row_mask:0xf bank_mask:0xf
	v_mov_b32_dpp v115, v102 row_ror:8 row_mask:0xf bank_mask:0xf
	v_mov_b32_dpp v116, v103 row_ror:8 row_mask:0xf bank_mask:0xf
	v_mov_b32_dpp v110, v97 row_ror:8 row_mask:0xf bank_mask:0xf
	v_mov_b32_dpp v111, v98 row_ror:8 row_mask:0xf bank_mask:0xf
	v_mov_b32_dpp v112, v99 row_ror:8 row_mask:0xf bank_mask:0xf
	v_cndmask_b32_e64 v116, v116, v99, s[6:7]
	v_cndmask_b32_e64 v115, v115, v98, s[6:7]
	v_cndmask_b32_e64 v99, v114, v97, s[6:7]
	v_cndmask_b32_e64 v97, v113, v96, s[6:7]
	v_cndmask_b32_e64 v114, v103, v112, s[6:7]
	v_cndmask_b32_e64 v117, v102, v111, s[6:7]
	v_cndmask_b32_e64 v113, v101, v110, s[6:7]
	v_cndmask_b32_e64 v109, v100, v109, s[6:7]
	v_lshlrev_b32_e32 v96, 16, v97
	v_and_b32_e32 v97, 0xffff0000, v97
	v_lshlrev_b32_e32 v98, 16, v99
	v_and_b32_e32 v99, 0xffff0000, v99
	v_lshlrev_b32_e32 v100, 16, v115
	v_and_b32_e32 v101, 0xffff0000, v115
	v_lshlrev_b32_e32 v102, 16, v116
	v_and_b32_e32 v103, 0xffff0000, v116
	v_pk_fma_f32 v[94:95], v[94:95], v[108:109], v[98:99] op_sel_hi:[1,0,1]
	v_pk_fma_f32 v[92:93], v[92:93], v[108:109], v[96:97] op_sel_hi:[1,0,1]
	v_pk_fma_f32 v[90:91], v[90:91], v[108:109], v[102:103] op_sel_hi:[1,0,1]
	v_pk_fma_f32 v[88:89], v[88:89], v[108:109], v[100:101] op_sel_hi:[1,0,1]
	v_lshlrev_b32_e32 v110, 16, v109
	v_and_b32_e32 v111, 0xffff0000, v109
	v_lshlrev_b32_e32 v112, 16, v113
	v_and_b32_e32 v113, 0xffff0000, v113
	v_cvt_pk_bf16_f32 v92, v92, v93
	v_cvt_pk_bf16_f32 v93, v94, v95
	v_cvt_pk_bf16_f32 v94, v88, v89
	v_cvt_pk_bf16_f32 v95, v90, v91
	v_lshlrev_b32_e32 v88, 16, v117
	v_and_b32_e32 v89, 0xffff0000, v117
	v_lshlrev_b32_e32 v90, 16, v114
	v_and_b32_e32 v91, 0xffff0000, v114
	v_pk_fma_f32 v[86:87], v[86:87], v[108:109], v[112:113] op_sel_hi:[1,0,1]
	v_pk_fma_f32 v[84:85], v[84:85], v[108:109], v[110:111] op_sel_hi:[1,0,1]
	v_pk_fma_f32 v[82:83], v[82:83], v[108:109], v[90:91] op_sel_hi:[1,0,1]
	v_pk_fma_f32 v[80:81], v[80:81], v[108:109], v[88:89] op_sel_hi:[1,0,1]
	v_cvt_pk_bf16_f32 v84, v84, v85
	v_cvt_pk_bf16_f32 v85, v86, v87
	v_cvt_pk_bf16_f32 v86, v80, v81
	v_cvt_pk_bf16_f32 v87, v82, v83
	s_nop 0
	v_mov_b32_dpp v88, v92 row_ror:8 row_mask:0xf bank_mask:0xf
	v_mov_b32_dpp v89, v93 row_ror:8 row_mask:0xf bank_mask:0xf
	v_mov_b32_dpp v80, v84 row_ror:8 row_mask:0xf bank_mask:0xf
	v_mov_b32_dpp v81, v85 row_ror:8 row_mask:0xf bank_mask:0xf
	v_mov_b32_dpp v82, v86 row_ror:8 row_mask:0xf bank_mask:0xf
	v_mov_b32_dpp v83, v87 row_ror:8 row_mask:0xf bank_mask:0xf
	v_cndmask_b32_e64 v84, v84, v88, s[6:7]
	v_cndmask_b32_e64 v85, v85, v89, s[6:7]
	v_lshl_add_u64 v[88:89], s[8:9], 0, v[104:105]
	v_cndmask_b32_e64 v80, v80, v92, s[6:7]
	v_cndmask_b32_e64 v81, v81, v93, s[6:7]
	v_cndmask_b32_e64 v82, v82, v94, s[6:7]
	v_cndmask_b32_e64 v83, v83, v95, s[6:7]
	v_lshl_add_u64 v[88:89], v[88:89], 0, v[146:147]
	v_mov_b32_dpp v90, v94 row_ror:8 row_mask:0xf bank_mask:0xf
	v_mov_b32_dpp v91, v95 row_ror:8 row_mask:0xf bank_mask:0xf
	global_store_dwordx4 v[88:89], v[80:83], off
	v_cndmask_b32_e64 v86, v86, v90, s[6:7]
	v_cndmask_b32_e64 v87, v87, v91, s[6:7]
	v_lshl_add_u64 v[80:81], s[8:9], 0, v[106:107]
	v_lshl_add_u64 v[80:81], v[80:81], 0, v[146:147]
	global_store_dwordx4 v[80:81], v[84:87], off
	v_or_b32_e32 v80, 48, v150
	v_ashrrev_i32_e32 v81, 31, v80
	v_lshl_add_u64 v[82:83], v[80:81], 2, s[10:11]
	v_sub_u32_e32 v80, v80, v152
	v_add_u32_e32 v80, v80, v154
	v_ashrrev_i32_e32 v81, 31, v80
	v_lshlrev_b64 v[88:89], 12, v[80:81]
	v_lshl_add_u64 v[80:81], s[16:17], 0, v[88:89]
	v_lshl_add_u64 v[90:91], v[88:89], 0, s[36:37]
	v_lshl_add_u64 v[80:81], v[80:81], 0, v[146:147]
	v_lshl_add_u64 v[84:85], s[16:17], 0, v[90:91]
	s_waitcnt vmcnt(18)
	s_nop 0
	v_mov_b32_e32 v92, v206
	s_nop 0
	v_mov_b64_e32 v[80:81], v[224:225]
	v_mov_b64_e32 v[82:83], v[226:227]
	v_lshl_add_u64 v[84:85], v[84:85], 0, v[146:147]
	v_mov_b64_e32 v[84:85], v[228:229]
	v_mov_b64_e32 v[86:87], v[230:231]
	s_nop 1
	s_waitcnt vmcnt(27)
	v_fmamk_f32 v92, v92, 0x3a000000, v159
	v_rcp_f32_e32 v92, v92
	v_mov_b32_dpp v93, v80 row_ror:8 row_mask:0xf bank_mask:0xf
	v_mov_b32_dpp v97, v84 row_ror:8 row_mask:0xf bank_mask:0xf
	v_mov_b32_dpp v98, v85 row_ror:8 row_mask:0xf bank_mask:0xf
	v_mov_b32_dpp v99, v86 row_ror:8 row_mask:0xf bank_mask:0xf
	v_mov_b32_dpp v100, v87 row_ror:8 row_mask:0xf bank_mask:0xf
	v_mov_b32_dpp v94, v81 row_ror:8 row_mask:0xf bank_mask:0xf
	v_mov_b32_dpp v95, v82 row_ror:8 row_mask:0xf bank_mask:0xf
	v_mov_b32_dpp v96, v83 row_ror:8 row_mask:0xf bank_mask:0xf
	v_cndmask_b32_e64 v100, v100, v83, s[6:7]
	v_cndmask_b32_e64 v99, v99, v82, s[6:7]
	v_cndmask_b32_e64 v83, v98, v81, s[6:7]
	v_cndmask_b32_e64 v81, v97, v80, s[6:7]
	v_cndmask_b32_e64 v96, v87, v96, s[6:7]
	v_cndmask_b32_e64 v95, v86, v95, s[6:7]
	v_cndmask_b32_e64 v94, v85, v94, s[6:7]
	v_cndmask_b32_e64 v93, v84, v93, s[6:7]
	v_lshlrev_b32_e32 v80, 16, v81
	v_and_b32_e32 v81, 0xffff0000, v81
	v_lshlrev_b32_e32 v82, 16, v83
	v_and_b32_e32 v83, 0xffff0000, v83
	v_lshlrev_b32_e32 v84, 16, v99
	v_and_b32_e32 v85, 0xffff0000, v99
	v_lshlrev_b32_e32 v86, 16, v100
	v_and_b32_e32 v87, 0xffff0000, v100
	v_pk_fma_f32 v[78:79], v[78:79], v[92:93], v[82:83] op_sel_hi:[1,0,1]
	v_pk_fma_f32 v[76:77], v[76:77], v[92:93], v[80:81] op_sel_hi:[1,0,1]
	v_pk_fma_f32 v[74:75], v[74:75], v[92:93], v[86:87] op_sel_hi:[1,0,1]
	v_pk_fma_f32 v[72:73], v[72:73], v[92:93], v[84:85] op_sel_hi:[1,0,1]
	v_cvt_pk_bf16_f32 v80, v76, v77
; __device__ __forceinline__ void store_pair_lines(bf16_t* O, int ldc, int row, int fr, int col0, u32x4 wA, u32x4 wB) {
;     const u32x4 sA = {dpp_ror8(wA.x), dpp_ror8(wA.y), dpp_ror8(wA.z), dpp_ror8(wA.w)}, sB = {dpp_ror8(wB.x), dpp_ror8(wB.y), dpp_ror8(wB.z), dpp_ror8(wB.w)};
;     const bool lo = fr < 8;
;     const u32x4 o1 = lo ? wA : sB, o2 = lo ? sA : wB;
;     const int r1 = row - fr + (fr & 7), cb = col0 + (lo ? 0 : 8);
;     *(u32x4*)(O + (size_t)r1 * ldc + cb) = o1;
;     *(u32x4*)(O + (size_t)(r1 + 8) * ldc + cb) = o2;
; }
;     const bool lo = fr < 8;
;     const int r1 = row - fr + (fr & 7), cb = col0 + (lo ? 0 : boff);
;     const u32x4 l1 = *(const u32x4*)(P + (size_t)r1 * ld + cb), l2 = *(const u32x4*)(P + (size_t)(r1 + 8) * ld + cb);
;     const u32x4 s1 = {dpp_ror8(l1.x), dpp_ror8(l1.y), dpp_ror8(l1.z), dpp_ror8(l1.w)}, s2 = {dpp_ror8(l2.x), dpp_ror8(l2.y), dpp_ror8(l2.z), dpp_ror8(l2.w)};
;     wA = lo ? l1 : s2; wB = lo ? s1 : l2;
;     __device__ __forceinline__ void operator()(const f32x4 (&acc)[2][2][4][2], const Unit& u, int wr, int wc, int fr, int fq) const {
;     ...
;             for (int m = 0; m < 4; ++m) { const int row = row0 + ai * HALF + m * 16; const size_t off = (size_t)row * D + col0; float sq = 0.f; u32x4 w[2];
;                 const float sc = rsin ? __builtin_amdgcn_rcpf(rsin[row] * (1.f / D) + EPS) : 1.0f;
;                 u32x4 rr[2]; if (R) load_pair_lines(R, D, row, fr, col0, rr[0], rr[1]);
; #pragma unroll
;                 for (int bj = 0; bj < 2; ++bj) { f32x4 r0, r1;
;                     if (R) { const u32x4 rw = rr[bj]; r0 = (f32x4){bflo(rw.x), bfhi(rw.x), bflo(rw.y), bfhi(rw.y)}; r1 = (f32x4){bflo(rw.z), bfhi(rw.z), bflo(rw.w), bfhi(rw.w)}; }
;                     else { const float* rp = (row < 8192 ? src_p + off : src_s + (off - (size_t)8192 * D)) + 8 * bj; r0 = *(const f32x4*)rp; r1 = *(const f32x4*)(rp + 4); }
;                     const f32x4 o0 = r0 + acc[ai][bj][m][0] * sc, o1 = r1 + acc[ai][bj][m][1] * sc;
;                     sq += (o0[0] * o0[0] + o0[1] * o0[1]) + (o0[2] * o0[2] + o0[3] * o0[3]) + (o1[0] * o1[0] + o1[1] * o1[1]) + (o1[2] * o1[2] + o1[3] * o1[3]);
;                     w[bj].x = cvt_pk_bf16(o0[0], o0[1]); w[bj].y = cvt_pk_bf16(o0[2], o0[3]); w[bj].z = cvt_pk_bf16(o1[0], o1[1]); w[bj].w = cvt_pk_bf16(o1[2], o1[3]); }
;                 store_pair_lines(O, D, row, fr, col0, w[0], w[1]);
	v_cvt_pk_bf16_f32 v81, v78, v79
	v_lshlrev_b32_e32 v76, 16, v95
	v_cvt_pk_bf16_f32 v82, v72, v73
	v_cvt_pk_bf16_f32 v83, v74, v75
	v_lshlrev_b32_e32 v72, 16, v93
	v_and_b32_e32 v73, 0xffff0000, v93
	v_lshlrev_b32_e32 v74, 16, v94
	v_and_b32_e32 v75, 0xffff0000, v94
	v_and_b32_e32 v77, 0xffff0000, v95
	v_lshlrev_b32_e32 v78, 16, v96
	v_and_b32_e32 v79, 0xffff0000, v96
	v_pk_fma_f32 v[70:71], v[70:71], v[92:93], v[74:75] op_sel_hi:[1,0,1]
	v_pk_fma_f32 v[68:69], v[68:69], v[92:93], v[72:73] op_sel_hi:[1,0,1]
	v_pk_fma_f32 v[66:67], v[66:67], v[92:93], v[78:79] op_sel_hi:[1,0,1]
	v_pk_fma_f32 v[64:65], v[64:65], v[92:93], v[76:77] op_sel_hi:[1,0,1]
	v_cvt_pk_bf16_f32 v68, v68, v69
	v_cvt_pk_bf16_f32 v69, v70, v71
	v_cvt_pk_bf16_f32 v70, v64, v65
	v_cvt_pk_bf16_f32 v71, v66, v67
	s_nop 0
	v_mov_b32_dpp v72, v80 row_ror:8 row_mask:0xf bank_mask:0xf
	v_mov_b32_dpp v73, v81 row_ror:8 row_mask:0xf bank_mask:0xf
	v_mov_b32_dpp v64, v68 row_ror:8 row_mask:0xf bank_mask:0xf
	v_mov_b32_dpp v65, v69 row_ror:8 row_mask:0xf bank_mask:0xf
	v_mov_b32_dpp v66, v70 row_ror:8 row_mask:0xf bank_mask:0xf
	v_mov_b32_dpp v67, v71 row_ror:8 row_mask:0xf bank_mask:0xf
	v_cndmask_b32_e64 v68, v68, v72, s[6:7]
	v_cndmask_b32_e64 v69, v69, v73, s[6:7]
	v_lshl_add_u64 v[72:73], s[8:9], 0, v[88:89]
	v_cndmask_b32_e64 v64, v64, v80, s[6:7]
	v_cndmask_b32_e64 v65, v65, v81, s[6:7]
	v_cndmask_b32_e64 v66, v66, v82, s[6:7]
	v_cndmask_b32_e64 v67, v67, v83, s[6:7]
	v_lshl_add_u64 v[72:73], v[72:73], 0, v[146:147]
	v_mov_b32_dpp v74, v82 row_ror:8 row_mask:0xf bank_mask:0xf
	v_mov_b32_dpp v75, v83 row_ror:8 row_mask:0xf bank_mask:0xf
	global_store_dwordx4 v[72:73], v[64:67], off
	v_cndmask_b32_e64 v70, v70, v74, s[6:7]
	v_cndmask_b32_e64 v71, v71, v75, s[6:7]
	v_lshl_add_u64 v[64:65], s[8:9], 0, v[90:91]
	v_lshl_add_u64 v[64:65], v[64:65], 0, v[146:147]
	global_store_dwordx4 v[64:65], v[68:71], off
	v_sub_u32_e32 v64, v150, v152
	v_add_u32_e32 v77, v64, v154
	v_add_u32_e32 v64, 0x80, v77
	v_ashrrev_i32_e32 v65, 31, v64
	v_lshlrev_b64 v[72:73], 12, v[64:65]
	v_lshl_add_u64 v[64:65], s[16:17], 0, v[72:73]
	v_lshl_add_u64 v[74:75], v[72:73], 0, s[36:37]
	v_lshl_add_u64 v[64:65], v[64:65], 0, v[146:147]
	v_lshl_add_u64 v[68:69], s[16:17], 0, v[74:75]
	s_waitcnt vmcnt(17)
	s_nop 0
	v_mov_b32_e32 v76, v207
	s_nop 0
	v_mov_b64_e32 v[64:65], v[232:233]
	v_mov_b64_e32 v[66:67], v[234:235]
	v_lshl_add_u64 v[68:69], v[68:69], 0, v[146:147]
	v_mov_b64_e32 v[68:69], v[236:237]
	v_mov_b64_e32 v[70:71], v[238:239]
	s_nop 1
	s_waitcnt vmcnt(29)
	v_fmamk_f32 v76, v76, 0x3a000000, v159
	v_rcp_f32_e32 v76, v76
	v_mov_b32_dpp v78, v64 row_ror:8 row_mask:0xf bank_mask:0xf
	v_mov_b32_dpp v82, v68 row_ror:8 row_mask:0xf bank_mask:0xf
	v_mov_b32_dpp v83, v69 row_ror:8 row_mask:0xf bank_mask:0xf
	v_mov_b32_dpp v84, v70 row_ror:8 row_mask:0xf bank_mask:0xf
	v_mov_b32_dpp v85, v71 row_ror:8 row_mask:0xf bank_mask:0xf
	v_mov_b32_dpp v79, v65 row_ror:8 row_mask:0xf bank_mask:0xf
	v_mov_b32_dpp v80, v66 row_ror:8 row_mask:0xf bank_mask:0xf
	v_mov_b32_dpp v81, v67 row_ror:8 row_mask:0xf bank_mask:0xf
	v_cndmask_b32_e64 v85, v85, v67, s[6:7]
	v_cndmask_b32_e64 v84, v84, v66, s[6:7]
	v_cndmask_b32_e64 v67, v83, v65, s[6:7]
	v_cndmask_b32_e64 v65, v82, v64, s[6:7]
	v_cndmask_b32_e64 v81, v71, v81, s[6:7]
	v_cndmask_b32_e64 v80, v70, v80, s[6:7]
	v_cndmask_b32_e64 v79, v69, v79, s[6:7]
	v_cndmask_b32_e64 v78, v68, v78, s[6:7]
	v_lshlrev_b32_e32 v64, 16, v65
	v_and_b32_e32 v65, 0xffff0000, v65
	v_lshlrev_b32_e32 v66, 16, v67
	v_and_b32_e32 v67, 0xffff0000, v67
	v_lshlrev_b32_e32 v68, 16, v84
	v_and_b32_e32 v69, 0xffff0000, v84
	v_lshlrev_b32_e32 v70, 16, v85
	v_and_b32_e32 v71, 0xffff0000, v85
	v_pk_fma_f32 v[62:63], v[62:63], v[76:77], v[66:67] op_sel_hi:[1,0,1]
	v_pk_fma_f32 v[60:61], v[60:61], v[76:77], v[64:65] op_sel_hi:[1,0,1]
	v_pk_fma_f32 v[58:59], v[58:59], v[76:77], v[70:71] op_sel_hi:[1,0,1]
	v_pk_fma_f32 v[56:57], v[56:57], v[76:77], v[68:69] op_sel_hi:[1,0,1]
	v_cvt_pk_bf16_f32 v64, v60, v61
	v_cvt_pk_bf16_f32 v65, v62, v63
	v_lshlrev_b32_e32 v60, 16, v80
	v_cvt_pk_bf16_f32 v66, v56, v57
	v_cvt_pk_bf16_f32 v67, v58, v59
	v_lshlrev_b32_e32 v56, 16, v78
	v_and_b32_e32 v57, 0xffff0000, v78
	v_lshlrev_b32_e32 v58, 16, v79
	v_and_b32_e32 v59, 0xffff0000, v79
	v_and_b32_e32 v61, 0xffff0000, v80
	v_lshlrev_b32_e32 v62, 16, v81
	v_and_b32_e32 v63, 0xffff0000, v81
	v_pk_fma_f32 v[54:55], v[54:55], v[76:77], v[58:59] op_sel_hi:[1,0,1]
	v_pk_fma_f32 v[52:53], v[52:53], v[76:77], v[56:57] op_sel_hi:[1,0,1]
	v_pk_fma_f32 v[50:51], v[50:51], v[76:77], v[62:63] op_sel_hi:[1,0,1]
	v_pk_fma_f32 v[48:49], v[48:49], v[76:77], v[60:61] op_sel_hi:[1,0,1]
	v_cvt_pk_bf16_f32 v52, v52, v53
	v_cvt_pk_bf16_f32 v53, v54, v55
	v_cvt_pk_bf16_f32 v54, v48, v49
	v_cvt_pk_bf16_f32 v55, v50, v51
	s_nop 0
	v_mov_b32_dpp v56, v64 row_ror:8 row_mask:0xf bank_mask:0xf
	v_mov_b32_dpp v57, v65 row_ror:8 row_mask:0xf bank_mask:0xf
	v_mov_b32_dpp v48, v52 row_ror:8 row_mask:0xf bank_mask:0xf
	v_mov_b32_dpp v49, v53 row_ror:8 row_mask:0xf bank_mask:0xf
	v_mov_b32_dpp v50, v54 row_ror:8 row_mask:0xf bank_mask:0xf
	v_mov_b32_dpp v51, v55 row_ror:8 row_mask:0xf bank_mask:0xf
	v_cndmask_b32_e64 v52, v52, v56, s[6:7]
	v_cndmask_b32_e64 v53, v53, v57, s[6:7]
	v_lshl_add_u64 v[56:57], s[8:9], 0, v[72:73]
	v_cndmask_b32_e64 v48, v48, v64, s[6:7]
	v_cndmask_b32_e64 v49, v49, v65, s[6:7]
	v_cndmask_b32_e64 v50, v50, v66, s[6:7]
	v_cndmask_b32_e64 v51, v51, v67, s[6:7]
	v_lshl_add_u64 v[56:57], v[56:57], 0, v[146:147]
	v_mov_b32_dpp v58, v66 row_ror:8 row_mask:0xf bank_mask:0xf
	v_mov_b32_dpp v59, v67 row_ror:8 row_mask:0xf bank_mask:0xf
	global_store_dwordx4 v[56:57], v[48:51], off
	v_cndmask_b32_e64 v54, v54, v58, s[6:7]
	v_cndmask_b32_e64 v55, v55, v59, s[6:7]
	v_lshl_add_u64 v[48:49], s[8:9], 0, v[74:75]
	v_lshl_add_u64 v[48:49], v[48:49], 0, v[146:147]
	global_store_dwordx4 v[48:49], v[52:55], off
	v_add_u32_e32 v48, 0x90, v77
	v_ashrrev_i32_e32 v49, 31, v48
	v_lshlrev_b64 v[56:57], 12, v[48:49]
	v_lshl_add_u64 v[48:49], s[16:17], 0, v[56:57]
	v_lshl_add_u64 v[58:59], v[56:57], 0, s[36:37]
	v_lshl_add_u64 v[48:49], v[48:49], 0, v[146:147]
	v_lshl_add_u64 v[52:53], s[16:17], 0, v[58:59]
	s_waitcnt vmcnt(16)
; __device__ __forceinline__ void store_pair_lines(bf16_t* O, int ldc, int row, int fr, int col0, u32x4 wA, u32x4 wB) {
;     const u32x4 sA = {dpp_ror8(wA.x), dpp_ror8(wA.y), dpp_ror8(wA.z), dpp_ror8(wA.w)}, sB = {dpp_ror8(wB.x), dpp_ror8(wB.y), dpp_ror8(wB.z), dpp_ror8(wB.w)};
;     const bool lo = fr < 8;
;     const u32x4 o1 = lo ? wA : sB, o2 = lo ? sA : wB;
;     const int r1 = row - fr + (fr & 7), cb = col0 + (lo ? 0 : 8);
;     *(u32x4*)(O + (size_t)r1 * ldc + cb) = o1;
;     *(u32x4*)(O + (size_t)(r1 + 8) * ldc + cb) = o2;
; }
;     const bool lo = fr < 8;
;     const int r1 = row - fr + (fr & 7), cb = col0 + (lo ? 0 : boff);
;     const u32x4 l1 = *(const u32x4*)(P + (size_t)r1 * ld + cb), l2 = *(const u32x4*)(P + (size_t)(r1 + 8) * ld + cb);
;     const u32x4 s1 = {dpp_ror8(l1.x), dpp_ror8(l1.y), dpp_ror8(l1.z), dpp_ror8(l1.w)}, s2 = {dpp_ror8(l2.x), dpp_ror8(l2.y), dpp_ror8(l2.z), dpp_ror8(l2.w)};
;     wA = lo ? l1 : s2; wB = lo ? s1 : l2;
;     __device__ __forceinline__ void operator()(const f32x4 (&acc)[2][2][4][2], const Unit& u, int wr, int wc, int fr, int fq) const {
;     ...
;             for (int m = 0; m < 4; ++m) { const int row = row0 + ai * HALF + m * 16; const size_t off = (size_t)row * D + col0; float sq = 0.f; u32x4 w[2];
;                 const float sc = rsin ? __builtin_amdgcn_rcpf(rsin[row] * (1.f / D) + EPS) : 1.0f;
;                 u32x4 rr[2]; if (R) load_pair_lines(R, D, row, fr, col0, rr[0], rr[1]);
; #pragma unroll
;                 for (int bj = 0; bj < 2; ++bj) { f32x4 r0, r1;
;                     if (R) { const u32x4 rw = rr[bj]; r0 = (f32x4){bflo(rw.x), bfhi(rw.x), bflo(rw.y), bfhi(rw.y)}; r1 = (f32x4){bflo(rw.z), bfhi(rw.z), bflo(rw.w), bfhi(rw.w)}; }
;                     else { const float* rp = (row < 8192 ? src_p + off : src_s + (off - (size_t)8192 * D)) + 8 * bj; r0 = *(const f32x4*)rp; r1 = *(const f32x4*)(rp + 4); }
;                     const f32x4 o0 = r0 + acc[ai][bj][m][0] * sc, o1 = r1 + acc[ai][bj][m][1] * sc;
;                     sq += (o0[0] * o0[0] + o0[1] * o0[1]) + (o0[2] * o0[2] + o0[3] * o0[3]) + (o1[0] * o1[0] + o1[1] * o1[1]) + (o1[2] * o1[2] + o1[3] * o1[3]);
;                     w[bj].x = cvt_pk_bf16(o0[0], o0[1]); w[bj].y = cvt_pk_bf16(o0[2], o0[3]); w[bj].z = cvt_pk_bf16(o1[0], o1[1]); w[bj].w = cvt_pk_bf16(o1[2], o1[3]); }
;                 store_pair_lines(O, D, row, fr, col0, w[0], w[1]);
	s_nop 0
	v_mov_b32_e32 v60, v240
	s_nop 0
	v_mov_b64_e32 v[48:49], v[244:245]
	v_mov_b64_e32 v[50:51], v[246:247]
	v_lshl_add_u64 v[52:53], v[52:53], 0, v[146:147]
	v_mov_b64_e32 v[52:53], v[248:249]
	v_mov_b64_e32 v[54:55], v[250:251]
	s_nop 1
	s_waitcnt vmcnt(31)
	v_fmamk_f32 v60, v60, 0x3a000000, v159
	v_rcp_f32_e32 v60, v60
	v_mov_b32_dpp v61, v48 row_ror:8 row_mask:0xf bank_mask:0xf
	v_mov_b32_dpp v65, v52 row_ror:8 row_mask:0xf bank_mask:0xf
	v_mov_b32_dpp v66, v53 row_ror:8 row_mask:0xf bank_mask:0xf
	v_mov_b32_dpp v67, v54 row_ror:8 row_mask:0xf bank_mask:0xf
	v_mov_b32_dpp v68, v55 row_ror:8 row_mask:0xf bank_mask:0xf
	v_mov_b32_dpp v62, v49 row_ror:8 row_mask:0xf bank_mask:0xf
	v_mov_b32_dpp v63, v50 row_ror:8 row_mask:0xf bank_mask:0xf
	v_mov_b32_dpp v64, v51 row_ror:8 row_mask:0xf bank_mask:0xf
	v_cndmask_b32_e64 v68, v68, v51, s[6:7]
	v_cndmask_b32_e64 v67, v67, v50, s[6:7]
	v_cndmask_b32_e64 v51, v66, v49, s[6:7]
	v_cndmask_b32_e64 v49, v65, v48, s[6:7]
	v_cndmask_b32_e64 v64, v55, v64, s[6:7]
	v_cndmask_b32_e64 v63, v54, v63, s[6:7]
	v_cndmask_b32_e64 v62, v53, v62, s[6:7]
	v_cndmask_b32_e64 v61, v52, v61, s[6:7]
	v_lshlrev_b32_e32 v48, 16, v49
	v_and_b32_e32 v49, 0xffff0000, v49
	v_lshlrev_b32_e32 v50, 16, v51
	v_and_b32_e32 v51, 0xffff0000, v51
	v_lshlrev_b32_e32 v52, 16, v67
	v_and_b32_e32 v53, 0xffff0000, v67
	v_lshlrev_b32_e32 v54, 16, v68
	v_and_b32_e32 v55, 0xffff0000, v68
	v_pk_fma_f32 v[46:47], v[46:47], v[60:61], v[50:51] op_sel_hi:[1,0,1]
	v_pk_fma_f32 v[44:45], v[44:45], v[60:61], v[48:49] op_sel_hi:[1,0,1]
	v_pk_fma_f32 v[42:43], v[42:43], v[60:61], v[54:55] op_sel_hi:[1,0,1]
	v_pk_fma_f32 v[40:41], v[40:41], v[60:61], v[52:53] op_sel_hi:[1,0,1]
	v_cvt_pk_bf16_f32 v48, v44, v45
	v_cvt_pk_bf16_f32 v49, v46, v47
	v_lshlrev_b32_e32 v44, 16, v63
	v_cvt_pk_bf16_f32 v50, v40, v41
	v_cvt_pk_bf16_f32 v51, v42, v43
	v_lshlrev_b32_e32 v40, 16, v61
	v_and_b32_e32 v41, 0xffff0000, v61
	v_lshlrev_b32_e32 v42, 16, v62
	v_and_b32_e32 v43, 0xffff0000, v62
	v_and_b32_e32 v45, 0xffff0000, v63
	v_lshlrev_b32_e32 v46, 16, v64
	v_and_b32_e32 v47, 0xffff0000, v64
	v_pk_fma_f32 v[38:39], v[38:39], v[60:61], v[42:43] op_sel_hi:[1,0,1]
	v_pk_fma_f32 v[36:37], v[36:37], v[60:61], v[40:41] op_sel_hi:[1,0,1]
	v_pk_fma_f32 v[34:35], v[34:35], v[60:61], v[46:47] op_sel_hi:[1,0,1]
	v_pk_fma_f32 v[32:33], v[32:33], v[60:61], v[44:45] op_sel_hi:[1,0,1]
	v_cvt_pk_bf16_f32 v36, v36, v37
	v_cvt_pk_bf16_f32 v37, v38, v39
	v_cvt_pk_bf16_f32 v38, v32, v33
	v_cvt_pk_bf16_f32 v39, v34, v35
	s_nop 0
	v_mov_b32_dpp v40, v48 row_ror:8 row_mask:0xf bank_mask:0xf
	v_mov_b32_dpp v41, v49 row_ror:8 row_mask:0xf bank_mask:0xf
	v_mov_b32_dpp v32, v36 row_ror:8 row_mask:0xf bank_mask:0xf
	v_mov_b32_dpp v33, v37 row_ror:8 row_mask:0xf bank_mask:0xf
	v_mov_b32_dpp v34, v38 row_ror:8 row_mask:0xf bank_mask:0xf
	v_mov_b32_dpp v35, v39 row_ror:8 row_mask:0xf bank_mask:0xf
	v_cndmask_b32_e64 v36, v36, v40, s[6:7]
	v_cndmask_b32_e64 v37, v37, v41, s[6:7]
	v_lshl_add_u64 v[40:41], s[8:9], 0, v[56:57]
	v_cndmask_b32_e64 v32, v32, v48, s[6:7]
	v_cndmask_b32_e64 v33, v33, v49, s[6:7]
	v_cndmask_b32_e64 v34, v34, v50, s[6:7]
	v_cndmask_b32_e64 v35, v35, v51, s[6:7]
	v_lshl_add_u64 v[40:41], v[40:41], 0, v[146:147]
	v_mov_b32_dpp v42, v50 row_ror:8 row_mask:0xf bank_mask:0xf
	v_mov_b32_dpp v43, v51 row_ror:8 row_mask:0xf bank_mask:0xf
	global_store_dwordx4 v[40:41], v[32:35], off
	v_cndmask_b32_e64 v38, v38, v42, s[6:7]
	v_cndmask_b32_e64 v39, v39, v43, s[6:7]
	v_lshl_add_u64 v[32:33], s[8:9], 0, v[58:59]
	v_lshl_add_u64 v[32:33], v[32:33], 0, v[146:147]
	global_store_dwordx4 v[32:33], v[36:39], off
	v_add_u32_e32 v32, 0xa0, v77
	v_ashrrev_i32_e32 v33, 31, v32
	v_lshlrev_b64 v[40:41], 12, v[32:33]
	v_lshl_add_u64 v[42:43], v[40:41], 0, s[36:37]
	s_waitcnt vmcnt(13)
	s_nop 0
	v_mov_b32_e32 v44, v204
	v_lshl_add_u64 v[32:33], s[16:17], 0, v[40:41]
	v_lshl_add_u64 v[36:37], s[16:17], 0, v[42:43]
	v_lshl_add_u64 v[32:33], v[32:33], 0, v[146:147]
	v_lshl_add_u64 v[36:37], v[36:37], 0, v[146:147]
	v_mov_b64_e32 v[32:33], v[208:209]
	v_mov_b64_e32 v[34:35], v[210:211]
	v_mov_b64_e32 v[36:37], v[212:213]
	v_mov_b64_e32 v[38:39], v[214:215]
	s_nop 1
	s_waitcnt vmcnt(33)
	v_fmamk_f32 v44, v44, 0x3a000000, v159
	v_rcp_f32_e32 v44, v44
	v_mov_b32_dpp v45, v32 row_ror:8 row_mask:0xf bank_mask:0xf
	v_mov_b32_dpp v46, v33 row_ror:8 row_mask:0xf bank_mask:0xf
	v_mov_b32_dpp v49, v36 row_ror:8 row_mask:0xf bank_mask:0xf
	v_mov_b32_dpp v50, v37 row_ror:8 row_mask:0xf bank_mask:0xf
	v_mov_b32_dpp v51, v38 row_ror:8 row_mask:0xf bank_mask:0xf
	v_mov_b32_dpp v52, v39 row_ror:8 row_mask:0xf bank_mask:0xf
	v_mov_b32_dpp v47, v34 row_ror:8 row_mask:0xf bank_mask:0xf
	v_mov_b32_dpp v48, v35 row_ror:8 row_mask:0xf bank_mask:0xf
	v_cndmask_b32_e64 v52, v52, v35, s[6:7]
	v_cndmask_b32_e64 v51, v51, v34, s[6:7]
	v_cndmask_b32_e64 v35, v50, v33, s[6:7]
	v_cndmask_b32_e64 v33, v49, v32, s[6:7]
	v_cndmask_b32_e64 v48, v39, v48, s[6:7]
	v_cndmask_b32_e64 v47, v38, v47, s[6:7]
	v_cndmask_b32_e64 v46, v37, v46, s[6:7]
	v_cndmask_b32_e64 v45, v36, v45, s[6:7]
	v_lshlrev_b32_e32 v32, 16, v33
	v_and_b32_e32 v33, 0xffff0000, v33
	v_lshlrev_b32_e32 v34, 16, v35
	v_and_b32_e32 v35, 0xffff0000, v35
	v_lshlrev_b32_e32 v36, 16, v51
	v_and_b32_e32 v37, 0xffff0000, v51
	v_lshlrev_b32_e32 v38, 16, v52
	v_and_b32_e32 v39, 0xffff0000, v52
	v_pk_fma_f32 v[30:31], v[30:31], v[44:45], v[34:35] op_sel_hi:[1,0,1]
	v_pk_fma_f32 v[28:29], v[28:29], v[44:45], v[32:33] op_sel_hi:[1,0,1]
	v_pk_fma_f32 v[26:27], v[26:27], v[44:45], v[38:39] op_sel_hi:[1,0,1]
	v_pk_fma_f32 v[24:25], v[24:25], v[44:45], v[36:37] op_sel_hi:[1,0,1]
; __device__ __forceinline__ unsigned cvt_pk_bf16(float lo, float hi) { unsigned r; asm volatile("v_cvt_pk_bf16_f32 %0, %1, %2" : "=v"(r) : "v"(lo), "v"(hi)); return r; }
; __device__ __forceinline__ float bflo(unsigned w) { return __uint_as_float(w << 16); }
; __device__ __forceinline__ float bfhi(unsigned w) { return __uint_as_float(w & 0xffff0000u); }
; __device__ __forceinline__ void store_pair_lines(bf16_t* O, int ldc, int row, int fr, int col0, u32x4 wA, u32x4 wB) {
;     const u32x4 sA = {dpp_ror8(wA.x), dpp_ror8(wA.y), dpp_ror8(wA.z), dpp_ror8(wA.w)}, sB = {dpp_ror8(wB.x), dpp_ror8(wB.y), dpp_ror8(wB.z), dpp_ror8(wB.w)};
;     const bool lo = fr < 8;
;     const u32x4 o1 = lo ? wA : sB, o2 = lo ? sA : wB;
;     const int r1 = row - fr + (fr & 7), cb = col0 + (lo ? 0 : 8);
;     *(u32x4*)(O + (size_t)r1 * ldc + cb) = o1;
;     *(u32x4*)(O + (size_t)(r1 + 8) * ldc + cb) = o2;
; }
;     __device__ __forceinline__ void operator()(const f32x4 (&acc)[2][2][4][2], const Unit& u, int wr, int wc, int fr, int fq) const {
;     ...
;             for (int m = 0; m < 4; ++m) { const int row = row0 + ai * HALF + m * 16; const size_t off = (size_t)row * D + col0; float sq = 0.f; u32x4 w[2];
;                 const float sc = rsin ? __builtin_amdgcn_rcpf(rsin[row] * (1.f / D) + EPS) : 1.0f;
;                 u32x4 rr[2]; if (R) load_pair_lines(R, D, row, fr, col0, rr[0], rr[1]);
; #pragma unroll
;                 for (int bj = 0; bj < 2; ++bj) { f32x4 r0, r1;
;                     if (R) { const u32x4 rw = rr[bj]; r0 = (f32x4){bflo(rw.x), bfhi(rw.x), bflo(rw.y), bfhi(rw.y)}; r1 = (f32x4){bflo(rw.z), bfhi(rw.z), bflo(rw.w), bfhi(rw.w)}; }
;                     else { const float* rp = (row < 8192 ? src_p + off : src_s + (off - (size_t)8192 * D)) + 8 * bj; r0 = *(const f32x4*)rp; r1 = *(const f32x4*)(rp + 4); }
;                     const f32x4 o0 = r0 + acc[ai][bj][m][0] * sc, o1 = r1 + acc[ai][bj][m][1] * sc;
;                     sq += (o0[0] * o0[0] + o0[1] * o0[1]) + (o0[2] * o0[2] + o0[3] * o0[3]) + (o1[0] * o1[0] + o1[1] * o1[1]) + (o1[2] * o1[2] + o1[3] * o1[3]);
;                     w[bj].x = cvt_pk_bf16(o0[0], o0[1]); w[bj].y = cvt_pk_bf16(o0[2], o0[3]); w[bj].z = cvt_pk_bf16(o1[0], o1[1]); w[bj].w = cvt_pk_bf16(o1[2], o1[3]); }
;                 store_pair_lines(O, D, row, fr, col0, w[0], w[1]);
	v_cvt_pk_bf16_f32 v32, v28, v29
	v_cvt_pk_bf16_f32 v33, v30, v31
	v_lshlrev_b32_e32 v28, 16, v47
	v_cvt_pk_bf16_f32 v34, v24, v25
	v_cvt_pk_bf16_f32 v35, v26, v27
	v_lshlrev_b32_e32 v24, 16, v45
	v_and_b32_e32 v25, 0xffff0000, v45
	v_lshlrev_b32_e32 v26, 16, v46
	v_and_b32_e32 v27, 0xffff0000, v46
	v_and_b32_e32 v29, 0xffff0000, v47
	v_lshlrev_b32_e32 v30, 16, v48
	v_and_b32_e32 v31, 0xffff0000, v48
	v_pk_fma_f32 v[22:23], v[22:23], v[44:45], v[26:27] op_sel_hi:[1,0,1]
	v_pk_fma_f32 v[20:21], v[20:21], v[44:45], v[24:25] op_sel_hi:[1,0,1]
	v_pk_fma_f32 v[18:19], v[18:19], v[44:45], v[30:31] op_sel_hi:[1,0,1]
	v_pk_fma_f32 v[16:17], v[16:17], v[44:45], v[28:29] op_sel_hi:[1,0,1]
	v_cvt_pk_bf16_f32 v20, v20, v21
	v_cvt_pk_bf16_f32 v21, v22, v23
	v_cvt_pk_bf16_f32 v22, v16, v17
	v_cvt_pk_bf16_f32 v23, v18, v19
	s_nop 0
	v_mov_b32_dpp v24, v32 row_ror:8 row_mask:0xf bank_mask:0xf
	v_mov_b32_dpp v25, v33 row_ror:8 row_mask:0xf bank_mask:0xf
	v_mov_b32_dpp v16, v20 row_ror:8 row_mask:0xf bank_mask:0xf
	v_mov_b32_dpp v17, v21 row_ror:8 row_mask:0xf bank_mask:0xf
	v_mov_b32_dpp v18, v22 row_ror:8 row_mask:0xf bank_mask:0xf
	v_mov_b32_dpp v19, v23 row_ror:8 row_mask:0xf bank_mask:0xf
	v_cndmask_b32_e64 v20, v20, v24, s[6:7]
	v_cndmask_b32_e64 v21, v21, v25, s[6:7]
	v_lshl_add_u64 v[24:25], s[8:9], 0, v[40:41]
	v_cndmask_b32_e64 v16, v16, v32, s[6:7]
	v_cndmask_b32_e64 v17, v17, v33, s[6:7]
	v_cndmask_b32_e64 v18, v18, v34, s[6:7]
	v_cndmask_b32_e64 v19, v19, v35, s[6:7]
	v_lshl_add_u64 v[24:25], v[24:25], 0, v[146:147]
	v_mov_b32_dpp v26, v34 row_ror:8 row_mask:0xf bank_mask:0xf
	v_mov_b32_dpp v27, v35 row_ror:8 row_mask:0xf bank_mask:0xf
	global_store_dwordx4 v[24:25], v[16:19], off
	v_cndmask_b32_e64 v22, v22, v26, s[6:7]
	v_cndmask_b32_e64 v23, v23, v27, s[6:7]
	v_lshl_add_u64 v[16:17], s[8:9], 0, v[42:43]
	v_lshl_add_u64 v[16:17], v[16:17], 0, v[146:147]
	global_store_dwordx4 v[16:17], v[20:23], off
	v_add_u32_e32 v16, 0xb0, v77
	v_ashrrev_i32_e32 v17, 31, v16
	v_lshlrev_b64 v[24:25], 12, v[16:17]
	v_lshl_add_u64 v[26:27], v[24:25], 0, s[36:37]
	s_waitcnt vmcnt(10)
	s_nop 0
	v_mov_b32_e32 v28, v205
	v_lshl_add_u64 v[16:17], s[16:17], 0, v[24:25]
	v_lshl_add_u64 v[20:21], s[16:17], 0, v[26:27]
	v_lshl_add_u64 v[16:17], v[16:17], 0, v[146:147]
	v_lshl_add_u64 v[20:21], v[20:21], 0, v[146:147]
	v_mov_b64_e32 v[16:17], v[216:217]
	v_mov_b64_e32 v[18:19], v[218:219]
	v_mov_b64_e32 v[20:21], v[220:221]
	v_mov_b64_e32 v[22:23], v[222:223]
	s_nop 1
	s_waitcnt vmcnt(35)
	v_fmamk_f32 v28, v28, 0x3a000000, v159
	v_rcp_f32_e32 v28, v28
	v_mov_b32_dpp v29, v16 row_ror:8 row_mask:0xf bank_mask:0xf
	v_mov_b32_dpp v30, v17 row_ror:8 row_mask:0xf bank_mask:0xf
	v_mov_b32_dpp v33, v20 row_ror:8 row_mask:0xf bank_mask:0xf
	v_mov_b32_dpp v34, v21 row_ror:8 row_mask:0xf bank_mask:0xf
	v_mov_b32_dpp v35, v22 row_ror:8 row_mask:0xf bank_mask:0xf
	v_mov_b32_dpp v36, v23 row_ror:8 row_mask:0xf bank_mask:0xf
	v_mov_b32_dpp v31, v18 row_ror:8 row_mask:0xf bank_mask:0xf
	v_mov_b32_dpp v32, v19 row_ror:8 row_mask:0xf bank_mask:0xf
	v_cndmask_b32_e64 v36, v36, v19, s[6:7]
	v_cndmask_b32_e64 v35, v35, v18, s[6:7]
	v_cndmask_b32_e64 v19, v34, v17, s[6:7]
	v_cndmask_b32_e64 v17, v33, v16, s[6:7]
	v_cndmask_b32_e64 v32, v23, v32, s[6:7]
	v_cndmask_b32_e64 v31, v22, v31, s[6:7]
	v_cndmask_b32_e64 v30, v21, v30, s[6:7]
	v_cndmask_b32_e64 v29, v20, v29, s[6:7]
	v_lshlrev_b32_e32 v16, 16, v17
	v_and_b32_e32 v17, 0xffff0000, v17
	v_lshlrev_b32_e32 v18, 16, v19
	v_and_b32_e32 v19, 0xffff0000, v19
	v_lshlrev_b32_e32 v20, 16, v35
	v_and_b32_e32 v21, 0xffff0000, v35
	v_lshlrev_b32_e32 v22, 16, v36
	v_and_b32_e32 v23, 0xffff0000, v36
	v_pk_fma_f32 v[14:15], v[14:15], v[28:29], v[18:19] op_sel_hi:[1,0,1]
	v_pk_fma_f32 v[12:13], v[12:13], v[28:29], v[16:17] op_sel_hi:[1,0,1]
	v_pk_fma_f32 v[10:11], v[10:11], v[28:29], v[22:23] op_sel_hi:[1,0,1]
	v_pk_fma_f32 v[8:9], v[8:9], v[28:29], v[20:21] op_sel_hi:[1,0,1]
	v_cvt_pk_bf16_f32 v16, v12, v13
	v_cvt_pk_bf16_f32 v17, v14, v15
	v_lshlrev_b32_e32 v12, 16, v31
	v_cvt_pk_bf16_f32 v18, v8, v9
	v_cvt_pk_bf16_f32 v19, v10, v11
	v_lshlrev_b32_e32 v8, 16, v29
	v_and_b32_e32 v9, 0xffff0000, v29
	v_lshlrev_b32_e32 v10, 16, v30
	v_and_b32_e32 v11, 0xffff0000, v30
	v_and_b32_e32 v13, 0xffff0000, v31
	v_lshlrev_b32_e32 v14, 16, v32
	v_and_b32_e32 v15, 0xffff0000, v32
	v_pk_fma_f32 v[6:7], v[6:7], v[28:29], v[10:11] op_sel_hi:[1,0,1]
	v_pk_fma_f32 v[4:5], v[4:5], v[28:29], v[8:9] op_sel_hi:[1,0,1]
	v_pk_fma_f32 v[2:3], v[2:3], v[28:29], v[14:15] op_sel_hi:[1,0,1]
	v_pk_fma_f32 v[0:1], v[0:1], v[28:29], v[12:13] op_sel_hi:[1,0,1]
	v_cvt_pk_bf16_f32 v4, v4, v5
	v_cvt_pk_bf16_f32 v5, v6, v7
	v_cvt_pk_bf16_f32 v6, v0, v1
	v_cvt_pk_bf16_f32 v7, v2, v3
	s_nop 0
	v_mov_b32_dpp v8, v16 row_ror:8 row_mask:0xf bank_mask:0xf
	v_mov_b32_dpp v9, v17 row_ror:8 row_mask:0xf bank_mask:0xf
	v_mov_b32_dpp v0, v4 row_ror:8 row_mask:0xf bank_mask:0xf
	v_mov_b32_dpp v1, v5 row_ror:8 row_mask:0xf bank_mask:0xf
	v_mov_b32_dpp v2, v6 row_ror:8 row_mask:0xf bank_mask:0xf
	v_mov_b32_dpp v3, v7 row_ror:8 row_mask:0xf bank_mask:0xf
	v_cndmask_b32_e64 v4, v4, v8, s[6:7]
	v_cndmask_b32_e64 v5, v5, v9, s[6:7]
	v_lshl_add_u64 v[8:9], s[8:9], 0, v[24:25]
	v_cndmask_b32_e64 v0, v0, v16, s[6:7]
	v_cndmask_b32_e64 v1, v1, v17, s[6:7]
	v_cndmask_b32_e64 v2, v2, v18, s[6:7]
	v_cndmask_b32_e64 v3, v3, v19, s[6:7]
	v_lshl_add_u64 v[8:9], v[8:9], 0, v[146:147]
	v_mov_b32_dpp v10, v18 row_ror:8 row_mask:0xf bank_mask:0xf
	v_mov_b32_dpp v11, v19 row_ror:8 row_mask:0xf bank_mask:0xf
	global_store_dwordx4 v[8:9], v[0:3], off
	v_cndmask_b32_e64 v6, v6, v10, s[6:7]
	v_cndmask_b32_e64 v7, v7, v11, s[6:7]
	v_lshl_add_u64 v[0:1], s[8:9], 0, v[26:27]
	v_lshl_add_u64 v[0:1], v[0:1], 0, v[146:147]
	global_store_dwordx4 v[0:1], v[4:7], off
	s_cbranch_vccz .LBB0_798
	s_waitcnt vmcnt(0)
	s_cmpk_gt_u32 s56, 0xff
	s_cbranch_scc1 .LBB0_810
	s_barrier

; #define PG8_STAGE(bufoff, gbase, voff) do { _Pragma("unroll") for (int _i = 0; _i < 2; ++_i) \
;         __builtin_amdgcn_global_load_lds((const unsigned*)((const char*)(gbase) + (voff)[_i]), (LAS unsigned*)(lds + (bufoff) + ldsw + _i * 8192), 16, 0, 0); } while (0)
; #define PG8_LDA(dst, b, h) do { _Pragma("unroll") for (int m = 0; m < 4; ++m) _Pragma("unroll") for (int k = 0; k < 2; ++k) dst[m][k] = *(const LAS bf16x8*)(lds + PG8_SA(b, h) + aoff + m * 2048 + k * 1024); } while (0)
; #define PG8_LDB(dst, b, h) do { _Pragma("unroll") for (int n = 0; n < 2; ++n) _Pragma("unroll") for (int k = 0; k < 2; ++k) dst[n][k] = *(const LAS bf16x8*)(lds + PG8_SB(b, h) + boff + n * 2048 + k * 1024); } while (0)
; #define PG8_MMA(ai, bj, At, Bt) do { __builtin_amdgcn_s_setprio(1); _Pragma("unroll") for (int m = 0; m < 4; ++m) _Pragma("unroll") for (int n = 0; n < 2; ++n) _Pragma("unroll") for (int k = 0; k < 2; ++k) \
;         acc[ai][bj][m][n] = __builtin_amdgcn_mfma_f32_16x16x32_bf16(Bt[n][k], At[m][k], acc[ai][bj][m][n], 0, 0, 0); __builtin_amdgcn_s_setprio(0); } while (0)
; #define PG8_WAIT_V(n) asm volatile("s_waitcnt vmcnt(" #n ")" ::: "memory")
; #define PG8_WAIT_L(n) asm volatile("s_waitcnt lgkmcnt(" #n ")" ::: "memory")
; #define PG8_BAR __builtin_amdgcn_s_barrier()
; #define PG8_SCHED __builtin_amdgcn_sched_barrier(0)
; template <class Epi>
; __device__ __forceinline__ void gemm_phase(LAS unsigned char* lds, const Gemm g, const StaticOrder& S, const Epi& E) {
;     ...
;             PG8_LDB(B0, 0, 0); PG8_SCHED; PG8_LDA(At, 0, 0); PG8_STAGE(PG8_SA(1, 1), a1 + hstep, voffA);
;             PG8_WAIT_L(8); PG8_BAR; PG8_WAIT_L(0); PG8_MMA(0, 0, At, B0); PG8_BAR; PG8_SCHED;
;             PG8_LDB(B1, 0, 1); PG8_STAGE(PG8_SB(0, 0), b2, voffB0);
;             PG8_BAR; PG8_WAIT_L(0); PG8_MMA(0, 1, At, B1); PG8_BAR;
;             PG8_LDA(At, 0, 1); PG8_STAGE(PG8_SA(0, 0), a2, voffA);
;             PG8_BAR; PG8_WAIT_L(0); PG8_MMA(1, 0, At, B0); PG8_BAR; PG8_SCHED;
;             PG8_STAGE(PG8_SB(0, 1), b2, voffB1);
;             PG8_WAIT_V(6); PG8_BAR; PG8_MMA(1, 1, At, B1); PG8_BAR;
.LBB0_882:
	ds_read_b128 v[32:35], v177
	ds_read_b128 v[40:43], v177 offset:1024
	ds_read_b128 v[48:51], v177 offset:2048
	ds_read_b128 v[52:55], v177 offset:3072
	s_add_u32 s33, s60, 0xfff80080
	s_addc_u32 s62, s61, -1
	s_cmp_eq_u32 s86, 28
	s_cselect_b32 s63, s49, s62
	s_cselect_b32 s62, s57, s33
	s_cselect_b32 s65, s47, s85
	s_cselect_b32 s64, s83, s84
	v_lshl_add_u64 v[170:171], s[60:61], 0, v[156:157]
	s_add_i32 m0, s59, 0xc000
	ds_read_b128 v[162:165], v178
	ds_read_b128 v[166:169], v178 offset:1024
	ds_read_b128 v[182:185], v178 offset:2048
	ds_read_b128 v[186:189], v178 offset:3072
	ds_read_b128 v[190:193], v178 offset:4096
	ds_read_b128 v[194:197], v178 offset:5120
	ds_read_b128 v[198:201], v178 offset:6144
	ds_read_b128 v[204:207], v178 offset:7168
	global_load_lds_dwordx4 v[170:171], off
	v_lshl_add_u64 v[170:171], s[60:61], 0, v[158:159]
	s_add_i32 m0, s59, 0xe000
	s_nop 0
	global_load_lds_dwordx4 v[170:171], off
	s_waitcnt lgkmcnt(8)
	s_barrier
	s_waitcnt lgkmcnt(0)
	v_mfma_f32_16x16x32_bf16 v[140:143], v[32:35], v[162:165], v[140:143]
	v_mfma_f32_16x16x32_bf16 v[136:139], v[48:51], v[162:165], v[136:139]
	v_mfma_f32_16x16x32_bf16 v[124:127], v[32:35], v[182:185], v[124:127]
	v_mfma_f32_16x16x32_bf16 v[120:123], v[48:51], v[182:185], v[120:123]
	v_mfma_f32_16x16x32_bf16 v[108:111], v[32:35], v[190:193], v[108:111]
	v_mfma_f32_16x16x32_bf16 v[104:107], v[48:51], v[190:193], v[104:107]
	v_mfma_f32_16x16x32_bf16 v[92:95], v[32:35], v[198:201], v[92:95]
	v_mfma_f32_16x16x32_bf16 v[88:91], v[48:51], v[198:201], v[88:91]
	v_mfma_f32_16x16x32_bf16 v[140:143], v[40:43], v[166:169], v[140:143]
	v_mfma_f32_16x16x32_bf16 v[136:139], v[52:55], v[166:169], v[136:139]
	v_mfma_f32_16x16x32_bf16 v[124:127], v[40:43], v[186:189], v[124:127]
	v_mfma_f32_16x16x32_bf16 v[120:123], v[52:55], v[186:189], v[120:123]
	v_mfma_f32_16x16x32_bf16 v[108:111], v[40:43], v[194:197], v[108:111]
	v_mfma_f32_16x16x32_bf16 v[104:107], v[52:55], v[194:197], v[104:107]
	v_mfma_f32_16x16x32_bf16 v[92:95], v[40:43], v[204:207], v[92:95]
	v_mfma_f32_16x16x32_bf16 v[88:91], v[52:55], v[204:207], v[88:91]
	s_barrier
	s_add_i32 s33, s81, s69
	v_lshl_add_u64 v[170:171], s[64:65], 0, v[146:147]
	s_mov_b32 m0, s33
	ds_read_b128 v[208:211], v179
	ds_read_b128 v[212:215], v179 offset:1024
	ds_read_b128 v[216:219], v179 offset:2048
	ds_read_b128 v[220:223], v179 offset:3072
	global_load_lds_dwordx4 v[170:171], off
	v_lshl_add_u64 v[224:225], s[64:65], 0, v[152:153]
	s_add_i32 m0, s33, 0x2000
	s_nop 0
	global_load_lds_dwordx4 v[224:225], off
	s_waitcnt lgkmcnt(0)
	s_barrier
	s_waitcnt lgkmcnt(0)
	v_mfma_f32_16x16x32_bf16 v[132:135], v[208:211], v[162:165], v[132:135]
	v_mfma_f32_16x16x32_bf16 v[128:131], v[216:219], v[162:165], v[128:131]
	v_mfma_f32_16x16x32_bf16 v[116:119], v[208:211], v[182:185], v[116:119]
	v_mfma_f32_16x16x32_bf16 v[112:115], v[216:219], v[182:185], v[112:115]
	v_mfma_f32_16x16x32_bf16 v[100:103], v[208:211], v[190:193], v[100:103]
	v_mfma_f32_16x16x32_bf16 v[96:99], v[216:219], v[190:193], v[96:99]
	v_mfma_f32_16x16x32_bf16 v[84:87], v[208:211], v[198:201], v[84:87]
	v_mfma_f32_16x16x32_bf16 v[80:83], v[216:219], v[198:201], v[80:83]
	v_mfma_f32_16x16x32_bf16 v[132:135], v[212:215], v[166:169], v[132:135]
	v_mfma_f32_16x16x32_bf16 v[128:131], v[220:223], v[166:169], v[128:131]
	v_mfma_f32_16x16x32_bf16 v[116:119], v[212:215], v[186:189], v[116:119]
	v_mfma_f32_16x16x32_bf16 v[112:115], v[220:223], v[186:189], v[112:115]
	v_mfma_f32_16x16x32_bf16 v[100:103], v[212:215], v[194:197], v[100:103]
	v_mfma_f32_16x16x32_bf16 v[96:99], v[220:223], v[194:197], v[96:99]
	v_mfma_f32_16x16x32_bf16 v[84:87], v[212:215], v[204:207], v[84:87]
	v_mfma_f32_16x16x32_bf16 v[80:83], v[220:223], v[204:207], v[80:83]
	s_mov_b32 m0, s59
	v_lshl_add_u64 v[226:227], s[62:63], 0, v[144:145]
	s_barrier
	ds_read_b128 v[162:165], v178 offset:16384
	ds_read_b128 v[166:169], v178 offset:17408
	ds_read_b128 v[182:185], v178 offset:18432
	ds_read_b128 v[186:189], v178 offset:19456
	ds_read_b128 v[190:193], v178 offset:20480
	ds_read_b128 v[194:197], v178 offset:21504
	ds_read_b128 v[198:201], v178 offset:22528
	ds_read_b128 v[204:207], v178 offset:23552
	global_load_lds_dwordx4 v[226:227], off
	v_lshl_add_u64 v[228:229], s[62:63], 0, v[150:151]
	s_mov_b32 m0, s70
	s_nop 0
	global_load_lds_dwordx4 v[228:229], off
	s_add_i32 s33, s82, s69
	v_lshl_add_u64 v[230:231], s[64:65], 0, v[148:149]
	s_mov_b32 m0, s33
	v_lshl_add_u64 v[232:233], s[64:65], 0, v[154:155]
	global_load_lds_dwordx4 v[230:231], off
	s_add_i32 m0, s33, 0x2000
	s_nop 0
	global_load_lds_dwordx4 v[232:233], off
	s_waitcnt vmcnt(6)
	s_barrier
; #define PG8_STAGE(bufoff, gbase, voff) do { _Pragma("unroll") for (int _i = 0; _i < 2; ++_i) \
;         __builtin_amdgcn_global_load_lds((const unsigned*)((const char*)(gbase) + (voff)[_i]), (LAS unsigned*)(lds + (bufoff) + ldsw + _i * 8192), 16, 0, 0); } while (0)
; #define PG8_LDA(dst, b, h) do { _Pragma("unroll") for (int m = 0; m < 4; ++m) _Pragma("unroll") for (int k = 0; k < 2; ++k) dst[m][k] = *(const LAS bf16x8*)(lds + PG8_SA(b, h) + aoff + m * 2048 + k * 1024); } while (0)
; #define PG8_LDB(dst, b, h) do { _Pragma("unroll") for (int n = 0; n < 2; ++n) _Pragma("unroll") for (int k = 0; k < 2; ++k) dst[n][k] = *(const LAS bf16x8*)(lds + PG8_SB(b, h) + boff + n * 2048 + k * 1024); } while (0)
; #define PG8_MMA(ai, bj, At, Bt) do { __builtin_amdgcn_s_setprio(1); _Pragma("unroll") for (int m = 0; m < 4; ++m) _Pragma("unroll") for (int n = 0; n < 2; ++n) _Pragma("unroll") for (int k = 0; k < 2; ++k) \
;         acc[ai][bj][m][n] = __builtin_amdgcn_mfma_f32_16x16x32_bf16(Bt[n][k], At[m][k], acc[ai][bj][m][n], 0, 0, 0); __builtin_amdgcn_s_setprio(0); } while (0)
; #define PG8_WAIT_V(n) asm volatile("s_waitcnt vmcnt(" #n ")" ::: "memory")
; #define PG8_WAIT_L(n) asm volatile("s_waitcnt lgkmcnt(" #n ")" ::: "memory")
; #define PG8_BAR __builtin_amdgcn_s_barrier()
; #define PG8_SCHED __builtin_amdgcn_sched_barrier(0)
; template <class Epi>
; __device__ __forceinline__ void gemm_phase(LAS unsigned char* lds, const Gemm g, const StaticOrder& S, const Epi& E) {
;     ...
;             PG8_WAIT_V(6); PG8_BAR; PG8_MMA(1, 1, At, B1); PG8_BAR;
;             PG8_LDB(B0, 1, 0); PG8_SCHED; PG8_LDA(At, 1, 0); PG8_STAGE(PG8_SA(0, 1), a2 + hstep, voffA);
;             PG8_WAIT_L(8); PG8_BAR; PG8_WAIT_L(0); PG8_MMA(0, 0, At, B0); PG8_BAR; PG8_SCHED;
;             PG8_LDB(B1, 1, 1); PG8_STAGE(PG8_SB(1, 0), b3, voffB0);
;             PG8_BAR; PG8_WAIT_L(0); PG8_MMA(0, 1, At, B1); PG8_BAR;
;             PG8_LDA(At, 1, 1); PG8_STAGE(PG8_SA(1, 0), a3, voffA);
;             PG8_BAR; PG8_WAIT_L(0); PG8_MMA(1, 0, At, B0); PG8_BAR; PG8_SCHED;
	s_waitcnt lgkmcnt(0)
	v_mfma_f32_16x16x32_bf16 v[76:79], v[32:35], v[162:165], v[76:79]
	v_mfma_f32_16x16x32_bf16 v[72:75], v[48:51], v[162:165], v[72:75]
	v_mfma_f32_16x16x32_bf16 v[60:63], v[32:35], v[182:185], v[60:63]
	v_mfma_f32_16x16x32_bf16 v[56:59], v[48:51], v[182:185], v[56:59]
	v_mfma_f32_16x16x32_bf16 v[28:31], v[32:35], v[190:193], v[28:31]
	v_mfma_f32_16x16x32_bf16 v[24:27], v[48:51], v[190:193], v[24:27]
	v_mfma_f32_16x16x32_bf16 v[12:15], v[32:35], v[198:201], v[12:15]
	v_mfma_f32_16x16x32_bf16 v[8:11], v[48:51], v[198:201], v[8:11]
	v_mfma_f32_16x16x32_bf16 v[76:79], v[40:43], v[166:169], v[76:79]
	v_mfma_f32_16x16x32_bf16 v[72:75], v[52:55], v[166:169], v[72:75]
	v_mfma_f32_16x16x32_bf16 v[60:63], v[40:43], v[186:189], v[60:63]
	v_mfma_f32_16x16x32_bf16 v[56:59], v[52:55], v[186:189], v[56:59]
	v_mfma_f32_16x16x32_bf16 v[28:31], v[40:43], v[194:197], v[28:31]
	v_mfma_f32_16x16x32_bf16 v[24:27], v[52:55], v[194:197], v[24:27]
	v_mfma_f32_16x16x32_bf16 v[12:15], v[40:43], v[204:207], v[12:15]
	v_mfma_f32_16x16x32_bf16 v[8:11], v[52:55], v[204:207], v[8:11]
	v_mfma_f32_16x16x32_bf16 v[44:47], v[208:211], v[182:185], v[44:47]
	v_mfma_f32_16x16x32_bf16 v[36:39], v[216:219], v[182:185], v[36:39]
	v_mfma_f32_16x16x32_bf16 v[20:23], v[208:211], v[190:193], v[20:23]
	v_mfma_f32_16x16x32_bf16 v[16:19], v[216:219], v[190:193], v[16:19]
	v_mfma_f32_16x16x32_bf16 v[4:7], v[208:211], v[198:201], v[4:7]
	v_mfma_f32_16x16x32_bf16 v[0:3], v[216:219], v[198:201], v[0:3]
	v_mfma_f32_16x16x32_bf16 v[32:35], v[208:211], v[162:165], v[68:71]
	v_mfma_f32_16x16x32_bf16 v[40:43], v[216:219], v[162:165], v[64:67]
	v_mfma_f32_16x16x32_bf16 v[44:47], v[212:215], v[186:189], v[44:47]
	v_mfma_f32_16x16x32_bf16 v[36:39], v[220:223], v[186:189], v[36:39]
	v_mfma_f32_16x16x32_bf16 v[20:23], v[212:215], v[194:197], v[20:23]
	v_mfma_f32_16x16x32_bf16 v[16:19], v[220:223], v[194:197], v[16:19]
	v_mfma_f32_16x16x32_bf16 v[4:7], v[212:215], v[204:207], v[4:7]
	v_mfma_f32_16x16x32_bf16 v[0:3], v[220:223], v[204:207], v[0:3]
	v_mfma_f32_16x16x32_bf16 v[32:35], v[212:215], v[166:169], v[32:35]
	v_mfma_f32_16x16x32_bf16 v[40:43], v[220:223], v[166:169], v[40:43]
	s_add_i32 s33, 0, 0x18000
	v_add_u32_e32 v68, s33, v173
	s_barrier
	ds_read_b128 v[48:51], v68
	ds_read_b128 v[52:55], v68 offset:1024
	ds_read_b128 v[64:67], v68 offset:2048
	ds_read_b128 v[68:71], v68 offset:3072
	s_add_u32 s62, s62, 0x80000
	s_addc_u32 s63, s63, 0
	s_mov_b32 m0, s71
	v_lshl_add_u64 v[208:209], s[62:63], 0, v[144:145]
	ds_read_b128 v[162:165], v178 offset:32768
	ds_read_b128 v[166:169], v178 offset:33792
	ds_read_b128 v[182:185], v178 offset:34816
	ds_read_b128 v[186:189], v178 offset:35840
	ds_read_b128 v[190:193], v178 offset:36864
	ds_read_b128 v[194:197], v178 offset:37888
	ds_read_b128 v[198:201], v178 offset:38912
	ds_read_b128 v[204:207], v178 offset:39936
	global_load_lds_dwordx4 v[208:209], off
	v_lshl_add_u64 v[208:209], s[62:63], 0, v[150:151]
	s_mov_b32 m0, s72
	s_nop 0
	global_load_lds_dwordx4 v[208:209], off
	s_waitcnt lgkmcnt(8)
	s_barrier
	s_waitcnt lgkmcnt(0)
	v_mfma_f32_16x16x32_bf16 v[140:143], v[48:51], v[162:165], v[140:143]
	v_mfma_f32_16x16x32_bf16 v[136:139], v[64:67], v[162:165], v[136:139]
	v_mfma_f32_16x16x32_bf16 v[124:127], v[48:51], v[182:185], v[124:127]
	v_mfma_f32_16x16x32_bf16 v[120:123], v[64:67], v[182:185], v[120:123]
	v_mfma_f32_16x16x32_bf16 v[108:111], v[48:51], v[190:193], v[108:111]
	v_mfma_f32_16x16x32_bf16 v[104:107], v[64:67], v[190:193], v[104:107]
	v_mfma_f32_16x16x32_bf16 v[92:95], v[48:51], v[198:201], v[92:95]
	v_mfma_f32_16x16x32_bf16 v[88:91], v[64:67], v[198:201], v[88:91]
	v_mfma_f32_16x16x32_bf16 v[140:143], v[52:55], v[166:169], v[140:143]
	v_mfma_f32_16x16x32_bf16 v[136:139], v[68:71], v[166:169], v[136:139]
	v_mfma_f32_16x16x32_bf16 v[124:127], v[52:55], v[186:189], v[124:127]
	v_mfma_f32_16x16x32_bf16 v[120:123], v[68:71], v[186:189], v[120:123]
	v_mfma_f32_16x16x32_bf16 v[108:111], v[52:55], v[194:197], v[108:111]
	v_mfma_f32_16x16x32_bf16 v[104:107], v[68:71], v[194:197], v[104:107]
	v_mfma_f32_16x16x32_bf16 v[92:95], v[52:55], v[204:207], v[92:95]
	v_mfma_f32_16x16x32_bf16 v[88:91], v[68:71], v[204:207], v[88:91]
	s_barrier
	s_add_i32 s62, 0, 0x1c000
	s_add_i32 s33, s33, s69
	v_add_u32_e32 v181, s62, v173
	v_lshl_add_u64 v[170:171], v[170:171], 0, s[42:43]
	s_mov_b32 m0, s33
	ds_read_b128 v[208:211], v181
	ds_read_b128 v[212:215], v181 offset:1024
	ds_read_b128 v[216:219], v181 offset:2048
	ds_read_b128 v[220:223], v181 offset:3072
	global_load_lds_dwordx4 v[170:171], off
	v_lshl_add_u64 v[170:171], v[224:225], 0, s[42:43]
	s_add_i32 m0, s33, 0x2000
	s_nop 0
	global_load_lds_dwordx4 v[170:171], off
	s_waitcnt lgkmcnt(0)
	s_barrier
	s_waitcnt lgkmcnt(0)
	v_mfma_f32_16x16x32_bf16 v[132:135], v[208:211], v[162:165], v[132:135]
	v_mfma_f32_16x16x32_bf16 v[128:131], v[216:219], v[162:165], v[128:131]
	v_mfma_f32_16x16x32_bf16 v[116:119], v[208:211], v[182:185], v[116:119]
	v_mfma_f32_16x16x32_bf16 v[112:115], v[216:219], v[182:185], v[112:115]
	v_mfma_f32_16x16x32_bf16 v[100:103], v[208:211], v[190:193], v[100:103]
	v_mfma_f32_16x16x32_bf16 v[96:99], v[216:219], v[190:193], v[96:99]
	v_mfma_f32_16x16x32_bf16 v[84:87], v[208:211], v[198:201], v[84:87]
	v_mfma_f32_16x16x32_bf16 v[80:83], v[216:219], v[198:201], v[80:83]
	v_mfma_f32_16x16x32_bf16 v[132:135], v[212:215], v[166:169], v[132:135]
	v_mfma_f32_16x16x32_bf16 v[128:131], v[220:223], v[166:169], v[128:131]
	v_mfma_f32_16x16x32_bf16 v[116:119], v[212:215], v[186:189], v[116:119]
	v_mfma_f32_16x16x32_bf16 v[112:115], v[220:223], v[186:189], v[112:115]
	v_mfma_f32_16x16x32_bf16 v[100:103], v[212:215], v[194:197], v[100:103]
	v_mfma_f32_16x16x32_bf16 v[96:99], v[220:223], v[194:197], v[96:99]
	v_mfma_f32_16x16x32_bf16 v[84:87], v[212:215], v[204:207], v[84:87]
	v_mfma_f32_16x16x32_bf16 v[80:83], v[220:223], v[204:207], v[80:83]
	s_mov_b32 m0, s74
	v_lshl_add_u64 v[170:171], v[226:227], 0, s[42:43]
	s_barrier
; #define PG8_STAGE(bufoff, gbase, voff) do { _Pragma("unroll") for (int _i = 0; _i < 2; ++_i) \
;         __builtin_amdgcn_global_load_lds((const unsigned*)((const char*)(gbase) + (voff)[_i]), (LAS unsigned*)(lds + (bufoff) + ldsw + _i * 8192), 16, 0, 0); } while (0)
; #define PG8_LDA(dst, b, h) do { _Pragma("unroll") for (int m = 0; m < 4; ++m) _Pragma("unroll") for (int k = 0; k < 2; ++k) dst[m][k] = *(const LAS bf16x8*)(lds + PG8_SA(b, h) + aoff + m * 2048 + k * 1024); } while (0)
; #define PG8_MMA(ai, bj, At, Bt) do { __builtin_amdgcn_s_setprio(1); _Pragma("unroll") for (int m = 0; m < 4; ++m) _Pragma("unroll") for (int n = 0; n < 2; ++n) _Pragma("unroll") for (int k = 0; k < 2; ++k) \
;         acc[ai][bj][m][n] = __builtin_amdgcn_mfma_f32_16x16x32_bf16(Bt[n][k], At[m][k], acc[ai][bj][m][n], 0, 0, 0); __builtin_amdgcn_s_setprio(0); } while (0)
; #define PG8_WAIT_V(n) asm volatile("s_waitcnt vmcnt(" #n ")" ::: "memory")
; #define PG8_WAIT_L(n) asm volatile("s_waitcnt lgkmcnt(" #n ")" ::: "memory")
; #define PG8_BAR __builtin_amdgcn_s_barrier()
;     __device__ __forceinline__ void operator()(const f32x4 (&acc)[2][2][4][2], const Unit& u, int wr, int wc, int fr, int fq) const {
;         const int row0 = u.pm * BM + wr * 64 + fr, col0 = u.pn * BM + wc * 64 + 16 * fq;
;         f32x4 gv[2][2];
; #pragma unroll
;         for (int bj = 0; bj < 2; ++bj) { gv[bj][0] = *(const f32x4*)(g + col0 + 8 * bj); gv[bj][1] = *(const f32x4*)(g + col0 + 8 * bj + 4); }
; #pragma unroll
;         for (int ai = 0; ai < 2; ++ai)
; #pragma unroll
;             for (int m = 0; m < 4; ++m) { const int row = row0 + ai * HALF + m * 16; const size_t off = (size_t)row * D + col0; const float ri = __builtin_amdgcn_rsqf(sse[row] * (1.f / D) + EPS); float sq = 0.f; u32x4 w[2];
;                 u32x4 rr[2], ee[2]; load_pair_lines(R, D, row, fr, col0, rr[0], rr[1]); load_pair_lines(E, D, row, fr, col0, ee[0], ee[1]);
; template <class Epi>
; __device__ __forceinline__ void gemm_phase(LAS unsigned char* lds, const Gemm g, const StaticOrder& S, const Epi& E) {
;     ...
;             PG8_LDA(At, 1, 1); PG8_STAGE(PG8_SA(1, 0), a3, voffA);
;             PG8_BAR; PG8_WAIT_L(0); PG8_MMA(1, 0, At, B0); PG8_BAR; PG8_SCHED;
;             PG8_STAGE(PG8_SB(1, 1), b3, voffB1);
;             PG8_WAIT_V(6); PG8_BAR; PG8_MMA(1, 1, At, B1); PG8_BAR;
;         }
	ds_read_b128 v[162:165], v178 offset:49152
	ds_read_b128 v[166:169], v178 offset:50176
	ds_read_b128 v[182:185], v178 offset:51200
	ds_read_b128 v[186:189], v178 offset:52224
	ds_read_b128 v[190:193], v178 offset:53248
	ds_read_b128 v[194:197], v178 offset:54272
	ds_read_b128 v[198:201], v178 offset:55296
	ds_read_b128 v[204:207], v178 offset:56320
	global_load_lds_dwordx4 v[170:171], off
	v_lshl_add_u64 v[170:171], v[228:229], 0, s[42:43]
	s_mov_b32 m0, s75
	s_nop 0
	global_load_lds_dwordx4 v[170:171], off
	s_add_i32 s33, s62, s69
	v_lshl_add_u64 v[250:251], v[230:231], 0, s[42:43]
	s_mov_b32 m0, s33
	s_nop 0
	global_load_lds_dwordx4 v[250:251], off
	v_lshl_add_u64 v[250:251], v[232:233], 0, s[42:43]
	s_add_i32 m0, s33, 0x2000
	s_nop 0
	global_load_lds_dwordx4 v[250:251], off
	s_waitcnt vmcnt(6)
	s_barrier
	s_waitcnt lgkmcnt(0)
	v_mfma_f32_16x16x32_bf16 v[76:79], v[48:51], v[162:165], v[76:79]
	v_mfma_f32_16x16x32_bf16 v[72:75], v[64:67], v[162:165], v[72:75]
	v_mfma_f32_16x16x32_bf16 v[60:63], v[48:51], v[182:185], v[60:63]
	v_mfma_f32_16x16x32_bf16 v[56:59], v[64:67], v[182:185], v[56:59]
	v_mfma_f32_16x16x32_bf16 v[28:31], v[48:51], v[190:193], v[28:31]
	v_mfma_f32_16x16x32_bf16 v[24:27], v[64:67], v[190:193], v[24:27]
	v_mfma_f32_16x16x32_bf16 v[12:15], v[48:51], v[198:201], v[12:15]
	v_mfma_f32_16x16x32_bf16 v[8:11], v[64:67], v[198:201], v[8:11]
	v_mfma_f32_16x16x32_bf16 v[76:79], v[52:55], v[166:169], v[76:79]
	v_mfma_f32_16x16x32_bf16 v[72:75], v[68:71], v[166:169], v[72:75]
	v_mfma_f32_16x16x32_bf16 v[60:63], v[52:55], v[186:189], v[60:63]
	v_mfma_f32_16x16x32_bf16 v[56:59], v[68:71], v[186:189], v[56:59]
	v_mfma_f32_16x16x32_bf16 v[28:31], v[52:55], v[194:197], v[28:31]
	v_mfma_f32_16x16x32_bf16 v[24:27], v[68:71], v[194:197], v[24:27]
	v_mfma_f32_16x16x32_bf16 v[12:15], v[52:55], v[204:207], v[12:15]
	v_mfma_f32_16x16x32_bf16 v[8:11], v[68:71], v[204:207], v[8:11]
	v_mfma_f32_16x16x32_bf16 v[32:35], v[208:211], v[162:165], v[32:35]
	v_mfma_f32_16x16x32_bf16 v[68:71], v[212:215], v[166:169], v[32:35]
	v_mfma_f32_16x16x32_bf16 v[32:35], v[216:219], v[162:165], v[40:43]
	v_mfma_f32_16x16x32_bf16 v[64:67], v[220:223], v[166:169], v[32:35]
	v_mfma_f32_16x16x32_bf16 v[32:35], v[208:211], v[182:185], v[44:47]
	v_mfma_f32_16x16x32_bf16 v[44:47], v[212:215], v[186:189], v[32:35]
	v_mfma_f32_16x16x32_bf16 v[32:35], v[216:219], v[182:185], v[36:39]
	v_mfma_f32_16x16x32_bf16 v[20:23], v[208:211], v[190:193], v[20:23]
	v_mfma_f32_16x16x32_bf16 v[16:19], v[216:219], v[190:193], v[16:19]
	v_mfma_f32_16x16x32_bf16 v[4:7], v[208:211], v[198:201], v[4:7]
	v_mfma_f32_16x16x32_bf16 v[0:3], v[216:219], v[198:201], v[0:3]
	v_mfma_f32_16x16x32_bf16 v[36:39], v[220:223], v[186:189], v[32:35]
	v_mfma_f32_16x16x32_bf16 v[20:23], v[212:215], v[194:197], v[20:23]
	v_mfma_f32_16x16x32_bf16 v[16:19], v[220:223], v[194:197], v[16:19]
	v_mfma_f32_16x16x32_bf16 v[4:7], v[212:215], v[204:207], v[4:7]
	v_mfma_f32_16x16x32_bf16 v[0:3], v[220:223], v[204:207], v[0:3]
	s_add_i32 s86, s86, 2
	s_add_u32 s60, s60, 0x100
	s_addc_u32 s61, s61, 0
	s_add_u32 s84, s84, 0x100
	s_addc_u32 s85, s85, 0
	s_cmp_gt_u32 s86, 29
	s_barrier
	s_cbranch_scc0 .LBB0_882
	s_lshl_b32 s33, s58, 8
	s_add_i32 s33, s33, s77
	v_lshl_or_b32 v32, s56, 8, v176
	v_or_b32_e32 v40, s33, v174
	v_or_b32_e32 v34, v32, v175
	v_ashrrev_i32_e32 v41, 31, v40
	v_ashrrev_i32_e32 v35, 31, v34
	v_lshlrev_b64 v[168:169], 12, v[40:41]
	v_lshl_add_u64 v[42:43], s[16:17], 0, v[168:169]
	v_lshlrev_b64 v[162:163], 1, v[34:35]
	v_lshl_add_u64 v[34:35], v[42:43], 0, v[162:163]
	global_load_dwordx4 v[182:185], v[34:35], off
	v_or_b32_e32 v34, 8, v40
	v_ashrrev_i32_e32 v35, 31, v34
	v_or_b32_e32 v164, s33, v172
	v_lshlrev_b64 v[170:171], 12, v[34:35]
	v_ashrrev_i32_e32 v165, 31, v164
	v_lshl_add_u64 v[34:35], s[16:17], 0, v[170:171]
	v_lshl_add_u64 v[166:167], v[164:165], 2, s[40:41]
	v_lshl_add_u64 v[34:35], v[34:35], 0, v[162:163]
	global_load_dword v181, v[166:167], off
	v_lshl_add_u64 v[40:41], s[38:39], 0, v[168:169]
	global_load_dwordx4 v[190:193], v[34:35], off
	v_lshl_add_u64 v[34:35], s[38:39], 0, v[170:171]
	v_lshl_add_u64 v[40:41], v[40:41], 0, v[162:163]
	v_lshl_add_u64 v[34:35], v[34:35], 0, v[162:163]
	global_load_dwordx4 v[186:189], v[40:41], off
	global_load_dwordx4 v[194:197], v[34:35], off
	v_ashrrev_i32_e32 v33, 31, v32
	v_lshl_add_u64 v[40:41], v[32:33], 2, s[10:11]
	global_load_dwordx4 v[52:55], v[40:41], off
	global_load_dwordx4 v[48:51], v[40:41], off offset:16
	global_load_dwordx4 v[32:35], v[40:41], off offset:48
	s_nop 0
	global_load_dwordx4 v[40:43], v[40:41], off offset:32
	v_or_b32_e32 v216, 16, v164
	v_ashrrev_i32_e32 v217, 31, v216
	v_lshl_add_u64 v[218:219], v[216:217], 2, s[40:41]
	global_load_dword v226, v[218:219], off
	v_sub_u32_e32 v218, v216, v172
	v_add_u32_e32 v218, v218, v174
	v_ashrrev_i32_e32 v219, 31, v218
	v_lshlrev_b64 v[218:219], 12, v[218:219]
	v_lshl_add_u64 v[220:221], s[16:17], 0, v[218:219]
	v_lshl_add_u64 v[220:221], v[220:221], 0, v[162:163]
	global_load_dwordx4 v[228:231], v[220:221], off
	v_lshl_add_u64 v[220:221], s[38:39], 0, v[218:219]
	v_lshl_add_u64 v[220:221], v[220:221], 0, v[162:163]
	global_load_dwordx4 v[232:235], v[220:221], off
	v_lshl_add_u64 v[220:221], v[218:219], 0, s[44:45]
	v_lshl_add_u64 v[224:225], s[38:39], 0, v[220:221]
	v_lshl_add_u64 v[222:223], s[16:17], 0, v[220:221]
	v_lshl_add_u64 v[224:225], v[224:225], 0, v[162:163]
	v_lshl_add_u64 v[222:223], v[222:223], 0, v[162:163]
	global_load_dwordx4 v[236:239], v[224:225], off
	global_load_dwordx4 v[240:243], v[222:223], off
	v_mul_f32_e32 v140, 0xbfb8aa3b, v140
	v_exp_f32_e32 v140, v140
	v_mul_f32_e32 v141, 0xbfb8aa3b, v141
	v_exp_f32_e32 v141, v141
	v_add_f32_e32 v140, 1.0, v140
	v_rcp_f32_e32 v140, v140
	v_add_f32_e32 v141, 1.0, v141
	v_rcp_f32_e32 v141, v141
	v_mul_f32_e32 v136, 0xbfb8aa3b, v136
	v_exp_f32_e32 v136, v136
	v_mul_f32_e32 v137, 0xbfb8aa3b, v137
	v_exp_f32_e32 v137, v137
	v_add_f32_e32 v136, 1.0, v136
	v_rcp_f32_e32 v136, v136
	v_add_f32_e32 v137, 1.0, v137
	v_mul_f32_e32 v132, 0xbfb8aa3b, v132
	v_rcp_f32_e32 v137, v137
	v_exp_f32_e32 v132, v132
	v_mul_f32_e32 v133, 0xbfb8aa3b, v133
	v_exp_f32_e32 v133, v133
	v_add_f32_e32 v132, 1.0, v132
	v_rcp_f32_e32 v132, v132
	v_add_f32_e32 v133, 1.0, v133
	v_rcp_f32_e32 v133, v133
	v_mul_f32_e32 v128, 0xbfb8aa3b, v128
	v_exp_f32_e32 v128, v128
	v_mul_f32_e32 v129, 0xbfb8aa3b, v129
	v_exp_f32_e32 v129, v129
	v_add_f32_e32 v128, 1.0, v128
	v_rcp_f32_e32 v128, v128
	v_add_f32_e32 v129, 1.0, v129
	v_rcp_f32_e32 v129, v129
	s_waitcnt vmcnt(5)
; __device__ __forceinline__ unsigned cvt_pk_bf16(float lo, float hi) { unsigned r; asm volatile("v_cvt_pk_bf16_f32 %0, %1, %2" : "=v"(r) : "v"(lo), "v"(hi)); return r; }
; __device__ __forceinline__ float bflo(unsigned w) { return __uint_as_float(w << 16); }
; __device__ __forceinline__ float bfhi(unsigned w) { return __uint_as_float(w & 0xffff0000u); }
;     __device__ __forceinline__ void operator()(const f32x4 (&acc)[2][2][4][2], const Unit& u, int wr, int wc, int fr, int fq) const {
;     ...
;             for (int m = 0; m < 4; ++m) { const int row = row0 + ai * HALF + m * 16; const size_t off = (size_t)row * D + col0; const float ri = __builtin_amdgcn_rsqf(sse[row] * (1.f / D) + EPS); float sq = 0.f; u32x4 w[2];
;                 u32x4 rr[2], ee[2]; load_pair_lines(R, D, row, fr, col0, rr[0], rr[1]); load_pair_lines(E, D, row, fr, col0, ee[0], ee[1]);
; #pragma unroll
;                 for (int bj = 0; bj < 2; ++bj) { const u32x4 rw = rr[bj], ew = ee[bj];
;                     const float r[8] = {bflo(rw.x), bfhi(rw.x), bflo(rw.y), bfhi(rw.y), bflo(rw.z), bfhi(rw.z), bflo(rw.w), bfhi(rw.w)};
;                     const float e[8] = {bflo(ew.x), bfhi(ew.x), bflo(ew.y), bfhi(ew.y), bflo(ew.z), bfhi(ew.z), bflo(ew.w), bfhi(ew.w)};
;                     float o[8];
; #pragma unroll
;                     for (int j = 0; j < 8; ++j) { const float a = acc[ai][bj][m][j >> 2][j & 3]; const float gg = gv[bj][j >> 2][j & 3];
;                         o[j] = r[j] + e[j] * ri * gg * __builtin_amdgcn_rcpf(1.f + __builtin_amdgcn_exp2f(-a * LOG2E)); }
;                     if (OUT) { *(f32x4*)(OUT + off + 8 * bj) = (f32x4){o[0], o[1], o[2], o[3]}; *(f32x4*)(OUT + off + 8 * bj + 4) = (f32x4){o[4], o[5], o[6], o[7]}; }
;                     else { sq += (o[0] * o[0] + o[1] * o[1]) + (o[2] * o[2] + o[3] * o[3]) + (o[4] * o[4] + o[5] * o[5]) + (o[6] * o[6] + o[7] * o[7]);
;                         w[bj].x = cvt_pk_bf16(o[0], o[1]); w[bj].y = cvt_pk_bf16(o[2], o[3]); w[bj].z = cvt_pk_bf16(o[4], o[5]); w[bj].w = cvt_pk_bf16(o[6], o[7]); } }
;                 if (!OUT) { store_pair_lines(O, D, row, fr, col0, w[0], w[1]);
;                     sq += __shfl_xor(sq, 16); sq += __shfl_xor(sq, 32); if (fq == 0) unsafeAtomicAdd(ssout + row, sq); } }
	v_mov_b32_dpp v198, v182 row_ror:8 row_mask:0xf bank_mask:0xf
	v_mov_b32_dpp v199, v183 row_ror:8 row_mask:0xf bank_mask:0xf
	v_mov_b32_dpp v200, v184 row_ror:8 row_mask:0xf bank_mask:0xf
	v_mov_b32_dpp v201, v185 row_ror:8 row_mask:0xf bank_mask:0xf
	v_fmamk_f32 v181, v181, 0x3a000000, v180
	v_rsq_f32_e32 v181, v181
	v_mov_b32_dpp v204, v190 row_ror:8 row_mask:0xf bank_mask:0xf
	v_cndmask_b32_e64 v182, v204, v182, s[6:7]
	v_cndmask_b32_e64 v190, v190, v198, s[6:7]
	v_lshlrev_b32_e32 v198, 16, v182
	v_mov_b32_dpp v208, v186 row_ror:8 row_mask:0xf bank_mask:0xf
	v_mov_b32_dpp v212, v194 row_ror:8 row_mask:0xf bank_mask:0xf
	v_cndmask_b32_e64 v186, v212, v186, s[6:7]
	v_lshlrev_b32_e32 v204, 16, v186
	v_mul_f32_e32 v204, v181, v204
	v_and_b32_e32 v186, 0xffff0000, v186
	v_mul_f32_e32 v204, v52, v204
	v_fmac_f32_e32 v198, v140, v204
	v_mul_f32_e32 v140, v181, v186
	v_and_b32_e32 v182, 0xffff0000, v182
	v_mul_f32_e32 v140, v53, v140
	v_fmac_f32_e32 v182, v141, v140
	v_mul_f32_e32 v140, 0xbfb8aa3b, v142
	v_exp_f32_e32 v140, v140
	v_mul_f32_e32 v142, 0xbfb8aa3b, v143
	v_exp_f32_e32 v142, v142
	v_mov_b32_dpp v213, v195 row_ror:8 row_mask:0xf bank_mask:0xf
	v_add_f32_e32 v140, 1.0, v140
	v_mov_b32_dpp v209, v187 row_ror:8 row_mask:0xf bank_mask:0xf
	v_mov_b32_dpp v205, v191 row_ror:8 row_mask:0xf bank_mask:0xf
	v_cndmask_b32_e64 v187, v213, v187, s[6:7]
	v_rcp_f32_e32 v140, v140
	v_cndmask_b32_e64 v183, v205, v183, s[6:7]
	v_lshlrev_b32_e32 v205, 16, v187
	v_add_f32_e32 v142, 1.0, v142
	v_mul_f32_e32 v141, v181, v205
	v_rcp_f32_e32 v142, v142
	v_cndmask_b32_e64 v191, v191, v199, s[6:7]
	v_mov_b32_dpp v214, v196 row_ror:8 row_mask:0xf bank_mask:0xf
	v_lshlrev_b32_e32 v199, 16, v183
	v_and_b32_e32 v187, 0xffff0000, v187
	v_mul_f32_e32 v141, v54, v141
	v_mov_b32_dpp v210, v188 row_ror:8 row_mask:0xf bank_mask:0xf
	v_mov_b32_dpp v206, v192 row_ror:8 row_mask:0xf bank_mask:0xf
	v_cndmask_b32_e64 v188, v214, v188, s[6:7]
	v_fmac_f32_e32 v199, v140, v141
	v_mul_f32_e32 v140, v181, v187
	v_cndmask_b32_e64 v184, v206, v184, s[6:7]
	v_and_b32_e32 v183, 0xffff0000, v183
	v_lshlrev_b32_e32 v206, 16, v188
	v_mul_f32_e32 v140, v55, v140
	v_fmac_f32_e32 v183, v142, v140
	v_mul_f32_e32 v140, v181, v206
	v_cndmask_b32_e64 v192, v192, v200, s[6:7]
	v_lshlrev_b32_e32 v200, 16, v184
	v_and_b32_e32 v188, 0xffff0000, v188
	v_mul_f32_e32 v140, v48, v140
	v_fmac_f32_e32 v200, v136, v140
	v_mul_f32_e32 v136, v181, v188
	v_and_b32_e32 v184, 0xffff0000, v184
	v_mul_f32_e32 v136, v49, v136
	v_fmac_f32_e32 v184, v137, v136
	v_mul_f32_e32 v136, 0xbfb8aa3b, v138
	v_cndmask_b32_e64 v194, v194, v208, s[6:7]
	v_exp_f32_e32 v136, v136
	v_mul_f32_e32 v138, 0xbfb8aa3b, v139
	v_lshlrev_b32_e32 v187, 16, v194
	v_exp_f32_e32 v138, v138
	v_mul_f32_e32 v187, v181, v187
	v_lshlrev_b32_e32 v141, 16, v190
	v_and_b32_e32 v188, 0xffff0000, v194
	v_mul_f32_e32 v187, v40, v187
	v_mov_b32_dpp v215, v197 row_ror:8 row_mask:0xf bank_mask:0xf
	v_add_f32_e32 v136, 1.0, v136
	v_fmac_f32_e32 v141, v132, v187
	v_mul_f32_e32 v132, v181, v188
	v_mov_b32_dpp v211, v189 row_ror:8 row_mask:0xf bank_mask:0xf
	v_mov_b32_dpp v207, v193 row_ror:8 row_mask:0xf bank_mask:0xf
	v_cndmask_b32_e64 v189, v215, v189, s[6:7]
	v_rcp_f32_e32 v136, v136
	v_and_b32_e32 v142, 0xffff0000, v190
	v_mul_f32_e32 v132, v41, v132
	v_cndmask_b32_e64 v185, v207, v185, s[6:7]
	v_lshlrev_b32_e32 v207, 16, v189
	v_add_f32_e32 v138, 1.0, v138
	v_fmac_f32_e32 v142, v133, v132
	v_mul_f32_e32 v132, 0xbfb8aa3b, v134
	v_mul_f32_e32 v137, v181, v207
	v_rcp_f32_e32 v138, v138
	v_exp_f32_e32 v132, v132
	v_cndmask_b32_e64 v193, v193, v201, s[6:7]
	v_lshlrev_b32_e32 v201, 16, v185
	v_and_b32_e32 v189, 0xffff0000, v189
	v_mul_f32_e32 v137, v50, v137
	v_mul_f32_e32 v134, 0xbfb8aa3b, v135
	v_fmac_f32_e32 v201, v136, v137
	v_mul_f32_e32 v136, v181, v189
	v_exp_f32_e32 v134, v134
	v_and_b32_e32 v185, 0xffff0000, v185
	v_mul_f32_e32 v136, v51, v136
	v_fmac_f32_e32 v185, v138, v136
	v_mul_f32_e32 v136, v182, v182
	v_mul_f32_e32 v137, v183, v183
	v_add_f32_e32 v132, 1.0, v132
	v_cndmask_b32_e64 v195, v195, v209, s[6:7]
	v_fmac_f32_e32 v136, v198, v198
	v_fmac_f32_e32 v137, v199, v199
	v_rcp_f32_e32 v132, v132
	v_add_f32_e32 v136, v136, v137
	v_mul_f32_e32 v137, v184, v184
; __device__ __forceinline__ unsigned cvt_pk_bf16(float lo, float hi) { unsigned r; asm volatile("v_cvt_pk_bf16_f32 %0, %1, %2" : "=v"(r) : "v"(lo), "v"(hi)); return r; }
; __device__ __forceinline__ unsigned dpp_ror8(unsigned x) { return (unsigned)__builtin_amdgcn_update_dpp(0, (int)x, 0x128, 0xf, 0xf, false); }
; __device__ __forceinline__ void store_pair_lines(bf16_t* O, int ldc, int row, int fr, int col0, u32x4 wA, u32x4 wB) {
;     const u32x4 sA = {dpp_ror8(wA.x), dpp_ror8(wA.y), dpp_ror8(wA.z), dpp_ror8(wA.w)}, sB = {dpp_ror8(wB.x), dpp_ror8(wB.y), dpp_ror8(wB.z), dpp_ror8(wB.w)};
;     const bool lo = fr < 8;
;     const u32x4 o1 = lo ? wA : sB, o2 = lo ? sA : wB;
;     const int r1 = row - fr + (fr & 7), cb = col0 + (lo ? 0 : 8);
;     *(u32x4*)(O + (size_t)r1 * ldc + cb) = o1;
;     *(u32x4*)(O + (size_t)(r1 + 8) * ldc + cb) = o2;
; }
;     __device__ __forceinline__ void operator()(const f32x4 (&acc)[2][2][4][2], const Unit& u, int wr, int wc, int fr, int fq) const {
;     ...
;                     for (int j = 0; j < 8; ++j) { const float a = acc[ai][bj][m][j >> 2][j & 3]; const float gg = gv[bj][j >> 2][j & 3];
;                         o[j] = r[j] + e[j] * ri * gg * __builtin_amdgcn_rcpf(1.f + __builtin_amdgcn_exp2f(-a * LOG2E)); }
;                     if (OUT) { *(f32x4*)(OUT + off + 8 * bj) = (f32x4){o[0], o[1], o[2], o[3]}; *(f32x4*)(OUT + off + 8 * bj + 4) = (f32x4){o[4], o[5], o[6], o[7]}; }
;                     else { sq += (o[0] * o[0] + o[1] * o[1]) + (o[2] * o[2] + o[3] * o[3]) + (o[4] * o[4] + o[5] * o[5]) + (o[6] * o[6] + o[7] * o[7]);
;                         w[bj].x = cvt_pk_bf16(o[0], o[1]); w[bj].y = cvt_pk_bf16(o[2], o[3]); w[bj].z = cvt_pk_bf16(o[4], o[5]); w[bj].w = cvt_pk_bf16(o[6], o[7]); } }
;                 if (!OUT) { store_pair_lines(O, D, row, fr, col0, w[0], w[1]);
;                     sq += __shfl_xor(sq, 16); sq += __shfl_xor(sq, 32); if (fq == 0) unsafeAtomicAdd(ssout + row, sq); } }
	v_lshlrev_b32_e32 v189, 16, v195
	v_add_f32_e32 v134, 1.0, v134
	v_fmac_f32_e32 v137, v200, v200
	v_mul_f32_e32 v133, v181, v189
	v_rcp_f32_e32 v134, v134
	v_add_f32_e32 v136, v137, v136
	v_mul_f32_e32 v137, v185, v185
	v_lshlrev_b32_e32 v143, 16, v191
	v_and_b32_e32 v190, 0xffff0000, v195
	v_mul_f32_e32 v133, v42, v133
	v_cndmask_b32_e64 v196, v196, v210, s[6:7]
	v_fmac_f32_e32 v137, v201, v201
	v_fmac_f32_e32 v143, v132, v133
	v_mul_f32_e32 v132, v181, v190
	v_add_f32_e32 v136, v137, v136
	v_cvt_pk_bf16_f32 v137, v198, v182
	v_and_b32_e32 v182, 0xffff0000, v191
	v_lshlrev_b32_e32 v191, 16, v196
	v_mul_f32_e32 v132, v43, v132
	v_fmac_f32_e32 v182, v134, v132
	v_mul_f32_e32 v132, v181, v191
	v_cvt_pk_bf16_f32 v138, v199, v183
	v_cvt_pk_bf16_f32 v139, v200, v184
	v_lshlrev_b32_e32 v183, 16, v192
	v_and_b32_e32 v184, 0xffff0000, v192
	v_and_b32_e32 v192, 0xffff0000, v196
	v_mul_f32_e32 v132, v32, v132
	v_fmac_f32_e32 v183, v128, v132
	v_mul_f32_e32 v128, v181, v192
	v_mul_f32_e32 v128, v33, v128
	v_fmac_f32_e32 v184, v129, v128
	v_mul_f32_e32 v128, 0xbfb8aa3b, v130
	v_exp_f32_e32 v128, v128
	v_mul_f32_e32 v130, 0xbfb8aa3b, v131
	v_exp_f32_e32 v130, v130
	v_cndmask_b32_e64 v197, v197, v211, s[6:7]
	v_add_f32_e32 v128, 1.0, v128
	v_rcp_f32_e32 v128, v128
	v_cvt_pk_bf16_f32 v140, v201, v185
	v_lshlrev_b32_e32 v185, 16, v193
	v_and_b32_e32 v186, 0xffff0000, v193
	v_lshlrev_b32_e32 v193, 16, v197
	v_add_f32_e32 v130, 1.0, v130
	v_mul_f32_e32 v129, v181, v193
	v_rcp_f32_e32 v130, v130
	v_and_b32_e32 v194, 0xffff0000, v197
	v_mul_f32_e32 v129, v34, v129
	v_fmac_f32_e32 v185, v128, v129
	v_mul_f32_e32 v128, v181, v194
	v_mul_f32_e32 v128, v35, v128
	v_fmac_f32_e32 v186, v130, v128
	v_mul_f32_e32 v128, v142, v142
	v_mul_f32_e32 v129, v182, v182
	v_fmac_f32_e32 v128, v141, v141
	v_fmac_f32_e32 v129, v143, v143
	v_add_f32_e32 v128, v128, v129
	v_mul_f32_e32 v129, v184, v184
	v_fmac_f32_e32 v129, v183, v183
	v_add_f32_e32 v128, v129, v128
	v_mul_f32_e32 v129, v186, v186
	v_fmac_f32_e32 v129, v185, v185
	v_add_f32_e32 v128, v129, v128
	v_add_f32_e32 v135, v128, v136
	v_cvt_pk_bf16_f32 v128, v141, v142
	v_cvt_pk_bf16_f32 v129, v143, v182
	v_mov_b32_dpp v143, v138 row_ror:8 row_mask:0xf bank_mask:0xf
	v_mov_b32_dpp v130, v128 row_ror:8 row_mask:0xf bank_mask:0xf
	v_mov_b32_dpp v134, v137 row_ror:8 row_mask:0xf bank_mask:0xf
	v_cndmask_b32_e64 v130, v130, v137, s[6:7]
	v_mov_b32_dpp v131, v129 row_ror:8 row_mask:0xf bank_mask:0xf
	v_cndmask_b32_e64 v137, v129, v143, s[6:7]
	v_and_b32_e32 v129, 64, v203
	v_cndmask_b32_e64 v136, v128, v134, s[6:7]
	v_xor_b32_e32 v128, 16, v203
	v_add_u32_e32 v143, 64, v129
	v_cmp_lt_i32_e32 vcc, v128, v143
	v_cvt_pk_bf16_f32 v141, v183, v184
	v_mov_b32_e32 v181, 0
	v_mov_b32_e32 v133, 0
	v_cndmask_b32_e32 v128, v203, v128, vcc
	v_lshlrev_b32_e32 v134, 2, v128
	v_mov_b32_e32 v183, v135
	s_nop 1
	v_permlane16_swap_b32_e32 v183, v135
	v_cvt_pk_bf16_f32 v142, v185, v186
	v_mov_b32_dpp v181, v139 row_ror:8 row_mask:0xf bank_mask:0xf
	v_mov_b32_e32 v182, 0
	v_mov_b32_dpp v133, v142 row_ror:8 row_mask:0xf bank_mask:0xf
	v_lshl_add_u64 v[128:129], s[36:37], 0, v[168:169]
	v_mov_b32_dpp v182, v140 row_ror:8 row_mask:0xf bank_mask:0xf
	v_mov_b32_dpp v132, v141 row_ror:8 row_mask:0xf bank_mask:0xf
	v_cndmask_b32_e64 v131, v131, v138, s[6:7]
	v_cndmask_b32_e64 v133, v133, v140, s[6:7]
	v_cndmask_b32_e64 v138, v141, v181, s[6:7]
	v_lshl_add_u64 v[140:141], v[128:129], 0, v[162:163]
	v_xor_b32_e32 v129, 32, v203
	v_cmp_lt_i32_e32 vcc, v129, v143
	s_waitcnt lgkmcnt(0)
	v_add_f32_e32 v128, v135, v183
	v_cndmask_b32_e64 v132, v132, v139, s[6:7]
	v_cndmask_b32_e32 v129, v203, v129, vcc
	v_lshlrev_b32_e32 v135, 2, v129
	v_mov_b32_e32 v129, v128
	s_nop 1
	v_permlane32_swap_b32_e32 v129, v128
	global_store_dwordx4 v[140:141], v[130:133], off
	v_cndmask_b32_e64 v139, v142, v182, s[6:7]
	s_nop 0
	v_lshl_add_u64 v[130:131], s[36:37], 0, v[170:171]
	v_lshl_add_u64 v[130:131], v[130:131], 0, v[162:163]
	global_store_dwordx4 v[130:131], v[136:139], off
	s_and_saveexec_b64 s[56:57], s[8:9]
	s_cbranch_execz .LBB0_885
	v_lshl_add_u64 v[130:131], v[164:165], 2, s[18:19]
	s_waitcnt lgkmcnt(0)
	v_add_f32_e32 v128, v128, v129
	global_atomic_add_f32 v[130:131], v128, off

; #define PG8_STAGE(bufoff, gbase, voff) do { _Pragma("unroll") for (int _i = 0; _i < 2; ++_i) \
;         __builtin_amdgcn_global_load_lds((const unsigned*)((const char*)(gbase) + (voff)[_i]), (LAS unsigned*)(lds + (bufoff) + ldsw + _i * 8192), 16, 0, 0); } while (0)
; #define PG8_LDA(dst, b, h) do { _Pragma("unroll") for (int m = 0; m < 4; ++m) _Pragma("unroll") for (int k = 0; k < 2; ++k) dst[m][k] = *(const LAS bf16x8*)(lds + PG8_SA(b, h) + aoff + m * 2048 + k * 1024); } while (0)
; #define PG8_LDB(dst, b, h) do { _Pragma("unroll") for (int n = 0; n < 2; ++n) _Pragma("unroll") for (int k = 0; k < 2; ++k) dst[n][k] = *(const LAS bf16x8*)(lds + PG8_SB(b, h) + boff + n * 2048 + k * 1024); } while (0)
; #define PG8_MMA(ai, bj, At, Bt) do { __builtin_amdgcn_s_setprio(1); _Pragma("unroll") for (int m = 0; m < 4; ++m) _Pragma("unroll") for (int n = 0; n < 2; ++n) _Pragma("unroll") for (int k = 0; k < 2; ++k) \
;         acc[ai][bj][m][n] = __builtin_amdgcn_mfma_f32_16x16x32_bf16(Bt[n][k], At[m][k], acc[ai][bj][m][n], 0, 0, 0); __builtin_amdgcn_s_setprio(0); } while (0)
; #define PG8_WAIT_V(n) asm volatile("s_waitcnt vmcnt(" #n ")" ::: "memory")
; #define PG8_WAIT_L(n) asm volatile("s_waitcnt lgkmcnt(" #n ")" ::: "memory")
; #define PG8_BAR __builtin_amdgcn_s_barrier()
; #define PG8_SCHED __builtin_amdgcn_sched_barrier(0)
; template <class Epi>
; __device__ __forceinline__ void gemm_phase(LAS unsigned char* lds, const Gemm g, const StaticOrder& S, const Epi& E) {
;     ...
;             PG8_LDB(B0, 0, 0); PG8_SCHED; PG8_LDA(At, 0, 0); PG8_STAGE(PG8_SA(1, 1), a1 + hstep, voffA);
;             PG8_WAIT_L(8); PG8_BAR; PG8_WAIT_L(0); PG8_MMA(0, 0, At, B0); PG8_BAR; PG8_SCHED;
;             PG8_LDB(B1, 0, 1); PG8_STAGE(PG8_SB(0, 0), b2, voffB0);
;             PG8_BAR; PG8_WAIT_L(0); PG8_MMA(0, 1, At, B1); PG8_BAR;
;             PG8_LDA(At, 0, 1); PG8_STAGE(PG8_SA(0, 0), a2, voffA);
;             PG8_BAR; PG8_WAIT_L(0); PG8_MMA(1, 0, At, B0); PG8_BAR; PG8_SCHED;
;             PG8_STAGE(PG8_SB(0, 1), b2, voffB1);
;             PG8_WAIT_V(6); PG8_BAR; PG8_MMA(1, 1, At, B1); PG8_BAR;
.LBB0_962:
	ds_read_b128 v[146:149], v158
	ds_read_b128 v[150:153], v158 offset:1024
	ds_read_b128 v[162:165], v158 offset:2048
	ds_read_b128 v[166:169], v158 offset:3072
	s_add_u32 s33, s46, 0xfff80080
	s_addc_u32 s48, s47, -1
	s_cmp_eq_u32 s77, 28
	s_cselect_b32 s49, s37, s48
	s_cselect_b32 s48, s72, s33
	s_cselect_b32 s51, s19, s75
	s_cselect_b32 s50, s73, s74
	v_lshl_add_u64 v[204:205], s[46:47], 0, v[140:141]
	s_add_i32 m0, s45, 0xc000
	ds_read_b128 v[170:173], v159
	ds_read_b128 v[174:177], v159 offset:1024
	ds_read_b128 v[178:181], v159 offset:2048
	ds_read_b128 v[182:185], v159 offset:3072
	ds_read_b128 v[186:189], v159 offset:4096
	ds_read_b128 v[190:193], v159 offset:5120
	ds_read_b128 v[194:197], v159 offset:6144
	ds_read_b128 v[198:201], v159 offset:7168
	global_load_lds_dwordx4 v[204:205], off
	v_lshl_add_u64 v[204:205], s[46:47], 0, v[142:143]
	s_add_i32 m0, s45, 0xe000
	s_nop 0
	global_load_lds_dwordx4 v[204:205], off
	s_waitcnt lgkmcnt(8)
	s_barrier
	s_waitcnt lgkmcnt(0)
	v_mfma_f32_16x16x32_bf16 v[124:127], v[146:149], v[170:173], v[124:127]
	v_mfma_f32_16x16x32_bf16 v[120:123], v[162:165], v[170:173], v[120:123]
	v_mfma_f32_16x16x32_bf16 v[108:111], v[146:149], v[178:181], v[108:111]
	v_mfma_f32_16x16x32_bf16 v[104:107], v[162:165], v[178:181], v[104:107]
	v_mfma_f32_16x16x32_bf16 v[92:95], v[146:149], v[186:189], v[92:95]
	v_mfma_f32_16x16x32_bf16 v[88:91], v[162:165], v[186:189], v[88:91]
	v_mfma_f32_16x16x32_bf16 v[76:79], v[146:149], v[194:197], v[76:79]
	v_mfma_f32_16x16x32_bf16 v[72:75], v[162:165], v[194:197], v[72:75]
	v_mfma_f32_16x16x32_bf16 v[124:127], v[150:153], v[174:177], v[124:127]
	v_mfma_f32_16x16x32_bf16 v[120:123], v[166:169], v[174:177], v[120:123]
	v_mfma_f32_16x16x32_bf16 v[108:111], v[150:153], v[182:185], v[108:111]
	v_mfma_f32_16x16x32_bf16 v[104:107], v[166:169], v[182:185], v[104:107]
	v_mfma_f32_16x16x32_bf16 v[92:95], v[150:153], v[190:193], v[92:95]
	v_mfma_f32_16x16x32_bf16 v[88:91], v[166:169], v[190:193], v[88:91]
	v_mfma_f32_16x16x32_bf16 v[76:79], v[150:153], v[198:201], v[76:79]
	v_mfma_f32_16x16x32_bf16 v[72:75], v[166:169], v[198:201], v[72:75]
	s_barrier
	s_add_i32 s33, s68, s57
	v_lshl_add_u64 v[220:221], s[50:51], 0, v[134:135]
	s_mov_b32 m0, s33
	ds_read_b128 v[204:207], v160
	ds_read_b128 v[208:211], v160 offset:1024
	ds_read_b128 v[212:215], v160 offset:2048
	ds_read_b128 v[216:219], v160 offset:3072
	global_load_lds_dwordx4 v[220:221], off
	v_lshl_add_u64 v[222:223], s[50:51], 0, v[128:129]
	s_add_i32 m0, s33, 0x2000
	s_nop 0
	global_load_lds_dwordx4 v[222:223], off
	s_waitcnt lgkmcnt(0)
	s_barrier
	s_waitcnt lgkmcnt(0)
	v_mfma_f32_16x16x32_bf16 v[116:119], v[204:207], v[170:173], v[116:119]
	v_mfma_f32_16x16x32_bf16 v[112:115], v[212:215], v[170:173], v[112:115]
	v_mfma_f32_16x16x32_bf16 v[100:103], v[204:207], v[178:181], v[100:103]
	v_mfma_f32_16x16x32_bf16 v[96:99], v[212:215], v[178:181], v[96:99]
	v_mfma_f32_16x16x32_bf16 v[84:87], v[204:207], v[186:189], v[84:87]
	v_mfma_f32_16x16x32_bf16 v[80:83], v[212:215], v[186:189], v[80:83]
	v_mfma_f32_16x16x32_bf16 v[68:71], v[204:207], v[194:197], v[68:71]
	v_mfma_f32_16x16x32_bf16 v[64:67], v[212:215], v[194:197], v[64:67]
	v_mfma_f32_16x16x32_bf16 v[116:119], v[208:211], v[174:177], v[116:119]
	v_mfma_f32_16x16x32_bf16 v[112:115], v[216:219], v[174:177], v[112:115]
	v_mfma_f32_16x16x32_bf16 v[100:103], v[208:211], v[182:185], v[100:103]
	v_mfma_f32_16x16x32_bf16 v[96:99], v[216:219], v[182:185], v[96:99]
	v_mfma_f32_16x16x32_bf16 v[84:87], v[208:211], v[190:193], v[84:87]
	v_mfma_f32_16x16x32_bf16 v[80:83], v[216:219], v[190:193], v[80:83]
	v_mfma_f32_16x16x32_bf16 v[68:71], v[208:211], v[198:201], v[68:71]
	v_mfma_f32_16x16x32_bf16 v[64:67], v[216:219], v[198:201], v[64:67]
	s_mov_b32 m0, s45
	v_lshl_add_u64 v[224:225], s[48:49], 0, v[138:139]
	s_barrier
	ds_read_b128 v[170:173], v159 offset:16384
	ds_read_b128 v[174:177], v159 offset:17408
	ds_read_b128 v[178:181], v159 offset:18432
	ds_read_b128 v[182:185], v159 offset:19456
	ds_read_b128 v[186:189], v159 offset:20480
	ds_read_b128 v[190:193], v159 offset:21504
	ds_read_b128 v[194:197], v159 offset:22528
	ds_read_b128 v[198:201], v159 offset:23552
	global_load_lds_dwordx4 v[224:225], off
	v_lshl_add_u64 v[226:227], s[48:49], 0, v[132:133]
	s_mov_b32 m0, s59
	s_nop 0
	global_load_lds_dwordx4 v[226:227], off
	s_add_i32 s33, s69, s57
	v_lshl_add_u64 v[228:229], s[50:51], 0, v[136:137]
	s_mov_b32 m0, s33
	v_lshl_add_u64 v[230:231], s[50:51], 0, v[130:131]
	global_load_lds_dwordx4 v[228:229], off
	s_add_i32 m0, s33, 0x2000
	s_nop 0
	global_load_lds_dwordx4 v[230:231], off
	s_waitcnt vmcnt(6)
	s_barrier
; #define PG8_STAGE(bufoff, gbase, voff) do { _Pragma("unroll") for (int _i = 0; _i < 2; ++_i) \
;         __builtin_amdgcn_global_load_lds((const unsigned*)((const char*)(gbase) + (voff)[_i]), (LAS unsigned*)(lds + (bufoff) + ldsw + _i * 8192), 16, 0, 0); } while (0)
; #define PG8_LDA(dst, b, h) do { _Pragma("unroll") for (int m = 0; m < 4; ++m) _Pragma("unroll") for (int k = 0; k < 2; ++k) dst[m][k] = *(const LAS bf16x8*)(lds + PG8_SA(b, h) + aoff + m * 2048 + k * 1024); } while (0)
; #define PG8_LDB(dst, b, h) do { _Pragma("unroll") for (int n = 0; n < 2; ++n) _Pragma("unroll") for (int k = 0; k < 2; ++k) dst[n][k] = *(const LAS bf16x8*)(lds + PG8_SB(b, h) + boff + n * 2048 + k * 1024); } while (0)
; #define PG8_MMA(ai, bj, At, Bt) do { __builtin_amdgcn_s_setprio(1); _Pragma("unroll") for (int m = 0; m < 4; ++m) _Pragma("unroll") for (int n = 0; n < 2; ++n) _Pragma("unroll") for (int k = 0; k < 2; ++k) \
;         acc[ai][bj][m][n] = __builtin_amdgcn_mfma_f32_16x16x32_bf16(Bt[n][k], At[m][k], acc[ai][bj][m][n], 0, 0, 0); __builtin_amdgcn_s_setprio(0); } while (0)
; #define PG8_WAIT_V(n) asm volatile("s_waitcnt vmcnt(" #n ")" ::: "memory")
; #define PG8_WAIT_L(n) asm volatile("s_waitcnt lgkmcnt(" #n ")" ::: "memory")
; #define PG8_BAR __builtin_amdgcn_s_barrier()
; #define PG8_SCHED __builtin_amdgcn_sched_barrier(0)
; template <class Epi>
; __device__ __forceinline__ void gemm_phase(LAS unsigned char* lds, const Gemm g, const StaticOrder& S, const Epi& E) {
;     ...
;             PG8_WAIT_V(6); PG8_BAR; PG8_MMA(1, 1, At, B1); PG8_BAR;
;             PG8_LDB(B0, 1, 0); PG8_SCHED; PG8_LDA(At, 1, 0); PG8_STAGE(PG8_SA(0, 1), a2 + hstep, voffA);
;             PG8_WAIT_L(8); PG8_BAR; PG8_WAIT_L(0); PG8_MMA(0, 0, At, B0); PG8_BAR; PG8_SCHED;
;             PG8_LDB(B1, 1, 1); PG8_STAGE(PG8_SB(1, 0), b3, voffB0);
;             PG8_BAR; PG8_WAIT_L(0); PG8_MMA(0, 1, At, B1); PG8_BAR;
;             PG8_LDA(At, 1, 1); PG8_STAGE(PG8_SA(1, 0), a3, voffA);
;             PG8_BAR; PG8_WAIT_L(0); PG8_MMA(1, 0, At, B0); PG8_BAR; PG8_SCHED;
	s_waitcnt lgkmcnt(0)
	v_mfma_f32_16x16x32_bf16 v[60:63], v[146:149], v[170:173], v[60:63]
	v_mfma_f32_16x16x32_bf16 v[56:59], v[162:165], v[170:173], v[56:59]
	v_mfma_f32_16x16x32_bf16 v[44:47], v[146:149], v[178:181], v[44:47]
	v_mfma_f32_16x16x32_bf16 v[40:43], v[162:165], v[178:181], v[40:43]
	v_mfma_f32_16x16x32_bf16 v[28:31], v[146:149], v[186:189], v[28:31]
	v_mfma_f32_16x16x32_bf16 v[24:27], v[162:165], v[186:189], v[24:27]
	v_mfma_f32_16x16x32_bf16 v[12:15], v[146:149], v[194:197], v[12:15]
	v_mfma_f32_16x16x32_bf16 v[8:11], v[162:165], v[194:197], v[8:11]
	v_mfma_f32_16x16x32_bf16 v[60:63], v[150:153], v[174:177], v[60:63]
	v_mfma_f32_16x16x32_bf16 v[56:59], v[166:169], v[174:177], v[56:59]
	v_mfma_f32_16x16x32_bf16 v[44:47], v[150:153], v[182:185], v[44:47]
	v_mfma_f32_16x16x32_bf16 v[40:43], v[166:169], v[182:185], v[40:43]
	v_mfma_f32_16x16x32_bf16 v[28:31], v[150:153], v[190:193], v[28:31]
	v_mfma_f32_16x16x32_bf16 v[24:27], v[166:169], v[190:193], v[24:27]
	v_mfma_f32_16x16x32_bf16 v[12:15], v[150:153], v[198:201], v[12:15]
	v_mfma_f32_16x16x32_bf16 v[8:11], v[166:169], v[198:201], v[8:11]
	v_mfma_f32_16x16x32_bf16 v[52:55], v[204:207], v[170:173], v[52:55]
	v_mfma_f32_16x16x32_bf16 v[48:51], v[212:215], v[170:173], v[48:51]
	v_mfma_f32_16x16x32_bf16 v[36:39], v[204:207], v[178:181], v[36:39]
	v_mfma_f32_16x16x32_bf16 v[32:35], v[212:215], v[178:181], v[32:35]
	v_mfma_f32_16x16x32_bf16 v[20:23], v[204:207], v[186:189], v[20:23]
	v_mfma_f32_16x16x32_bf16 v[16:19], v[212:215], v[186:189], v[16:19]
	v_mfma_f32_16x16x32_bf16 v[4:7], v[204:207], v[194:197], v[4:7]
	v_mfma_f32_16x16x32_bf16 v[0:3], v[212:215], v[194:197], v[0:3]
	v_mfma_f32_16x16x32_bf16 v[52:55], v[208:211], v[174:177], v[52:55]
	v_mfma_f32_16x16x32_bf16 v[48:51], v[216:219], v[174:177], v[48:51]
	v_mfma_f32_16x16x32_bf16 v[36:39], v[208:211], v[182:185], v[36:39]
	v_mfma_f32_16x16x32_bf16 v[32:35], v[216:219], v[182:185], v[32:35]
	v_mfma_f32_16x16x32_bf16 v[20:23], v[208:211], v[190:193], v[20:23]
	v_mfma_f32_16x16x32_bf16 v[16:19], v[216:219], v[190:193], v[16:19]
	v_mfma_f32_16x16x32_bf16 v[4:7], v[208:211], v[198:201], v[4:7]
	v_mfma_f32_16x16x32_bf16 v[0:3], v[216:219], v[198:201], v[0:3]
	s_add_i32 s33, 0, 0x18000
	v_add_u32_e32 v166, s33, v155
	s_barrier
	ds_read_b128 v[146:149], v166
	ds_read_b128 v[150:153], v166 offset:1024
	ds_read_b128 v[162:165], v166 offset:2048
	ds_read_b128 v[166:169], v166 offset:3072
	s_add_u32 s48, s48, 0x80000
	s_addc_u32 s49, s49, 0
	s_mov_b32 m0, s60
	v_lshl_add_u64 v[204:205], s[48:49], 0, v[138:139]
	ds_read_b128 v[170:173], v159 offset:32768
	ds_read_b128 v[174:177], v159 offset:33792
	ds_read_b128 v[178:181], v159 offset:34816
	ds_read_b128 v[182:185], v159 offset:35840
	ds_read_b128 v[186:189], v159 offset:36864
	ds_read_b128 v[190:193], v159 offset:37888
	ds_read_b128 v[194:197], v159 offset:38912
	ds_read_b128 v[198:201], v159 offset:39936
	global_load_lds_dwordx4 v[204:205], off
	v_lshl_add_u64 v[204:205], s[48:49], 0, v[132:133]
	s_mov_b32 m0, s61
	s_nop 0
	global_load_lds_dwordx4 v[204:205], off
	s_waitcnt lgkmcnt(8)
	s_barrier
	s_waitcnt lgkmcnt(0)
	v_mfma_f32_16x16x32_bf16 v[124:127], v[146:149], v[170:173], v[124:127]
	v_mfma_f32_16x16x32_bf16 v[120:123], v[162:165], v[170:173], v[120:123]
	v_mfma_f32_16x16x32_bf16 v[108:111], v[146:149], v[178:181], v[108:111]
	v_mfma_f32_16x16x32_bf16 v[104:107], v[162:165], v[178:181], v[104:107]
	v_mfma_f32_16x16x32_bf16 v[92:95], v[146:149], v[186:189], v[92:95]
	v_mfma_f32_16x16x32_bf16 v[88:91], v[162:165], v[186:189], v[88:91]
	v_mfma_f32_16x16x32_bf16 v[76:79], v[146:149], v[194:197], v[76:79]
	v_mfma_f32_16x16x32_bf16 v[72:75], v[162:165], v[194:197], v[72:75]
	v_mfma_f32_16x16x32_bf16 v[124:127], v[150:153], v[174:177], v[124:127]
	v_mfma_f32_16x16x32_bf16 v[120:123], v[166:169], v[174:177], v[120:123]
	v_mfma_f32_16x16x32_bf16 v[108:111], v[150:153], v[182:185], v[108:111]
	v_mfma_f32_16x16x32_bf16 v[104:107], v[166:169], v[182:185], v[104:107]
	v_mfma_f32_16x16x32_bf16 v[92:95], v[150:153], v[190:193], v[92:95]
	v_mfma_f32_16x16x32_bf16 v[88:91], v[166:169], v[190:193], v[88:91]
	v_mfma_f32_16x16x32_bf16 v[76:79], v[150:153], v[198:201], v[76:79]
	v_mfma_f32_16x16x32_bf16 v[72:75], v[166:169], v[198:201], v[72:75]
	s_barrier
	s_add_i32 s48, 0, 0x1c000
	s_add_i32 s33, s33, s57
	v_add_u32_e32 v216, s48, v155
	v_lshl_add_u64 v[220:221], v[220:221], 0, s[16:17]
	s_mov_b32 m0, s33
	ds_read_b128 v[204:207], v216
	ds_read_b128 v[208:211], v216 offset:1024
	ds_read_b128 v[212:215], v216 offset:2048
	ds_read_b128 v[216:219], v216 offset:3072
	global_load_lds_dwordx4 v[220:221], off
	v_lshl_add_u64 v[220:221], v[222:223], 0, s[16:17]
	s_add_i32 m0, s33, 0x2000
	s_nop 0
	global_load_lds_dwordx4 v[220:221], off
	s_waitcnt lgkmcnt(0)
	s_barrier
	s_waitcnt lgkmcnt(0)
	v_mfma_f32_16x16x32_bf16 v[116:119], v[204:207], v[170:173], v[116:119]
	v_mfma_f32_16x16x32_bf16 v[112:115], v[212:215], v[170:173], v[112:115]
	v_mfma_f32_16x16x32_bf16 v[100:103], v[204:207], v[178:181], v[100:103]
	v_mfma_f32_16x16x32_bf16 v[96:99], v[212:215], v[178:181], v[96:99]
	v_mfma_f32_16x16x32_bf16 v[84:87], v[204:207], v[186:189], v[84:87]
	v_mfma_f32_16x16x32_bf16 v[80:83], v[212:215], v[186:189], v[80:83]
	v_mfma_f32_16x16x32_bf16 v[68:71], v[204:207], v[194:197], v[68:71]
	v_mfma_f32_16x16x32_bf16 v[64:67], v[212:215], v[194:197], v[64:67]
	v_mfma_f32_16x16x32_bf16 v[116:119], v[208:211], v[174:177], v[116:119]
	v_mfma_f32_16x16x32_bf16 v[112:115], v[216:219], v[174:177], v[112:115]
	v_mfma_f32_16x16x32_bf16 v[100:103], v[208:211], v[182:185], v[100:103]
	v_mfma_f32_16x16x32_bf16 v[96:99], v[216:219], v[182:185], v[96:99]
	v_mfma_f32_16x16x32_bf16 v[84:87], v[208:211], v[190:193], v[84:87]
	v_mfma_f32_16x16x32_bf16 v[80:83], v[216:219], v[190:193], v[80:83]
	v_mfma_f32_16x16x32_bf16 v[68:71], v[208:211], v[198:201], v[68:71]
	v_mfma_f32_16x16x32_bf16 v[64:67], v[216:219], v[198:201], v[64:67]
	s_mov_b32 m0, s63
	v_lshl_add_u64 v[220:221], v[224:225], 0, s[16:17]
	s_barrier
; #define PG8_STAGE(bufoff, gbase, voff) do { _Pragma("unroll") for (int _i = 0; _i < 2; ++_i) \
;         __builtin_amdgcn_global_load_lds((const unsigned*)((const char*)(gbase) + (voff)[_i]), (LAS unsigned*)(lds + (bufoff) + ldsw + _i * 8192), 16, 0, 0); } while (0)
; #define PG8_LDA(dst, b, h) do { _Pragma("unroll") for (int m = 0; m < 4; ++m) _Pragma("unroll") for (int k = 0; k < 2; ++k) dst[m][k] = *(const LAS bf16x8*)(lds + PG8_SA(b, h) + aoff + m * 2048 + k * 1024); } while (0)
; #define PG8_MMA(ai, bj, At, Bt) do { __builtin_amdgcn_s_setprio(1); _Pragma("unroll") for (int m = 0; m < 4; ++m) _Pragma("unroll") for (int n = 0; n < 2; ++n) _Pragma("unroll") for (int k = 0; k < 2; ++k) \
;         acc[ai][bj][m][n] = __builtin_amdgcn_mfma_f32_16x16x32_bf16(Bt[n][k], At[m][k], acc[ai][bj][m][n], 0, 0, 0); __builtin_amdgcn_s_setprio(0); } while (0)
; #define PG8_WAIT_V(n) asm volatile("s_waitcnt vmcnt(" #n ")" ::: "memory")
; #define PG8_WAIT_L(n) asm volatile("s_waitcnt lgkmcnt(" #n ")" ::: "memory")
; #define PG8_BAR __builtin_amdgcn_s_barrier()
; #define PG8_SCHED __builtin_amdgcn_sched_barrier(0)
;     __device__ __forceinline__ void operator()(const f32x4 (&acc)[2][2][4][2], const Unit& u, int wr, int wc, int fr, int fq) const {
;         const int row0 = u.pm * BM + wr * 64 + fr; const int col0 = u.pn * BM + wc * 64 + 16 * fq;
; #pragma unroll
;         for (int ai = 0; ai < 2; ++ai)
; #pragma unroll
;             for (int m = 0; m < 4; ++m) { const int row = row0 + ai * HALF + m * 16;
;                 const float rs = ssin ? __builtin_amdgcn_rsqf(ssin[row] * (1.f / D) + EPS) : 1.0f; float sq = 0.f; u32x4 w[2];
; template <class Epi>
; __device__ __forceinline__ void gemm_phase(LAS unsigned char* lds, const Gemm g, const StaticOrder& S, const Epi& E) {
;     ...
;             PG8_LDA(At, 1, 1); PG8_STAGE(PG8_SA(1, 0), a3, voffA);
;             PG8_BAR; PG8_WAIT_L(0); PG8_MMA(1, 0, At, B0); PG8_BAR; PG8_SCHED;
;             PG8_STAGE(PG8_SB(1, 1), b3, voffB1);
;             PG8_WAIT_V(6); PG8_BAR; PG8_MMA(1, 1, At, B1); PG8_BAR;
;         }
	ds_read_b128 v[170:173], v159 offset:49152
	ds_read_b128 v[174:177], v159 offset:50176
	ds_read_b128 v[178:181], v159 offset:51200
	ds_read_b128 v[182:185], v159 offset:52224
	ds_read_b128 v[186:189], v159 offset:53248
	ds_read_b128 v[190:193], v159 offset:54272
	ds_read_b128 v[194:197], v159 offset:55296
	ds_read_b128 v[198:201], v159 offset:56320
	global_load_lds_dwordx4 v[220:221], off
	v_lshl_add_u64 v[220:221], v[226:227], 0, s[16:17]
	s_mov_b32 m0, s64
	s_nop 0
	global_load_lds_dwordx4 v[220:221], off
	s_add_i32 s33, s48, s57
	v_lshl_add_u64 v[250:251], v[228:229], 0, s[16:17]
	s_mov_b32 m0, s33
	s_nop 0
	global_load_lds_dwordx4 v[250:251], off
	v_lshl_add_u64 v[250:251], v[230:231], 0, s[16:17]
	s_add_i32 m0, s33, 0x2000
	s_nop 0
	global_load_lds_dwordx4 v[250:251], off
	s_waitcnt vmcnt(6)
	s_barrier
	s_waitcnt lgkmcnt(0)
	v_mfma_f32_16x16x32_bf16 v[60:63], v[146:149], v[170:173], v[60:63]
	v_mfma_f32_16x16x32_bf16 v[56:59], v[162:165], v[170:173], v[56:59]
	v_mfma_f32_16x16x32_bf16 v[44:47], v[146:149], v[178:181], v[44:47]
	v_mfma_f32_16x16x32_bf16 v[40:43], v[162:165], v[178:181], v[40:43]
	v_mfma_f32_16x16x32_bf16 v[28:31], v[146:149], v[186:189], v[28:31]
	v_mfma_f32_16x16x32_bf16 v[24:27], v[162:165], v[186:189], v[24:27]
	v_mfma_f32_16x16x32_bf16 v[12:15], v[146:149], v[194:197], v[12:15]
	v_mfma_f32_16x16x32_bf16 v[8:11], v[162:165], v[194:197], v[8:11]
	v_mfma_f32_16x16x32_bf16 v[60:63], v[150:153], v[174:177], v[60:63]
	v_mfma_f32_16x16x32_bf16 v[56:59], v[166:169], v[174:177], v[56:59]
	v_mfma_f32_16x16x32_bf16 v[44:47], v[150:153], v[182:185], v[44:47]
	v_mfma_f32_16x16x32_bf16 v[40:43], v[166:169], v[182:185], v[40:43]
	v_mfma_f32_16x16x32_bf16 v[28:31], v[150:153], v[190:193], v[28:31]
	v_mfma_f32_16x16x32_bf16 v[24:27], v[166:169], v[190:193], v[24:27]
	v_mfma_f32_16x16x32_bf16 v[12:15], v[150:153], v[198:201], v[12:15]
	v_mfma_f32_16x16x32_bf16 v[8:11], v[166:169], v[198:201], v[8:11]
	v_mfma_f32_16x16x32_bf16 v[52:55], v[204:207], v[170:173], v[52:55]
	v_mfma_f32_16x16x32_bf16 v[48:51], v[212:215], v[170:173], v[48:51]
	v_mfma_f32_16x16x32_bf16 v[36:39], v[204:207], v[178:181], v[36:39]
	v_mfma_f32_16x16x32_bf16 v[32:35], v[212:215], v[178:181], v[32:35]
	v_mfma_f32_16x16x32_bf16 v[20:23], v[204:207], v[186:189], v[20:23]
	v_mfma_f32_16x16x32_bf16 v[16:19], v[212:215], v[186:189], v[16:19]
	v_mfma_f32_16x16x32_bf16 v[4:7], v[204:207], v[194:197], v[4:7]
	v_mfma_f32_16x16x32_bf16 v[0:3], v[212:215], v[194:197], v[0:3]
	v_mfma_f32_16x16x32_bf16 v[52:55], v[208:211], v[174:177], v[52:55]
	v_mfma_f32_16x16x32_bf16 v[48:51], v[216:219], v[174:177], v[48:51]
	v_mfma_f32_16x16x32_bf16 v[36:39], v[208:211], v[182:185], v[36:39]
	v_mfma_f32_16x16x32_bf16 v[32:35], v[216:219], v[182:185], v[32:35]
	v_mfma_f32_16x16x32_bf16 v[20:23], v[208:211], v[190:193], v[20:23]
	v_mfma_f32_16x16x32_bf16 v[16:19], v[216:219], v[190:193], v[16:19]
	v_mfma_f32_16x16x32_bf16 v[4:7], v[208:211], v[198:201], v[4:7]
	v_mfma_f32_16x16x32_bf16 v[0:3], v[216:219], v[198:201], v[0:3]
	s_add_i32 s77, s77, 2
	s_add_u32 s46, s46, 0x100
	s_addc_u32 s47, s47, 0
	s_add_u32 s74, s74, 0x100
	s_addc_u32 s75, s75, 0
	s_cmp_gt_u32 s77, 29
	s_barrier
	s_cbranch_scc0 .LBB0_962
	s_lshl_b32 s19, s44, 8
	s_add_i32 s19, s19, s65
	v_or_b32_e32 v152, s19, v154
	v_ashrrev_i32_e32 v153, 31, v152
	v_lshl_add_u64 v[150:151], v[152:153], 2, s[10:11]
	global_load_dword v153, v[150:151], off
	v_or_b32_e32 v180, 16, v152
	v_ashrrev_i32_e32 v181, 31, v180
	v_lshl_add_u64 v[182:183], v[180:181], 2, s[10:11]
	global_load_dword v179, v[182:183], off
	v_or_b32_e32 v180, 32, v152
	v_ashrrev_i32_e32 v181, 31, v180
	v_lshl_add_u64 v[182:183], v[180:181], 2, s[10:11]
	global_load_dword v184, v[182:183], off
	v_or_b32_e32 v180, 48, v152
	v_ashrrev_i32_e32 v181, 31, v180
	v_lshl_add_u64 v[182:183], v[180:181], 2, s[10:11]
	global_load_dword v185, v[182:183], off
	global_load_dword v186, v[150:151], off offset:512
	global_load_dword v187, v[150:151], off offset:576
	global_load_dword v188, v[150:151], off offset:640
	global_load_dword v189, v[150:151], off offset:704
	v_lshl_or_b32 v148, s71, 8, v157
	v_mov_b32_e32 v169, 0
	v_mov_b64_e32 v[146:147], s[8:9]
	v_ashrrev_i32_e32 v149, 31, v148
	v_or_b32_e32 v164, s19, v156
	v_lshlrev_b64 v[148:149], 1, v[148:149]
	v_mad_i64_i32 v[162:163], s[46:47], v164, s70, v[146:147]
	v_or_b32_e32 v165, 8, v164
	v_or_b32_e32 v164, 16, v152
	v_lshl_add_u64 v[162:163], v[162:163], 0, v[148:149]
	v_mad_i64_i32 v[166:167], s[46:47], v165, s70, v[146:147]
	v_ashrrev_i32_e32 v165, 31, v164
	v_lshl_add_u64 v[166:167], v[166:167], 0, v[148:149]
	v_lshl_add_u64 v[170:171], v[164:165], 2, s[10:11]
	s_and_b64 vcc, exec, s[40:41]
	s_mov_b32 s71, s18
	s_mov_b32 s44, s36
	s_mov_b64 s[48:49], s[42:43]
	s_waitcnt vmcnt(7)
; __device__ __forceinline__ unsigned cvt_pk_bf16(float lo, float hi) { unsigned r; asm volatile("v_cvt_pk_bf16_f32 %0, %1, %2" : "=v"(r) : "v"(lo), "v"(hi)); return r; }
; __device__ __forceinline__ unsigned dpp_ror8(unsigned x) { return (unsigned)__builtin_amdgcn_update_dpp(0, (int)x, 0x128, 0xf, 0xf, false); }
; __device__ __forceinline__ void store_pair_lines(bf16_t* O, int ldc, int row, int fr, int col0, u32x4 wA, u32x4 wB) {
;     const u32x4 sA = {dpp_ror8(wA.x), dpp_ror8(wA.y), dpp_ror8(wA.z), dpp_ror8(wA.w)}, sB = {dpp_ror8(wB.x), dpp_ror8(wB.y), dpp_ror8(wB.z), dpp_ror8(wB.w)};
;     const bool lo = fr < 8;
;     const u32x4 o1 = lo ? wA : sB, o2 = lo ? sA : wB;
;     const int r1 = row - fr + (fr & 7), cb = col0 + (lo ? 0 : 8);
;     *(u32x4*)(O + (size_t)r1 * ldc + cb) = o1;
;     *(u32x4*)(O + (size_t)(r1 + 8) * ldc + cb) = o2;
; }
;     __device__ __forceinline__ void operator()(const f32x4 (&acc)[2][2][4][2], const Unit& u, int wr, int wc, int fr, int fq) const {
;     ...
;             for (int m = 0; m < 4; ++m) { const int row = row0 + ai * HALF + m * 16;
;                 const float rs = ssin ? __builtin_amdgcn_rsqf(ssin[row] * (1.f / D) + EPS) : 1.0f; float sq = 0.f; u32x4 w[2];
; #pragma unroll
;                 for (int bj = 0; bj < 2; ++bj) { f32x4 v0 = acc[ai][bj][m][0] * rs, v1 = acc[ai][bj][m][1] * rs;
;                     if (ACT == 1) {
; #pragma unroll
;                         for (int j = 0; j < 4; ++j) { const float a = fmaxf(v0[j], 0.f), b = fmaxf(v1[j], 0.f); v0[j] = a * a; v1[j] = b * b; } }
;                     sq += (v0[0] * v0[0] + v0[1] * v0[1]) + (v0[2] * v0[2] + v0[3] * v0[3]) + (v1[0] * v1[0] + v1[1] * v1[1]) + (v1[2] * v1[2] + v1[3] * v1[3]);
;                     w[bj].x = cvt_pk_bf16(v0[0], v0[1]); w[bj].y = cvt_pk_bf16(v0[2], v0[3]); w[bj].z = cvt_pk_bf16(v1[0], v1[1]); w[bj].w = cvt_pk_bf16(v1[2], v1[3]); }
;                 store_pair_lines(O, ldc, row, fr, col0, w[0], w[1]);
	v_fmamk_f32 v153, v153, 0x3a000000, v161
	v_rsq_f32_e32 v168, v153
	v_mov_b32_e32 v153, 0
	v_pk_mul_f32 v[124:125], v[124:125], v[168:169] op_sel_hi:[1,0]
	v_pk_mul_f32 v[120:121], v[120:121], v[168:169] op_sel_hi:[1,0]
	v_pk_mul_f32 v[118:119], v[118:119], v[168:169] op_sel_hi:[1,0]
	v_pk_mul_f32 v[116:117], v[116:117], v[168:169] op_sel_hi:[1,0]
	v_pk_mul_f32 v[126:127], v[126:127], v[168:169] op_sel_hi:[1,0]
	v_pk_mul_f32 v[122:123], v[122:123], v[168:169] op_sel_hi:[1,0]
	v_pk_mul_f32 v[114:115], v[114:115], v[168:169] op_sel_hi:[1,0]
	v_pk_mul_f32 v[112:113], v[112:113], v[168:169] op_sel_hi:[1,0]
	v_cvt_pk_bf16_f32 v124, v124, v125
	v_cvt_pk_bf16_f32 v125, v126, v127
	v_cvt_pk_bf16_f32 v120, v120, v121
	v_cvt_pk_bf16_f32 v121, v122, v123
	v_cvt_pk_bf16_f32 v116, v116, v117
	v_cvt_pk_bf16_f32 v117, v118, v119
	s_nop 0
	v_cvt_pk_bf16_f32 v118, v112, v113
	v_cvt_pk_bf16_f32 v119, v114, v115
	s_nop 0
	v_mov_b32_dpp v169, v124 row_ror:8 row_mask:0xf bank_mask:0xf
	v_mov_b32_dpp v172, v125 row_ror:8 row_mask:0xf bank_mask:0xf
	v_mov_b32_dpp v175, v116 row_ror:8 row_mask:0xf bank_mask:0xf
	v_mov_b32_dpp v176, v117 row_ror:8 row_mask:0xf bank_mask:0xf
	v_mov_b32_dpp v177, v118 row_ror:8 row_mask:0xf bank_mask:0xf
	v_mov_b32_dpp v178, v119 row_ror:8 row_mask:0xf bank_mask:0xf
	v_mov_b32_dpp v173, v120 row_ror:8 row_mask:0xf bank_mask:0xf
	v_mov_b32_dpp v174, v121 row_ror:8 row_mask:0xf bank_mask:0xf
	v_cndmask_b32_e64 v112, v175, v124, s[6:7]
	v_cndmask_b32_e64 v113, v176, v125, s[6:7]
	v_cndmask_b32_e64 v114, v177, v120, s[6:7]
	v_cndmask_b32_e64 v115, v178, v121, s[6:7]
	v_cndmask_b32_e64 v116, v116, v169, s[6:7]
	v_cndmask_b32_e64 v117, v117, v172, s[6:7]
	v_cndmask_b32_e64 v118, v118, v173, s[6:7]
	v_cndmask_b32_e64 v119, v119, v174, s[6:7]
	global_store_dwordx4 v[162:163], v[112:115], off
	global_store_dwordx4 v[166:167], v[116:119], off
	s_waitcnt vmcnt(8)
	s_nop 0
	v_mov_b32_e32 v118, v179
	s_nop 1
	v_or_b32_e32 v112, 32, v152
	v_mov_b32_e32 v119, 0
	v_sub_u32_e32 v114, v164, v154
	v_ashrrev_i32_e32 v113, 31, v112
	v_add_u32_e32 v120, v114, v156
	v_lshl_add_u64 v[114:115], v[112:113], 2, s[10:11]
	v_mad_i64_i32 v[116:117], s[46:47], v120, s70, v[146:147]
	v_add_u32_e32 v113, 8, v120
	v_lshl_add_u64 v[116:117], v[116:117], 0, v[148:149]
	v_mad_i64_i32 v[120:121], s[46:47], v113, s70, v[146:147]
	v_lshl_add_u64 v[120:121], v[120:121], 0, v[148:149]
	s_waitcnt vmcnt(9)
	v_fmamk_f32 v118, v118, 0x3a000000, v161
	v_rsq_f32_e32 v118, v118
	s_nop 0
	v_pk_mul_f32 v[108:109], v[108:109], v[118:119] op_sel_hi:[1,0]
	v_pk_mul_f32 v[104:105], v[104:105], v[118:119] op_sel_hi:[1,0]
	v_pk_mul_f32 v[102:103], v[102:103], v[118:119] op_sel_hi:[1,0]
	v_pk_mul_f32 v[100:101], v[100:101], v[118:119] op_sel_hi:[1,0]
	v_pk_mul_f32 v[110:111], v[110:111], v[118:119] op_sel_hi:[1,0]
	v_pk_mul_f32 v[106:107], v[106:107], v[118:119] op_sel_hi:[1,0]
	v_pk_mul_f32 v[98:99], v[98:99], v[118:119] op_sel_hi:[1,0]
	v_pk_mul_f32 v[96:97], v[96:97], v[118:119] op_sel_hi:[1,0]
	v_cvt_pk_bf16_f32 v108, v108, v109
	v_cvt_pk_bf16_f32 v109, v110, v111
	v_cvt_pk_bf16_f32 v104, v104, v105
	v_cvt_pk_bf16_f32 v105, v106, v107
	v_cvt_pk_bf16_f32 v100, v100, v101
	v_cvt_pk_bf16_f32 v101, v102, v103
	s_nop 0
	v_cvt_pk_bf16_f32 v102, v96, v97
	v_cvt_pk_bf16_f32 v103, v98, v99
	s_nop 0
	v_mov_b32_dpp v119, v108 row_ror:8 row_mask:0xf bank_mask:0xf
	v_mov_b32_dpp v122, v109 row_ror:8 row_mask:0xf bank_mask:0xf
	v_mov_b32_dpp v125, v100 row_ror:8 row_mask:0xf bank_mask:0xf
	v_mov_b32_dpp v126, v101 row_ror:8 row_mask:0xf bank_mask:0xf
	v_mov_b32_dpp v127, v102 row_ror:8 row_mask:0xf bank_mask:0xf
	v_mov_b32_dpp v153, v103 row_ror:8 row_mask:0xf bank_mask:0xf
	v_mov_b32_dpp v123, v104 row_ror:8 row_mask:0xf bank_mask:0xf
	v_mov_b32_dpp v124, v105 row_ror:8 row_mask:0xf bank_mask:0xf
	v_cndmask_b32_e64 v96, v125, v108, s[6:7]
	v_cndmask_b32_e64 v97, v126, v109, s[6:7]
	v_cndmask_b32_e64 v98, v127, v104, s[6:7]
	v_cndmask_b32_e64 v99, v153, v105, s[6:7]
	v_cndmask_b32_e64 v100, v100, v119, s[6:7]
	v_cndmask_b32_e64 v101, v101, v122, s[6:7]
	v_cndmask_b32_e64 v102, v102, v123, s[6:7]
	v_cndmask_b32_e64 v103, v103, v124, s[6:7]
	global_store_dwordx4 v[116:117], v[96:99], off
	global_store_dwordx4 v[120:121], v[100:103], off
	s_waitcnt vmcnt(9)
	s_nop 0
	v_mov_b32_e32 v102, v184
	s_nop 1
	v_or_b32_e32 v96, 48, v152
	v_mov_b32_e32 v103, 0
	v_sub_u32_e32 v98, v112, v154
	v_ashrrev_i32_e32 v97, 31, v96
	v_add_u32_e32 v104, v98, v156
	v_lshl_add_u64 v[98:99], v[96:97], 2, s[10:11]
	v_mad_i64_i32 v[100:101], s[46:47], v104, s70, v[146:147]
	v_add_u32_e32 v97, 8, v104
	v_lshl_add_u64 v[100:101], v[100:101], 0, v[148:149]
	v_mad_i64_i32 v[104:105], s[46:47], v97, s70, v[146:147]
	v_lshl_add_u64 v[104:105], v[104:105], 0, v[148:149]
	s_waitcnt vmcnt(11)
; __device__ __forceinline__ unsigned cvt_pk_bf16(float lo, float hi) { unsigned r; asm volatile("v_cvt_pk_bf16_f32 %0, %1, %2" : "=v"(r) : "v"(lo), "v"(hi)); return r; }
; __device__ __forceinline__ unsigned dpp_ror8(unsigned x) { return (unsigned)__builtin_amdgcn_update_dpp(0, (int)x, 0x128, 0xf, 0xf, false); }
; __device__ __forceinline__ void store_pair_lines(bf16_t* O, int ldc, int row, int fr, int col0, u32x4 wA, u32x4 wB) {
;     const u32x4 sA = {dpp_ror8(wA.x), dpp_ror8(wA.y), dpp_ror8(wA.z), dpp_ror8(wA.w)}, sB = {dpp_ror8(wB.x), dpp_ror8(wB.y), dpp_ror8(wB.z), dpp_ror8(wB.w)};
;     const bool lo = fr < 8;
;     const u32x4 o1 = lo ? wA : sB, o2 = lo ? sA : wB;
;     const int r1 = row - fr + (fr & 7), cb = col0 + (lo ? 0 : 8);
;     *(u32x4*)(O + (size_t)r1 * ldc + cb) = o1;
;     *(u32x4*)(O + (size_t)(r1 + 8) * ldc + cb) = o2;
; }
;     __device__ __forceinline__ void operator()(const f32x4 (&acc)[2][2][4][2], const Unit& u, int wr, int wc, int fr, int fq) const {
;     ...
;             for (int m = 0; m < 4; ++m) { const int row = row0 + ai * HALF + m * 16;
;                 const float rs = ssin ? __builtin_amdgcn_rsqf(ssin[row] * (1.f / D) + EPS) : 1.0f; float sq = 0.f; u32x4 w[2];
; #pragma unroll
;                 for (int bj = 0; bj < 2; ++bj) { f32x4 v0 = acc[ai][bj][m][0] * rs, v1 = acc[ai][bj][m][1] * rs;
;                     if (ACT == 1) {
; #pragma unroll
;                         for (int j = 0; j < 4; ++j) { const float a = fmaxf(v0[j], 0.f), b = fmaxf(v1[j], 0.f); v0[j] = a * a; v1[j] = b * b; } }
;                     sq += (v0[0] * v0[0] + v0[1] * v0[1]) + (v0[2] * v0[2] + v0[3] * v0[3]) + (v1[0] * v1[0] + v1[1] * v1[1]) + (v1[2] * v1[2] + v1[3] * v1[3]);
;                     w[bj].x = cvt_pk_bf16(v0[0], v0[1]); w[bj].y = cvt_pk_bf16(v0[2], v0[3]); w[bj].z = cvt_pk_bf16(v1[0], v1[1]); w[bj].w = cvt_pk_bf16(v1[2], v1[3]); }
;                 store_pair_lines(O, ldc, row, fr, col0, w[0], w[1]);
	v_fmamk_f32 v102, v102, 0x3a000000, v161
	v_rsq_f32_e32 v102, v102
	s_nop 0
	v_pk_mul_f32 v[92:93], v[92:93], v[102:103] op_sel_hi:[1,0]
	v_pk_mul_f32 v[88:89], v[88:89], v[102:103] op_sel_hi:[1,0]
	v_pk_mul_f32 v[86:87], v[86:87], v[102:103] op_sel_hi:[1,0]
	v_pk_mul_f32 v[84:85], v[84:85], v[102:103] op_sel_hi:[1,0]
	v_pk_mul_f32 v[94:95], v[94:95], v[102:103] op_sel_hi:[1,0]
	v_pk_mul_f32 v[90:91], v[90:91], v[102:103] op_sel_hi:[1,0]
	v_pk_mul_f32 v[82:83], v[82:83], v[102:103] op_sel_hi:[1,0]
	v_pk_mul_f32 v[80:81], v[80:81], v[102:103] op_sel_hi:[1,0]
	v_cvt_pk_bf16_f32 v92, v92, v93
	v_cvt_pk_bf16_f32 v93, v94, v95
	v_cvt_pk_bf16_f32 v88, v88, v89
	v_cvt_pk_bf16_f32 v89, v90, v91
	v_cvt_pk_bf16_f32 v84, v84, v85
	v_cvt_pk_bf16_f32 v85, v86, v87
	s_nop 0
	v_cvt_pk_bf16_f32 v86, v80, v81
	v_cvt_pk_bf16_f32 v87, v82, v83
	s_nop 0
	v_mov_b32_dpp v103, v92 row_ror:8 row_mask:0xf bank_mask:0xf
	v_mov_b32_dpp v106, v93 row_ror:8 row_mask:0xf bank_mask:0xf
	v_mov_b32_dpp v109, v84 row_ror:8 row_mask:0xf bank_mask:0xf
	v_mov_b32_dpp v110, v85 row_ror:8 row_mask:0xf bank_mask:0xf
	v_mov_b32_dpp v111, v86 row_ror:8 row_mask:0xf bank_mask:0xf
	v_mov_b32_dpp v113, v87 row_ror:8 row_mask:0xf bank_mask:0xf
	v_mov_b32_dpp v107, v88 row_ror:8 row_mask:0xf bank_mask:0xf
	v_mov_b32_dpp v108, v89 row_ror:8 row_mask:0xf bank_mask:0xf
	v_cndmask_b32_e64 v80, v109, v92, s[6:7]
	v_cndmask_b32_e64 v81, v110, v93, s[6:7]
	v_cndmask_b32_e64 v82, v111, v88, s[6:7]
	v_cndmask_b32_e64 v83, v113, v89, s[6:7]
	v_cndmask_b32_e64 v84, v84, v103, s[6:7]
	v_cndmask_b32_e64 v85, v85, v106, s[6:7]
	v_cndmask_b32_e64 v86, v86, v107, s[6:7]
	v_cndmask_b32_e64 v87, v87, v108, s[6:7]
	global_store_dwordx4 v[100:101], v[80:83], off
	global_store_dwordx4 v[104:105], v[84:87], off
	s_waitcnt vmcnt(10)
	s_nop 0
	v_mov_b32_e32 v82, v185
	s_nop 1
	v_mov_b32_e32 v83, 0
	v_sub_u32_e32 v80, v96, v154
	v_add_u32_e32 v84, v80, v156
	v_mad_i64_i32 v[80:81], s[46:47], v84, s70, v[146:147]
	v_add_u32_e32 v84, 8, v84
	v_lshl_add_u64 v[80:81], v[80:81], 0, v[148:149]
	v_mad_i64_i32 v[84:85], s[46:47], v84, s70, v[146:147]
	v_lshl_add_u64 v[84:85], v[84:85], 0, v[148:149]
	s_waitcnt vmcnt(13)
	v_fmamk_f32 v82, v82, 0x3a000000, v161
	v_rsq_f32_e32 v82, v82
	s_nop 0
	v_pk_mul_f32 v[76:77], v[76:77], v[82:83] op_sel_hi:[1,0]
	v_pk_mul_f32 v[72:73], v[72:73], v[82:83] op_sel_hi:[1,0]
	v_pk_mul_f32 v[70:71], v[70:71], v[82:83] op_sel_hi:[1,0]
	v_pk_mul_f32 v[68:69], v[68:69], v[82:83] op_sel_hi:[1,0]
	v_pk_mul_f32 v[78:79], v[78:79], v[82:83] op_sel_hi:[1,0]
	v_pk_mul_f32 v[74:75], v[74:75], v[82:83] op_sel_hi:[1,0]
	v_pk_mul_f32 v[66:67], v[66:67], v[82:83] op_sel_hi:[1,0]
	v_pk_mul_f32 v[64:65], v[64:65], v[82:83] op_sel_hi:[1,0]
	v_cvt_pk_bf16_f32 v76, v76, v77
	v_cvt_pk_bf16_f32 v77, v78, v79
	v_cvt_pk_bf16_f32 v72, v72, v73
	v_cvt_pk_bf16_f32 v73, v74, v75
	v_cvt_pk_bf16_f32 v68, v68, v69
	v_cvt_pk_bf16_f32 v69, v70, v71
	s_nop 0
	v_cvt_pk_bf16_f32 v70, v64, v65
	v_cvt_pk_bf16_f32 v71, v66, v67
	s_nop 0
	v_mov_b32_dpp v83, v76 row_ror:8 row_mask:0xf bank_mask:0xf
	v_mov_b32_dpp v86, v77 row_ror:8 row_mask:0xf bank_mask:0xf
	v_mov_b32_dpp v89, v68 row_ror:8 row_mask:0xf bank_mask:0xf
	v_mov_b32_dpp v90, v69 row_ror:8 row_mask:0xf bank_mask:0xf
	v_mov_b32_dpp v91, v70 row_ror:8 row_mask:0xf bank_mask:0xf
	v_mov_b32_dpp v92, v71 row_ror:8 row_mask:0xf bank_mask:0xf
	v_mov_b32_dpp v87, v72 row_ror:8 row_mask:0xf bank_mask:0xf
	v_mov_b32_dpp v88, v73 row_ror:8 row_mask:0xf bank_mask:0xf
	v_cndmask_b32_e64 v64, v89, v76, s[6:7]
	v_cndmask_b32_e64 v65, v90, v77, s[6:7]
	v_cndmask_b32_e64 v66, v91, v72, s[6:7]
	v_cndmask_b32_e64 v67, v92, v73, s[6:7]
	v_cndmask_b32_e64 v68, v68, v83, s[6:7]
	v_cndmask_b32_e64 v69, v69, v86, s[6:7]
	v_cndmask_b32_e64 v70, v70, v87, s[6:7]
	v_cndmask_b32_e64 v71, v71, v88, s[6:7]
	global_store_dwordx4 v[80:81], v[64:67], off
	global_store_dwordx4 v[84:85], v[68:71], off
	s_waitcnt vmcnt(11)
	s_nop 0
	v_mov_b32_e32 v66, v186
	s_nop 1
	v_sub_u32_e32 v64, v152, v154
	v_mov_b32_e32 v67, 0
	v_add_u32_e32 v77, v64, v156
	v_add_u32_e32 v64, 0x80, v77
	v_add_u32_e32 v68, 0x88, v77
	v_mad_i64_i32 v[64:65], s[46:47], v64, s70, v[146:147]
	v_mad_i64_i32 v[68:69], s[46:47], v68, s70, v[146:147]
	v_lshl_add_u64 v[64:65], v[64:65], 0, v[148:149]
	v_lshl_add_u64 v[68:69], v[68:69], 0, v[148:149]
	s_waitcnt vmcnt(15)
	v_fmamk_f32 v66, v66, 0x3a000000, v161
	v_rsq_f32_e32 v66, v66
	s_nop 0
	v_pk_mul_f32 v[60:61], v[60:61], v[66:67] op_sel_hi:[1,0]
	v_pk_mul_f32 v[56:57], v[56:57], v[66:67] op_sel_hi:[1,0]
	v_pk_mul_f32 v[54:55], v[54:55], v[66:67] op_sel_hi:[1,0]
	v_pk_mul_f32 v[52:53], v[52:53], v[66:67] op_sel_hi:[1,0]
	v_pk_mul_f32 v[62:63], v[62:63], v[66:67] op_sel_hi:[1,0]
	v_pk_mul_f32 v[58:59], v[58:59], v[66:67] op_sel_hi:[1,0]
	v_pk_mul_f32 v[50:51], v[50:51], v[66:67] op_sel_hi:[1,0]
	v_pk_mul_f32 v[48:49], v[48:49], v[66:67] op_sel_hi:[1,0]
	v_cvt_pk_bf16_f32 v60, v60, v61
	v_cvt_pk_bf16_f32 v61, v62, v63
	v_cvt_pk_bf16_f32 v56, v56, v57
	v_cvt_pk_bf16_f32 v57, v58, v59
	v_cvt_pk_bf16_f32 v52, v52, v53
	v_cvt_pk_bf16_f32 v53, v54, v55
	s_nop 0
	v_cvt_pk_bf16_f32 v54, v48, v49
	v_cvt_pk_bf16_f32 v55, v50, v51
	s_nop 0
	v_mov_b32_dpp v67, v60 row_ror:8 row_mask:0xf bank_mask:0xf
	v_mov_b32_dpp v70, v61 row_ror:8 row_mask:0xf bank_mask:0xf
	v_mov_b32_dpp v73, v52 row_ror:8 row_mask:0xf bank_mask:0xf
	v_mov_b32_dpp v74, v53 row_ror:8 row_mask:0xf bank_mask:0xf
	v_mov_b32_dpp v75, v54 row_ror:8 row_mask:0xf bank_mask:0xf
	v_mov_b32_dpp v76, v55 row_ror:8 row_mask:0xf bank_mask:0xf
	v_mov_b32_dpp v71, v56 row_ror:8 row_mask:0xf bank_mask:0xf
	v_mov_b32_dpp v72, v57 row_ror:8 row_mask:0xf bank_mask:0xf
	v_cndmask_b32_e64 v48, v73, v60, s[6:7]
	v_cndmask_b32_e64 v49, v74, v61, s[6:7]
	v_cndmask_b32_e64 v50, v75, v56, s[6:7]
	v_cndmask_b32_e64 v51, v76, v57, s[6:7]
	v_cndmask_b32_e64 v52, v52, v67, s[6:7]
	v_cndmask_b32_e64 v53, v53, v70, s[6:7]
	v_cndmask_b32_e64 v54, v54, v71, s[6:7]
	v_cndmask_b32_e64 v55, v55, v72, s[6:7]
	global_store_dwordx4 v[64:65], v[48:51], off
	global_store_dwordx4 v[68:69], v[52:55], off
	s_waitcnt vmcnt(12)
; __device__ __forceinline__ unsigned cvt_pk_bf16(float lo, float hi) { unsigned r; asm volatile("v_cvt_pk_bf16_f32 %0, %1, %2" : "=v"(r) : "v"(lo), "v"(hi)); return r; }
; __device__ __forceinline__ unsigned dpp_ror8(unsigned x) { return (unsigned)__builtin_amdgcn_update_dpp(0, (int)x, 0x128, 0xf, 0xf, false); }
; __device__ __forceinline__ void store_pair_lines(bf16_t* O, int ldc, int row, int fr, int col0, u32x4 wA, u32x4 wB) {
;     const u32x4 sA = {dpp_ror8(wA.x), dpp_ror8(wA.y), dpp_ror8(wA.z), dpp_ror8(wA.w)}, sB = {dpp_ror8(wB.x), dpp_ror8(wB.y), dpp_ror8(wB.z), dpp_ror8(wB.w)};
;     const bool lo = fr < 8;
;     const u32x4 o1 = lo ? wA : sB, o2 = lo ? sA : wB;
;     const int r1 = row - fr + (fr & 7), cb = col0 + (lo ? 0 : 8);
;     *(u32x4*)(O + (size_t)r1 * ldc + cb) = o1;
;     *(u32x4*)(O + (size_t)(r1 + 8) * ldc + cb) = o2;
; }
;     __device__ __forceinline__ void operator()(const f32x4 (&acc)[2][2][4][2], const Unit& u, int wr, int wc, int fr, int fq) const {
;     ...
;             for (int m = 0; m < 4; ++m) { const int row = row0 + ai * HALF + m * 16;
;                 const float rs = ssin ? __builtin_amdgcn_rsqf(ssin[row] * (1.f / D) + EPS) : 1.0f; float sq = 0.f; u32x4 w[2];
; #pragma unroll
;                 for (int bj = 0; bj < 2; ++bj) { f32x4 v0 = acc[ai][bj][m][0] * rs, v1 = acc[ai][bj][m][1] * rs;
;                     if (ACT == 1) {
; #pragma unroll
;                         for (int j = 0; j < 4; ++j) { const float a = fmaxf(v0[j], 0.f), b = fmaxf(v1[j], 0.f); v0[j] = a * a; v1[j] = b * b; } }
;                     sq += (v0[0] * v0[0] + v0[1] * v0[1]) + (v0[2] * v0[2] + v0[3] * v0[3]) + (v1[0] * v1[0] + v1[1] * v1[1]) + (v1[2] * v1[2] + v1[3] * v1[3]);
;                     w[bj].x = cvt_pk_bf16(v0[0], v0[1]); w[bj].y = cvt_pk_bf16(v0[2], v0[3]); w[bj].z = cvt_pk_bf16(v1[0], v1[1]); w[bj].w = cvt_pk_bf16(v1[2], v1[3]); }
;                 store_pair_lines(O, ldc, row, fr, col0, w[0], w[1]);
	s_nop 0
	v_mov_b32_e32 v50, v187
	s_nop 1
	v_mov_b32_e32 v51, 0
	v_add_u32_e32 v48, 0x90, v77
	v_add_u32_e32 v52, 0x98, v77
	v_mad_i64_i32 v[48:49], s[46:47], v48, s70, v[146:147]
	v_mad_i64_i32 v[52:53], s[46:47], v52, s70, v[146:147]
	v_lshl_add_u64 v[48:49], v[48:49], 0, v[148:149]
	v_lshl_add_u64 v[52:53], v[52:53], 0, v[148:149]
	s_waitcnt vmcnt(17)
	v_fmamk_f32 v50, v50, 0x3a000000, v161
	v_rsq_f32_e32 v50, v50
	s_nop 0
	v_pk_mul_f32 v[44:45], v[44:45], v[50:51] op_sel_hi:[1,0]
	v_pk_mul_f32 v[40:41], v[40:41], v[50:51] op_sel_hi:[1,0]
	v_pk_mul_f32 v[38:39], v[38:39], v[50:51] op_sel_hi:[1,0]
	v_pk_mul_f32 v[36:37], v[36:37], v[50:51] op_sel_hi:[1,0]
	v_pk_mul_f32 v[46:47], v[46:47], v[50:51] op_sel_hi:[1,0]
	v_pk_mul_f32 v[42:43], v[42:43], v[50:51] op_sel_hi:[1,0]
	v_pk_mul_f32 v[34:35], v[34:35], v[50:51] op_sel_hi:[1,0]
	v_pk_mul_f32 v[32:33], v[32:33], v[50:51] op_sel_hi:[1,0]
	v_cvt_pk_bf16_f32 v44, v44, v45
	v_cvt_pk_bf16_f32 v45, v46, v47
	v_cvt_pk_bf16_f32 v40, v40, v41
	v_cvt_pk_bf16_f32 v41, v42, v43
	v_cvt_pk_bf16_f32 v36, v36, v37
	v_cvt_pk_bf16_f32 v37, v38, v39
	s_nop 0
	v_cvt_pk_bf16_f32 v38, v32, v33
	v_cvt_pk_bf16_f32 v39, v34, v35
	s_nop 0
	v_mov_b32_dpp v51, v44 row_ror:8 row_mask:0xf bank_mask:0xf
	v_mov_b32_dpp v54, v45 row_ror:8 row_mask:0xf bank_mask:0xf
	v_mov_b32_dpp v57, v36 row_ror:8 row_mask:0xf bank_mask:0xf
	v_mov_b32_dpp v58, v37 row_ror:8 row_mask:0xf bank_mask:0xf
	v_mov_b32_dpp v59, v38 row_ror:8 row_mask:0xf bank_mask:0xf
	v_mov_b32_dpp v60, v39 row_ror:8 row_mask:0xf bank_mask:0xf
	v_mov_b32_dpp v55, v40 row_ror:8 row_mask:0xf bank_mask:0xf
	v_mov_b32_dpp v56, v41 row_ror:8 row_mask:0xf bank_mask:0xf
	v_cndmask_b32_e64 v32, v57, v44, s[6:7]
	v_cndmask_b32_e64 v33, v58, v45, s[6:7]
	v_cndmask_b32_e64 v34, v59, v40, s[6:7]
	v_cndmask_b32_e64 v35, v60, v41, s[6:7]
	v_cndmask_b32_e64 v36, v36, v51, s[6:7]
	v_cndmask_b32_e64 v37, v37, v54, s[6:7]
	v_cndmask_b32_e64 v38, v38, v55, s[6:7]
	v_cndmask_b32_e64 v39, v39, v56, s[6:7]
	global_store_dwordx4 v[48:49], v[32:35], off
	global_store_dwordx4 v[52:53], v[36:39], off
	s_waitcnt vmcnt(13)
	s_nop 0
	v_mov_b32_e32 v34, v188
	s_nop 1
	v_mov_b32_e32 v35, 0
	v_add_u32_e32 v32, 0xa0, v77
	v_add_u32_e32 v36, 0xa8, v77
	v_mad_i64_i32 v[32:33], s[46:47], v32, s70, v[146:147]
	v_mad_i64_i32 v[36:37], s[46:47], v36, s70, v[146:147]
	v_lshl_add_u64 v[32:33], v[32:33], 0, v[148:149]
	v_lshl_add_u64 v[36:37], v[36:37], 0, v[148:149]
	s_mov_b64 s[46:47], s[38:39]
	s_waitcnt vmcnt(19)
	v_fmamk_f32 v34, v34, 0x3a000000, v161
	v_rsq_f32_e32 v34, v34
	s_nop 0
	v_pk_mul_f32 v[28:29], v[28:29], v[34:35] op_sel_hi:[1,0]
	v_pk_mul_f32 v[24:25], v[24:25], v[34:35] op_sel_hi:[1,0]
	v_pk_mul_f32 v[22:23], v[22:23], v[34:35] op_sel_hi:[1,0]
	v_pk_mul_f32 v[20:21], v[20:21], v[34:35] op_sel_hi:[1,0]
	v_pk_mul_f32 v[30:31], v[30:31], v[34:35] op_sel_hi:[1,0]
	v_pk_mul_f32 v[26:27], v[26:27], v[34:35] op_sel_hi:[1,0]
	v_pk_mul_f32 v[18:19], v[18:19], v[34:35] op_sel_hi:[1,0]
	v_pk_mul_f32 v[16:17], v[16:17], v[34:35] op_sel_hi:[1,0]
	v_cvt_pk_bf16_f32 v28, v28, v29
	v_cvt_pk_bf16_f32 v29, v30, v31
	v_cvt_pk_bf16_f32 v24, v24, v25
	v_cvt_pk_bf16_f32 v25, v26, v27
	v_cvt_pk_bf16_f32 v20, v20, v21
	v_cvt_pk_bf16_f32 v21, v22, v23
	s_nop 0
	v_cvt_pk_bf16_f32 v22, v16, v17
	v_cvt_pk_bf16_f32 v23, v18, v19
	s_nop 0
	v_mov_b32_dpp v35, v28 row_ror:8 row_mask:0xf bank_mask:0xf
	v_mov_b32_dpp v38, v29 row_ror:8 row_mask:0xf bank_mask:0xf
	v_mov_b32_dpp v41, v20 row_ror:8 row_mask:0xf bank_mask:0xf
	v_mov_b32_dpp v42, v21 row_ror:8 row_mask:0xf bank_mask:0xf
	v_mov_b32_dpp v43, v22 row_ror:8 row_mask:0xf bank_mask:0xf
	v_mov_b32_dpp v44, v23 row_ror:8 row_mask:0xf bank_mask:0xf
	v_mov_b32_dpp v39, v24 row_ror:8 row_mask:0xf bank_mask:0xf
	v_mov_b32_dpp v40, v25 row_ror:8 row_mask:0xf bank_mask:0xf
	v_cndmask_b32_e64 v16, v41, v28, s[6:7]
	v_cndmask_b32_e64 v17, v42, v29, s[6:7]
	v_cndmask_b32_e64 v18, v43, v24, s[6:7]
	v_cndmask_b32_e64 v19, v44, v25, s[6:7]
	v_cndmask_b32_e64 v20, v20, v35, s[6:7]
	v_cndmask_b32_e64 v21, v21, v38, s[6:7]
	v_cndmask_b32_e64 v22, v22, v39, s[6:7]
	v_cndmask_b32_e64 v23, v23, v40, s[6:7]
	global_store_dwordx4 v[32:33], v[16:19], off
	global_store_dwordx4 v[36:37], v[20:23], off
	s_waitcnt vmcnt(14)
	s_nop 0
	v_mov_b32_e32 v18, v189
	s_nop 1
	v_mov_b32_e32 v19, 0
	v_add_u32_e32 v16, 0xb0, v77
	v_add_u32_e32 v20, 0xb8, v77
	v_mad_i64_i32 v[16:17], s[38:39], v16, s70, v[146:147]
	v_mad_i64_i32 v[20:21], s[38:39], v20, s70, v[146:147]
	v_lshl_add_u64 v[16:17], v[16:17], 0, v[148:149]
	v_lshl_add_u64 v[20:21], v[20:21], 0, v[148:149]
	s_waitcnt vmcnt(21)
	v_fmamk_f32 v18, v18, 0x3a000000, v161
	v_rsq_f32_e32 v18, v18
	s_nop 0
	v_pk_mul_f32 v[12:13], v[12:13], v[18:19] op_sel_hi:[1,0]
	v_pk_mul_f32 v[8:9], v[8:9], v[18:19] op_sel_hi:[1,0]
	v_pk_mul_f32 v[6:7], v[6:7], v[18:19] op_sel_hi:[1,0]
	v_pk_mul_f32 v[4:5], v[4:5], v[18:19] op_sel_hi:[1,0]
	v_pk_mul_f32 v[14:15], v[14:15], v[18:19] op_sel_hi:[1,0]
	v_pk_mul_f32 v[10:11], v[10:11], v[18:19] op_sel_hi:[1,0]
	v_pk_mul_f32 v[2:3], v[2:3], v[18:19] op_sel_hi:[1,0]
	v_pk_mul_f32 v[0:1], v[0:1], v[18:19] op_sel_hi:[1,0]
	v_cvt_pk_bf16_f32 v12, v12, v13
	v_cvt_pk_bf16_f32 v13, v14, v15
	v_cvt_pk_bf16_f32 v8, v8, v9
	v_cvt_pk_bf16_f32 v9, v10, v11
	v_cvt_pk_bf16_f32 v4, v4, v5
	v_cvt_pk_bf16_f32 v5, v6, v7
	s_nop 0
	v_cvt_pk_bf16_f32 v6, v0, v1
	v_cvt_pk_bf16_f32 v7, v2, v3
	s_nop 0
	v_mov_b32_dpp v19, v12 row_ror:8 row_mask:0xf bank_mask:0xf
	v_mov_b32_dpp v22, v13 row_ror:8 row_mask:0xf bank_mask:0xf
	v_mov_b32_dpp v25, v4 row_ror:8 row_mask:0xf bank_mask:0xf
	v_mov_b32_dpp v26, v5 row_ror:8 row_mask:0xf bank_mask:0xf
	v_mov_b32_dpp v27, v6 row_ror:8 row_mask:0xf bank_mask:0xf
	v_mov_b32_dpp v28, v7 row_ror:8 row_mask:0xf bank_mask:0xf
	v_mov_b32_dpp v23, v8 row_ror:8 row_mask:0xf bank_mask:0xf
	v_mov_b32_dpp v24, v9 row_ror:8 row_mask:0xf bank_mask:0xf
	v_cndmask_b32_e64 v0, v25, v12, s[6:7]
	v_cndmask_b32_e64 v1, v26, v13, s[6:7]
	v_cndmask_b32_e64 v2, v27, v8, s[6:7]
	v_cndmask_b32_e64 v3, v28, v9, s[6:7]
	v_cndmask_b32_e64 v4, v4, v19, s[6:7]
	v_cndmask_b32_e64 v5, v5, v22, s[6:7]
	v_cndmask_b32_e64 v6, v6, v23, s[6:7]
	v_cndmask_b32_e64 v7, v7, v24, s[6:7]
	global_store_dwordx4 v[16:17], v[0:3], off
	global_store_dwordx4 v[20:21], v[4:7], off
	s_cbranch_vccz .LBB0_958
	s_waitcnt vmcnt(0)
	s_cmpk_gt_u32 s52, 0xff
	s_cbranch_scc1 .LBB0_966
	s_barrier

; #define PG8_STAGE(bufoff, gbase, voff) do { _Pragma("unroll") for (int _i = 0; _i < 2; ++_i) \
;         __builtin_amdgcn_global_load_lds((const unsigned*)((const char*)(gbase) + (voff)[_i]), (LAS unsigned*)(lds + (bufoff) + ldsw + _i * 8192), 16, 0, 0); } while (0)
; #define PG8_LDA(dst, b, h) do { _Pragma("unroll") for (int m = 0; m < 4; ++m) _Pragma("unroll") for (int k = 0; k < 2; ++k) dst[m][k] = *(const LAS bf16x8*)(lds + PG8_SA(b, h) + aoff + m * 2048 + k * 1024); } while (0)
; #define PG8_LDB(dst, b, h) do { _Pragma("unroll") for (int n = 0; n < 2; ++n) _Pragma("unroll") for (int k = 0; k < 2; ++k) dst[n][k] = *(const LAS bf16x8*)(lds + PG8_SB(b, h) + boff + n * 2048 + k * 1024); } while (0)
; #define PG8_MMA(ai, bj, At, Bt) do { __builtin_amdgcn_s_setprio(1); _Pragma("unroll") for (int m = 0; m < 4; ++m) _Pragma("unroll") for (int n = 0; n < 2; ++n) _Pragma("unroll") for (int k = 0; k < 2; ++k) \
;         acc[ai][bj][m][n] = __builtin_amdgcn_mfma_f32_16x16x32_bf16(Bt[n][k], At[m][k], acc[ai][bj][m][n], 0, 0, 0); __builtin_amdgcn_s_setprio(0); } while (0)
; #define PG8_WAIT_V(n) asm volatile("s_waitcnt vmcnt(" #n ")" ::: "memory")
; #define PG8_WAIT_L(n) asm volatile("s_waitcnt lgkmcnt(" #n ")" ::: "memory")
; #define PG8_BAR __builtin_amdgcn_s_barrier()
; #define PG8_SCHED __builtin_amdgcn_sched_barrier(0)
; template <class Epi>
; __device__ __forceinline__ void gemm_phase(LAS unsigned char* lds, const Gemm g, const StaticOrder& S, const Epi& E) {
;     ...
;             PG8_LDB(B0, 0, 0); PG8_SCHED; PG8_LDA(At, 0, 0); PG8_STAGE(PG8_SA(1, 1), a1 + hstep, voffA);
;             PG8_WAIT_L(8); PG8_BAR; PG8_WAIT_L(0); PG8_MMA(0, 0, At, B0); PG8_BAR; PG8_SCHED;
;             PG8_LDB(B1, 0, 1); PG8_STAGE(PG8_SB(0, 0), b2, voffB0);
;             PG8_BAR; PG8_WAIT_L(0); PG8_MMA(0, 1, At, B1); PG8_BAR;
;             PG8_LDA(At, 0, 1); PG8_STAGE(PG8_SA(0, 0), a2, voffA);
;             PG8_BAR; PG8_WAIT_L(0); PG8_MMA(1, 0, At, B0); PG8_BAR; PG8_SCHED;
;             PG8_STAGE(PG8_SB(0, 1), b2, voffB1);
;             PG8_WAIT_V(6); PG8_BAR; PG8_MMA(1, 1, At, B1); PG8_BAR;
.LBB0_1245:
	ds_read_b128 v[146:149], v154
	ds_read_b128 v[158:161], v154 offset:1024
	ds_read_b128 v[162:165], v154 offset:2048
	ds_read_b128 v[166:169], v154 offset:3072
	s_add_u32 s33, s46, 0xfff80080
	s_addc_u32 s48, s47, -1
	s_cmp_eq_u32 s73, 28
	s_cselect_b32 s49, s35, s48
	s_cselect_b32 s48, s43, s33
	s_cselect_b32 s51, s31, s72
	s_cselect_b32 s50, s70, s71
	v_lshl_add_u64 v[204:205], s[46:47], 0, v[140:141]
	s_add_i32 m0, s45, 0xc000
	ds_read_b128 v[170:173], v155
	ds_read_b128 v[174:177], v155 offset:1024
	ds_read_b128 v[178:181], v155 offset:2048
	ds_read_b128 v[182:185], v155 offset:3072
	ds_read_b128 v[186:189], v155 offset:4096
	ds_read_b128 v[190:193], v155 offset:5120
	ds_read_b128 v[194:197], v155 offset:6144
	ds_read_b128 v[198:201], v155 offset:7168
	global_load_lds_dwordx4 v[204:205], off
	v_lshl_add_u64 v[204:205], s[46:47], 0, v[142:143]
	s_add_i32 m0, s45, 0xe000
	s_nop 0
	global_load_lds_dwordx4 v[204:205], off
	s_waitcnt lgkmcnt(8)
	s_barrier
	s_waitcnt lgkmcnt(0)
	v_mfma_f32_16x16x32_bf16 v[124:127], v[146:149], v[170:173], v[124:127]
	v_mfma_f32_16x16x32_bf16 v[120:123], v[162:165], v[170:173], v[120:123]
	v_mfma_f32_16x16x32_bf16 v[108:111], v[146:149], v[178:181], v[108:111]
	v_mfma_f32_16x16x32_bf16 v[104:107], v[162:165], v[178:181], v[104:107]
	v_mfma_f32_16x16x32_bf16 v[92:95], v[146:149], v[186:189], v[92:95]
	v_mfma_f32_16x16x32_bf16 v[88:91], v[162:165], v[186:189], v[88:91]
	v_mfma_f32_16x16x32_bf16 v[76:79], v[146:149], v[194:197], v[76:79]
	v_mfma_f32_16x16x32_bf16 v[72:75], v[162:165], v[194:197], v[72:75]
	v_mfma_f32_16x16x32_bf16 v[124:127], v[158:161], v[174:177], v[124:127]
	v_mfma_f32_16x16x32_bf16 v[120:123], v[166:169], v[174:177], v[120:123]
	v_mfma_f32_16x16x32_bf16 v[108:111], v[158:161], v[182:185], v[108:111]
	v_mfma_f32_16x16x32_bf16 v[104:107], v[166:169], v[182:185], v[104:107]
	v_mfma_f32_16x16x32_bf16 v[92:95], v[158:161], v[190:193], v[92:95]
	v_mfma_f32_16x16x32_bf16 v[88:91], v[166:169], v[190:193], v[88:91]
	v_mfma_f32_16x16x32_bf16 v[76:79], v[158:161], v[198:201], v[76:79]
	v_mfma_f32_16x16x32_bf16 v[72:75], v[166:169], v[198:201], v[72:75]
	s_barrier
	s_add_i32 s33, s68, s57
	v_lshl_add_u64 v[220:221], s[50:51], 0, v[130:131]
	s_mov_b32 m0, s33
	ds_read_b128 v[204:207], v156
	ds_read_b128 v[208:211], v156 offset:1024
	ds_read_b128 v[212:215], v156 offset:2048
	ds_read_b128 v[216:219], v156 offset:3072
	global_load_lds_dwordx4 v[220:221], off
	v_lshl_add_u64 v[222:223], s[50:51], 0, v[136:137]
	s_add_i32 m0, s33, 0x2000
	s_nop 0
	global_load_lds_dwordx4 v[222:223], off
	s_waitcnt lgkmcnt(0)
	s_barrier
	s_waitcnt lgkmcnt(0)
	v_mfma_f32_16x16x32_bf16 v[116:119], v[204:207], v[170:173], v[116:119]
	v_mfma_f32_16x16x32_bf16 v[112:115], v[212:215], v[170:173], v[112:115]
	v_mfma_f32_16x16x32_bf16 v[100:103], v[204:207], v[178:181], v[100:103]
	v_mfma_f32_16x16x32_bf16 v[96:99], v[212:215], v[178:181], v[96:99]
	v_mfma_f32_16x16x32_bf16 v[84:87], v[204:207], v[186:189], v[84:87]
	v_mfma_f32_16x16x32_bf16 v[80:83], v[212:215], v[186:189], v[80:83]
	v_mfma_f32_16x16x32_bf16 v[68:71], v[204:207], v[194:197], v[68:71]
	v_mfma_f32_16x16x32_bf16 v[64:67], v[212:215], v[194:197], v[64:67]
	v_mfma_f32_16x16x32_bf16 v[116:119], v[208:211], v[174:177], v[116:119]
	v_mfma_f32_16x16x32_bf16 v[112:115], v[216:219], v[174:177], v[112:115]
	v_mfma_f32_16x16x32_bf16 v[100:103], v[208:211], v[182:185], v[100:103]
	v_mfma_f32_16x16x32_bf16 v[96:99], v[216:219], v[182:185], v[96:99]
	v_mfma_f32_16x16x32_bf16 v[84:87], v[208:211], v[190:193], v[84:87]
	v_mfma_f32_16x16x32_bf16 v[80:83], v[216:219], v[190:193], v[80:83]
	v_mfma_f32_16x16x32_bf16 v[68:71], v[208:211], v[198:201], v[68:71]
	v_mfma_f32_16x16x32_bf16 v[64:67], v[216:219], v[198:201], v[64:67]
	s_mov_b32 m0, s45
	v_lshl_add_u64 v[224:225], s[48:49], 0, v[128:129]
	s_barrier
	ds_read_b128 v[170:173], v155 offset:16384
	ds_read_b128 v[174:177], v155 offset:17408
	ds_read_b128 v[178:181], v155 offset:18432
	ds_read_b128 v[182:185], v155 offset:19456
	ds_read_b128 v[186:189], v155 offset:20480
	ds_read_b128 v[190:193], v155 offset:21504
	ds_read_b128 v[194:197], v155 offset:22528
	ds_read_b128 v[198:201], v155 offset:23552
	global_load_lds_dwordx4 v[224:225], off
	v_lshl_add_u64 v[226:227], s[48:49], 0, v[134:135]
	s_mov_b32 m0, s58
	s_nop 0
	global_load_lds_dwordx4 v[226:227], off
	s_add_i32 s33, s69, s57
	v_lshl_add_u64 v[228:229], s[50:51], 0, v[132:133]
	s_mov_b32 m0, s33
	v_lshl_add_u64 v[230:231], s[50:51], 0, v[138:139]
	global_load_lds_dwordx4 v[228:229], off
	s_add_i32 m0, s33, 0x2000
	s_nop 0
	global_load_lds_dwordx4 v[230:231], off
	s_waitcnt vmcnt(6)
	s_barrier
; #define PG8_STAGE(bufoff, gbase, voff) do { _Pragma("unroll") for (int _i = 0; _i < 2; ++_i) \
;         __builtin_amdgcn_global_load_lds((const unsigned*)((const char*)(gbase) + (voff)[_i]), (LAS unsigned*)(lds + (bufoff) + ldsw + _i * 8192), 16, 0, 0); } while (0)
; #define PG8_LDA(dst, b, h) do { _Pragma("unroll") for (int m = 0; m < 4; ++m) _Pragma("unroll") for (int k = 0; k < 2; ++k) dst[m][k] = *(const LAS bf16x8*)(lds + PG8_SA(b, h) + aoff + m * 2048 + k * 1024); } while (0)
; #define PG8_LDB(dst, b, h) do { _Pragma("unroll") for (int n = 0; n < 2; ++n) _Pragma("unroll") for (int k = 0; k < 2; ++k) dst[n][k] = *(const LAS bf16x8*)(lds + PG8_SB(b, h) + boff + n * 2048 + k * 1024); } while (0)
; #define PG8_MMA(ai, bj, At, Bt) do { __builtin_amdgcn_s_setprio(1); _Pragma("unroll") for (int m = 0; m < 4; ++m) _Pragma("unroll") for (int n = 0; n < 2; ++n) _Pragma("unroll") for (int k = 0; k < 2; ++k) \
;         acc[ai][bj][m][n] = __builtin_amdgcn_mfma_f32_16x16x32_bf16(Bt[n][k], At[m][k], acc[ai][bj][m][n], 0, 0, 0); __builtin_amdgcn_s_setprio(0); } while (0)
; #define PG8_WAIT_V(n) asm volatile("s_waitcnt vmcnt(" #n ")" ::: "memory")
; #define PG8_WAIT_L(n) asm volatile("s_waitcnt lgkmcnt(" #n ")" ::: "memory")
; #define PG8_BAR __builtin_amdgcn_s_barrier()
; #define PG8_SCHED __builtin_amdgcn_sched_barrier(0)
; template <class Epi>
; __device__ __forceinline__ void gemm_phase(LAS unsigned char* lds, const Gemm g, const StaticOrder& S, const Epi& E) {
;     ...
;             PG8_WAIT_V(6); PG8_BAR; PG8_MMA(1, 1, At, B1); PG8_BAR;
;             PG8_LDB(B0, 1, 0); PG8_SCHED; PG8_LDA(At, 1, 0); PG8_STAGE(PG8_SA(0, 1), a2 + hstep, voffA);
;             PG8_WAIT_L(8); PG8_BAR; PG8_WAIT_L(0); PG8_MMA(0, 0, At, B0); PG8_BAR; PG8_SCHED;
;             PG8_LDB(B1, 1, 1); PG8_STAGE(PG8_SB(1, 0), b3, voffB0);
;             PG8_BAR; PG8_WAIT_L(0); PG8_MMA(0, 1, At, B1); PG8_BAR;
;             PG8_LDA(At, 1, 1); PG8_STAGE(PG8_SA(1, 0), a3, voffA);
;             PG8_BAR; PG8_WAIT_L(0); PG8_MMA(1, 0, At, B0); PG8_BAR; PG8_SCHED;
	s_waitcnt lgkmcnt(0)
	v_mfma_f32_16x16x32_bf16 v[60:63], v[146:149], v[170:173], v[60:63]
	v_mfma_f32_16x16x32_bf16 v[56:59], v[162:165], v[170:173], v[56:59]
	v_mfma_f32_16x16x32_bf16 v[44:47], v[146:149], v[178:181], v[44:47]
	v_mfma_f32_16x16x32_bf16 v[40:43], v[162:165], v[178:181], v[40:43]
	v_mfma_f32_16x16x32_bf16 v[28:31], v[146:149], v[186:189], v[28:31]
	v_mfma_f32_16x16x32_bf16 v[24:27], v[162:165], v[186:189], v[24:27]
	v_mfma_f32_16x16x32_bf16 v[12:15], v[146:149], v[194:197], v[12:15]
	v_mfma_f32_16x16x32_bf16 v[8:11], v[162:165], v[194:197], v[8:11]
	v_mfma_f32_16x16x32_bf16 v[60:63], v[158:161], v[174:177], v[60:63]
	v_mfma_f32_16x16x32_bf16 v[56:59], v[166:169], v[174:177], v[56:59]
	v_mfma_f32_16x16x32_bf16 v[44:47], v[158:161], v[182:185], v[44:47]
	v_mfma_f32_16x16x32_bf16 v[40:43], v[166:169], v[182:185], v[40:43]
	v_mfma_f32_16x16x32_bf16 v[28:31], v[158:161], v[190:193], v[28:31]
	v_mfma_f32_16x16x32_bf16 v[24:27], v[166:169], v[190:193], v[24:27]
	v_mfma_f32_16x16x32_bf16 v[12:15], v[158:161], v[198:201], v[12:15]
	v_mfma_f32_16x16x32_bf16 v[8:11], v[166:169], v[198:201], v[8:11]
	v_mfma_f32_16x16x32_bf16 v[52:55], v[204:207], v[170:173], v[52:55]
	v_mfma_f32_16x16x32_bf16 v[48:51], v[212:215], v[170:173], v[48:51]
	v_mfma_f32_16x16x32_bf16 v[36:39], v[204:207], v[178:181], v[36:39]
	v_mfma_f32_16x16x32_bf16 v[32:35], v[212:215], v[178:181], v[32:35]
	v_mfma_f32_16x16x32_bf16 v[20:23], v[204:207], v[186:189], v[20:23]
	v_mfma_f32_16x16x32_bf16 v[16:19], v[212:215], v[186:189], v[16:19]
	v_mfma_f32_16x16x32_bf16 v[4:7], v[204:207], v[194:197], v[4:7]
	v_mfma_f32_16x16x32_bf16 v[0:3], v[212:215], v[194:197], v[0:3]
	v_mfma_f32_16x16x32_bf16 v[52:55], v[208:211], v[174:177], v[52:55]
	v_mfma_f32_16x16x32_bf16 v[48:51], v[216:219], v[174:177], v[48:51]
	v_mfma_f32_16x16x32_bf16 v[36:39], v[208:211], v[182:185], v[36:39]
	v_mfma_f32_16x16x32_bf16 v[32:35], v[216:219], v[182:185], v[32:35]
	v_mfma_f32_16x16x32_bf16 v[20:23], v[208:211], v[190:193], v[20:23]
	v_mfma_f32_16x16x32_bf16 v[16:19], v[216:219], v[190:193], v[16:19]
	v_mfma_f32_16x16x32_bf16 v[4:7], v[208:211], v[198:201], v[4:7]
	v_mfma_f32_16x16x32_bf16 v[0:3], v[216:219], v[198:201], v[0:3]
	s_add_i32 s33, 0, 0x18000
	v_add_u32_e32 v157, s33, v151
	s_barrier
	ds_read_b128 v[146:149], v157
	ds_read_b128 v[158:161], v157 offset:1024
	ds_read_b128 v[162:165], v157 offset:2048
	ds_read_b128 v[166:169], v157 offset:3072
	s_add_u32 s48, s48, 0x80000
	s_addc_u32 s49, s49, 0
	s_mov_b32 m0, s59
	v_lshl_add_u64 v[204:205], s[48:49], 0, v[128:129]
	ds_read_b128 v[170:173], v155 offset:32768
	ds_read_b128 v[174:177], v155 offset:33792
	ds_read_b128 v[178:181], v155 offset:34816
	ds_read_b128 v[182:185], v155 offset:35840
	ds_read_b128 v[186:189], v155 offset:36864
	ds_read_b128 v[190:193], v155 offset:37888
	ds_read_b128 v[194:197], v155 offset:38912
	ds_read_b128 v[198:201], v155 offset:39936
	global_load_lds_dwordx4 v[204:205], off
	v_lshl_add_u64 v[204:205], s[48:49], 0, v[134:135]
	s_mov_b32 m0, s60
	s_nop 0
	global_load_lds_dwordx4 v[204:205], off
	s_waitcnt lgkmcnt(8)
	s_barrier
	s_waitcnt lgkmcnt(0)
	v_mfma_f32_16x16x32_bf16 v[124:127], v[146:149], v[170:173], v[124:127]
	v_mfma_f32_16x16x32_bf16 v[120:123], v[162:165], v[170:173], v[120:123]
	v_mfma_f32_16x16x32_bf16 v[108:111], v[146:149], v[178:181], v[108:111]
	v_mfma_f32_16x16x32_bf16 v[104:107], v[162:165], v[178:181], v[104:107]
	v_mfma_f32_16x16x32_bf16 v[92:95], v[146:149], v[186:189], v[92:95]
	v_mfma_f32_16x16x32_bf16 v[88:91], v[162:165], v[186:189], v[88:91]
	v_mfma_f32_16x16x32_bf16 v[76:79], v[146:149], v[194:197], v[76:79]
	v_mfma_f32_16x16x32_bf16 v[72:75], v[162:165], v[194:197], v[72:75]
	v_mfma_f32_16x16x32_bf16 v[124:127], v[158:161], v[174:177], v[124:127]
	v_mfma_f32_16x16x32_bf16 v[120:123], v[166:169], v[174:177], v[120:123]
	v_mfma_f32_16x16x32_bf16 v[108:111], v[158:161], v[182:185], v[108:111]
	v_mfma_f32_16x16x32_bf16 v[104:107], v[166:169], v[182:185], v[104:107]
	v_mfma_f32_16x16x32_bf16 v[92:95], v[158:161], v[190:193], v[92:95]
	v_mfma_f32_16x16x32_bf16 v[88:91], v[166:169], v[190:193], v[88:91]
	v_mfma_f32_16x16x32_bf16 v[76:79], v[158:161], v[198:201], v[76:79]
	v_mfma_f32_16x16x32_bf16 v[72:75], v[166:169], v[198:201], v[72:75]
	s_barrier
	s_add_i32 s48, 0, 0x1c000
	s_add_i32 s33, s33, s57
	v_add_u32_e32 v157, s48, v151
	v_lshl_add_u64 v[220:221], v[220:221], 0, s[26:27]
	s_mov_b32 m0, s33
	ds_read_b128 v[204:207], v157
	ds_read_b128 v[208:211], v157 offset:1024
	ds_read_b128 v[212:215], v157 offset:2048
	ds_read_b128 v[216:219], v157 offset:3072
	global_load_lds_dwordx4 v[220:221], off
	v_lshl_add_u64 v[220:221], v[222:223], 0, s[26:27]
	s_add_i32 m0, s33, 0x2000
	s_nop 0
	global_load_lds_dwordx4 v[220:221], off
	s_waitcnt lgkmcnt(0)
	s_barrier
	s_waitcnt lgkmcnt(0)
	v_mfma_f32_16x16x32_bf16 v[116:119], v[204:207], v[170:173], v[116:119]
	v_mfma_f32_16x16x32_bf16 v[112:115], v[212:215], v[170:173], v[112:115]
	v_mfma_f32_16x16x32_bf16 v[100:103], v[204:207], v[178:181], v[100:103]
	v_mfma_f32_16x16x32_bf16 v[96:99], v[212:215], v[178:181], v[96:99]
	v_mfma_f32_16x16x32_bf16 v[84:87], v[204:207], v[186:189], v[84:87]
	v_mfma_f32_16x16x32_bf16 v[80:83], v[212:215], v[186:189], v[80:83]
	v_mfma_f32_16x16x32_bf16 v[68:71], v[204:207], v[194:197], v[68:71]
	v_mfma_f32_16x16x32_bf16 v[64:67], v[212:215], v[194:197], v[64:67]
	v_mfma_f32_16x16x32_bf16 v[116:119], v[208:211], v[174:177], v[116:119]
	v_mfma_f32_16x16x32_bf16 v[112:115], v[216:219], v[174:177], v[112:115]
	v_mfma_f32_16x16x32_bf16 v[100:103], v[208:211], v[182:185], v[100:103]
	v_mfma_f32_16x16x32_bf16 v[96:99], v[216:219], v[182:185], v[96:99]
	v_mfma_f32_16x16x32_bf16 v[84:87], v[208:211], v[190:193], v[84:87]
	v_mfma_f32_16x16x32_bf16 v[80:83], v[216:219], v[190:193], v[80:83]
	v_mfma_f32_16x16x32_bf16 v[68:71], v[208:211], v[198:201], v[68:71]
	v_mfma_f32_16x16x32_bf16 v[64:67], v[216:219], v[198:201], v[64:67]
	s_mov_b32 m0, s62
	v_lshl_add_u64 v[220:221], v[224:225], 0, s[26:27]
	s_barrier
; #define PG8_STAGE(bufoff, gbase, voff) do { _Pragma("unroll") for (int _i = 0; _i < 2; ++_i) \
;         __builtin_amdgcn_global_load_lds((const unsigned*)((const char*)(gbase) + (voff)[_i]), (LAS unsigned*)(lds + (bufoff) + ldsw + _i * 8192), 16, 0, 0); } while (0)
; #define PG8_MMA(ai, bj, At, Bt) do { __builtin_amdgcn_s_setprio(1); _Pragma("unroll") for (int m = 0; m < 4; ++m) _Pragma("unroll") for (int n = 0; n < 2; ++n) _Pragma("unroll") for (int k = 0; k < 2; ++k) \
;         acc[ai][bj][m][n] = __builtin_amdgcn_mfma_f32_16x16x32_bf16(Bt[n][k], At[m][k], acc[ai][bj][m][n], 0, 0, 0); __builtin_amdgcn_s_setprio(0); } while (0)
; #define PG8_WAIT_V(n) asm volatile("s_waitcnt vmcnt(" #n ")" ::: "memory")
; #define PG8_WAIT_L(n) asm volatile("s_waitcnt lgkmcnt(" #n ")" ::: "memory")
; #define PG8_BAR __builtin_amdgcn_s_barrier()
; #define PG8_SCHED __builtin_amdgcn_sched_barrier(0)
;     __device__ __forceinline__ void operator()(const f32x4 (&acc)[2][2][4][2], const Unit& u, int wr, int wc, int fr, int fq) const {
;     ...
;             for (int m = 0; m < 4; ++m) { const int row = row0 + ai * HALF + m * 16; const size_t off = (size_t)row * D + col0; float sq = 0.f; u32x4 w[2];
;                 const float sc = rsin ? __builtin_amdgcn_rcpf(rsin[row] * (1.f / D) + EPS) : 1.0f;
;                 u32x4 rr[2]; if (R) load_pair_lines(R, D, row, fr, col0, rr[0], rr[1]);
; template <class Epi>
; __device__ __forceinline__ void gemm_phase(LAS unsigned char* lds, const Gemm g, const StaticOrder& S, const Epi& E) {
;     ...
;             PG8_BAR; PG8_WAIT_L(0); PG8_MMA(1, 0, At, B0); PG8_BAR; PG8_SCHED;
;             PG8_STAGE(PG8_SB(1, 1), b3, voffB1);
;             PG8_WAIT_V(6); PG8_BAR; PG8_MMA(1, 1, At, B1); PG8_BAR;
;         }
	ds_read_b128 v[170:173], v155 offset:49152
	ds_read_b128 v[174:177], v155 offset:50176
	ds_read_b128 v[178:181], v155 offset:51200
	ds_read_b128 v[182:185], v155 offset:52224
	ds_read_b128 v[186:189], v155 offset:53248
	ds_read_b128 v[190:193], v155 offset:54272
	ds_read_b128 v[194:197], v155 offset:55296
	ds_read_b128 v[198:201], v155 offset:56320
	global_load_lds_dwordx4 v[220:221], off
	v_lshl_add_u64 v[220:221], v[226:227], 0, s[26:27]
	s_mov_b32 m0, s63
	s_nop 0
	global_load_lds_dwordx4 v[220:221], off
	s_add_i32 s33, s48, s57
	v_lshl_add_u64 v[250:251], v[228:229], 0, s[26:27]
	s_mov_b32 m0, s33
	s_nop 0
	global_load_lds_dwordx4 v[250:251], off
	v_lshl_add_u64 v[250:251], v[230:231], 0, s[26:27]
	s_add_i32 m0, s33, 0x2000
	s_nop 0
	global_load_lds_dwordx4 v[250:251], off
	s_waitcnt vmcnt(6)
	s_barrier
	s_waitcnt lgkmcnt(0)
	v_mfma_f32_16x16x32_bf16 v[60:63], v[146:149], v[170:173], v[60:63]
	v_mfma_f32_16x16x32_bf16 v[56:59], v[162:165], v[170:173], v[56:59]
	v_mfma_f32_16x16x32_bf16 v[44:47], v[146:149], v[178:181], v[44:47]
	v_mfma_f32_16x16x32_bf16 v[40:43], v[162:165], v[178:181], v[40:43]
	v_mfma_f32_16x16x32_bf16 v[28:31], v[146:149], v[186:189], v[28:31]
	v_mfma_f32_16x16x32_bf16 v[24:27], v[162:165], v[186:189], v[24:27]
	v_mfma_f32_16x16x32_bf16 v[12:15], v[146:149], v[194:197], v[12:15]
	v_mfma_f32_16x16x32_bf16 v[8:11], v[162:165], v[194:197], v[8:11]
	v_mfma_f32_16x16x32_bf16 v[60:63], v[158:161], v[174:177], v[60:63]
	v_mfma_f32_16x16x32_bf16 v[56:59], v[166:169], v[174:177], v[56:59]
	v_mfma_f32_16x16x32_bf16 v[44:47], v[158:161], v[182:185], v[44:47]
	v_mfma_f32_16x16x32_bf16 v[40:43], v[166:169], v[182:185], v[40:43]
	v_mfma_f32_16x16x32_bf16 v[28:31], v[158:161], v[190:193], v[28:31]
	v_mfma_f32_16x16x32_bf16 v[24:27], v[166:169], v[190:193], v[24:27]
	v_mfma_f32_16x16x32_bf16 v[12:15], v[158:161], v[198:201], v[12:15]
	v_mfma_f32_16x16x32_bf16 v[8:11], v[166:169], v[198:201], v[8:11]
	v_mfma_f32_16x16x32_bf16 v[52:55], v[204:207], v[170:173], v[52:55]
	v_mfma_f32_16x16x32_bf16 v[48:51], v[212:215], v[170:173], v[48:51]
	v_mfma_f32_16x16x32_bf16 v[36:39], v[204:207], v[178:181], v[36:39]
	v_mfma_f32_16x16x32_bf16 v[32:35], v[212:215], v[178:181], v[32:35]
	v_mfma_f32_16x16x32_bf16 v[20:23], v[204:207], v[186:189], v[20:23]
	v_mfma_f32_16x16x32_bf16 v[16:19], v[212:215], v[186:189], v[16:19]
	v_mfma_f32_16x16x32_bf16 v[4:7], v[204:207], v[194:197], v[4:7]
	v_mfma_f32_16x16x32_bf16 v[0:3], v[212:215], v[194:197], v[0:3]
	v_mfma_f32_16x16x32_bf16 v[52:55], v[208:211], v[174:177], v[52:55]
	v_mfma_f32_16x16x32_bf16 v[48:51], v[216:219], v[174:177], v[48:51]
	v_mfma_f32_16x16x32_bf16 v[36:39], v[208:211], v[182:185], v[36:39]
	v_mfma_f32_16x16x32_bf16 v[32:35], v[216:219], v[182:185], v[32:35]
	v_mfma_f32_16x16x32_bf16 v[20:23], v[208:211], v[190:193], v[20:23]
	v_mfma_f32_16x16x32_bf16 v[16:19], v[216:219], v[190:193], v[16:19]
	v_mfma_f32_16x16x32_bf16 v[4:7], v[208:211], v[198:201], v[4:7]
	v_mfma_f32_16x16x32_bf16 v[0:3], v[216:219], v[198:201], v[0:3]
	s_add_i32 s73, s73, 2
	s_add_u32 s46, s46, 0x100
	s_addc_u32 s47, s47, 0
	s_add_u32 s71, s71, 0x100
	s_addc_u32 s72, s72, 0
	s_cmp_gt_u32 s73, 29
	s_barrier
	s_cbranch_scc0 .LBB0_1245
	s_lshl_b32 s31, s44, 8
	s_add_i32 s31, s31, s64
	v_or_b32_e32 v148, s31, v152
	v_ashrrev_i32_e32 v149, 31, v148
	v_lshlrev_b64 v[166:167], 12, v[148:149]
	v_or_b32_e32 v148, 8, v148
	v_lshl_or_b32 v146, s42, 8, v153
	v_ashrrev_i32_e32 v149, 31, v148
	v_ashrrev_i32_e32 v147, 31, v146
	v_lshlrev_b64 v[168:169], 12, v[148:149]
	v_lshl_add_u64 v[158:159], s[10:11], 0, v[166:167]
	v_lshlrev_b64 v[146:147], 1, v[146:147]
	v_lshl_add_u64 v[148:149], s[10:11], 0, v[168:169]
	v_lshl_add_u64 v[158:159], v[158:159], 0, v[146:147]
	v_lshl_add_u64 v[148:149], v[148:149], 0, v[146:147]
	global_load_dwordx4 v[158:161], v[158:159], off
	global_load_dwordx4 v[162:165], v[148:149], off
	v_or_b32_e32 v194, s31, v150
	v_or_b32_e32 v184, 16, v194
	v_sub_u32_e32 v185, v184, v150
	v_add_u32_e32 v186, v185, v152
	v_ashrrev_i32_e32 v187, 31, v186
	v_lshlrev_b64 v[190:191], 12, v[186:187]
	v_lshl_add_u64 v[192:193], v[190:191], 0, s[28:29]
	v_lshl_add_u64 v[186:187], s[10:11], 0, v[190:191]
	v_lshl_add_u64 v[188:189], s[10:11], 0, v[192:193]
	v_lshl_add_u64 v[186:187], v[186:187], 0, v[146:147]
	v_lshl_add_u64 v[188:189], v[188:189], 0, v[146:147]
	global_load_dwordx4 v[196:199], v[186:187], off
	global_load_dwordx4 v[204:207], v[188:189], off
	v_or_b32_e32 v194, s31, v150
	v_or_b32_e32 v184, 32, v194
	v_sub_u32_e32 v185, v184, v150
	v_add_u32_e32 v186, v185, v152
	v_ashrrev_i32_e32 v187, 31, v186
	v_lshlrev_b64 v[190:191], 12, v[186:187]
	v_lshl_add_u64 v[192:193], v[190:191], 0, s[28:29]
	v_lshl_add_u64 v[186:187], s[10:11], 0, v[190:191]
	v_lshl_add_u64 v[188:189], s[10:11], 0, v[192:193]
	v_lshl_add_u64 v[186:187], v[186:187], 0, v[146:147]
	v_lshl_add_u64 v[188:189], v[188:189], 0, v[146:147]
	global_load_dwordx4 v[208:211], v[186:187], off
	global_load_dwordx4 v[212:215], v[188:189], off
	v_or_b32_e32 v194, s31, v150
	v_or_b32_e32 v184, 48, v194
	v_sub_u32_e32 v185, v184, v150
	v_add_u32_e32 v186, v185, v152
	v_ashrrev_i32_e32 v187, 31, v186
	v_lshlrev_b64 v[190:191], 12, v[186:187]
	v_lshl_add_u64 v[192:193], v[190:191], 0, s[28:29]
	v_lshl_add_u64 v[186:187], s[10:11], 0, v[190:191]
	v_lshl_add_u64 v[188:189], s[10:11], 0, v[192:193]
	v_lshl_add_u64 v[186:187], v[186:187], 0, v[146:147]
	v_lshl_add_u64 v[188:189], v[188:189], 0, v[146:147]
	global_load_dwordx4 v[216:219], v[186:187], off
	global_load_dwordx4 v[220:223], v[188:189], off
	v_or_b32_e32 v194, s31, v150
	v_add_u32_e32 v184, 0x80, v194
; __device__ __forceinline__ void store_pair_lines(bf16_t* O, int ldc, int row, int fr, int col0, u32x4 wA, u32x4 wB) {
;     const u32x4 sA = {dpp_ror8(wA.x), dpp_ror8(wA.y), dpp_ror8(wA.z), dpp_ror8(wA.w)}, sB = {dpp_ror8(wB.x), dpp_ror8(wB.y), dpp_ror8(wB.z), dpp_ror8(wB.w)};
;     const bool lo = fr < 8;
;     const u32x4 o1 = lo ? wA : sB, o2 = lo ? sA : wB;
;     const int r1 = row - fr + (fr & 7), cb = col0 + (lo ? 0 : 8);
;     *(u32x4*)(O + (size_t)r1 * ldc + cb) = o1;
;     *(u32x4*)(O + (size_t)(r1 + 8) * ldc + cb) = o2;
; }
;     const bool lo = fr < 8;
;     const int r1 = row - fr + (fr & 7), cb = col0 + (lo ? 0 : boff);
;     const u32x4 l1 = *(const u32x4*)(P + (size_t)r1 * ld + cb), l2 = *(const u32x4*)(P + (size_t)(r1 + 8) * ld + cb);
;     __device__ __forceinline__ void operator()(const f32x4 (&acc)[2][2][4][2], const Unit& u, int wr, int wc, int fr, int fq) const {
;     ...
;             for (int m = 0; m < 4; ++m) { const int row = row0 + ai * HALF + m * 16; const size_t off = (size_t)row * D + col0; float sq = 0.f; u32x4 w[2];
;                 const float sc = rsin ? __builtin_amdgcn_rcpf(rsin[row] * (1.f / D) + EPS) : 1.0f;
;                 u32x4 rr[2]; if (R) load_pair_lines(R, D, row, fr, col0, rr[0], rr[1]);
; #pragma unroll
;                 for (int bj = 0; bj < 2; ++bj) { f32x4 r0, r1;
;                     if (R) { const u32x4 rw = rr[bj]; r0 = (f32x4){bflo(rw.x), bfhi(rw.x), bflo(rw.y), bfhi(rw.y)}; r1 = (f32x4){bflo(rw.z), bfhi(rw.z), bflo(rw.w), bfhi(rw.w)}; }
;                     else { const float* rp = (row < 8192 ? src_p + off : src_s + (off - (size_t)8192 * D)) + 8 * bj; r0 = *(const f32x4*)rp; r1 = *(const f32x4*)(rp + 4); }
;                     const f32x4 o0 = r0 + acc[ai][bj][m][0] * sc, o1 = r1 + acc[ai][bj][m][1] * sc;
;                     sq += (o0[0] * o0[0] + o0[1] * o0[1]) + (o0[2] * o0[2] + o0[3] * o0[3]) + (o1[0] * o1[0] + o1[1] * o1[1]) + (o1[2] * o1[2] + o1[3] * o1[3]);
;                     w[bj].x = cvt_pk_bf16(o0[0], o0[1]); w[bj].y = cvt_pk_bf16(o0[2], o0[3]); w[bj].z = cvt_pk_bf16(o1[0], o1[1]); w[bj].w = cvt_pk_bf16(o1[2], o1[3]); }
;                 store_pair_lines(O, D, row, fr, col0, w[0], w[1]);
;                 if (ssout) { sq += __shfl_xor(sq, 16); sq += __shfl_xor(sq, 32); if (fq == 0) unsafeAtomicAdd(ssout + row, sq); } }
	v_sub_u32_e32 v185, v184, v150
	v_add_u32_e32 v186, v185, v152
	v_ashrrev_i32_e32 v187, 31, v186
	v_lshlrev_b64 v[190:191], 12, v[186:187]
	v_lshl_add_u64 v[192:193], v[190:191], 0, s[28:29]
	v_lshl_add_u64 v[186:187], s[10:11], 0, v[190:191]
	v_lshl_add_u64 v[188:189], s[10:11], 0, v[192:193]
	v_lshl_add_u64 v[186:187], v[186:187], 0, v[146:147]
	v_lshl_add_u64 v[188:189], v[188:189], 0, v[146:147]
	global_load_dwordx4 v[224:227], v[186:187], off
	global_load_dwordx4 v[228:231], v[188:189], off
	v_or_b32_e32 v194, s31, v150
	v_add_u32_e32 v184, 0x90, v194
	v_sub_u32_e32 v185, v184, v150
	v_add_u32_e32 v186, v185, v152
	v_ashrrev_i32_e32 v187, 31, v186
	v_lshlrev_b64 v[190:191], 12, v[186:187]
	v_lshl_add_u64 v[192:193], v[190:191], 0, s[28:29]
	v_lshl_add_u64 v[186:187], s[10:11], 0, v[190:191]
	v_lshl_add_u64 v[188:189], s[10:11], 0, v[192:193]
	v_lshl_add_u64 v[186:187], v[186:187], 0, v[146:147]
	v_lshl_add_u64 v[188:189], v[188:189], 0, v[146:147]
	global_load_dwordx4 v[232:235], v[186:187], off
	global_load_dwordx4 v[236:239], v[188:189], off
	v_or_b32_e32 v194, s31, v150
	v_add_u32_e32 v184, 0xa0, v194
	v_sub_u32_e32 v185, v184, v150
	v_add_u32_e32 v186, v185, v152
	v_ashrrev_i32_e32 v187, 31, v186
	v_lshlrev_b64 v[190:191], 12, v[186:187]
	v_lshl_add_u64 v[192:193], v[190:191], 0, s[28:29]
	v_lshl_add_u64 v[186:187], s[10:11], 0, v[190:191]
	v_lshl_add_u64 v[188:189], s[10:11], 0, v[192:193]
	v_lshl_add_u64 v[186:187], v[186:187], 0, v[146:147]
	v_lshl_add_u64 v[188:189], v[188:189], 0, v[146:147]
	global_load_dwordx4 v[240:243], v[186:187], off
	global_load_dwordx4 v[244:247], v[188:189], off
	v_or_b32_e32 v148, s31, v150
	s_waitcnt vmcnt(12)
	v_mov_b32_dpp v149, v158 row_ror:8 row_mask:0xf bank_mask:0xf
	v_mov_b32_dpp v157, v159 row_ror:8 row_mask:0xf bank_mask:0xf
	v_mov_b32_dpp v171, v161 row_ror:8 row_mask:0xf bank_mask:0xf
	v_mov_b32_dpp v172, v162 row_ror:8 row_mask:0xf bank_mask:0xf
	v_mov_b32_dpp v173, v163 row_ror:8 row_mask:0xf bank_mask:0xf
	v_mov_b32_dpp v170, v160 row_ror:8 row_mask:0xf bank_mask:0xf
	v_mov_b32_dpp v174, v164 row_ror:8 row_mask:0xf bank_mask:0xf
	v_mov_b32_dpp v175, v165 row_ror:8 row_mask:0xf bank_mask:0xf
	v_cndmask_b32_e64 v165, v165, v171, s[6:7]
	v_cndmask_b32_e64 v157, v163, v157, s[6:7]
	v_cndmask_b32_e64 v149, v162, v149, s[6:7]
	v_cndmask_b32_e64 v173, v173, v159, s[6:7]
	v_cndmask_b32_e64 v171, v172, v158, s[6:7]
	v_cndmask_b32_e64 v164, v164, v170, s[6:7]
	v_cndmask_b32_e64 v177, v175, v161, s[6:7]
	v_cndmask_b32_e64 v175, v174, v160, s[6:7]
	v_lshlrev_b32_e32 v158, 16, v149
	v_and_b32_e32 v159, 0xffff0000, v149
	v_lshlrev_b32_e32 v160, 16, v157
	v_and_b32_e32 v161, 0xffff0000, v157
	v_lshlrev_b32_e32 v170, 16, v171
	v_and_b32_e32 v171, 0xffff0000, v171
	v_lshlrev_b32_e32 v172, 16, v173
	v_and_b32_e32 v173, 0xffff0000, v173
	v_lshlrev_b32_e32 v174, 16, v175
	v_and_b32_e32 v175, 0xffff0000, v175
	v_pk_add_f32 v[160:161], v[118:119], v[160:161]
	v_pk_add_f32 v[158:159], v[116:117], v[158:159]
	v_pk_add_f32 v[116:117], v[126:127], v[172:173]
	v_pk_add_f32 v[118:119], v[124:125], v[170:171]
	v_lshlrev_b32_e32 v176, 16, v177
	v_and_b32_e32 v177, 0xffff0000, v177
	v_pk_add_f32 v[120:121], v[120:121], v[174:175]
	v_mul_f32_e32 v124, v119, v119
	v_mul_f32_e32 v125, v117, v117
	v_lshlrev_b32_e32 v162, 16, v164
	v_and_b32_e32 v163, 0xffff0000, v164
	v_lshlrev_b32_e32 v164, 16, v165
	v_and_b32_e32 v165, 0xffff0000, v165
	v_pk_add_f32 v[122:123], v[122:123], v[176:177]
	v_mul_f32_e32 v126, v121, v121
	v_fmac_f32_e32 v124, v118, v118
	v_fmac_f32_e32 v125, v116, v116
	v_pk_add_f32 v[114:115], v[114:115], v[164:165]
	v_mul_f32_e32 v127, v123, v123
	v_cvt_pk_bf16_f32 v119, v118, v119
	v_cvt_pk_bf16_f32 v117, v116, v117
	v_cvt_pk_bf16_f32 v121, v120, v121
	v_fmac_f32_e32 v126, v120, v120
	v_add_f32_e32 v116, v124, v125
	v_pk_add_f32 v[112:113], v[112:113], v[162:163]
	v_cvt_pk_bf16_f32 v123, v122, v123
	v_cvt_pk_bf16_f32 v149, v158, v159
	v_cvt_pk_bf16_f32 v157, v160, v161
	v_fmac_f32_e32 v127, v122, v122
	v_cvt_pk_bf16_f32 v162, v112, v113
	v_cvt_pk_bf16_f32 v163, v114, v115
	v_add_f32_e32 v116, v126, v116
	v_mov_b32_dpp v182, v149 row_ror:8 row_mask:0xf bank_mask:0xf
	v_mov_b32_dpp v120, v163 row_ror:8 row_mask:0xf bank_mask:0xf
	v_mul_f32_e32 v115, v115, v115
	v_mov_b32_dpp v178, v119 row_ror:8 row_mask:0xf bank_mask:0xf
	v_mov_b32_dpp v181, v123 row_ror:8 row_mask:0xf bank_mask:0xf
	v_add_f32_e32 v122, v127, v116
	v_cndmask_b32_e64 v116, v182, v119, s[6:7]
	v_cndmask_b32_e64 v119, v120, v123, s[6:7]
	v_fmac_f32_e32 v115, v114, v114
	v_mul_f32_e32 v114, v159, v159
	v_mul_f32_e32 v123, v161, v161
	v_fmac_f32_e32 v114, v158, v158
	v_fmac_f32_e32 v123, v160, v160
	v_mul_f32_e32 v113, v113, v113
	v_add_f32_e32 v114, v114, v123
	v_fmac_f32_e32 v113, v112, v112
	v_add_f32_e32 v112, v113, v114
	v_add_f32_e32 v112, v115, v112
	v_and_b32_e32 v113, 64, v203
	v_add_f32_e32 v115, v112, v122
	v_xor_b32_e32 v112, 16, v203
	v_add_u32_e32 v126, 64, v113
	v_cmp_lt_i32_e32 vcc, v112, v126
	v_mov_b32_e32 v118, 0
	v_mov_b32_dpp v183, v157 row_ror:8 row_mask:0xf bank_mask:0xf
	v_cndmask_b32_e32 v112, v203, v112, vcc
	v_lshlrev_b32_e32 v114, 2, v112
	v_mov_b32_e32 v127, v115
	s_nop 1
	v_permlane16_swap_b32_e32 v127, v115
	v_lshl_add_u64 v[112:113], s[16:17], 0, v[166:167]
	v_lshl_add_u64 v[124:125], v[112:113], 0, v[146:147]
	v_xor_b32_e32 v113, 32, v203
	v_cmp_lt_i32_e32 vcc, v113, v126
	s_waitcnt lgkmcnt(0)
	v_add_f32_e32 v112, v115, v127
	v_mov_b32_dpp v118, v162 row_ror:8 row_mask:0xf bank_mask:0xf
	v_cndmask_b32_e32 v113, v203, v113, vcc
	v_lshlrev_b32_e32 v115, 2, v113
	v_mov_b32_e32 v113, v112
	s_nop 1
	v_permlane32_swap_b32_e32 v113, v112
	v_mov_b32_dpp v179, v117 row_ror:8 row_mask:0xf bank_mask:0xf
	v_cndmask_b32_e64 v117, v183, v117, s[6:7]
	v_cndmask_b32_e64 v118, v118, v121, s[6:7]
	v_mov_b32_dpp v180, v121 row_ror:8 row_mask:0xf bank_mask:0xf
	global_store_dwordx4 v[124:125], v[116:119], off
	v_cndmask_b32_e64 v120, v149, v178, s[6:7]
	v_cndmask_b32_e64 v121, v157, v179, s[6:7]
	v_lshl_add_u64 v[116:117], s[16:17], 0, v[168:169]
	v_cndmask_b32_e64 v122, v162, v180, s[6:7]
	v_cndmask_b32_e64 v123, v163, v181, s[6:7]
	v_lshl_add_u64 v[116:117], v[116:117], 0, v[146:147]
	global_store_dwordx4 v[116:117], v[120:123], off
	s_and_saveexec_b64 s[42:43], s[8:9]
	s_cbranch_execz .LBB0_1248
	v_ashrrev_i32_e32 v149, 31, v148
	s_waitcnt lgkmcnt(0)
	v_add_f32_e32 v116, v112, v113
	v_lshl_add_u64 v[112:113], v[148:149], 2, s[18:19]
	global_atomic_add_f32 v[112:113], v116, off
; __device__ __forceinline__ void store_pair_lines(bf16_t* O, int ldc, int row, int fr, int col0, u32x4 wA, u32x4 wB) {
;     const u32x4 sA = {dpp_ror8(wA.x), dpp_ror8(wA.y), dpp_ror8(wA.z), dpp_ror8(wA.w)}, sB = {dpp_ror8(wB.x), dpp_ror8(wB.y), dpp_ror8(wB.z), dpp_ror8(wB.w)};
;     const bool lo = fr < 8;
;     const u32x4 o1 = lo ? wA : sB, o2 = lo ? sA : wB;
;     const int r1 = row - fr + (fr & 7), cb = col0 + (lo ? 0 : 8);
;     *(u32x4*)(O + (size_t)r1 * ldc + cb) = o1;
;     *(u32x4*)(O + (size_t)(r1 + 8) * ldc + cb) = o2;
; }
;     const bool lo = fr < 8;
;     const int r1 = row - fr + (fr & 7), cb = col0 + (lo ? 0 : boff);
;     const u32x4 l1 = *(const u32x4*)(P + (size_t)r1 * ld + cb), l2 = *(const u32x4*)(P + (size_t)(r1 + 8) * ld + cb);
;     __device__ __forceinline__ void operator()(const f32x4 (&acc)[2][2][4][2], const Unit& u, int wr, int wc, int fr, int fq) const {
;     ...
;             for (int m = 0; m < 4; ++m) { const int row = row0 + ai * HALF + m * 16; const size_t off = (size_t)row * D + col0; float sq = 0.f; u32x4 w[2];
;                 const float sc = rsin ? __builtin_amdgcn_rcpf(rsin[row] * (1.f / D) + EPS) : 1.0f;
;                 u32x4 rr[2]; if (R) load_pair_lines(R, D, row, fr, col0, rr[0], rr[1]);
; #pragma unroll
;                 for (int bj = 0; bj < 2; ++bj) { f32x4 r0, r1;
;                     if (R) { const u32x4 rw = rr[bj]; r0 = (f32x4){bflo(rw.x), bfhi(rw.x), bflo(rw.y), bfhi(rw.y)}; r1 = (f32x4){bflo(rw.z), bfhi(rw.z), bflo(rw.w), bfhi(rw.w)}; }
;                     else { const float* rp = (row < 8192 ? src_p + off : src_s + (off - (size_t)8192 * D)) + 8 * bj; r0 = *(const f32x4*)rp; r1 = *(const f32x4*)(rp + 4); }
;                     const f32x4 o0 = r0 + acc[ai][bj][m][0] * sc, o1 = r1 + acc[ai][bj][m][1] * sc;
;                     sq += (o0[0] * o0[0] + o0[1] * o0[1]) + (o0[2] * o0[2] + o0[3] * o0[3]) + (o1[0] * o1[0] + o1[1] * o1[1]) + (o1[2] * o1[2] + o1[3] * o1[3]);
;                     w[bj].x = cvt_pk_bf16(o0[0], o0[1]); w[bj].y = cvt_pk_bf16(o0[2], o0[3]); w[bj].z = cvt_pk_bf16(o1[0], o1[1]); w[bj].w = cvt_pk_bf16(o1[2], o1[3]); }
;                 store_pair_lines(O, D, row, fr, col0, w[0], w[1]);
;                 if (ssout) { sq += __shfl_xor(sq, 16); sq += __shfl_xor(sq, 32); if (fq == 0) unsafeAtomicAdd(ssout + row, sq); } }
.LBB0_1248:
	s_or_b64 exec, exec, s[42:43]
	v_or_b32_e32 v112, 16, v148
	s_waitcnt lgkmcnt(0)
	v_sub_u32_e32 v113, v112, v150
	v_add_u32_e32 v116, v113, v152
	v_ashrrev_i32_e32 v117, 31, v116
	v_lshlrev_b64 v[124:125], 12, v[116:117]
	v_lshl_add_u64 v[126:127], v[124:125], 0, s[28:29]
	v_lshl_add_u64 v[116:117], s[10:11], 0, v[124:125]
	v_lshl_add_u64 v[120:121], s[10:11], 0, v[126:127]
	v_lshl_add_u64 v[116:117], v[116:117], 0, v[146:147]
	v_lshl_add_u64 v[120:121], v[120:121], 0, v[146:147]
	s_waitcnt vmcnt(12)
	s_nop 0
	v_mov_b64_e32 v[116:117], v[196:197]
	v_mov_b64_e32 v[118:119], v[198:199]
	v_mov_b64_e32 v[120:121], v[204:205]
	v_mov_b64_e32 v[122:123], v[206:207]
	s_nop 1
	v_add_u32_e32 v184, 0xb0, v148
	v_sub_u32_e32 v185, v184, v150
	v_add_u32_e32 v186, v185, v152
	v_ashrrev_i32_e32 v187, 31, v186
	v_lshlrev_b64 v[190:191], 12, v[186:187]
	v_lshl_add_u64 v[192:193], v[190:191], 0, s[28:29]
	v_lshl_add_u64 v[186:187], s[10:11], 0, v[190:191]
	v_lshl_add_u64 v[188:189], s[10:11], 0, v[192:193]
	v_lshl_add_u64 v[186:187], v[186:187], 0, v[146:147]
	v_lshl_add_u64 v[188:189], v[188:189], 0, v[146:147]
	global_load_dwordx4 v[196:199], v[186:187], off
	global_load_dwordx4 v[204:207], v[188:189], off
	s_waitcnt vmcnt(16)
	v_mov_b32_dpp v113, v116 row_ror:8 row_mask:0xf bank_mask:0xf
	v_mov_b32_dpp v149, v117 row_ror:8 row_mask:0xf bank_mask:0xf
	v_mov_b32_dpp v157, v118 row_ror:8 row_mask:0xf bank_mask:0xf
	v_mov_b32_dpp v158, v119 row_ror:8 row_mask:0xf bank_mask:0xf
	s_waitcnt vmcnt(16)
	v_mov_b32_dpp v159, v120 row_ror:8 row_mask:0xf bank_mask:0xf
	v_mov_b32_dpp v160, v121 row_ror:8 row_mask:0xf bank_mask:0xf
	v_mov_b32_dpp v161, v122 row_ror:8 row_mask:0xf bank_mask:0xf
	v_mov_b32_dpp v162, v123 row_ror:8 row_mask:0xf bank_mask:0xf
	v_cndmask_b32_e64 v123, v123, v158, s[6:7]
	v_cndmask_b32_e64 v122, v122, v157, s[6:7]
	v_cndmask_b32_e64 v121, v121, v149, s[6:7]
	v_cndmask_b32_e64 v113, v120, v113, s[6:7]
	v_cndmask_b32_e64 v157, v161, v118, s[6:7]
	v_cndmask_b32_e64 v161, v160, v117, s[6:7]
	v_cndmask_b32_e64 v159, v159, v116, s[6:7]
	v_cndmask_b32_e64 v149, v162, v119, s[6:7]
	v_lshlrev_b32_e32 v116, 16, v113
	v_and_b32_e32 v117, 0xffff0000, v113
	v_lshlrev_b32_e32 v118, 16, v121
	v_and_b32_e32 v119, 0xffff0000, v121
	v_lshlrev_b32_e32 v120, 16, v122
	v_and_b32_e32 v121, 0xffff0000, v122
	v_lshlrev_b32_e32 v122, 16, v123
	v_and_b32_e32 v123, 0xffff0000, v123
	v_lshlrev_b32_e32 v158, 16, v159
	v_and_b32_e32 v159, 0xffff0000, v159
	v_lshlrev_b32_e32 v160, 16, v161
	v_and_b32_e32 v161, 0xffff0000, v161
	v_lshlrev_b32_e32 v162, 16, v157
	v_and_b32_e32 v163, 0xffff0000, v157
	v_lshlrev_b32_e32 v164, 16, v149
	v_and_b32_e32 v165, 0xffff0000, v149
	v_pk_add_f32 v[116:117], v[100:101], v[116:117]
	v_pk_add_f32 v[122:123], v[98:99], v[122:123]
	v_pk_add_f32 v[98:99], v[110:111], v[160:161]
	v_pk_add_f32 v[100:101], v[108:109], v[158:159]
	v_pk_add_f32 v[118:119], v[102:103], v[118:119]
	v_pk_add_f32 v[102:103], v[106:107], v[164:165]
	v_pk_add_f32 v[104:105], v[104:105], v[162:163]
	v_mul_f32_e32 v106, v101, v101
	v_mul_f32_e32 v107, v99, v99
	v_mul_f32_e32 v108, v105, v105
	v_fmac_f32_e32 v106, v100, v100
	v_fmac_f32_e32 v107, v98, v98
	v_pk_add_f32 v[96:97], v[96:97], v[120:121]
	v_mul_f32_e32 v109, v103, v103
	v_cvt_pk_bf16_f32 v101, v100, v101
	v_fmac_f32_e32 v108, v104, v104
	v_add_f32_e32 v100, v106, v107
	v_mul_f32_e32 v106, v117, v117
	v_mul_f32_e32 v107, v119, v119
	v_cvt_pk_bf16_f32 v99, v98, v99
	v_cvt_pk_bf16_f32 v105, v104, v105
	v_cvt_pk_bf16_f32 v103, v102, v103
	v_cvt_pk_bf16_f32 v110, v116, v117
	v_cvt_pk_bf16_f32 v111, v118, v119
	v_cvt_pk_bf16_f32 v113, v96, v97
	v_fmac_f32_e32 v109, v102, v102
	v_add_f32_e32 v100, v108, v100
	v_mov_b32_dpp v172, v113 row_ror:8 row_mask:0xf bank_mask:0xf
	v_fmac_f32_e32 v106, v116, v116
	v_fmac_f32_e32 v107, v118, v118
	v_mul_f32_e32 v97, v97, v97
	v_mov_b32_dpp v168, v105 row_ror:8 row_mask:0xf bank_mask:0xf
	v_add_f32_e32 v104, v109, v100
	v_cndmask_b32_e64 v100, v172, v105, s[6:7]
	v_mul_f32_e32 v105, v123, v123
	v_add_f32_e32 v106, v106, v107
	v_fmac_f32_e32 v97, v96, v96
	v_fmac_f32_e32 v105, v122, v122
	v_add_f32_e32 v96, v97, v106
	v_add_f32_e32 v96, v105, v96
	v_add_f32_e32 v108, v96, v104
	v_mov_b32_e32 v109, v108
	s_nop 1
	v_permlane16_swap_b32_e32 v109, v108
	v_lshl_add_u64 v[96:97], s[16:17], 0, v[124:125]
	v_lshl_add_u64 v[106:107], v[96:97], 0, v[146:147]
	v_cvt_pk_bf16_f32 v120, v122, v123
	v_mov_b32_dpp v170, v110 row_ror:8 row_mask:0xf bank_mask:0xf
	s_waitcnt lgkmcnt(0)
	v_add_f32_e32 v96, v108, v109
	v_mov_b32_e32 v97, v96
	s_nop 1
	v_permlane32_swap_b32_e32 v97, v96
	v_mov_b32_dpp v171, v111 row_ror:8 row_mask:0xf bank_mask:0xf
	v_mov_b32_dpp v173, v120 row_ror:8 row_mask:0xf bank_mask:0xf
	v_mov_b32_dpp v166, v101 row_ror:8 row_mask:0xf bank_mask:0xf
	v_mov_b32_dpp v167, v99 row_ror:8 row_mask:0xf bank_mask:0xf
	v_cndmask_b32_e64 v98, v170, v101, s[6:7]
	v_cndmask_b32_e64 v99, v171, v99, s[6:7]
	v_cndmask_b32_e64 v101, v173, v103, s[6:7]
	v_mov_b32_dpp v169, v103 row_ror:8 row_mask:0xf bank_mask:0xf
	global_store_dwordx4 v[106:107], v[98:101], off
	v_cndmask_b32_e64 v102, v110, v166, s[6:7]
	v_cndmask_b32_e64 v103, v111, v167, s[6:7]
	v_lshl_add_u64 v[98:99], s[16:17], 0, v[126:127]
	v_cndmask_b32_e64 v104, v113, v168, s[6:7]
	v_cndmask_b32_e64 v105, v120, v169, s[6:7]
	v_lshl_add_u64 v[98:99], v[98:99], 0, v[146:147]
	global_store_dwordx4 v[98:99], v[102:105], off
	s_and_saveexec_b64 s[42:43], s[8:9]
	s_cbranch_execz .LBB0_1250
	v_ashrrev_i32_e32 v113, 31, v112
	s_waitcnt lgkmcnt(0)
	v_add_f32_e32 v98, v96, v97
	v_lshl_add_u64 v[96:97], v[112:113], 2, s[18:19]
	global_atomic_add_f32 v[96:97], v98, off
; __device__ __forceinline__ void store_pair_lines(bf16_t* O, int ldc, int row, int fr, int col0, u32x4 wA, u32x4 wB) {
;     const u32x4 sA = {dpp_ror8(wA.x), dpp_ror8(wA.y), dpp_ror8(wA.z), dpp_ror8(wA.w)}, sB = {dpp_ror8(wB.x), dpp_ror8(wB.y), dpp_ror8(wB.z), dpp_ror8(wB.w)};
;     const bool lo = fr < 8;
;     const u32x4 o1 = lo ? wA : sB, o2 = lo ? sA : wB;
;     const int r1 = row - fr + (fr & 7), cb = col0 + (lo ? 0 : 8);
;     *(u32x4*)(O + (size_t)r1 * ldc + cb) = o1;
;     *(u32x4*)(O + (size_t)(r1 + 8) * ldc + cb) = o2;
; }
;     const bool lo = fr < 8;
;     const int r1 = row - fr + (fr & 7), cb = col0 + (lo ? 0 : boff);
;     const u32x4 l1 = *(const u32x4*)(P + (size_t)r1 * ld + cb), l2 = *(const u32x4*)(P + (size_t)(r1 + 8) * ld + cb);
;     __device__ __forceinline__ void operator()(const f32x4 (&acc)[2][2][4][2], const Unit& u, int wr, int wc, int fr, int fq) const {
;     ...
;             for (int m = 0; m < 4; ++m) { const int row = row0 + ai * HALF + m * 16; const size_t off = (size_t)row * D + col0; float sq = 0.f; u32x4 w[2];
;                 const float sc = rsin ? __builtin_amdgcn_rcpf(rsin[row] * (1.f / D) + EPS) : 1.0f;
;                 u32x4 rr[2]; if (R) load_pair_lines(R, D, row, fr, col0, rr[0], rr[1]);
; #pragma unroll
;                 for (int bj = 0; bj < 2; ++bj) { f32x4 r0, r1;
;                     if (R) { const u32x4 rw = rr[bj]; r0 = (f32x4){bflo(rw.x), bfhi(rw.x), bflo(rw.y), bfhi(rw.y)}; r1 = (f32x4){bflo(rw.z), bfhi(rw.z), bflo(rw.w), bfhi(rw.w)}; }
;                     else { const float* rp = (row < 8192 ? src_p + off : src_s + (off - (size_t)8192 * D)) + 8 * bj; r0 = *(const f32x4*)rp; r1 = *(const f32x4*)(rp + 4); }
;                     const f32x4 o0 = r0 + acc[ai][bj][m][0] * sc, o1 = r1 + acc[ai][bj][m][1] * sc;
;                     sq += (o0[0] * o0[0] + o0[1] * o0[1]) + (o0[2] * o0[2] + o0[3] * o0[3]) + (o1[0] * o1[0] + o1[1] * o1[1]) + (o1[2] * o1[2] + o1[3] * o1[3]);
;                     w[bj].x = cvt_pk_bf16(o0[0], o0[1]); w[bj].y = cvt_pk_bf16(o0[2], o0[3]); w[bj].z = cvt_pk_bf16(o1[0], o1[1]); w[bj].w = cvt_pk_bf16(o1[2], o1[3]); }
;                 store_pair_lines(O, D, row, fr, col0, w[0], w[1]);
;                 if (ssout) { sq += __shfl_xor(sq, 16); sq += __shfl_xor(sq, 32); if (fq == 0) unsafeAtomicAdd(ssout + row, sq); } }
.LBB0_1250:
	s_or_b64 exec, exec, s[42:43]
	v_or_b32_e32 v96, 32, v148
	s_waitcnt lgkmcnt(0)
	v_sub_u32_e32 v97, v96, v150
	v_add_u32_e32 v98, v97, v152
	v_ashrrev_i32_e32 v99, 31, v98
	v_lshlrev_b64 v[106:107], 12, v[98:99]
	v_lshl_add_u64 v[108:109], v[106:107], 0, s[28:29]
	v_lshl_add_u64 v[98:99], s[10:11], 0, v[106:107]
	v_lshl_add_u64 v[102:103], s[10:11], 0, v[108:109]
	v_lshl_add_u64 v[98:99], v[98:99], 0, v[146:147]
	v_lshl_add_u64 v[102:103], v[102:103], 0, v[146:147]
	s_waitcnt vmcnt(14)
	s_nop 0
	v_mov_b64_e32 v[98:99], v[208:209]
	v_mov_b64_e32 v[100:101], v[210:211]
	v_mov_b64_e32 v[102:103], v[212:213]
	v_mov_b64_e32 v[104:105], v[214:215]
	s_nop 1
	s_waitcnt vmcnt(18)
	v_mov_b32_dpp v97, v98 row_ror:8 row_mask:0xf bank_mask:0xf
	v_mov_b32_dpp v110, v99 row_ror:8 row_mask:0xf bank_mask:0xf
	v_mov_b32_dpp v111, v100 row_ror:8 row_mask:0xf bank_mask:0xf
	v_mov_b32_dpp v112, v101 row_ror:8 row_mask:0xf bank_mask:0xf
	s_waitcnt vmcnt(18)
	v_mov_b32_dpp v113, v102 row_ror:8 row_mask:0xf bank_mask:0xf
	v_mov_b32_dpp v116, v103 row_ror:8 row_mask:0xf bank_mask:0xf
	v_mov_b32_dpp v117, v104 row_ror:8 row_mask:0xf bank_mask:0xf
	v_mov_b32_dpp v118, v105 row_ror:8 row_mask:0xf bank_mask:0xf
	v_cndmask_b32_e64 v105, v105, v112, s[6:7]
	v_cndmask_b32_e64 v104, v104, v111, s[6:7]
	v_cndmask_b32_e64 v103, v103, v110, s[6:7]
	v_cndmask_b32_e64 v97, v102, v97, s[6:7]
	v_cndmask_b32_e64 v116, v116, v99, s[6:7]
	v_cndmask_b32_e64 v111, v113, v98, s[6:7]
	v_cndmask_b32_e64 v119, v118, v101, s[6:7]
	v_cndmask_b32_e64 v117, v117, v100, s[6:7]
	v_lshlrev_b32_e32 v98, 16, v97
	v_and_b32_e32 v99, 0xffff0000, v97
	v_lshlrev_b32_e32 v100, 16, v103
	v_and_b32_e32 v101, 0xffff0000, v103
	v_lshlrev_b32_e32 v102, 16, v104
	v_and_b32_e32 v103, 0xffff0000, v104
	v_lshlrev_b32_e32 v104, 16, v105
	v_and_b32_e32 v105, 0xffff0000, v105
	v_lshlrev_b32_e32 v110, 16, v111
	v_and_b32_e32 v111, 0xffff0000, v111
	v_lshlrev_b32_e32 v112, 16, v116
	v_and_b32_e32 v113, 0xffff0000, v116
	v_lshlrev_b32_e32 v116, 16, v117
	v_and_b32_e32 v117, 0xffff0000, v117
	v_lshlrev_b32_e32 v118, 16, v119
	v_and_b32_e32 v119, 0xffff0000, v119
	v_pk_add_f32 v[98:99], v[84:85], v[98:99]
	v_pk_add_f32 v[104:105], v[82:83], v[104:105]
	v_pk_add_f32 v[82:83], v[94:95], v[112:113]
	v_pk_add_f32 v[84:85], v[92:93], v[110:111]
	v_pk_add_f32 v[100:101], v[86:87], v[100:101]
	v_pk_add_f32 v[86:87], v[90:91], v[118:119]
	v_pk_add_f32 v[88:89], v[88:89], v[116:117]
	v_mul_f32_e32 v90, v85, v85
	v_mul_f32_e32 v91, v83, v83
	v_mul_f32_e32 v92, v89, v89
	v_fmac_f32_e32 v90, v84, v84
	v_fmac_f32_e32 v91, v82, v82
	v_pk_add_f32 v[80:81], v[80:81], v[102:103]
	v_mul_f32_e32 v93, v87, v87
	v_cvt_pk_bf16_f32 v85, v84, v85
	v_fmac_f32_e32 v92, v88, v88
	v_add_f32_e32 v84, v90, v91
	v_mul_f32_e32 v90, v99, v99
	v_mul_f32_e32 v91, v101, v101
	v_cvt_pk_bf16_f32 v83, v82, v83
	v_cvt_pk_bf16_f32 v89, v88, v89
	v_cvt_pk_bf16_f32 v87, v86, v87
	v_cvt_pk_bf16_f32 v94, v98, v99
	v_cvt_pk_bf16_f32 v95, v100, v101
	v_cvt_pk_bf16_f32 v97, v80, v81
	v_fmac_f32_e32 v93, v86, v86
	v_add_f32_e32 v84, v92, v84
	v_mov_b32_dpp v126, v97 row_ror:8 row_mask:0xf bank_mask:0xf
	v_fmac_f32_e32 v90, v98, v98
	v_fmac_f32_e32 v91, v100, v100
	v_mul_f32_e32 v81, v81, v81
	v_mov_b32_dpp v122, v89 row_ror:8 row_mask:0xf bank_mask:0xf
	v_add_f32_e32 v88, v93, v84
	v_cndmask_b32_e64 v84, v126, v89, s[6:7]
	v_mul_f32_e32 v89, v105, v105
	v_add_f32_e32 v90, v90, v91
	v_fmac_f32_e32 v81, v80, v80
	v_fmac_f32_e32 v89, v104, v104
	v_add_f32_e32 v80, v81, v90
	v_add_f32_e32 v80, v89, v80
	v_add_f32_e32 v92, v80, v88
	v_mov_b32_e32 v93, v92
	s_nop 1
	v_permlane16_swap_b32_e32 v93, v92
	v_lshl_add_u64 v[80:81], s[16:17], 0, v[106:107]
	v_lshl_add_u64 v[90:91], v[80:81], 0, v[146:147]
	v_cvt_pk_bf16_f32 v102, v104, v105
	v_mov_b32_dpp v124, v94 row_ror:8 row_mask:0xf bank_mask:0xf
	s_waitcnt lgkmcnt(0)
	v_add_f32_e32 v80, v92, v93
	v_mov_b32_e32 v81, v80
	s_nop 1
	v_permlane32_swap_b32_e32 v81, v80
	v_mov_b32_dpp v125, v95 row_ror:8 row_mask:0xf bank_mask:0xf
	v_mov_b32_dpp v127, v102 row_ror:8 row_mask:0xf bank_mask:0xf
	v_mov_b32_dpp v120, v85 row_ror:8 row_mask:0xf bank_mask:0xf
	v_mov_b32_dpp v121, v83 row_ror:8 row_mask:0xf bank_mask:0xf
	v_cndmask_b32_e64 v82, v124, v85, s[6:7]
	v_cndmask_b32_e64 v83, v125, v83, s[6:7]
	v_cndmask_b32_e64 v85, v127, v87, s[6:7]
	v_mov_b32_dpp v123, v87 row_ror:8 row_mask:0xf bank_mask:0xf
	global_store_dwordx4 v[90:91], v[82:85], off
	v_cndmask_b32_e64 v86, v94, v120, s[6:7]
	v_cndmask_b32_e64 v87, v95, v121, s[6:7]
	v_lshl_add_u64 v[82:83], s[16:17], 0, v[108:109]
	v_cndmask_b32_e64 v88, v97, v122, s[6:7]
	v_cndmask_b32_e64 v89, v102, v123, s[6:7]
	v_lshl_add_u64 v[82:83], v[82:83], 0, v[146:147]
	global_store_dwordx4 v[82:83], v[86:89], off
	s_and_saveexec_b64 s[42:43], s[8:9]
	s_cbranch_execz .LBB0_1252
	v_ashrrev_i32_e32 v97, 31, v96
	s_waitcnt lgkmcnt(0)
	v_add_f32_e32 v82, v80, v81
	v_lshl_add_u64 v[80:81], v[96:97], 2, s[18:19]
	global_atomic_add_f32 v[80:81], v82, off
; __device__ __forceinline__ void store_pair_lines(bf16_t* O, int ldc, int row, int fr, int col0, u32x4 wA, u32x4 wB) {
;     const u32x4 sA = {dpp_ror8(wA.x), dpp_ror8(wA.y), dpp_ror8(wA.z), dpp_ror8(wA.w)}, sB = {dpp_ror8(wB.x), dpp_ror8(wB.y), dpp_ror8(wB.z), dpp_ror8(wB.w)};
;     const bool lo = fr < 8;
;     const u32x4 o1 = lo ? wA : sB, o2 = lo ? sA : wB;
;     const int r1 = row - fr + (fr & 7), cb = col0 + (lo ? 0 : 8);
;     *(u32x4*)(O + (size_t)r1 * ldc + cb) = o1;
;     *(u32x4*)(O + (size_t)(r1 + 8) * ldc + cb) = o2;
; }
;     const bool lo = fr < 8;
;     const int r1 = row - fr + (fr & 7), cb = col0 + (lo ? 0 : boff);
;     const u32x4 l1 = *(const u32x4*)(P + (size_t)r1 * ld + cb), l2 = *(const u32x4*)(P + (size_t)(r1 + 8) * ld + cb);
;     __device__ __forceinline__ void operator()(const f32x4 (&acc)[2][2][4][2], const Unit& u, int wr, int wc, int fr, int fq) const {
;     ...
;             for (int m = 0; m < 4; ++m) { const int row = row0 + ai * HALF + m * 16; const size_t off = (size_t)row * D + col0; float sq = 0.f; u32x4 w[2];
;                 const float sc = rsin ? __builtin_amdgcn_rcpf(rsin[row] * (1.f / D) + EPS) : 1.0f;
;                 u32x4 rr[2]; if (R) load_pair_lines(R, D, row, fr, col0, rr[0], rr[1]);
; #pragma unroll
;                 for (int bj = 0; bj < 2; ++bj) { f32x4 r0, r1;
;                     if (R) { const u32x4 rw = rr[bj]; r0 = (f32x4){bflo(rw.x), bfhi(rw.x), bflo(rw.y), bfhi(rw.y)}; r1 = (f32x4){bflo(rw.z), bfhi(rw.z), bflo(rw.w), bfhi(rw.w)}; }
;                     else { const float* rp = (row < 8192 ? src_p + off : src_s + (off - (size_t)8192 * D)) + 8 * bj; r0 = *(const f32x4*)rp; r1 = *(const f32x4*)(rp + 4); }
;                     const f32x4 o0 = r0 + acc[ai][bj][m][0] * sc, o1 = r1 + acc[ai][bj][m][1] * sc;
;                     sq += (o0[0] * o0[0] + o0[1] * o0[1]) + (o0[2] * o0[2] + o0[3] * o0[3]) + (o1[0] * o1[0] + o1[1] * o1[1]) + (o1[2] * o1[2] + o1[3] * o1[3]);
;                     w[bj].x = cvt_pk_bf16(o0[0], o0[1]); w[bj].y = cvt_pk_bf16(o0[2], o0[3]); w[bj].z = cvt_pk_bf16(o1[0], o1[1]); w[bj].w = cvt_pk_bf16(o1[2], o1[3]); }
;                 store_pair_lines(O, D, row, fr, col0, w[0], w[1]);
;                 if (ssout) { sq += __shfl_xor(sq, 16); sq += __shfl_xor(sq, 32); if (fq == 0) unsafeAtomicAdd(ssout + row, sq); } }
.LBB0_1252:
	s_or_b64 exec, exec, s[42:43]
	v_or_b32_e32 v80, 48, v148
	s_waitcnt lgkmcnt(0)
	v_sub_u32_e32 v81, v80, v150
	v_add_u32_e32 v82, v81, v152
	v_ashrrev_i32_e32 v83, 31, v82
	v_lshlrev_b64 v[90:91], 12, v[82:83]
	v_lshl_add_u64 v[92:93], v[90:91], 0, s[28:29]
	v_lshl_add_u64 v[82:83], s[10:11], 0, v[90:91]
	v_lshl_add_u64 v[86:87], s[10:11], 0, v[92:93]
	v_lshl_add_u64 v[82:83], v[82:83], 0, v[146:147]
	v_lshl_add_u64 v[86:87], v[86:87], 0, v[146:147]
	s_waitcnt vmcnt(14)
	s_nop 0
	v_mov_b64_e32 v[82:83], v[216:217]
	v_mov_b64_e32 v[84:85], v[218:219]
	v_mov_b64_e32 v[86:87], v[220:221]
	v_mov_b64_e32 v[88:89], v[222:223]
	s_nop 1
	s_waitcnt vmcnt(20)
	v_mov_b32_dpp v81, v82 row_ror:8 row_mask:0xf bank_mask:0xf
	v_mov_b32_dpp v94, v83 row_ror:8 row_mask:0xf bank_mask:0xf
	v_mov_b32_dpp v95, v84 row_ror:8 row_mask:0xf bank_mask:0xf
	v_mov_b32_dpp v96, v85 row_ror:8 row_mask:0xf bank_mask:0xf
	s_waitcnt vmcnt(20)
	v_mov_b32_dpp v97, v86 row_ror:8 row_mask:0xf bank_mask:0xf
	v_mov_b32_dpp v98, v87 row_ror:8 row_mask:0xf bank_mask:0xf
	v_mov_b32_dpp v99, v88 row_ror:8 row_mask:0xf bank_mask:0xf
	v_mov_b32_dpp v100, v89 row_ror:8 row_mask:0xf bank_mask:0xf
	v_cndmask_b32_e64 v89, v89, v96, s[6:7]
	v_cndmask_b32_e64 v88, v88, v95, s[6:7]
	v_cndmask_b32_e64 v87, v87, v94, s[6:7]
	v_cndmask_b32_e64 v81, v86, v81, s[6:7]
	v_cndmask_b32_e64 v98, v98, v83, s[6:7]
	v_cndmask_b32_e64 v95, v97, v82, s[6:7]
	v_cndmask_b32_e64 v101, v100, v85, s[6:7]
	v_cndmask_b32_e64 v99, v99, v84, s[6:7]
	v_lshlrev_b32_e32 v82, 16, v81
	v_and_b32_e32 v83, 0xffff0000, v81
	v_lshlrev_b32_e32 v84, 16, v87
	v_and_b32_e32 v85, 0xffff0000, v87
	v_lshlrev_b32_e32 v86, 16, v88
	v_and_b32_e32 v87, 0xffff0000, v88
	v_lshlrev_b32_e32 v88, 16, v89
	v_and_b32_e32 v89, 0xffff0000, v89
	v_lshlrev_b32_e32 v94, 16, v95
	v_and_b32_e32 v95, 0xffff0000, v95
	v_lshlrev_b32_e32 v96, 16, v98
	v_and_b32_e32 v97, 0xffff0000, v98
	v_lshlrev_b32_e32 v98, 16, v99
	v_and_b32_e32 v99, 0xffff0000, v99
	v_lshlrev_b32_e32 v100, 16, v101
	v_and_b32_e32 v101, 0xffff0000, v101
	v_pk_add_f32 v[82:83], v[68:69], v[82:83]
	v_pk_add_f32 v[88:89], v[66:67], v[88:89]
	v_pk_add_f32 v[66:67], v[78:79], v[96:97]
	v_pk_add_f32 v[68:69], v[76:77], v[94:95]
	v_pk_add_f32 v[84:85], v[70:71], v[84:85]
	v_pk_add_f32 v[70:71], v[74:75], v[100:101]
	v_pk_add_f32 v[72:73], v[72:73], v[98:99]
	v_mul_f32_e32 v74, v69, v69
	v_mul_f32_e32 v75, v67, v67
	v_mul_f32_e32 v76, v73, v73
	v_fmac_f32_e32 v74, v68, v68
	v_fmac_f32_e32 v75, v66, v66
	v_pk_add_f32 v[64:65], v[64:65], v[86:87]
	v_mul_f32_e32 v77, v71, v71
	v_cvt_pk_bf16_f32 v69, v68, v69
	v_fmac_f32_e32 v76, v72, v72
	v_add_f32_e32 v68, v74, v75
	v_mul_f32_e32 v74, v83, v83
	v_mul_f32_e32 v75, v85, v85
	v_cvt_pk_bf16_f32 v67, v66, v67
	v_cvt_pk_bf16_f32 v73, v72, v73
	v_cvt_pk_bf16_f32 v71, v70, v71
	v_cvt_pk_bf16_f32 v78, v82, v83
	v_cvt_pk_bf16_f32 v79, v84, v85
	v_cvt_pk_bf16_f32 v81, v64, v65
	v_fmac_f32_e32 v77, v70, v70
	v_add_f32_e32 v68, v76, v68
	v_mov_b32_dpp v108, v81 row_ror:8 row_mask:0xf bank_mask:0xf
	v_fmac_f32_e32 v74, v82, v82
	v_fmac_f32_e32 v75, v84, v84
	v_mul_f32_e32 v65, v65, v65
	v_mov_b32_dpp v104, v73 row_ror:8 row_mask:0xf bank_mask:0xf
	v_add_f32_e32 v72, v77, v68
	v_cndmask_b32_e64 v68, v108, v73, s[6:7]
	v_mul_f32_e32 v73, v89, v89
	v_add_f32_e32 v74, v74, v75
	v_fmac_f32_e32 v65, v64, v64
	v_fmac_f32_e32 v73, v88, v88
	v_add_f32_e32 v64, v65, v74
	v_add_f32_e32 v64, v73, v64
	v_add_f32_e32 v76, v64, v72
	v_mov_b32_e32 v77, v76
	s_nop 1
	v_permlane16_swap_b32_e32 v77, v76
	v_lshl_add_u64 v[64:65], s[16:17], 0, v[90:91]
	v_lshl_add_u64 v[74:75], v[64:65], 0, v[146:147]
	v_cvt_pk_bf16_f32 v86, v88, v89
	v_mov_b32_dpp v106, v78 row_ror:8 row_mask:0xf bank_mask:0xf
	s_waitcnt lgkmcnt(0)
	v_add_f32_e32 v64, v76, v77
	v_mov_b32_e32 v65, v64
	s_nop 1
	v_permlane32_swap_b32_e32 v65, v64
	v_mov_b32_dpp v107, v79 row_ror:8 row_mask:0xf bank_mask:0xf
	v_mov_b32_dpp v109, v86 row_ror:8 row_mask:0xf bank_mask:0xf
	v_mov_b32_dpp v102, v69 row_ror:8 row_mask:0xf bank_mask:0xf
	v_mov_b32_dpp v103, v67 row_ror:8 row_mask:0xf bank_mask:0xf
	v_cndmask_b32_e64 v66, v106, v69, s[6:7]
	v_cndmask_b32_e64 v67, v107, v67, s[6:7]
	v_cndmask_b32_e64 v69, v109, v71, s[6:7]
	v_mov_b32_dpp v105, v71 row_ror:8 row_mask:0xf bank_mask:0xf
	global_store_dwordx4 v[74:75], v[66:69], off
	v_cndmask_b32_e64 v70, v78, v102, s[6:7]
	v_cndmask_b32_e64 v71, v79, v103, s[6:7]
	v_lshl_add_u64 v[66:67], s[16:17], 0, v[92:93]
	v_cndmask_b32_e64 v72, v81, v104, s[6:7]
	v_cndmask_b32_e64 v73, v86, v105, s[6:7]
	v_lshl_add_u64 v[66:67], v[66:67], 0, v[146:147]
	global_store_dwordx4 v[66:67], v[70:73], off
	s_and_saveexec_b64 s[42:43], s[8:9]
	s_cbranch_execz .LBB0_1254
	v_ashrrev_i32_e32 v81, 31, v80
	s_waitcnt lgkmcnt(0)
	v_add_f32_e32 v66, v64, v65
	v_lshl_add_u64 v[64:65], v[80:81], 2, s[18:19]
	global_atomic_add_f32 v[64:65], v66, off
; __device__ __forceinline__ void store_pair_lines(bf16_t* O, int ldc, int row, int fr, int col0, u32x4 wA, u32x4 wB) {
;     const u32x4 sA = {dpp_ror8(wA.x), dpp_ror8(wA.y), dpp_ror8(wA.z), dpp_ror8(wA.w)}, sB = {dpp_ror8(wB.x), dpp_ror8(wB.y), dpp_ror8(wB.z), dpp_ror8(wB.w)};
;     const bool lo = fr < 8;
;     const u32x4 o1 = lo ? wA : sB, o2 = lo ? sA : wB;
;     const int r1 = row - fr + (fr & 7), cb = col0 + (lo ? 0 : 8);
;     *(u32x4*)(O + (size_t)r1 * ldc + cb) = o1;
;     *(u32x4*)(O + (size_t)(r1 + 8) * ldc + cb) = o2;
; }
;     const bool lo = fr < 8;
;     const int r1 = row - fr + (fr & 7), cb = col0 + (lo ? 0 : boff);
;     const u32x4 l1 = *(const u32x4*)(P + (size_t)r1 * ld + cb), l2 = *(const u32x4*)(P + (size_t)(r1 + 8) * ld + cb);
;     __device__ __forceinline__ void operator()(const f32x4 (&acc)[2][2][4][2], const Unit& u, int wr, int wc, int fr, int fq) const {
;     ...
;             for (int m = 0; m < 4; ++m) { const int row = row0 + ai * HALF + m * 16; const size_t off = (size_t)row * D + col0; float sq = 0.f; u32x4 w[2];
;                 const float sc = rsin ? __builtin_amdgcn_rcpf(rsin[row] * (1.f / D) + EPS) : 1.0f;
;                 u32x4 rr[2]; if (R) load_pair_lines(R, D, row, fr, col0, rr[0], rr[1]);
; #pragma unroll
;                 for (int bj = 0; bj < 2; ++bj) { f32x4 r0, r1;
;                     if (R) { const u32x4 rw = rr[bj]; r0 = (f32x4){bflo(rw.x), bfhi(rw.x), bflo(rw.y), bfhi(rw.y)}; r1 = (f32x4){bflo(rw.z), bfhi(rw.z), bflo(rw.w), bfhi(rw.w)}; }
;                     else { const float* rp = (row < 8192 ? src_p + off : src_s + (off - (size_t)8192 * D)) + 8 * bj; r0 = *(const f32x4*)rp; r1 = *(const f32x4*)(rp + 4); }
;                     const f32x4 o0 = r0 + acc[ai][bj][m][0] * sc, o1 = r1 + acc[ai][bj][m][1] * sc;
;                     sq += (o0[0] * o0[0] + o0[1] * o0[1]) + (o0[2] * o0[2] + o0[3] * o0[3]) + (o1[0] * o1[0] + o1[1] * o1[1]) + (o1[2] * o1[2] + o1[3] * o1[3]);
;                     w[bj].x = cvt_pk_bf16(o0[0], o0[1]); w[bj].y = cvt_pk_bf16(o0[2], o0[3]); w[bj].z = cvt_pk_bf16(o1[0], o1[1]); w[bj].w = cvt_pk_bf16(o1[2], o1[3]); }
;                 store_pair_lines(O, D, row, fr, col0, w[0], w[1]);
;                 if (ssout) { sq += __shfl_xor(sq, 16); sq += __shfl_xor(sq, 32); if (fq == 0) unsafeAtomicAdd(ssout + row, sq); } }
.LBB0_1254:
	s_or_b64 exec, exec, s[42:43]
	v_add_u32_e32 v64, 0x80, v148
	s_waitcnt lgkmcnt(0)
	v_sub_u32_e32 v65, v64, v150
	v_add_u32_e32 v66, v65, v152
	v_ashrrev_i32_e32 v67, 31, v66
	v_lshlrev_b64 v[74:75], 12, v[66:67]
	v_lshl_add_u64 v[76:77], v[74:75], 0, s[28:29]
	v_lshl_add_u64 v[66:67], s[10:11], 0, v[74:75]
	v_lshl_add_u64 v[70:71], s[10:11], 0, v[76:77]
	v_lshl_add_u64 v[66:67], v[66:67], 0, v[146:147]
	v_lshl_add_u64 v[70:71], v[70:71], 0, v[146:147]
	s_waitcnt vmcnt(14)
	s_nop 0
	v_mov_b64_e32 v[66:67], v[224:225]
	v_mov_b64_e32 v[68:69], v[226:227]
	v_mov_b64_e32 v[70:71], v[228:229]
	v_mov_b64_e32 v[72:73], v[230:231]
	s_nop 1
	s_waitcnt vmcnt(22)
	v_mov_b32_dpp v65, v66 row_ror:8 row_mask:0xf bank_mask:0xf
	v_mov_b32_dpp v78, v67 row_ror:8 row_mask:0xf bank_mask:0xf
	v_mov_b32_dpp v79, v68 row_ror:8 row_mask:0xf bank_mask:0xf
	v_mov_b32_dpp v80, v69 row_ror:8 row_mask:0xf bank_mask:0xf
	s_waitcnt vmcnt(22)
	v_mov_b32_dpp v81, v70 row_ror:8 row_mask:0xf bank_mask:0xf
	v_mov_b32_dpp v82, v71 row_ror:8 row_mask:0xf bank_mask:0xf
	v_mov_b32_dpp v83, v72 row_ror:8 row_mask:0xf bank_mask:0xf
	v_mov_b32_dpp v84, v73 row_ror:8 row_mask:0xf bank_mask:0xf
	v_cndmask_b32_e64 v73, v73, v80, s[6:7]
	v_cndmask_b32_e64 v72, v72, v79, s[6:7]
	v_cndmask_b32_e64 v71, v71, v78, s[6:7]
	v_cndmask_b32_e64 v65, v70, v65, s[6:7]
	v_cndmask_b32_e64 v82, v82, v67, s[6:7]
	v_cndmask_b32_e64 v79, v81, v66, s[6:7]
	v_cndmask_b32_e64 v85, v84, v69, s[6:7]
	v_cndmask_b32_e64 v83, v83, v68, s[6:7]
	v_lshlrev_b32_e32 v66, 16, v65
	v_and_b32_e32 v67, 0xffff0000, v65
	v_lshlrev_b32_e32 v68, 16, v71
	v_and_b32_e32 v69, 0xffff0000, v71
	v_lshlrev_b32_e32 v70, 16, v72
	v_and_b32_e32 v71, 0xffff0000, v72
	v_lshlrev_b32_e32 v72, 16, v73
	v_and_b32_e32 v73, 0xffff0000, v73
	v_lshlrev_b32_e32 v78, 16, v79
	v_and_b32_e32 v79, 0xffff0000, v79
	v_lshlrev_b32_e32 v80, 16, v82
	v_and_b32_e32 v81, 0xffff0000, v82
	v_lshlrev_b32_e32 v82, 16, v83
	v_and_b32_e32 v83, 0xffff0000, v83
	v_lshlrev_b32_e32 v84, 16, v85
	v_and_b32_e32 v85, 0xffff0000, v85
	v_pk_add_f32 v[66:67], v[52:53], v[66:67]
	v_pk_add_f32 v[72:73], v[50:51], v[72:73]
	v_pk_add_f32 v[50:51], v[62:63], v[80:81]
	v_pk_add_f32 v[52:53], v[60:61], v[78:79]
	v_pk_add_f32 v[68:69], v[54:55], v[68:69]
	v_pk_add_f32 v[54:55], v[58:59], v[84:85]
	v_pk_add_f32 v[56:57], v[56:57], v[82:83]
	v_mul_f32_e32 v58, v53, v53
	v_mul_f32_e32 v59, v51, v51
	v_mul_f32_e32 v60, v57, v57
	v_fmac_f32_e32 v58, v52, v52
	v_fmac_f32_e32 v59, v50, v50
	v_pk_add_f32 v[48:49], v[48:49], v[70:71]
	v_mul_f32_e32 v61, v55, v55
	v_cvt_pk_bf16_f32 v53, v52, v53
	v_fmac_f32_e32 v60, v56, v56
	v_add_f32_e32 v52, v58, v59
	v_mul_f32_e32 v58, v67, v67
	v_mul_f32_e32 v59, v69, v69
	v_cvt_pk_bf16_f32 v51, v50, v51
	v_cvt_pk_bf16_f32 v57, v56, v57
	v_cvt_pk_bf16_f32 v55, v54, v55
	v_cvt_pk_bf16_f32 v62, v66, v67
	v_cvt_pk_bf16_f32 v63, v68, v69
	v_cvt_pk_bf16_f32 v65, v48, v49
	v_fmac_f32_e32 v61, v54, v54
	v_add_f32_e32 v52, v60, v52
	v_mov_b32_dpp v92, v65 row_ror:8 row_mask:0xf bank_mask:0xf
	v_fmac_f32_e32 v58, v66, v66
	v_fmac_f32_e32 v59, v68, v68
	v_mul_f32_e32 v49, v49, v49
	v_mov_b32_dpp v88, v57 row_ror:8 row_mask:0xf bank_mask:0xf
	v_add_f32_e32 v56, v61, v52
	v_cndmask_b32_e64 v52, v92, v57, s[6:7]
	v_mul_f32_e32 v57, v73, v73
	v_add_f32_e32 v58, v58, v59
	v_fmac_f32_e32 v49, v48, v48
	v_fmac_f32_e32 v57, v72, v72
	v_add_f32_e32 v48, v49, v58
	v_add_f32_e32 v48, v57, v48
	v_add_f32_e32 v60, v48, v56
	v_mov_b32_e32 v61, v60
	s_nop 1
	v_permlane16_swap_b32_e32 v61, v60
	v_lshl_add_u64 v[48:49], s[16:17], 0, v[74:75]
	v_lshl_add_u64 v[58:59], v[48:49], 0, v[146:147]
	v_cvt_pk_bf16_f32 v70, v72, v73
	v_mov_b32_dpp v90, v62 row_ror:8 row_mask:0xf bank_mask:0xf
	s_waitcnt lgkmcnt(0)
	v_add_f32_e32 v48, v60, v61
	v_mov_b32_e32 v49, v48
	s_nop 1
	v_permlane32_swap_b32_e32 v49, v48
	v_mov_b32_dpp v91, v63 row_ror:8 row_mask:0xf bank_mask:0xf
	v_mov_b32_dpp v93, v70 row_ror:8 row_mask:0xf bank_mask:0xf
	v_mov_b32_dpp v86, v53 row_ror:8 row_mask:0xf bank_mask:0xf
	v_mov_b32_dpp v87, v51 row_ror:8 row_mask:0xf bank_mask:0xf
	v_cndmask_b32_e64 v50, v90, v53, s[6:7]
	v_cndmask_b32_e64 v51, v91, v51, s[6:7]
	v_cndmask_b32_e64 v53, v93, v55, s[6:7]
	v_mov_b32_dpp v89, v55 row_ror:8 row_mask:0xf bank_mask:0xf
	global_store_dwordx4 v[58:59], v[50:53], off
	v_cndmask_b32_e64 v54, v62, v86, s[6:7]
	v_cndmask_b32_e64 v55, v63, v87, s[6:7]
	v_lshl_add_u64 v[50:51], s[16:17], 0, v[76:77]
	v_cndmask_b32_e64 v56, v65, v88, s[6:7]
	v_cndmask_b32_e64 v57, v70, v89, s[6:7]
	v_lshl_add_u64 v[50:51], v[50:51], 0, v[146:147]
	global_store_dwordx4 v[50:51], v[54:57], off
	s_and_saveexec_b64 s[42:43], s[8:9]
	s_cbranch_execz .LBB0_1256
	v_ashrrev_i32_e32 v65, 31, v64
	s_waitcnt lgkmcnt(0)
	v_add_f32_e32 v50, v48, v49
	v_lshl_add_u64 v[48:49], v[64:65], 2, s[18:19]
	global_atomic_add_f32 v[48:49], v50, off
; __device__ __forceinline__ void store_pair_lines(bf16_t* O, int ldc, int row, int fr, int col0, u32x4 wA, u32x4 wB) {
;     const u32x4 sA = {dpp_ror8(wA.x), dpp_ror8(wA.y), dpp_ror8(wA.z), dpp_ror8(wA.w)}, sB = {dpp_ror8(wB.x), dpp_ror8(wB.y), dpp_ror8(wB.z), dpp_ror8(wB.w)};
;     const bool lo = fr < 8;
;     const u32x4 o1 = lo ? wA : sB, o2 = lo ? sA : wB;
;     const int r1 = row - fr + (fr & 7), cb = col0 + (lo ? 0 : 8);
;     *(u32x4*)(O + (size_t)r1 * ldc + cb) = o1;
;     *(u32x4*)(O + (size_t)(r1 + 8) * ldc + cb) = o2;
; }
;     const bool lo = fr < 8;
;     const int r1 = row - fr + (fr & 7), cb = col0 + (lo ? 0 : boff);
;     const u32x4 l1 = *(const u32x4*)(P + (size_t)r1 * ld + cb), l2 = *(const u32x4*)(P + (size_t)(r1 + 8) * ld + cb);
;     __device__ __forceinline__ void operator()(const f32x4 (&acc)[2][2][4][2], const Unit& u, int wr, int wc, int fr, int fq) const {
;     ...
;             for (int m = 0; m < 4; ++m) { const int row = row0 + ai * HALF + m * 16; const size_t off = (size_t)row * D + col0; float sq = 0.f; u32x4 w[2];
;                 const float sc = rsin ? __builtin_amdgcn_rcpf(rsin[row] * (1.f / D) + EPS) : 1.0f;
;                 u32x4 rr[2]; if (R) load_pair_lines(R, D, row, fr, col0, rr[0], rr[1]);
; #pragma unroll
;                 for (int bj = 0; bj < 2; ++bj) { f32x4 r0, r1;
;                     if (R) { const u32x4 rw = rr[bj]; r0 = (f32x4){bflo(rw.x), bfhi(rw.x), bflo(rw.y), bfhi(rw.y)}; r1 = (f32x4){bflo(rw.z), bfhi(rw.z), bflo(rw.w), bfhi(rw.w)}; }
;                     else { const float* rp = (row < 8192 ? src_p + off : src_s + (off - (size_t)8192 * D)) + 8 * bj; r0 = *(const f32x4*)rp; r1 = *(const f32x4*)(rp + 4); }
;                     const f32x4 o0 = r0 + acc[ai][bj][m][0] * sc, o1 = r1 + acc[ai][bj][m][1] * sc;
;                     sq += (o0[0] * o0[0] + o0[1] * o0[1]) + (o0[2] * o0[2] + o0[3] * o0[3]) + (o1[0] * o1[0] + o1[1] * o1[1]) + (o1[2] * o1[2] + o1[3] * o1[3]);
;                     w[bj].x = cvt_pk_bf16(o0[0], o0[1]); w[bj].y = cvt_pk_bf16(o0[2], o0[3]); w[bj].z = cvt_pk_bf16(o1[0], o1[1]); w[bj].w = cvt_pk_bf16(o1[2], o1[3]); }
;                 store_pair_lines(O, D, row, fr, col0, w[0], w[1]);
;                 if (ssout) { sq += __shfl_xor(sq, 16); sq += __shfl_xor(sq, 32); if (fq == 0) unsafeAtomicAdd(ssout + row, sq); } }
.LBB0_1256:
	s_or_b64 exec, exec, s[42:43]
	v_add_u32_e32 v48, 0x90, v148
	s_waitcnt lgkmcnt(0)
	v_sub_u32_e32 v49, v48, v150
	v_add_u32_e32 v50, v49, v152
	v_ashrrev_i32_e32 v51, 31, v50
	v_lshlrev_b64 v[58:59], 12, v[50:51]
	v_lshl_add_u64 v[60:61], v[58:59], 0, s[28:29]
	v_lshl_add_u64 v[50:51], s[10:11], 0, v[58:59]
	v_lshl_add_u64 v[54:55], s[10:11], 0, v[60:61]
	v_lshl_add_u64 v[50:51], v[50:51], 0, v[146:147]
	v_lshl_add_u64 v[54:55], v[54:55], 0, v[146:147]
	s_waitcnt vmcnt(14)
	s_nop 0
	v_mov_b64_e32 v[50:51], v[232:233]
	v_mov_b64_e32 v[52:53], v[234:235]
	v_mov_b64_e32 v[54:55], v[236:237]
	v_mov_b64_e32 v[56:57], v[238:239]
	s_nop 1
	s_waitcnt vmcnt(24)
	v_mov_b32_dpp v49, v50 row_ror:8 row_mask:0xf bank_mask:0xf
	v_mov_b32_dpp v62, v51 row_ror:8 row_mask:0xf bank_mask:0xf
	v_mov_b32_dpp v63, v52 row_ror:8 row_mask:0xf bank_mask:0xf
	v_mov_b32_dpp v64, v53 row_ror:8 row_mask:0xf bank_mask:0xf
	s_waitcnt vmcnt(24)
	v_mov_b32_dpp v65, v54 row_ror:8 row_mask:0xf bank_mask:0xf
	v_mov_b32_dpp v66, v55 row_ror:8 row_mask:0xf bank_mask:0xf
	v_mov_b32_dpp v67, v56 row_ror:8 row_mask:0xf bank_mask:0xf
	v_mov_b32_dpp v68, v57 row_ror:8 row_mask:0xf bank_mask:0xf
	v_cndmask_b32_e64 v57, v57, v64, s[6:7]
	v_cndmask_b32_e64 v56, v56, v63, s[6:7]
	v_cndmask_b32_e64 v55, v55, v62, s[6:7]
	v_cndmask_b32_e64 v49, v54, v49, s[6:7]
	v_cndmask_b32_e64 v66, v66, v51, s[6:7]
	v_cndmask_b32_e64 v63, v65, v50, s[6:7]
	v_cndmask_b32_e64 v69, v68, v53, s[6:7]
	v_cndmask_b32_e64 v67, v67, v52, s[6:7]
	v_lshlrev_b32_e32 v50, 16, v49
	v_and_b32_e32 v51, 0xffff0000, v49
	v_lshlrev_b32_e32 v52, 16, v55
	v_and_b32_e32 v53, 0xffff0000, v55
	v_lshlrev_b32_e32 v54, 16, v56
	v_and_b32_e32 v55, 0xffff0000, v56
	v_lshlrev_b32_e32 v56, 16, v57
	v_and_b32_e32 v57, 0xffff0000, v57
	v_lshlrev_b32_e32 v62, 16, v63
	v_and_b32_e32 v63, 0xffff0000, v63
	v_lshlrev_b32_e32 v64, 16, v66
	v_and_b32_e32 v65, 0xffff0000, v66
	v_lshlrev_b32_e32 v66, 16, v67
	v_and_b32_e32 v67, 0xffff0000, v67
	v_lshlrev_b32_e32 v68, 16, v69
	v_and_b32_e32 v69, 0xffff0000, v69
	v_pk_add_f32 v[50:51], v[36:37], v[50:51]
	v_pk_add_f32 v[56:57], v[34:35], v[56:57]
	v_pk_add_f32 v[34:35], v[46:47], v[64:65]
	v_pk_add_f32 v[36:37], v[44:45], v[62:63]
	v_pk_add_f32 v[52:53], v[38:39], v[52:53]
	v_pk_add_f32 v[38:39], v[42:43], v[68:69]
	v_pk_add_f32 v[40:41], v[40:41], v[66:67]
	v_mul_f32_e32 v42, v37, v37
	v_mul_f32_e32 v43, v35, v35
	v_mul_f32_e32 v44, v41, v41
	v_fmac_f32_e32 v42, v36, v36
	v_fmac_f32_e32 v43, v34, v34
	v_pk_add_f32 v[32:33], v[32:33], v[54:55]
	v_mul_f32_e32 v45, v39, v39
	v_cvt_pk_bf16_f32 v37, v36, v37
	v_fmac_f32_e32 v44, v40, v40
	v_add_f32_e32 v36, v42, v43
	v_mul_f32_e32 v42, v51, v51
	v_mul_f32_e32 v43, v53, v53
	v_cvt_pk_bf16_f32 v35, v34, v35
	v_cvt_pk_bf16_f32 v41, v40, v41
	v_cvt_pk_bf16_f32 v39, v38, v39
	v_cvt_pk_bf16_f32 v46, v50, v51
	v_cvt_pk_bf16_f32 v47, v52, v53
	v_cvt_pk_bf16_f32 v49, v32, v33
	v_fmac_f32_e32 v45, v38, v38
	v_add_f32_e32 v36, v44, v36
	v_mov_b32_dpp v76, v49 row_ror:8 row_mask:0xf bank_mask:0xf
	v_fmac_f32_e32 v42, v50, v50
	v_fmac_f32_e32 v43, v52, v52
	v_mul_f32_e32 v33, v33, v33
	v_mov_b32_dpp v72, v41 row_ror:8 row_mask:0xf bank_mask:0xf
	v_add_f32_e32 v40, v45, v36
	v_cndmask_b32_e64 v36, v76, v41, s[6:7]
	v_mul_f32_e32 v41, v57, v57
	v_add_f32_e32 v42, v42, v43
	v_fmac_f32_e32 v33, v32, v32
	v_fmac_f32_e32 v41, v56, v56
	v_add_f32_e32 v32, v33, v42
	v_add_f32_e32 v32, v41, v32
	v_add_f32_e32 v44, v32, v40
	v_mov_b32_e32 v45, v44
	s_nop 1
	v_permlane16_swap_b32_e32 v45, v44
	v_lshl_add_u64 v[32:33], s[16:17], 0, v[58:59]
	v_lshl_add_u64 v[42:43], v[32:33], 0, v[146:147]
	v_cvt_pk_bf16_f32 v54, v56, v57
	v_mov_b32_dpp v74, v46 row_ror:8 row_mask:0xf bank_mask:0xf
	s_waitcnt lgkmcnt(0)
	v_add_f32_e32 v32, v44, v45
	v_mov_b32_e32 v33, v32
	s_nop 1
	v_permlane32_swap_b32_e32 v33, v32
	v_mov_b32_dpp v75, v47 row_ror:8 row_mask:0xf bank_mask:0xf
	v_mov_b32_dpp v77, v54 row_ror:8 row_mask:0xf bank_mask:0xf
	v_mov_b32_dpp v70, v37 row_ror:8 row_mask:0xf bank_mask:0xf
	v_mov_b32_dpp v71, v35 row_ror:8 row_mask:0xf bank_mask:0xf
	v_cndmask_b32_e64 v34, v74, v37, s[6:7]
	v_cndmask_b32_e64 v35, v75, v35, s[6:7]
	v_cndmask_b32_e64 v37, v77, v39, s[6:7]
	v_mov_b32_dpp v73, v39 row_ror:8 row_mask:0xf bank_mask:0xf
	global_store_dwordx4 v[42:43], v[34:37], off
	v_cndmask_b32_e64 v38, v46, v70, s[6:7]
	v_cndmask_b32_e64 v39, v47, v71, s[6:7]
	v_lshl_add_u64 v[34:35], s[16:17], 0, v[60:61]
	v_cndmask_b32_e64 v40, v49, v72, s[6:7]
	v_cndmask_b32_e64 v41, v54, v73, s[6:7]
	v_lshl_add_u64 v[34:35], v[34:35], 0, v[146:147]
	global_store_dwordx4 v[34:35], v[38:41], off
	s_and_saveexec_b64 s[42:43], s[8:9]
	s_cbranch_execz .LBB0_1258
	v_ashrrev_i32_e32 v49, 31, v48
	s_waitcnt lgkmcnt(0)
	v_add_f32_e32 v34, v32, v33
	v_lshl_add_u64 v[32:33], v[48:49], 2, s[18:19]
	global_atomic_add_f32 v[32:33], v34, off
; __device__ __forceinline__ void store_pair_lines(bf16_t* O, int ldc, int row, int fr, int col0, u32x4 wA, u32x4 wB) {
;     const u32x4 sA = {dpp_ror8(wA.x), dpp_ror8(wA.y), dpp_ror8(wA.z), dpp_ror8(wA.w)}, sB = {dpp_ror8(wB.x), dpp_ror8(wB.y), dpp_ror8(wB.z), dpp_ror8(wB.w)};
;     const bool lo = fr < 8;
;     const u32x4 o1 = lo ? wA : sB, o2 = lo ? sA : wB;
;     const int r1 = row - fr + (fr & 7), cb = col0 + (lo ? 0 : 8);
;     *(u32x4*)(O + (size_t)r1 * ldc + cb) = o1;
;     *(u32x4*)(O + (size_t)(r1 + 8) * ldc + cb) = o2;
; }
;     const bool lo = fr < 8;
;     const int r1 = row - fr + (fr & 7), cb = col0 + (lo ? 0 : boff);
;     const u32x4 l1 = *(const u32x4*)(P + (size_t)r1 * ld + cb), l2 = *(const u32x4*)(P + (size_t)(r1 + 8) * ld + cb);
;     __device__ __forceinline__ void operator()(const f32x4 (&acc)[2][2][4][2], const Unit& u, int wr, int wc, int fr, int fq) const {
;     ...
;             for (int m = 0; m < 4; ++m) { const int row = row0 + ai * HALF + m * 16; const size_t off = (size_t)row * D + col0; float sq = 0.f; u32x4 w[2];
;                 const float sc = rsin ? __builtin_amdgcn_rcpf(rsin[row] * (1.f / D) + EPS) : 1.0f;
;                 u32x4 rr[2]; if (R) load_pair_lines(R, D, row, fr, col0, rr[0], rr[1]);
; #pragma unroll
;                 for (int bj = 0; bj < 2; ++bj) { f32x4 r0, r1;
;                     if (R) { const u32x4 rw = rr[bj]; r0 = (f32x4){bflo(rw.x), bfhi(rw.x), bflo(rw.y), bfhi(rw.y)}; r1 = (f32x4){bflo(rw.z), bfhi(rw.z), bflo(rw.w), bfhi(rw.w)}; }
;                     else { const float* rp = (row < 8192 ? src_p + off : src_s + (off - (size_t)8192 * D)) + 8 * bj; r0 = *(const f32x4*)rp; r1 = *(const f32x4*)(rp + 4); }
;                     const f32x4 o0 = r0 + acc[ai][bj][m][0] * sc, o1 = r1 + acc[ai][bj][m][1] * sc;
;                     sq += (o0[0] * o0[0] + o0[1] * o0[1]) + (o0[2] * o0[2] + o0[3] * o0[3]) + (o1[0] * o1[0] + o1[1] * o1[1]) + (o1[2] * o1[2] + o1[3] * o1[3]);
;                     w[bj].x = cvt_pk_bf16(o0[0], o0[1]); w[bj].y = cvt_pk_bf16(o0[2], o0[3]); w[bj].z = cvt_pk_bf16(o1[0], o1[1]); w[bj].w = cvt_pk_bf16(o1[2], o1[3]); }
;                 store_pair_lines(O, D, row, fr, col0, w[0], w[1]);
;                 if (ssout) { sq += __shfl_xor(sq, 16); sq += __shfl_xor(sq, 32); if (fq == 0) unsafeAtomicAdd(ssout + row, sq); } }
.LBB0_1258:
	s_or_b64 exec, exec, s[42:43]
	v_add_u32_e32 v32, 0xa0, v148
	s_waitcnt lgkmcnt(0)
	v_sub_u32_e32 v33, v32, v150
	v_add_u32_e32 v34, v33, v152
	v_ashrrev_i32_e32 v35, 31, v34
	v_lshlrev_b64 v[42:43], 12, v[34:35]
	v_lshl_add_u64 v[44:45], v[42:43], 0, s[28:29]
	v_lshl_add_u64 v[34:35], s[10:11], 0, v[42:43]
	v_lshl_add_u64 v[38:39], s[10:11], 0, v[44:45]
	v_lshl_add_u64 v[34:35], v[34:35], 0, v[146:147]
	v_lshl_add_u64 v[38:39], v[38:39], 0, v[146:147]
	s_waitcnt vmcnt(14)
	s_nop 0
	v_mov_b64_e32 v[34:35], v[240:241]
	v_mov_b64_e32 v[36:37], v[242:243]
	v_mov_b64_e32 v[38:39], v[244:245]
	v_mov_b64_e32 v[40:41], v[246:247]
	s_nop 1
	s_waitcnt vmcnt(26)
	v_mov_b32_dpp v33, v34 row_ror:8 row_mask:0xf bank_mask:0xf
	v_mov_b32_dpp v46, v35 row_ror:8 row_mask:0xf bank_mask:0xf
	v_mov_b32_dpp v47, v36 row_ror:8 row_mask:0xf bank_mask:0xf
	v_mov_b32_dpp v48, v37 row_ror:8 row_mask:0xf bank_mask:0xf
	s_waitcnt vmcnt(26)
	v_mov_b32_dpp v49, v38 row_ror:8 row_mask:0xf bank_mask:0xf
	v_mov_b32_dpp v50, v39 row_ror:8 row_mask:0xf bank_mask:0xf
	v_mov_b32_dpp v51, v40 row_ror:8 row_mask:0xf bank_mask:0xf
	v_mov_b32_dpp v52, v41 row_ror:8 row_mask:0xf bank_mask:0xf
	v_cndmask_b32_e64 v41, v41, v48, s[6:7]
	v_cndmask_b32_e64 v40, v40, v47, s[6:7]
	v_cndmask_b32_e64 v39, v39, v46, s[6:7]
	v_cndmask_b32_e64 v33, v38, v33, s[6:7]
	v_cndmask_b32_e64 v50, v50, v35, s[6:7]
	v_cndmask_b32_e64 v47, v49, v34, s[6:7]
	v_cndmask_b32_e64 v53, v52, v37, s[6:7]
	v_cndmask_b32_e64 v51, v51, v36, s[6:7]
	v_lshlrev_b32_e32 v34, 16, v33
	v_and_b32_e32 v35, 0xffff0000, v33
	v_lshlrev_b32_e32 v36, 16, v39
	v_and_b32_e32 v37, 0xffff0000, v39
	v_lshlrev_b32_e32 v38, 16, v40
	v_and_b32_e32 v39, 0xffff0000, v40
	v_lshlrev_b32_e32 v40, 16, v41
	v_and_b32_e32 v41, 0xffff0000, v41
	v_lshlrev_b32_e32 v46, 16, v47
	v_and_b32_e32 v47, 0xffff0000, v47
	v_lshlrev_b32_e32 v48, 16, v50
	v_and_b32_e32 v49, 0xffff0000, v50
	v_lshlrev_b32_e32 v50, 16, v51
	v_and_b32_e32 v51, 0xffff0000, v51
	v_lshlrev_b32_e32 v52, 16, v53
	v_and_b32_e32 v53, 0xffff0000, v53
	v_pk_add_f32 v[34:35], v[20:21], v[34:35]
	v_pk_add_f32 v[40:41], v[18:19], v[40:41]
	v_pk_add_f32 v[18:19], v[30:31], v[48:49]
	v_pk_add_f32 v[20:21], v[28:29], v[46:47]
	v_pk_add_f32 v[36:37], v[22:23], v[36:37]
	v_pk_add_f32 v[22:23], v[26:27], v[52:53]
	v_pk_add_f32 v[24:25], v[24:25], v[50:51]
	v_mul_f32_e32 v26, v21, v21
	v_mul_f32_e32 v27, v19, v19
	v_mul_f32_e32 v28, v25, v25
	v_fmac_f32_e32 v26, v20, v20
	v_fmac_f32_e32 v27, v18, v18
	v_pk_add_f32 v[16:17], v[16:17], v[38:39]
	v_mul_f32_e32 v29, v23, v23
	v_cvt_pk_bf16_f32 v21, v20, v21
	v_fmac_f32_e32 v28, v24, v24
	v_add_f32_e32 v20, v26, v27
	v_mul_f32_e32 v26, v35, v35
	v_mul_f32_e32 v27, v37, v37
	v_cvt_pk_bf16_f32 v19, v18, v19
	v_cvt_pk_bf16_f32 v25, v24, v25
	v_cvt_pk_bf16_f32 v23, v22, v23
	v_cvt_pk_bf16_f32 v30, v34, v35
	v_cvt_pk_bf16_f32 v31, v36, v37
	v_cvt_pk_bf16_f32 v33, v16, v17
	v_fmac_f32_e32 v29, v22, v22
	v_add_f32_e32 v20, v28, v20
	v_mov_b32_dpp v60, v33 row_ror:8 row_mask:0xf bank_mask:0xf
	v_fmac_f32_e32 v26, v34, v34
	v_fmac_f32_e32 v27, v36, v36
	v_mul_f32_e32 v17, v17, v17
	v_mov_b32_dpp v56, v25 row_ror:8 row_mask:0xf bank_mask:0xf
	v_add_f32_e32 v24, v29, v20
	v_cndmask_b32_e64 v20, v60, v25, s[6:7]
	v_mul_f32_e32 v25, v41, v41
	v_add_f32_e32 v26, v26, v27
	v_fmac_f32_e32 v17, v16, v16
	v_fmac_f32_e32 v25, v40, v40
	v_add_f32_e32 v16, v17, v26
	v_add_f32_e32 v16, v25, v16
	v_add_f32_e32 v28, v16, v24
	v_mov_b32_e32 v29, v28
	s_nop 1
	v_permlane16_swap_b32_e32 v29, v28
	v_lshl_add_u64 v[16:17], s[16:17], 0, v[42:43]
	v_lshl_add_u64 v[26:27], v[16:17], 0, v[146:147]
	v_cvt_pk_bf16_f32 v38, v40, v41
	v_mov_b32_dpp v58, v30 row_ror:8 row_mask:0xf bank_mask:0xf
	s_waitcnt lgkmcnt(0)
	v_add_f32_e32 v16, v28, v29
	v_mov_b32_e32 v17, v16
	s_nop 1
	v_permlane32_swap_b32_e32 v17, v16
	v_mov_b32_dpp v59, v31 row_ror:8 row_mask:0xf bank_mask:0xf
	v_mov_b32_dpp v61, v38 row_ror:8 row_mask:0xf bank_mask:0xf
	v_mov_b32_dpp v54, v21 row_ror:8 row_mask:0xf bank_mask:0xf
	v_mov_b32_dpp v55, v19 row_ror:8 row_mask:0xf bank_mask:0xf
	v_cndmask_b32_e64 v18, v58, v21, s[6:7]
	v_cndmask_b32_e64 v19, v59, v19, s[6:7]
	v_cndmask_b32_e64 v21, v61, v23, s[6:7]
	v_mov_b32_dpp v57, v23 row_ror:8 row_mask:0xf bank_mask:0xf
	global_store_dwordx4 v[26:27], v[18:21], off
	v_cndmask_b32_e64 v22, v30, v54, s[6:7]
	v_cndmask_b32_e64 v23, v31, v55, s[6:7]
	v_lshl_add_u64 v[18:19], s[16:17], 0, v[44:45]
	v_cndmask_b32_e64 v24, v33, v56, s[6:7]
	v_cndmask_b32_e64 v25, v38, v57, s[6:7]
	v_lshl_add_u64 v[18:19], v[18:19], 0, v[146:147]
	global_store_dwordx4 v[18:19], v[22:25], off
	s_and_saveexec_b64 s[42:43], s[8:9]
	s_cbranch_execz .LBB0_1260
	v_ashrrev_i32_e32 v33, 31, v32
	s_waitcnt lgkmcnt(0)
	v_add_f32_e32 v18, v16, v17
	v_lshl_add_u64 v[16:17], v[32:33], 2, s[18:19]
	global_atomic_add_f32 v[16:17], v18, off
; __device__ __forceinline__ void store_pair_lines(bf16_t* O, int ldc, int row, int fr, int col0, u32x4 wA, u32x4 wB) {
;     const u32x4 sA = {dpp_ror8(wA.x), dpp_ror8(wA.y), dpp_ror8(wA.z), dpp_ror8(wA.w)}, sB = {dpp_ror8(wB.x), dpp_ror8(wB.y), dpp_ror8(wB.z), dpp_ror8(wB.w)};
;     const bool lo = fr < 8;
;     const u32x4 o1 = lo ? wA : sB, o2 = lo ? sA : wB;
;     const int r1 = row - fr + (fr & 7), cb = col0 + (lo ? 0 : 8);
;     *(u32x4*)(O + (size_t)r1 * ldc + cb) = o1;
;     *(u32x4*)(O + (size_t)(r1 + 8) * ldc + cb) = o2;
; }
;     const bool lo = fr < 8;
;     const int r1 = row - fr + (fr & 7), cb = col0 + (lo ? 0 : boff);
;     const u32x4 l1 = *(const u32x4*)(P + (size_t)r1 * ld + cb), l2 = *(const u32x4*)(P + (size_t)(r1 + 8) * ld + cb);
;     __device__ __forceinline__ void operator()(const f32x4 (&acc)[2][2][4][2], const Unit& u, int wr, int wc, int fr, int fq) const {
;     ...
;             for (int m = 0; m < 4; ++m) { const int row = row0 + ai * HALF + m * 16; const size_t off = (size_t)row * D + col0; float sq = 0.f; u32x4 w[2];
;                 const float sc = rsin ? __builtin_amdgcn_rcpf(rsin[row] * (1.f / D) + EPS) : 1.0f;
;                 u32x4 rr[2]; if (R) load_pair_lines(R, D, row, fr, col0, rr[0], rr[1]);
; #pragma unroll
;                 for (int bj = 0; bj < 2; ++bj) { f32x4 r0, r1;
;                     if (R) { const u32x4 rw = rr[bj]; r0 = (f32x4){bflo(rw.x), bfhi(rw.x), bflo(rw.y), bfhi(rw.y)}; r1 = (f32x4){bflo(rw.z), bfhi(rw.z), bflo(rw.w), bfhi(rw.w)}; }
;                     else { const float* rp = (row < 8192 ? src_p + off : src_s + (off - (size_t)8192 * D)) + 8 * bj; r0 = *(const f32x4*)rp; r1 = *(const f32x4*)(rp + 4); }
;                     const f32x4 o0 = r0 + acc[ai][bj][m][0] * sc, o1 = r1 + acc[ai][bj][m][1] * sc;
;                     sq += (o0[0] * o0[0] + o0[1] * o0[1]) + (o0[2] * o0[2] + o0[3] * o0[3]) + (o1[0] * o1[0] + o1[1] * o1[1]) + (o1[2] * o1[2] + o1[3] * o1[3]);
;                     w[bj].x = cvt_pk_bf16(o0[0], o0[1]); w[bj].y = cvt_pk_bf16(o0[2], o0[3]); w[bj].z = cvt_pk_bf16(o1[0], o1[1]); w[bj].w = cvt_pk_bf16(o1[2], o1[3]); }
;                 store_pair_lines(O, D, row, fr, col0, w[0], w[1]);
;                 if (ssout) { sq += __shfl_xor(sq, 16); sq += __shfl_xor(sq, 32); if (fq == 0) unsafeAtomicAdd(ssout + row, sq); } }
.LBB0_1260:
	s_or_b64 exec, exec, s[42:43]
	v_add_u32_e32 v16, 0xb0, v148
	s_waitcnt lgkmcnt(0)
	v_sub_u32_e32 v17, v16, v150
	v_add_u32_e32 v18, v17, v152
	v_ashrrev_i32_e32 v19, 31, v18
	v_lshlrev_b64 v[26:27], 12, v[18:19]
	v_lshl_add_u64 v[28:29], v[26:27], 0, s[28:29]
	v_lshl_add_u64 v[18:19], s[10:11], 0, v[26:27]
	v_lshl_add_u64 v[22:23], s[10:11], 0, v[28:29]
	v_lshl_add_u64 v[18:19], v[18:19], 0, v[146:147]
	v_lshl_add_u64 v[22:23], v[22:23], 0, v[146:147]
	s_waitcnt vmcnt(12)
	s_nop 0
	v_mov_b64_e32 v[18:19], v[196:197]
	v_mov_b64_e32 v[20:21], v[198:199]
	v_mov_b64_e32 v[22:23], v[204:205]
	v_mov_b64_e32 v[24:25], v[206:207]
	s_nop 1
	s_waitcnt vmcnt(28)
	v_mov_b32_dpp v17, v18 row_ror:8 row_mask:0xf bank_mask:0xf
	v_mov_b32_dpp v30, v19 row_ror:8 row_mask:0xf bank_mask:0xf
	v_mov_b32_dpp v31, v20 row_ror:8 row_mask:0xf bank_mask:0xf
	v_mov_b32_dpp v32, v21 row_ror:8 row_mask:0xf bank_mask:0xf
	s_waitcnt vmcnt(28)
	v_mov_b32_dpp v33, v22 row_ror:8 row_mask:0xf bank_mask:0xf
	v_mov_b32_dpp v34, v23 row_ror:8 row_mask:0xf bank_mask:0xf
	v_mov_b32_dpp v35, v24 row_ror:8 row_mask:0xf bank_mask:0xf
	v_mov_b32_dpp v36, v25 row_ror:8 row_mask:0xf bank_mask:0xf
	v_cndmask_b32_e64 v25, v25, v32, s[6:7]
	v_cndmask_b32_e64 v24, v24, v31, s[6:7]
	v_cndmask_b32_e64 v23, v23, v30, s[6:7]
	v_cndmask_b32_e64 v17, v22, v17, s[6:7]
	v_cndmask_b32_e64 v34, v34, v19, s[6:7]
	v_cndmask_b32_e64 v31, v33, v18, s[6:7]
	v_cndmask_b32_e64 v37, v36, v21, s[6:7]
	v_cndmask_b32_e64 v35, v35, v20, s[6:7]
	v_lshlrev_b32_e32 v18, 16, v17
	v_and_b32_e32 v19, 0xffff0000, v17
	v_lshlrev_b32_e32 v20, 16, v23
	v_and_b32_e32 v21, 0xffff0000, v23
	v_lshlrev_b32_e32 v22, 16, v24
	v_and_b32_e32 v23, 0xffff0000, v24
	v_lshlrev_b32_e32 v24, 16, v25
	v_and_b32_e32 v25, 0xffff0000, v25
	v_lshlrev_b32_e32 v30, 16, v31
	v_and_b32_e32 v31, 0xffff0000, v31
	v_lshlrev_b32_e32 v32, 16, v34
	v_and_b32_e32 v33, 0xffff0000, v34
	v_lshlrev_b32_e32 v34, 16, v35
	v_and_b32_e32 v35, 0xffff0000, v35
	v_lshlrev_b32_e32 v36, 16, v37
	v_and_b32_e32 v37, 0xffff0000, v37
	v_pk_add_f32 v[18:19], v[4:5], v[18:19]
	v_pk_add_f32 v[24:25], v[2:3], v[24:25]
	v_pk_add_f32 v[2:3], v[14:15], v[32:33]
	v_pk_add_f32 v[4:5], v[12:13], v[30:31]
	v_pk_add_f32 v[20:21], v[6:7], v[20:21]
	v_pk_add_f32 v[6:7], v[10:11], v[36:37]
	v_pk_add_f32 v[8:9], v[8:9], v[34:35]
	v_mul_f32_e32 v10, v5, v5
	v_mul_f32_e32 v11, v3, v3
	v_mul_f32_e32 v12, v9, v9
	v_fmac_f32_e32 v10, v4, v4
	v_fmac_f32_e32 v11, v2, v2
	v_pk_add_f32 v[0:1], v[0:1], v[22:23]
	v_mul_f32_e32 v13, v7, v7
	v_cvt_pk_bf16_f32 v5, v4, v5
	v_fmac_f32_e32 v12, v8, v8
	v_add_f32_e32 v4, v10, v11
	v_mul_f32_e32 v10, v19, v19
	v_mul_f32_e32 v11, v21, v21
	v_cvt_pk_bf16_f32 v3, v2, v3
	v_cvt_pk_bf16_f32 v9, v8, v9
	v_cvt_pk_bf16_f32 v7, v6, v7
	v_cvt_pk_bf16_f32 v14, v18, v19
	v_cvt_pk_bf16_f32 v15, v20, v21
	v_cvt_pk_bf16_f32 v17, v0, v1
	v_fmac_f32_e32 v13, v6, v6
	v_add_f32_e32 v4, v12, v4
	v_mov_b32_dpp v44, v17 row_ror:8 row_mask:0xf bank_mask:0xf
	v_fmac_f32_e32 v10, v18, v18
	v_fmac_f32_e32 v11, v20, v20
	v_mul_f32_e32 v1, v1, v1
	v_mov_b32_dpp v40, v9 row_ror:8 row_mask:0xf bank_mask:0xf
	v_add_f32_e32 v8, v13, v4
	v_cndmask_b32_e64 v4, v44, v9, s[6:7]
	v_mul_f32_e32 v9, v25, v25
	v_add_f32_e32 v10, v10, v11
	v_fmac_f32_e32 v1, v0, v0
	v_fmac_f32_e32 v9, v24, v24
	v_add_f32_e32 v0, v1, v10
	v_add_f32_e32 v0, v9, v0
	v_add_f32_e32 v12, v0, v8
	v_mov_b32_e32 v13, v12
	s_nop 1
	v_permlane16_swap_b32_e32 v13, v12
	v_lshl_add_u64 v[0:1], s[16:17], 0, v[26:27]
	v_lshl_add_u64 v[10:11], v[0:1], 0, v[146:147]
	v_cvt_pk_bf16_f32 v22, v24, v25
	v_mov_b32_dpp v42, v14 row_ror:8 row_mask:0xf bank_mask:0xf
	s_waitcnt lgkmcnt(0)
	v_add_f32_e32 v0, v12, v13
	v_mov_b32_e32 v1, v0
	s_nop 1
	v_permlane32_swap_b32_e32 v1, v0
	v_mov_b32_dpp v43, v15 row_ror:8 row_mask:0xf bank_mask:0xf
	v_mov_b32_dpp v45, v22 row_ror:8 row_mask:0xf bank_mask:0xf
	v_mov_b32_dpp v38, v5 row_ror:8 row_mask:0xf bank_mask:0xf
	v_mov_b32_dpp v39, v3 row_ror:8 row_mask:0xf bank_mask:0xf
	v_cndmask_b32_e64 v2, v42, v5, s[6:7]
	v_cndmask_b32_e64 v3, v43, v3, s[6:7]
	v_cndmask_b32_e64 v5, v45, v7, s[6:7]
	v_mov_b32_dpp v41, v7 row_ror:8 row_mask:0xf bank_mask:0xf
	global_store_dwordx4 v[10:11], v[2:5], off
	v_cndmask_b32_e64 v6, v14, v38, s[6:7]
	v_cndmask_b32_e64 v7, v15, v39, s[6:7]
	v_lshl_add_u64 v[2:3], s[16:17], 0, v[28:29]
	v_cndmask_b32_e64 v8, v17, v40, s[6:7]
	v_cndmask_b32_e64 v9, v22, v41, s[6:7]
	v_lshl_add_u64 v[2:3], v[2:3], 0, v[146:147]
	global_store_dwordx4 v[2:3], v[6:9], off
	s_and_saveexec_b64 s[42:43], s[8:9]
	s_cbranch_execz .LBB0_1236
	v_ashrrev_i32_e32 v17, 31, v16
	s_waitcnt lgkmcnt(0)
	v_add_f32_e32 v2, v0, v1
	v_lshl_add_u64 v[0:1], v[16:17], 2, s[18:19]
	global_atomic_add_f32 v[0:1], v2, off
	s_branch .LBB0_1236

; #define PG8_STAGE(bufoff, gbase, voff) do { _Pragma("unroll") for (int _i = 0; _i < 2; ++_i) \
;         __builtin_amdgcn_global_load_lds((const unsigned*)((const char*)(gbase) + (voff)[_i]), (LAS unsigned*)(lds + (bufoff) + ldsw + _i * 8192), 16, 0, 0); } while (0)
; #define PG8_LDA(dst, b, h) do { _Pragma("unroll") for (int m = 0; m < 4; ++m) _Pragma("unroll") for (int k = 0; k < 2; ++k) dst[m][k] = *(const LAS bf16x8*)(lds + PG8_SA(b, h) + aoff + m * 2048 + k * 1024); } while (0)
; #define PG8_LDB(dst, b, h) do { _Pragma("unroll") for (int n = 0; n < 2; ++n) _Pragma("unroll") for (int k = 0; k < 2; ++k) dst[n][k] = *(const LAS bf16x8*)(lds + PG8_SB(b, h) + boff + n * 2048 + k * 1024); } while (0)
; #define PG8_MMA(ai, bj, At, Bt) do { __builtin_amdgcn_s_setprio(1); _Pragma("unroll") for (int m = 0; m < 4; ++m) _Pragma("unroll") for (int n = 0; n < 2; ++n) _Pragma("unroll") for (int k = 0; k < 2; ++k) \
;         acc[ai][bj][m][n] = __builtin_amdgcn_mfma_f32_16x16x32_bf16(Bt[n][k], At[m][k], acc[ai][bj][m][n], 0, 0, 0); __builtin_amdgcn_s_setprio(0); } while (0)
; #define PG8_WAIT_V(n) asm volatile("s_waitcnt vmcnt(" #n ")" ::: "memory")
; #define PG8_WAIT_L(n) asm volatile("s_waitcnt lgkmcnt(" #n ")" ::: "memory")
; #define PG8_BAR __builtin_amdgcn_s_barrier()
; #define PG8_SCHED __builtin_amdgcn_sched_barrier(0)
; template <class Epi>
; __device__ __forceinline__ void gemm_phase(LAS unsigned char* lds, const Gemm g, const StaticOrder& S, const Epi& E) {
;     ...
;             PG8_LDB(B0, 0, 0); PG8_SCHED; PG8_LDA(At, 0, 0); PG8_STAGE(PG8_SA(1, 1), a1 + hstep, voffA);
;             PG8_WAIT_L(8); PG8_BAR; PG8_WAIT_L(0); PG8_MMA(0, 0, At, B0); PG8_BAR; PG8_SCHED;
;             PG8_LDB(B1, 0, 1); PG8_STAGE(PG8_SB(0, 0), b2, voffB0);
;             PG8_BAR; PG8_WAIT_L(0); PG8_MMA(0, 1, At, B1); PG8_BAR;
;             PG8_LDA(At, 0, 1); PG8_STAGE(PG8_SA(0, 0), a2, voffA);
;             PG8_BAR; PG8_WAIT_L(0); PG8_MMA(1, 0, At, B0); PG8_BAR; PG8_SCHED;
;             PG8_STAGE(PG8_SB(0, 1), b2, voffB1);
;             PG8_WAIT_V(6); PG8_BAR; PG8_MMA(1, 1, At, B1); PG8_BAR;
.LBB0_1603:
	ds_read_b128 v[40:43], v179
	ds_read_b128 v[44:47], v179 offset:1024
	ds_read_b128 v[56:59], v179 offset:2048
	ds_read_b128 v[60:63], v179 offset:3072
	s_add_u32 s36, s34, 0xfff80080
	s_addc_u32 s37, s35, -1
	s_cmp_eq_u32 s58, 28
	s_cselect_b32 s37, s23, s37
	s_cselect_b32 s36, s54, s36
	s_cselect_b32 s39, s19, s57
	s_cselect_b32 s38, s55, s56
	v_lshl_add_u64 v[172:173], s[34:35], 0, v[158:159]
	s_add_i32 m0, s31, 0xc000
	ds_read_b128 v[164:167], v180
	ds_read_b128 v[168:171], v180 offset:1024
	ds_read_b128 v[184:187], v180 offset:2048
	ds_read_b128 v[188:191], v180 offset:3072
	ds_read_b128 v[192:195], v180 offset:4096
	ds_read_b128 v[196:199], v180 offset:5120
	ds_read_b128 v[200:203], v180 offset:6144
	ds_read_b128 v[204:207], v180 offset:7168
	global_load_lds_dwordx4 v[172:173], off
	v_lshl_add_u64 v[172:173], s[34:35], 0, v[160:161]
	s_add_i32 m0, s31, 0xe000
	s_nop 0
	global_load_lds_dwordx4 v[172:173], off
	s_waitcnt lgkmcnt(8)
	s_barrier
	s_waitcnt lgkmcnt(0)
	v_mfma_f32_16x16x32_bf16 v[140:143], v[40:43], v[164:167], v[140:143]
	v_mfma_f32_16x16x32_bf16 v[136:139], v[56:59], v[164:167], v[136:139]
	v_mfma_f32_16x16x32_bf16 v[124:127], v[40:43], v[184:187], v[124:127]
	v_mfma_f32_16x16x32_bf16 v[120:123], v[56:59], v[184:187], v[120:123]
	v_mfma_f32_16x16x32_bf16 v[108:111], v[40:43], v[192:195], v[108:111]
	v_mfma_f32_16x16x32_bf16 v[104:107], v[56:59], v[192:195], v[104:107]
	v_mfma_f32_16x16x32_bf16 v[92:95], v[40:43], v[200:203], v[92:95]
	v_mfma_f32_16x16x32_bf16 v[88:91], v[56:59], v[200:203], v[88:91]
	v_mfma_f32_16x16x32_bf16 v[140:143], v[44:47], v[168:171], v[140:143]
	v_mfma_f32_16x16x32_bf16 v[136:139], v[60:63], v[168:171], v[136:139]
	v_mfma_f32_16x16x32_bf16 v[124:127], v[44:47], v[188:191], v[124:127]
	v_mfma_f32_16x16x32_bf16 v[120:123], v[60:63], v[188:191], v[120:123]
	v_mfma_f32_16x16x32_bf16 v[108:111], v[44:47], v[196:199], v[108:111]
	v_mfma_f32_16x16x32_bf16 v[104:107], v[60:63], v[196:199], v[104:107]
	v_mfma_f32_16x16x32_bf16 v[92:95], v[44:47], v[204:207], v[92:95]
	v_mfma_f32_16x16x32_bf16 v[88:91], v[60:63], v[204:207], v[88:91]
	s_barrier
	s_add_i32 s59, s51, s41
	v_lshl_add_u64 v[172:173], s[38:39], 0, v[146:147]
	s_mov_b32 m0, s59
	ds_read_b128 v[208:211], v181
	ds_read_b128 v[212:215], v181 offset:1024
	ds_read_b128 v[216:219], v181 offset:2048
	ds_read_b128 v[220:223], v181 offset:3072
	global_load_lds_dwordx4 v[172:173], off
	v_lshl_add_u64 v[224:225], s[38:39], 0, v[152:153]
	s_add_i32 m0, s59, 0x2000
	s_nop 0
	global_load_lds_dwordx4 v[224:225], off
	s_waitcnt lgkmcnt(0)
	s_barrier
	s_waitcnt lgkmcnt(0)
	v_mfma_f32_16x16x32_bf16 v[132:135], v[208:211], v[164:167], v[132:135]
	v_mfma_f32_16x16x32_bf16 v[128:131], v[216:219], v[164:167], v[128:131]
	v_mfma_f32_16x16x32_bf16 v[116:119], v[208:211], v[184:187], v[116:119]
	v_mfma_f32_16x16x32_bf16 v[112:115], v[216:219], v[184:187], v[112:115]
	v_mfma_f32_16x16x32_bf16 v[100:103], v[208:211], v[192:195], v[100:103]
	v_mfma_f32_16x16x32_bf16 v[96:99], v[216:219], v[192:195], v[96:99]
	v_mfma_f32_16x16x32_bf16 v[84:87], v[208:211], v[200:203], v[84:87]
	v_mfma_f32_16x16x32_bf16 v[80:83], v[216:219], v[200:203], v[80:83]
	v_mfma_f32_16x16x32_bf16 v[132:135], v[212:215], v[168:171], v[132:135]
	v_mfma_f32_16x16x32_bf16 v[128:131], v[220:223], v[168:171], v[128:131]
	v_mfma_f32_16x16x32_bf16 v[116:119], v[212:215], v[188:191], v[116:119]
	v_mfma_f32_16x16x32_bf16 v[112:115], v[220:223], v[188:191], v[112:115]
	v_mfma_f32_16x16x32_bf16 v[100:103], v[212:215], v[196:199], v[100:103]
	v_mfma_f32_16x16x32_bf16 v[96:99], v[220:223], v[196:199], v[96:99]
	v_mfma_f32_16x16x32_bf16 v[84:87], v[212:215], v[204:207], v[84:87]
	v_mfma_f32_16x16x32_bf16 v[80:83], v[220:223], v[204:207], v[80:83]
	s_mov_b32 m0, s31
	v_lshl_add_u64 v[226:227], s[36:37], 0, v[144:145]
	s_barrier
	ds_read_b128 v[164:167], v180 offset:16384
	ds_read_b128 v[168:171], v180 offset:17408
	ds_read_b128 v[184:187], v180 offset:18432
	ds_read_b128 v[188:191], v180 offset:19456
	ds_read_b128 v[192:195], v180 offset:20480
	ds_read_b128 v[196:199], v180 offset:21504
	ds_read_b128 v[200:203], v180 offset:22528
	ds_read_b128 v[204:207], v180 offset:23552
	global_load_lds_dwordx4 v[226:227], off
	v_lshl_add_u64 v[228:229], s[36:37], 0, v[150:151]
	s_mov_b32 m0, s42
	s_nop 0
	global_load_lds_dwordx4 v[228:229], off
	s_add_i32 s59, s52, s41
	v_lshl_add_u64 v[230:231], s[38:39], 0, v[148:149]
	s_mov_b32 m0, s59
	v_lshl_add_u64 v[232:233], s[38:39], 0, v[154:155]
	global_load_lds_dwordx4 v[230:231], off
	s_add_i32 m0, s59, 0x2000
	s_nop 0
	global_load_lds_dwordx4 v[232:233], off
	s_waitcnt vmcnt(6)
	s_barrier
; #define PG8_STAGE(bufoff, gbase, voff) do { _Pragma("unroll") for (int _i = 0; _i < 2; ++_i) \
;         __builtin_amdgcn_global_load_lds((const unsigned*)((const char*)(gbase) + (voff)[_i]), (LAS unsigned*)(lds + (bufoff) + ldsw + _i * 8192), 16, 0, 0); } while (0)
; #define PG8_LDA(dst, b, h) do { _Pragma("unroll") for (int m = 0; m < 4; ++m) _Pragma("unroll") for (int k = 0; k < 2; ++k) dst[m][k] = *(const LAS bf16x8*)(lds + PG8_SA(b, h) + aoff + m * 2048 + k * 1024); } while (0)
; #define PG8_LDB(dst, b, h) do { _Pragma("unroll") for (int n = 0; n < 2; ++n) _Pragma("unroll") for (int k = 0; k < 2; ++k) dst[n][k] = *(const LAS bf16x8*)(lds + PG8_SB(b, h) + boff + n * 2048 + k * 1024); } while (0)
; #define PG8_MMA(ai, bj, At, Bt) do { __builtin_amdgcn_s_setprio(1); _Pragma("unroll") for (int m = 0; m < 4; ++m) _Pragma("unroll") for (int n = 0; n < 2; ++n) _Pragma("unroll") for (int k = 0; k < 2; ++k) \
;         acc[ai][bj][m][n] = __builtin_amdgcn_mfma_f32_16x16x32_bf16(Bt[n][k], At[m][k], acc[ai][bj][m][n], 0, 0, 0); __builtin_amdgcn_s_setprio(0); } while (0)
; #define PG8_WAIT_V(n) asm volatile("s_waitcnt vmcnt(" #n ")" ::: "memory")
; #define PG8_WAIT_L(n) asm volatile("s_waitcnt lgkmcnt(" #n ")" ::: "memory")
; #define PG8_BAR __builtin_amdgcn_s_barrier()
; #define PG8_SCHED __builtin_amdgcn_sched_barrier(0)
; template <class Epi>
; __device__ __forceinline__ void gemm_phase(LAS unsigned char* lds, const Gemm g, const StaticOrder& S, const Epi& E) {
;     ...
;             PG8_WAIT_V(6); PG8_BAR; PG8_MMA(1, 1, At, B1); PG8_BAR;
;             PG8_LDB(B0, 1, 0); PG8_SCHED; PG8_LDA(At, 1, 0); PG8_STAGE(PG8_SA(0, 1), a2 + hstep, voffA);
;             PG8_WAIT_L(8); PG8_BAR; PG8_WAIT_L(0); PG8_MMA(0, 0, At, B0); PG8_BAR; PG8_SCHED;
;             PG8_LDB(B1, 1, 1); PG8_STAGE(PG8_SB(1, 0), b3, voffB0);
;             PG8_BAR; PG8_WAIT_L(0); PG8_MMA(0, 1, At, B1); PG8_BAR;
	s_waitcnt lgkmcnt(0)
	v_mfma_f32_16x16x32_bf16 v[76:79], v[40:43], v[164:167], v[76:79]
	v_mfma_f32_16x16x32_bf16 v[72:75], v[56:59], v[164:167], v[72:75]
	v_mfma_f32_16x16x32_bf16 v[52:55], v[40:43], v[184:187], v[52:55]
	v_mfma_f32_16x16x32_bf16 v[48:51], v[56:59], v[184:187], v[48:51]
	v_mfma_f32_16x16x32_bf16 v[28:31], v[40:43], v[192:195], v[28:31]
	v_mfma_f32_16x16x32_bf16 v[24:27], v[56:59], v[192:195], v[24:27]
	v_mfma_f32_16x16x32_bf16 v[12:15], v[40:43], v[200:203], v[12:15]
	v_mfma_f32_16x16x32_bf16 v[8:11], v[56:59], v[200:203], v[8:11]
	v_mfma_f32_16x16x32_bf16 v[76:79], v[44:47], v[168:171], v[76:79]
	v_mfma_f32_16x16x32_bf16 v[72:75], v[60:63], v[168:171], v[72:75]
	v_mfma_f32_16x16x32_bf16 v[52:55], v[44:47], v[188:191], v[52:55]
	v_mfma_f32_16x16x32_bf16 v[48:51], v[60:63], v[188:191], v[48:51]
	v_mfma_f32_16x16x32_bf16 v[28:31], v[44:47], v[196:199], v[28:31]
	v_mfma_f32_16x16x32_bf16 v[24:27], v[60:63], v[196:199], v[24:27]
	v_mfma_f32_16x16x32_bf16 v[12:15], v[44:47], v[204:207], v[12:15]
	v_mfma_f32_16x16x32_bf16 v[8:11], v[60:63], v[204:207], v[8:11]
	v_mfma_f32_16x16x32_bf16 v[36:39], v[208:211], v[184:187], v[36:39]
	v_mfma_f32_16x16x32_bf16 v[32:35], v[216:219], v[184:187], v[32:35]
	v_mfma_f32_16x16x32_bf16 v[20:23], v[208:211], v[192:195], v[20:23]
	v_mfma_f32_16x16x32_bf16 v[16:19], v[216:219], v[192:195], v[16:19]
	v_mfma_f32_16x16x32_bf16 v[4:7], v[208:211], v[200:203], v[4:7]
	v_mfma_f32_16x16x32_bf16 v[0:3], v[216:219], v[200:203], v[0:3]
	v_mfma_f32_16x16x32_bf16 v[40:43], v[208:211], v[164:167], v[68:71]
	v_mfma_f32_16x16x32_bf16 v[44:47], v[216:219], v[164:167], v[64:67]
	v_mfma_f32_16x16x32_bf16 v[36:39], v[212:215], v[188:191], v[36:39]
	v_mfma_f32_16x16x32_bf16 v[32:35], v[220:223], v[188:191], v[32:35]
	v_mfma_f32_16x16x32_bf16 v[20:23], v[212:215], v[196:199], v[20:23]
	v_mfma_f32_16x16x32_bf16 v[16:19], v[220:223], v[196:199], v[16:19]
	v_mfma_f32_16x16x32_bf16 v[4:7], v[212:215], v[204:207], v[4:7]
	v_mfma_f32_16x16x32_bf16 v[0:3], v[220:223], v[204:207], v[0:3]
	v_mfma_f32_16x16x32_bf16 v[40:43], v[212:215], v[168:171], v[40:43]
	v_mfma_f32_16x16x32_bf16 v[44:47], v[220:223], v[168:171], v[44:47]
	s_add_i32 s38, 0, 0x18000
	v_add_u32_e32 v68, s38, v175
	s_barrier
	ds_read_b128 v[56:59], v68
	ds_read_b128 v[60:63], v68 offset:1024
	ds_read_b128 v[64:67], v68 offset:2048
	ds_read_b128 v[68:71], v68 offset:3072
	s_add_u32 s36, s36, 0x80000
	s_addc_u32 s37, s37, 0
	s_mov_b32 m0, s43
	v_lshl_add_u64 v[208:209], s[36:37], 0, v[144:145]
	ds_read_b128 v[164:167], v180 offset:32768
	ds_read_b128 v[168:171], v180 offset:33792
	ds_read_b128 v[184:187], v180 offset:34816
	ds_read_b128 v[188:191], v180 offset:35840
	ds_read_b128 v[192:195], v180 offset:36864
	ds_read_b128 v[196:199], v180 offset:37888
	ds_read_b128 v[200:203], v180 offset:38912
	ds_read_b128 v[204:207], v180 offset:39936
	global_load_lds_dwordx4 v[208:209], off
	v_lshl_add_u64 v[208:209], s[36:37], 0, v[150:151]
	s_mov_b32 m0, s44
	s_nop 0
	global_load_lds_dwordx4 v[208:209], off
	s_waitcnt lgkmcnt(8)
	s_barrier
	s_waitcnt lgkmcnt(0)
	v_mfma_f32_16x16x32_bf16 v[140:143], v[56:59], v[164:167], v[140:143]
	v_mfma_f32_16x16x32_bf16 v[136:139], v[64:67], v[164:167], v[136:139]
	v_mfma_f32_16x16x32_bf16 v[124:127], v[56:59], v[184:187], v[124:127]
	v_mfma_f32_16x16x32_bf16 v[120:123], v[64:67], v[184:187], v[120:123]
	v_mfma_f32_16x16x32_bf16 v[108:111], v[56:59], v[192:195], v[108:111]
	v_mfma_f32_16x16x32_bf16 v[104:107], v[64:67], v[192:195], v[104:107]
	v_mfma_f32_16x16x32_bf16 v[92:95], v[56:59], v[200:203], v[92:95]
	v_mfma_f32_16x16x32_bf16 v[88:91], v[64:67], v[200:203], v[88:91]
	v_mfma_f32_16x16x32_bf16 v[140:143], v[60:63], v[168:171], v[140:143]
	v_mfma_f32_16x16x32_bf16 v[136:139], v[68:71], v[168:171], v[136:139]
	v_mfma_f32_16x16x32_bf16 v[124:127], v[60:63], v[188:191], v[124:127]
	v_mfma_f32_16x16x32_bf16 v[120:123], v[68:71], v[188:191], v[120:123]
	v_mfma_f32_16x16x32_bf16 v[108:111], v[60:63], v[196:199], v[108:111]
	v_mfma_f32_16x16x32_bf16 v[104:107], v[68:71], v[196:199], v[104:107]
	v_mfma_f32_16x16x32_bf16 v[92:95], v[60:63], v[204:207], v[92:95]
	v_mfma_f32_16x16x32_bf16 v[88:91], v[68:71], v[204:207], v[88:91]
	s_barrier
	s_add_i32 s36, 0, 0x1c000
	s_add_i32 s37, s38, s41
	v_add_u32_e32 v183, s36, v175
	v_lshl_add_u64 v[172:173], v[172:173], 0, s[14:15]
	s_mov_b32 m0, s37
	ds_read_b128 v[208:211], v183
	ds_read_b128 v[212:215], v183 offset:1024
	ds_read_b128 v[216:219], v183 offset:2048
	ds_read_b128 v[220:223], v183 offset:3072
	global_load_lds_dwordx4 v[172:173], off
	v_lshl_add_u64 v[172:173], v[224:225], 0, s[14:15]
	s_add_i32 m0, s37, 0x2000
	s_nop 0
	global_load_lds_dwordx4 v[172:173], off
	s_waitcnt lgkmcnt(0)
	s_barrier
	s_waitcnt lgkmcnt(0)
	v_mfma_f32_16x16x32_bf16 v[132:135], v[208:211], v[164:167], v[132:135]
	v_mfma_f32_16x16x32_bf16 v[128:131], v[216:219], v[164:167], v[128:131]
	v_mfma_f32_16x16x32_bf16 v[116:119], v[208:211], v[184:187], v[116:119]
	v_mfma_f32_16x16x32_bf16 v[112:115], v[216:219], v[184:187], v[112:115]
	v_mfma_f32_16x16x32_bf16 v[100:103], v[208:211], v[192:195], v[100:103]
	v_mfma_f32_16x16x32_bf16 v[96:99], v[216:219], v[192:195], v[96:99]
	v_mfma_f32_16x16x32_bf16 v[84:87], v[208:211], v[200:203], v[84:87]
	v_mfma_f32_16x16x32_bf16 v[80:83], v[216:219], v[200:203], v[80:83]
	v_mfma_f32_16x16x32_bf16 v[132:135], v[212:215], v[168:171], v[132:135]
	v_mfma_f32_16x16x32_bf16 v[128:131], v[220:223], v[168:171], v[128:131]
	v_mfma_f32_16x16x32_bf16 v[116:119], v[212:215], v[188:191], v[116:119]
	v_mfma_f32_16x16x32_bf16 v[112:115], v[220:223], v[188:191], v[112:115]
	v_mfma_f32_16x16x32_bf16 v[100:103], v[212:215], v[196:199], v[100:103]
	v_mfma_f32_16x16x32_bf16 v[96:99], v[220:223], v[196:199], v[96:99]
	v_mfma_f32_16x16x32_bf16 v[84:87], v[212:215], v[204:207], v[84:87]
	v_mfma_f32_16x16x32_bf16 v[80:83], v[220:223], v[204:207], v[80:83]
	s_mov_b32 m0, s47
	v_lshl_add_u64 v[172:173], v[226:227], 0, s[14:15]
	s_barrier
; #define PG8_STAGE(bufoff, gbase, voff) do { _Pragma("unroll") for (int _i = 0; _i < 2; ++_i) \
;         __builtin_amdgcn_global_load_lds((const unsigned*)((const char*)(gbase) + (voff)[_i]), (LAS unsigned*)(lds + (bufoff) + ldsw + _i * 8192), 16, 0, 0); } while (0)
; #define PG8_LDA(dst, b, h) do { _Pragma("unroll") for (int m = 0; m < 4; ++m) _Pragma("unroll") for (int k = 0; k < 2; ++k) dst[m][k] = *(const LAS bf16x8*)(lds + PG8_SA(b, h) + aoff + m * 2048 + k * 1024); } while (0)
; #define PG8_MMA(ai, bj, At, Bt) do { __builtin_amdgcn_s_setprio(1); _Pragma("unroll") for (int m = 0; m < 4; ++m) _Pragma("unroll") for (int n = 0; n < 2; ++n) _Pragma("unroll") for (int k = 0; k < 2; ++k) \
;         acc[ai][bj][m][n] = __builtin_amdgcn_mfma_f32_16x16x32_bf16(Bt[n][k], At[m][k], acc[ai][bj][m][n], 0, 0, 0); __builtin_amdgcn_s_setprio(0); } while (0)
; #define PG8_WAIT_V(n) asm volatile("s_waitcnt vmcnt(" #n ")" ::: "memory")
; #define PG8_BAR __builtin_amdgcn_s_barrier()
;     __device__ __forceinline__ void operator()(const f32x4 (&acc)[2][2][4][2], const Unit& u, int wr, int wc, int fr, int fq) const {
;         const int row0 = u.pm * BM + wr * 64 + fr, col0 = u.pn * BM + wc * 64 + 8 * fq;
;         f32x4 gv[2][2];
; #pragma unroll
;         for (int bj = 0; bj < 2; ++bj) { gv[bj][0] = *(const f32x4*)(g + col0 + 32 * bj); gv[bj][1] = *(const f32x4*)(g + col0 + 32 * bj + 4); }
;         const bool lo = fr < 8;
; #pragma unroll
;         for (int ai = 0; ai < 2; ++ai)
; #pragma unroll
;             for (int m = 0; m < 4; ++m) { const int row = row0 + ai * HALF + m * 16; const float ri = __builtin_amdgcn_rsqf(sse[row] * (1.f / D) + EPS);
;                 u32x4 rr[2], ee[2]; load_pair_lines(R, D, row, fr, col0, rr[0], rr[1], 32); load_pair_lines(E, D, row, fr, col0, ee[0], ee[1], 32);
;                 float* orow = OUT + (size_t)(row - fr + (fr & 7)) * D + col0 + (lo ? 0 : 4);
; template <class Epi>
; __device__ __forceinline__ void gemm_phase(LAS unsigned char* lds, const Gemm g, const StaticOrder& S, const Epi& E) {
;     ...
;             PG8_BAR; PG8_WAIT_L(0); PG8_MMA(0, 1, At, B1); PG8_BAR;
;             PG8_LDA(At, 1, 1); PG8_STAGE(PG8_SA(1, 0), a3, voffA);
;             PG8_BAR; PG8_WAIT_L(0); PG8_MMA(1, 0, At, B0); PG8_BAR; PG8_SCHED;
;             PG8_STAGE(PG8_SB(1, 1), b3, voffB1);
;             PG8_WAIT_V(6); PG8_BAR; PG8_MMA(1, 1, At, B1); PG8_BAR;
	ds_read_b128 v[164:167], v180 offset:49152
	ds_read_b128 v[168:171], v180 offset:50176
	ds_read_b128 v[184:187], v180 offset:51200
	ds_read_b128 v[188:191], v180 offset:52224
	ds_read_b128 v[192:195], v180 offset:53248
	ds_read_b128 v[196:199], v180 offset:54272
	ds_read_b128 v[200:203], v180 offset:55296
	ds_read_b128 v[204:207], v180 offset:56320
	global_load_lds_dwordx4 v[172:173], off
	v_lshl_add_u64 v[172:173], v[228:229], 0, s[14:15]
	s_mov_b32 m0, s48
	s_nop 0
	global_load_lds_dwordx4 v[172:173], off
	s_add_i32 s36, s36, s41
	v_lshl_add_u64 v[250:251], v[230:231], 0, s[14:15]
	s_mov_b32 m0, s36
	s_nop 0
	global_load_lds_dwordx4 v[250:251], off
	v_lshl_add_u64 v[250:251], v[232:233], 0, s[14:15]
	s_add_i32 m0, s36, 0x2000
	s_nop 0
	global_load_lds_dwordx4 v[250:251], off
	s_waitcnt vmcnt(6)
	s_barrier
	s_waitcnt lgkmcnt(0)
	v_mfma_f32_16x16x32_bf16 v[76:79], v[56:59], v[164:167], v[76:79]
	v_mfma_f32_16x16x32_bf16 v[72:75], v[64:67], v[164:167], v[72:75]
	v_mfma_f32_16x16x32_bf16 v[52:55], v[56:59], v[184:187], v[52:55]
	v_mfma_f32_16x16x32_bf16 v[48:51], v[64:67], v[184:187], v[48:51]
	v_mfma_f32_16x16x32_bf16 v[28:31], v[56:59], v[192:195], v[28:31]
	v_mfma_f32_16x16x32_bf16 v[24:27], v[64:67], v[192:195], v[24:27]
	v_mfma_f32_16x16x32_bf16 v[12:15], v[56:59], v[200:203], v[12:15]
	v_mfma_f32_16x16x32_bf16 v[8:11], v[64:67], v[200:203], v[8:11]
	v_mfma_f32_16x16x32_bf16 v[76:79], v[60:63], v[168:171], v[76:79]
	v_mfma_f32_16x16x32_bf16 v[72:75], v[68:71], v[168:171], v[72:75]
	v_mfma_f32_16x16x32_bf16 v[52:55], v[60:63], v[188:191], v[52:55]
	v_mfma_f32_16x16x32_bf16 v[48:51], v[68:71], v[188:191], v[48:51]
	v_mfma_f32_16x16x32_bf16 v[28:31], v[60:63], v[196:199], v[28:31]
	v_mfma_f32_16x16x32_bf16 v[24:27], v[68:71], v[196:199], v[24:27]
	v_mfma_f32_16x16x32_bf16 v[12:15], v[60:63], v[204:207], v[12:15]
	v_mfma_f32_16x16x32_bf16 v[8:11], v[68:71], v[204:207], v[8:11]
	v_mfma_f32_16x16x32_bf16 v[40:43], v[208:211], v[164:167], v[40:43]
	v_mfma_f32_16x16x32_bf16 v[68:71], v[212:215], v[168:171], v[40:43]
	v_mfma_f32_16x16x32_bf16 v[40:43], v[216:219], v[164:167], v[44:47]
	v_mfma_f32_16x16x32_bf16 v[36:39], v[208:211], v[184:187], v[36:39]
	v_mfma_f32_16x16x32_bf16 v[32:35], v[216:219], v[184:187], v[32:35]
	v_mfma_f32_16x16x32_bf16 v[20:23], v[208:211], v[192:195], v[20:23]
	v_mfma_f32_16x16x32_bf16 v[16:19], v[216:219], v[192:195], v[16:19]
	v_mfma_f32_16x16x32_bf16 v[4:7], v[208:211], v[200:203], v[4:7]
	v_mfma_f32_16x16x32_bf16 v[0:3], v[216:219], v[200:203], v[0:3]
	v_mfma_f32_16x16x32_bf16 v[64:67], v[220:223], v[168:171], v[40:43]
	v_mfma_f32_16x16x32_bf16 v[36:39], v[212:215], v[188:191], v[36:39]
	v_mfma_f32_16x16x32_bf16 v[32:35], v[220:223], v[188:191], v[32:35]
	v_mfma_f32_16x16x32_bf16 v[20:23], v[212:215], v[196:199], v[20:23]
	v_mfma_f32_16x16x32_bf16 v[16:19], v[220:223], v[196:199], v[16:19]
	v_mfma_f32_16x16x32_bf16 v[4:7], v[212:215], v[204:207], v[4:7]
	v_mfma_f32_16x16x32_bf16 v[0:3], v[220:223], v[204:207], v[0:3]
	s_add_i32 s58, s58, 2
	s_add_u32 s34, s34, 0x100
	s_addc_u32 s35, s35, 0
	s_add_u32 s56, s56, 0x100
	s_addc_u32 s57, s57, 0
	s_cmp_gt_u32 s58, 29
	s_barrier
	s_cbranch_scc0 .LBB0_1603
	s_lshl_b32 s19, s30, 8
	s_add_i32 s19, s19, s49
	v_lshl_or_b32 v40, s53, 8, v178
	v_or_b32_e32 v172, s19, v176
	v_or_b32_e32 v42, v40, v177
	v_ashrrev_i32_e32 v173, 31, v172
	v_or_b32_e32 v170, s19, v174
	v_ashrrev_i32_e32 v43, 31, v42
	v_lshlrev_b64 v[44:45], 12, v[172:173]
	v_ashrrev_i32_e32 v171, 31, v170
	v_lshl_add_u64 v[46:47], s[8:9], 0, v[44:45]
	v_lshlrev_b64 v[164:165], 1, v[42:43]
	v_lshl_add_u64 v[168:169], v[170:171], 2, s[6:7]
	v_lshl_add_u64 v[42:43], v[46:47], 0, v[164:165]
	global_load_dword v171, v[168:169], off
	global_load_dwordx4 v[184:187], v[42:43], off
	v_or_b32_e32 v42, 8, v172
	v_ashrrev_i32_e32 v43, 31, v42
	v_lshlrev_b64 v[42:43], 12, v[42:43]
	v_lshl_add_u64 v[46:47], s[8:9], 0, v[42:43]
	v_lshl_add_u64 v[44:45], s[10:11], 0, v[44:45]
	v_lshl_add_u64 v[42:43], s[10:11], 0, v[42:43]
	v_lshl_add_u64 v[46:47], v[46:47], 0, v[164:165]
	v_lshl_add_u64 v[44:45], v[44:45], 0, v[164:165]
	v_lshl_add_u64 v[42:43], v[42:43], 0, v[164:165]
	global_load_dwordx4 v[188:191], v[46:47], off
	global_load_dwordx4 v[192:195], v[44:45], off
	global_load_dwordx4 v[196:199], v[42:43], off
	v_ashrrev_i32_e32 v41, 31, v40
	v_lshlrev_b64 v[166:167], 2, v[40:41]
	v_lshl_add_u64 v[44:45], s[12:13], 0, v[166:167]
	global_load_dwordx4 v[56:59], v[44:45], off
	global_load_dwordx4 v[60:63], v[44:45], off offset:16
	v_mul_f32_e32 v40, 0xbfb8aa3b, v140
	v_exp_f32_e32 v215, v40
	global_load_dwordx4 v[40:43], v[44:45], off offset:128
	s_nop 0
	global_load_dwordx4 v[44:47], v[44:45], off offset:144
	v_or_b32_e32 v216, 16, v170
	v_ashrrev_i32_e32 v217, 31, v216
	v_lshl_add_u64 v[218:219], v[216:217], 2, s[6:7]
	v_sub_u32_e32 v216, v216, v174
	v_add_u32_e32 v222, v216, v176
	v_ashrrev_i32_e32 v223, 31, v222
	v_lshlrev_b64 v[216:217], 12, v[222:223]
	v_lshl_add_u64 v[224:225], v[216:217], 0, s[16:17]
	global_load_dword v228, v[218:219], off
	v_lshl_add_u64 v[218:219], s[8:9], 0, v[216:217]
	v_lshl_add_u64 v[220:221], s[8:9], 0, v[224:225]
	v_lshl_add_u64 v[216:217], s[10:11], 0, v[216:217]
	v_lshl_add_u64 v[218:219], v[218:219], 0, v[164:165]
	v_lshl_add_u64 v[220:221], v[220:221], 0, v[164:165]
	v_lshl_add_u64 v[216:217], v[216:217], 0, v[164:165]
	global_load_dwordx4 v[232:235], v[218:219], off
	global_load_dwordx4 v[236:239], v[220:221], off
	global_load_dwordx4 v[240:243], v[216:217], off
	v_lshl_add_u64 v[216:217], s[10:11], 0, v[224:225]
	v_lshl_add_u64 v[216:217], v[216:217], 0, v[164:165]
	global_load_dwordx4 v[244:247], v[216:217], off
; __device__ __forceinline__ float bflo(unsigned w) { return __uint_as_float(w << 16); }
; __device__ __forceinline__ float bfhi(unsigned w) { return __uint_as_float(w & 0xffff0000u); }
;     const bool lo = fr < 8;
;     const int r1 = row - fr + (fr & 7), cb = col0 + (lo ? 0 : boff);
;     const u32x4 l1 = *(const u32x4*)(P + (size_t)r1 * ld + cb), l2 = *(const u32x4*)(P + (size_t)(r1 + 8) * ld + cb);
;     const u32x4 s1 = {dpp_ror8(l1.x), dpp_ror8(l1.y), dpp_ror8(l1.z), dpp_ror8(l1.w)}, s2 = {dpp_ror8(l2.x), dpp_ror8(l2.y), dpp_ror8(l2.z), dpp_ror8(l2.w)};
;     wA = lo ? l1 : s2; wB = lo ? s1 : l2;
; }
;     __device__ __forceinline__ void operator()(const f32x4 (&acc)[2][2][4][2], const Unit& u, int wr, int wc, int fr, int fq) const {
;     ...
;             for (int m = 0; m < 4; ++m) { const int row = row0 + ai * HALF + m * 16; const float ri = __builtin_amdgcn_rsqf(sse[row] * (1.f / D) + EPS);
;                 u32x4 rr[2], ee[2]; load_pair_lines(R, D, row, fr, col0, rr[0], rr[1], 32); load_pair_lines(E, D, row, fr, col0, ee[0], ee[1], 32);
;                 float* orow = OUT + (size_t)(row - fr + (fr & 7)) * D + col0 + (lo ? 0 : 4);
; #pragma unroll
;                 for (int bj = 0; bj < 2; ++bj) { const u32x4 rw = rr[bj], ew = ee[bj];
;                     const float r[8] = {bflo(rw.x), bfhi(rw.x), bflo(rw.y), bfhi(rw.y), bflo(rw.z), bfhi(rw.z), bflo(rw.w), bfhi(rw.w)};
;                     const float e[8] = {bflo(ew.x), bfhi(ew.x), bflo(ew.y), bfhi(ew.y), bflo(ew.z), bfhi(ew.z), bflo(ew.w), bfhi(ew.w)};
;                     float o[8];
; #pragma unroll
;                     for (int j = 0; j < 8; ++j) { const float a = acc[ai][bj][m][j >> 2][j & 3]; const float gg = gv[bj][j >> 2][j & 3];
;                         o[j] = r[j] + e[j] * ri * gg * __builtin_amdgcn_rcpf(1.f + __builtin_amdgcn_exp2f(-a * LOG2E)); }
;                     f32x4 o1, o2;
; #pragma unroll
;                     for (int j = 0; j < 4; ++j) { const unsigned a = __float_as_uint(o[j]), b = __float_as_uint(o[4 + j]); const unsigned sa = dpp_ror8(a), sb = dpp_ror8(b);
;                         o1[j] = __uint_as_float(lo ? a : sb); o2[j] = __uint_as_float(lo ? sa : b); }
;                     *(f32x4*)(orow + 32 * bj) = o1; *(f32x4*)(orow + (size_t)8 * D + 32 * bj) = o2; } }
	v_mul_f32_e32 v141, 0xbfb8aa3b, v141
	v_mul_f32_e32 v136, 0xbfb8aa3b, v136
	v_mul_f32_e32 v137, 0xbfb8aa3b, v137
	v_exp_f32_e32 v141, v141
	v_mul_f32_e32 v142, 0xbfb8aa3b, v142
	v_exp_f32_e32 v136, v136
	v_exp_f32_e32 v137, v137
	v_exp_f32_e32 v142, v142
	v_mul_f32_e32 v143, 0xbfb8aa3b, v143
	v_exp_f32_e32 v143, v143
	v_add_f32_e32 v141, 1.0, v141
	v_add_f32_e32 v136, 1.0, v136
	v_add_f32_e32 v137, 1.0, v137
	v_rcp_f32_e32 v136, v136
	v_rcp_f32_e32 v137, v137
	v_mul_f32_e32 v138, 0xbfb8aa3b, v138
	v_mul_f32_e32 v139, 0xbfb8aa3b, v139
	v_exp_f32_e32 v138, v138
	v_exp_f32_e32 v139, v139
	v_add_f32_e32 v138, 1.0, v138
	v_add_f32_e32 v139, 1.0, v139
	v_rcp_f32_e32 v138, v138
	v_rcp_f32_e32 v139, v139
	v_mul_f32_e32 v128, 0xbfb8aa3b, v128
	v_mul_f32_e32 v129, 0xbfb8aa3b, v129
	v_exp_f32_e32 v128, v128
	v_exp_f32_e32 v129, v129
	v_mul_f32_e32 v132, 0xbfb8aa3b, v132
	v_mul_f32_e32 v133, 0xbfb8aa3b, v133
	v_exp_f32_e32 v132, v132
	v_exp_f32_e32 v133, v133
	v_lshlrev_b64 v[172:173], 13, v[172:173]
	v_add_f32_e32 v128, 1.0, v128
	v_add_f32_e32 v129, 1.0, v129
	v_lshl_add_u64 v[172:173], s[4:5], 0, v[172:173]
	v_rcp_f32_e32 v128, v128
	v_mul_f32_e32 v130, 0xbfb8aa3b, v130
	v_mul_f32_e32 v131, 0xbfb8aa3b, v131
	v_rcp_f32_e32 v129, v129
	v_lshl_add_u64 v[172:173], v[172:173], 0, v[166:167]
	v_exp_f32_e32 v130, v130
	v_exp_f32_e32 v131, v131
	v_lshl_add_u64 v[172:173], v[172:173], 0, v[156:157]
	s_waitcnt vmcnt(5)
	v_fmamk_f32 v140, v171, 0x3a000000, v182
	v_rsq_f32_e32 v140, v140
	v_mov_b32_dpp v200, v185 row_ror:8 row_mask:0xf bank_mask:0xf
	v_mov_b32_dpp v183, v184 row_ror:8 row_mask:0xf bank_mask:0xf
	v_mov_b32_dpp v201, v186 row_ror:8 row_mask:0xf bank_mask:0xf
	v_mov_b32_dpp v202, v187 row_ror:8 row_mask:0xf bank_mask:0xf
	v_add_f32_e32 v132, 1.0, v132
	v_add_f32_e32 v133, 1.0, v133
	v_rcp_f32_e32 v132, v132
	v_mul_f32_e32 v134, 0xbfb8aa3b, v134
	v_mul_f32_e32 v135, 0xbfb8aa3b, v135
	v_mov_b32_dpp v204, v189 row_ror:8 row_mask:0xf bank_mask:0xf
	v_cndmask_b32_e64 v171, v189, v200, s[0:1]
	v_mov_b32_dpp v213, v198 row_ror:8 row_mask:0xf bank_mask:0xf
	v_cndmask_b32_e64 v200, v204, v185, s[0:1]
	v_cndmask_b32_e64 v189, v213, v194, s[0:1]
	v_rcp_f32_e32 v185, v141
	v_add_f32_e32 v141, 1.0, v142
	v_mov_b32_dpp v203, v188 row_ror:8 row_mask:0xf bank_mask:0xf
	v_mov_b32_dpp v205, v190 row_ror:8 row_mask:0xf bank_mask:0xf
	v_mov_b32_dpp v206, v191 row_ror:8 row_mask:0xf bank_mask:0xf
	v_cndmask_b32_e64 v183, v188, v183, s[0:1]
	v_rcp_f32_e32 v142, v141
	v_add_f32_e32 v141, 1.0, v143
	v_lshlrev_b32_e32 v188, 16, v189
	v_and_b32_e32 v189, 0xffff0000, v189
	v_cndmask_b32_e64 v190, v190, v201, s[0:1]
	v_cndmask_b32_e64 v201, v206, v187, s[0:1]
	v_cndmask_b32_e64 v187, v205, v186, s[0:1]
	v_pk_mul_f32 v[188:189], v[140:141], v[188:189] op_sel_hi:[0,1]
	v_cndmask_b32_e64 v191, v191, v202, s[0:1]
	v_mov_b32_dpp v211, v196 row_ror:8 row_mask:0xf bank_mask:0xf
	v_cndmask_b32_e64 v202, v203, v184, s[0:1]
	v_add_f32_e32 v184, 1.0, v215
	v_lshlrev_b32_e32 v186, 16, v187
	v_and_b32_e32 v187, 0xffff0000, v187
	v_pk_mul_f32 v[188:189], v[60:61], v[188:189]
	v_mov_b32_dpp v207, v192 row_ror:8 row_mask:0xf bank_mask:0xf
	v_cndmask_b32_e64 v192, v211, v192, s[0:1]
	v_rcp_f32_e32 v184, v184
	v_rcp_f32_e32 v143, v141
	v_pk_fma_f32 v[188:189], v[136:137], v[188:189], v[186:187]
	v_mov_b32_e32 v141, v157
	v_lshlrev_b32_e32 v186, 16, v192
	v_and_b32_e32 v187, 0xffff0000, v192
	v_mov_b32_dpp v141, v188 row_ror:8 row_mask:0xf bank_mask:0xf
	v_mov_b32_dpp v214, v199 row_ror:8 row_mask:0xf bank_mask:0xf
	v_pk_mul_f32 v[186:187], v[140:141], v[186:187] op_sel_hi:[0,1]
	v_mov_b32_dpp v210, v195 row_ror:8 row_mask:0xf bank_mask:0xf
	v_cndmask_b32_e64 v195, v214, v195, s[0:1]
	v_lshlrev_b32_e32 v136, 16, v202
	v_and_b32_e32 v137, 0xffff0000, v202
	v_pk_mul_f32 v[186:187], v[56:57], v[186:187]
	v_mov_b32_dpp v212, v197 row_ror:8 row_mask:0xf bank_mask:0xf
	v_pk_fma_f32 v[136:137], v[184:185], v[186:187], v[136:137]
	v_lshlrev_b32_e32 v186, 16, v195
	v_and_b32_e32 v187, 0xffff0000, v195
	v_pk_mul_f32 v[186:187], v[140:141], v[186:187] op_sel_hi:[0,1]
	v_mov_b32_dpp v208, v193 row_ror:8 row_mask:0xf bank_mask:0xf
	v_cndmask_b32_e64 v193, v212, v193, s[0:1]
	v_lshlrev_b32_e32 v184, 16, v201
	v_and_b32_e32 v185, 0xffff0000, v201
	v_pk_mul_f32 v[186:187], v[62:63], v[186:187]
	v_mov_b32_dpp v209, v194 row_ror:8 row_mask:0xf bank_mask:0xf
	v_pk_fma_f32 v[184:185], v[138:139], v[186:187], v[184:185]
	v_lshlrev_b32_e32 v186, 16, v193
	v_and_b32_e32 v187, 0xffff0000, v193
	v_pk_mul_f32 v[186:187], v[140:141], v[186:187] op_sel_hi:[0,1]
	v_lshlrev_b32_e32 v138, 16, v200
	v_and_b32_e32 v139, 0xffff0000, v200
	v_pk_mul_f32 v[186:187], v[58:59], v[186:187]
	v_cndmask_b32_e64 v194, v197, v208, s[0:1]
	v_pk_fma_f32 v[138:139], v[142:143], v[186:187], v[138:139]
	v_mov_b32_e32 v142, v157
	v_mov_b32_e32 v143, v157
	v_cndmask_b32_e64 v197, v199, v210, s[0:1]
	v_cndmask_b32_e64 v198, v198, v209, s[0:1]
	v_mov_b32_e32 v199, v157
	v_mov_b32_e32 v195, v157
	v_mov_b32_e32 v201, v157
	v_mov_b32_dpp v142, v138 row_ror:8 row_mask:0xf bank_mask:0xf
	v_mov_b32_dpp v143, v139 row_ror:8 row_mask:0xf bank_mask:0xf
	v_mov_b32_dpp v199, v189 row_ror:8 row_mask:0xf bank_mask:0xf
	v_mov_b32_e32 v192, v157
	v_mov_b32_e32 v202, v157
	v_mov_b32_dpp v195, v184 row_ror:8 row_mask:0xf bank_mask:0xf
	v_mov_b32_dpp v201, v185 row_ror:8 row_mask:0xf bank_mask:0xf
	v_cndmask_b32_e64 v187, v185, v143, s[0:1]
	v_cndmask_b32_e64 v186, v184, v142, s[0:1]
	v_lshlrev_b32_e32 v142, 16, v198
	v_and_b32_e32 v143, 0xffff0000, v198
	v_mov_b32_dpp v192, v136 row_ror:8 row_mask:0xf bank_mask:0xf
	v_mov_b32_dpp v202, v137 row_ror:8 row_mask:0xf bank_mask:0xf
; __device__ __forceinline__ float bflo(unsigned w) { return __uint_as_float(w << 16); }
; __device__ __forceinline__ float bfhi(unsigned w) { return __uint_as_float(w & 0xffff0000u); }
; __device__ __forceinline__ unsigned dpp_ror8(unsigned x) { return (unsigned)__builtin_amdgcn_update_dpp(0, (int)x, 0x128, 0xf, 0xf, false); }
;     const bool lo = fr < 8;
;     const int r1 = row - fr + (fr & 7), cb = col0 + (lo ? 0 : boff);
;     const u32x4 l1 = *(const u32x4*)(P + (size_t)r1 * ld + cb), l2 = *(const u32x4*)(P + (size_t)(r1 + 8) * ld + cb);
;     const u32x4 s1 = {dpp_ror8(l1.x), dpp_ror8(l1.y), dpp_ror8(l1.z), dpp_ror8(l1.w)}, s2 = {dpp_ror8(l2.x), dpp_ror8(l2.y), dpp_ror8(l2.z), dpp_ror8(l2.w)};
;     wA = lo ? l1 : s2; wB = lo ? s1 : l2;
; }
;     __device__ __forceinline__ void operator()(const f32x4 (&acc)[2][2][4][2], const Unit& u, int wr, int wc, int fr, int fq) const {
;     ...
;                 float* orow = OUT + (size_t)(row - fr + (fr & 7)) * D + col0 + (lo ? 0 : 4);
; #pragma unroll
;                 for (int bj = 0; bj < 2; ++bj) { const u32x4 rw = rr[bj], ew = ee[bj];
;                     const float r[8] = {bflo(rw.x), bfhi(rw.x), bflo(rw.y), bfhi(rw.y), bflo(rw.z), bfhi(rw.z), bflo(rw.w), bfhi(rw.w)};
;                     const float e[8] = {bflo(ew.x), bfhi(ew.x), bflo(ew.y), bfhi(ew.y), bflo(ew.z), bfhi(ew.z), bflo(ew.w), bfhi(ew.w)};
;                     float o[8];
; #pragma unroll
;                     for (int j = 0; j < 8; ++j) { const float a = acc[ai][bj][m][j >> 2][j & 3]; const float gg = gv[bj][j >> 2][j & 3];
;                         o[j] = r[j] + e[j] * ri * gg * __builtin_amdgcn_rcpf(1.f + __builtin_amdgcn_exp2f(-a * LOG2E)); }
;                     f32x4 o1, o2;
; #pragma unroll
;                     for (int j = 0; j < 4; ++j) { const unsigned a = __float_as_uint(o[j]), b = __float_as_uint(o[4 + j]); const unsigned sa = dpp_ror8(a), sb = dpp_ror8(b);
;                         o1[j] = __uint_as_float(lo ? a : sb); o2[j] = __uint_as_float(lo ? sa : b); }
;                     *(f32x4*)(orow + 32 * bj) = o1; *(f32x4*)(orow + (size_t)8 * D + 32 * bj) = o2; } }
	v_cndmask_b32_e64 v139, v201, v139, s[0:1]
	v_cndmask_b32_e64 v138, v195, v138, s[0:1]
	v_cndmask_b32_e64 v137, v199, v137, s[0:1]
	v_cndmask_b32_e64 v136, v141, v136, s[0:1]
	v_pk_mul_f32 v[142:143], v[140:141], v[142:143] op_sel_hi:[0,1]
	v_cndmask_b32_e64 v196, v196, v207, s[0:1]
	global_store_dwordx4 v[172:173], v[136:139], off
	v_rcp_f32_e32 v133, v133
	v_pk_mul_f32 v[142:143], v[44:45], v[142:143]
	v_lshlrev_b32_e32 v138, 16, v190
	v_and_b32_e32 v139, 0xffff0000, v190
	v_exp_f32_e32 v134, v134
	v_exp_f32_e32 v135, v135
	v_pk_fma_f32 v[138:139], v[128:129], v[142:143], v[138:139]
	v_lshlrev_b32_e32 v142, 16, v196
	v_and_b32_e32 v143, 0xffff0000, v196
	v_add_f32_e32 v130, 1.0, v130
	v_add_f32_e32 v131, 1.0, v131
	v_pk_mul_f32 v[142:143], v[140:141], v[142:143] op_sel_hi:[0,1]
	v_rcp_f32_e32 v130, v130
	v_rcp_f32_e32 v131, v131
	v_lshlrev_b32_e32 v128, 16, v183
	v_and_b32_e32 v129, 0xffff0000, v183
	v_pk_mul_f32 v[142:143], v[40:41], v[142:143]
	v_add_f32_e32 v134, 1.0, v134
	v_pk_fma_f32 v[128:129], v[132:133], v[142:143], v[128:129]
	v_lshlrev_b32_e32 v142, 16, v197
	v_and_b32_e32 v143, 0xffff0000, v197
	v_add_f32_e32 v135, 1.0, v135
	v_pk_mul_f32 v[142:143], v[140:141], v[142:143] op_sel_hi:[0,1]
	v_rcp_f32_e32 v134, v134
	v_rcp_f32_e32 v135, v135
	v_lshlrev_b32_e32 v132, 16, v191
	v_and_b32_e32 v133, 0xffff0000, v191
	v_pk_mul_f32 v[142:143], v[46:47], v[142:143]
	v_add_co_u32_e32 v136, vcc, s45, v172
	v_pk_fma_f32 v[132:133], v[130:131], v[142:143], v[132:133]
	v_lshlrev_b32_e32 v142, 16, v194
	v_and_b32_e32 v143, 0xffff0000, v194
	v_cndmask_b32_e64 v185, v189, v202, s[0:1]
	v_cndmask_b32_e64 v184, v188, v192, s[0:1]
	v_addc_co_u32_e32 v137, vcc, 0, v173, vcc
	v_pk_mul_f32 v[140:141], v[140:141], v[142:143] op_sel_hi:[0,1]
	global_store_dwordx4 v[136:137], v[184:187], off
	v_mov_b32_e32 v188, v157
	v_lshlrev_b32_e32 v130, 16, v171
	v_mov_b32_e32 v184, v157
	v_mov_b32_e32 v185, v157
	v_mov_b32_e32 v187, v157
	v_and_b32_e32 v131, 0xffff0000, v171
	v_pk_mul_f32 v[140:141], v[42:43], v[140:141]
	v_mov_b32_dpp v184, v138 row_ror:8 row_mask:0xf bank_mask:0xf
	v_mov_b32_dpp v185, v139 row_ror:8 row_mask:0xf bank_mask:0xf
	v_mov_b32_e32 v183, v157
	v_mov_b32_e32 v186, v157
	v_mov_b32_dpp v187, v132 row_ror:8 row_mask:0xf bank_mask:0xf
	v_mov_b32_dpp v188, v133 row_ror:8 row_mask:0xf bank_mask:0xf
	v_pk_fma_f32 v[130:131], v[134:135], v[140:141], v[130:131]
	v_mov_b32_e32 v134, v157
	v_mov_b32_e32 v135, v157
	v_mov_b32_dpp v183, v128 row_ror:8 row_mask:0xf bank_mask:0xf
	v_mov_b32_dpp v186, v129 row_ror:8 row_mask:0xf bank_mask:0xf
	v_mov_b32_dpp v134, v130 row_ror:8 row_mask:0xf bank_mask:0xf
	v_mov_b32_dpp v135, v131 row_ror:8 row_mask:0xf bank_mask:0xf
	v_cndmask_b32_e64 v131, v188, v131, s[0:1]
	v_cndmask_b32_e64 v130, v187, v130, s[0:1]
	v_cndmask_b32_e64 v129, v185, v129, s[0:1]
	v_cndmask_b32_e64 v128, v184, v128, s[0:1]
	v_cndmask_b32_e64 v135, v133, v135, s[0:1]
	v_cndmask_b32_e64 v134, v132, v134, s[0:1]
	v_cndmask_b32_e64 v133, v139, v186, s[0:1]
	v_cndmask_b32_e64 v132, v138, v183, s[0:1]
	global_store_dwordx4 v[172:173], v[128:131], off offset:128
	global_store_dwordx4 v[136:137], v[132:135], off offset:128
	v_mov_b32_e32 v183, v157
	v_or_b32_e32 v128, 16, v170
	v_ashrrev_i32_e32 v129, 31, v128
	v_lshl_add_u64 v[130:131], v[128:129], 2, s[6:7]
	v_sub_u32_e32 v128, v128, v174
	v_add_u32_e32 v142, v128, v176
	v_ashrrev_i32_e32 v143, 31, v142
	v_lshlrev_b64 v[128:129], 12, v[142:143]
	v_lshl_add_u64 v[172:173], v[128:129], 0, s[16:17]
	s_waitcnt vmcnt(4)
	s_nop 0
	v_mov_b32_e32 v171, v228
	v_lshl_add_u64 v[130:131], s[8:9], 0, v[128:129]
	v_lshl_add_u64 v[134:135], s[8:9], 0, v[172:173]
	v_lshl_add_u64 v[128:129], s[10:11], 0, v[128:129]
	v_lshl_add_u64 v[130:131], v[130:131], 0, v[164:165]
	v_lshl_add_u64 v[134:135], v[134:135], 0, v[164:165]
	v_lshl_add_u64 v[128:129], v[128:129], 0, v[164:165]
	v_mov_b64_e32 v[130:131], v[232:233]
	v_mov_b64_e32 v[132:133], v[234:235]
	v_mov_b32_e32 v189, v157
	v_mov_b64_e32 v[134:135], v[236:237]
	v_mov_b64_e32 v[136:137], v[238:239]
	v_mov_b32_e32 v190, v157
	v_mov_b64_e32 v[138:139], v[240:241]
	v_mov_b64_e32 v[140:141], v[242:243]
	v_lshl_add_u64 v[128:129], s[10:11], 0, v[172:173]
	v_lshl_add_u64 v[128:129], v[128:129], 0, v[164:165]
	v_mov_b64_e32 v[184:185], v[244:245]
	v_mov_b64_e32 v[186:187], v[246:247]
	s_nop 1
	v_or_b32_e32 v216, 32, v170
	v_ashrrev_i32_e32 v217, 31, v216
	v_lshl_add_u64 v[218:219], v[216:217], 2, s[6:7]
	v_sub_u32_e32 v216, v216, v174
	v_add_u32_e32 v224, v216, v176
	v_ashrrev_i32_e32 v225, 31, v224
	v_lshlrev_b64 v[216:217], 12, v[224:225]
	v_lshl_add_u64 v[222:223], v[216:217], 0, s[16:17]
	v_lshl_add_u64 v[220:221], s[8:9], 0, v[222:223]
	global_load_dword v228, v[218:219], off
	v_lshl_add_u64 v[218:219], s[8:9], 0, v[216:217]
	v_lshl_add_u64 v[220:221], v[220:221], 0, v[164:165]
	v_lshl_add_u64 v[216:217], s[10:11], 0, v[216:217]
	v_lshl_add_u64 v[218:219], v[218:219], 0, v[164:165]
	global_load_dwordx4 v[232:235], v[220:221], off
	v_lshl_add_u64 v[216:217], v[216:217], 0, v[164:165]
	global_load_dwordx4 v[236:239], v[218:219], off
	global_load_dwordx4 v[240:243], v[216:217], off
	v_lshl_add_u64 v[216:217], s[10:11], 0, v[222:223]
	v_lshl_add_u64 v[216:217], v[216:217], 0, v[164:165]
	global_load_dwordx4 v[244:247], v[216:217], off
	v_mov_b32_e32 v173, v157
	v_mov_b32_e32 v129, v157
	v_mov_b32_e32 v172, v157
	v_mov_b32_e32 v188, v157
	v_mul_f32_e32 v120, 0xbfb8aa3b, v120
	v_mul_f32_e32 v121, 0xbfb8aa3b, v121
	v_mul_f32_e32 v124, 0xbfb8aa3b, v124
	v_exp_f32_e32 v120, v120
	v_exp_f32_e32 v121, v121
	v_mul_f32_e32 v122, 0xbfb8aa3b, v122
	v_mul_f32_e32 v123, 0xbfb8aa3b, v123
; __device__ __forceinline__ float bflo(unsigned w) { return __uint_as_float(w << 16); }
; __device__ __forceinline__ float bfhi(unsigned w) { return __uint_as_float(w & 0xffff0000u); }
; __device__ __forceinline__ unsigned dpp_ror8(unsigned x) { return (unsigned)__builtin_amdgcn_update_dpp(0, (int)x, 0x128, 0xf, 0xf, false); }
;     __device__ __forceinline__ void operator()(const f32x4 (&acc)[2][2][4][2], const Unit& u, int wr, int wc, int fr, int fq) const {
;     ...
;             for (int m = 0; m < 4; ++m) { const int row = row0 + ai * HALF + m * 16; const float ri = __builtin_amdgcn_rsqf(sse[row] * (1.f / D) + EPS);
;                 u32x4 rr[2], ee[2]; load_pair_lines(R, D, row, fr, col0, rr[0], rr[1], 32); load_pair_lines(E, D, row, fr, col0, ee[0], ee[1], 32);
;                 float* orow = OUT + (size_t)(row - fr + (fr & 7)) * D + col0 + (lo ? 0 : 4);
; #pragma unroll
;                 for (int bj = 0; bj < 2; ++bj) { const u32x4 rw = rr[bj], ew = ee[bj];
;                     const float r[8] = {bflo(rw.x), bfhi(rw.x), bflo(rw.y), bfhi(rw.y), bflo(rw.z), bfhi(rw.z), bflo(rw.w), bfhi(rw.w)};
;                     const float e[8] = {bflo(ew.x), bfhi(ew.x), bflo(ew.y), bfhi(ew.y), bflo(ew.z), bfhi(ew.z), bflo(ew.w), bfhi(ew.w)};
;                     float o[8];
; #pragma unroll
;                     for (int j = 0; j < 8; ++j) { const float a = acc[ai][bj][m][j >> 2][j & 3]; const float gg = gv[bj][j >> 2][j & 3];
;                         o[j] = r[j] + e[j] * ri * gg * __builtin_amdgcn_rcpf(1.f + __builtin_amdgcn_exp2f(-a * LOG2E)); }
;                     f32x4 o1, o2;
; #pragma unroll
;                     for (int j = 0; j < 4; ++j) { const unsigned a = __float_as_uint(o[j]), b = __float_as_uint(o[4 + j]); const unsigned sa = dpp_ror8(a), sb = dpp_ror8(b);
;                         o1[j] = __uint_as_float(lo ? a : sb); o2[j] = __uint_as_float(lo ? sa : b); }
;                     *(f32x4*)(orow + 32 * bj) = o1; *(f32x4*)(orow + (size_t)8 * D + 32 * bj) = o2; } }
	v_add_f32_e32 v120, 1.0, v120
	v_add_f32_e32 v121, 1.0, v121
	v_rcp_f32_e32 v120, v120
	v_rcp_f32_e32 v121, v121
	v_exp_f32_e32 v122, v122
	v_exp_f32_e32 v123, v123
	v_mul_f32_e32 v126, 0xbfb8aa3b, v126
	v_mul_f32_e32 v127, 0xbfb8aa3b, v127
	v_exp_f32_e32 v126, v126
	v_exp_f32_e32 v127, v127
	v_add_f32_e32 v122, 1.0, v122
	v_add_f32_e32 v123, 1.0, v123
	v_rcp_f32_e32 v122, v122
	v_rcp_f32_e32 v123, v123
	v_add_f32_e32 v126, 1.0, v126
	v_add_f32_e32 v127, 1.0, v127
	v_mul_f32_e32 v112, 0xbfb8aa3b, v112
	v_mul_f32_e32 v113, 0xbfb8aa3b, v113
	v_rcp_f32_e32 v126, v126
	v_rcp_f32_e32 v127, v127
	v_exp_f32_e32 v112, v112
	v_exp_f32_e32 v113, v113
	v_mul_f32_e32 v116, 0xbfb8aa3b, v116
	v_mul_f32_e32 v117, 0xbfb8aa3b, v117
	v_exp_f32_e32 v116, v116
	v_exp_f32_e32 v117, v117
	v_add_f32_e32 v112, 1.0, v112
	v_add_f32_e32 v113, 1.0, v113
	v_rcp_f32_e32 v112, v112
	v_rcp_f32_e32 v113, v113
	v_mul_f32_e32 v114, 0xbfb8aa3b, v114
	v_mul_f32_e32 v115, 0xbfb8aa3b, v115
	v_add_f32_e32 v116, 1.0, v116
	v_add_f32_e32 v117, 1.0, v117
	v_exp_f32_e32 v114, v114
	v_exp_f32_e32 v115, v115
	v_rcp_f32_e32 v116, v116
	v_rcp_f32_e32 v117, v117
	v_mul_f32_e32 v118, 0xbfb8aa3b, v118
	v_mul_f32_e32 v119, 0xbfb8aa3b, v119
	v_exp_f32_e32 v118, v118
	v_exp_f32_e32 v119, v119
	v_add_f32_e32 v114, 1.0, v114
	v_add_f32_e32 v115, 1.0, v115
	v_rcp_f32_e32 v114, v114
	v_rcp_f32_e32 v115, v115
	v_add_f32_e32 v118, 1.0, v118
	v_add_f32_e32 v119, 1.0, v119
	v_rcp_f32_e32 v118, v118
	v_rcp_f32_e32 v119, v119
	v_mul_f32_e32 v104, 0xbfb8aa3b, v104
	v_mul_f32_e32 v105, 0xbfb8aa3b, v105
	v_mul_f32_e32 v108, 0xbfb8aa3b, v108
	v_exp_f32_e32 v104, v104
	s_waitcnt vmcnt(14)
	v_fmamk_f32 v128, v171, 0x3a000000, v182
	v_mov_b32_e32 v171, v157
	v_rsq_f32_e32 v128, v128
	v_exp_f32_e32 v105, v105
	v_add_f32_e32 v104, 1.0, v104
	v_rcp_f32_e32 v104, v104
	v_mul_f32_e32 v106, 0xbfb8aa3b, v106
	v_mov_b32_dpp v171, v131 row_ror:8 row_mask:0xf bank_mask:0xf
	v_mov_b32_dpp v173, v133 row_ror:8 row_mask:0xf bank_mask:0xf
	v_mov_b32_dpp v183, v134 row_ror:8 row_mask:0xf bank_mask:0xf
	v_mov_b32_dpp v189, v136 row_ror:8 row_mask:0xf bank_mask:0xf
	v_mov_b32_dpp v190, v137 row_ror:8 row_mask:0xf bank_mask:0xf
	v_mov_b32_dpp v129, v130 row_ror:8 row_mask:0xf bank_mask:0xf
	v_mov_b32_dpp v172, v132 row_ror:8 row_mask:0xf bank_mask:0xf
	v_mov_b32_dpp v188, v135 row_ror:8 row_mask:0xf bank_mask:0xf
	v_cndmask_b32_e64 v190, v190, v133, s[0:1]
	v_cndmask_b32_e64 v183, v183, v130, s[0:1]
	v_cndmask_b32_e64 v133, v189, v132, s[0:1]
	v_cndmask_b32_e64 v171, v135, v171, s[0:1]
	v_cndmask_b32_e64 v137, v137, v173, s[0:1]
	v_mov_b32_e32 v130, v157
	v_mov_b32_e32 v132, v157
	v_mov_b32_e32 v135, v157
	v_mov_b32_e32 v173, v157
	v_cndmask_b32_e64 v129, v134, v129, s[0:1]
	v_cndmask_b32_e64 v136, v136, v172, s[0:1]
	v_mov_b32_dpp v130, v138 row_ror:8 row_mask:0xf bank_mask:0xf
	v_mov_b32_dpp v132, v140 row_ror:8 row_mask:0xf bank_mask:0xf
	v_mov_b32_e32 v134, v157
	v_mov_b32_dpp v135, v184 row_ror:8 row_mask:0xf bank_mask:0xf
	v_mov_b32_e32 v172, v157
	v_mov_b32_dpp v173, v186 row_ror:8 row_mask:0xf bank_mask:0xf
	v_cndmask_b32_e64 v188, v188, v131, s[0:1]
	v_mov_b32_e32 v131, v157
	v_mov_b32_dpp v134, v141 row_ror:8 row_mask:0xf bank_mask:0xf
	v_mov_b32_dpp v172, v185 row_ror:8 row_mask:0xf bank_mask:0xf
	v_cndmask_b32_e64 v138, v135, v138, s[0:1]
	v_cndmask_b32_e64 v135, v173, v140, s[0:1]
	v_cndmask_b32_e64 v173, v184, v130, s[0:1]
	v_cndmask_b32_e64 v184, v186, v132, s[0:1]
	v_exp_f32_e32 v132, v124
	v_mul_f32_e32 v124, 0xbfb8aa3b, v125
	v_mov_b32_dpp v131, v139 row_ror:8 row_mask:0xf bank_mask:0xf
	v_cndmask_b32_e64 v139, v172, v139, s[0:1]
	v_cndmask_b32_e64 v172, v187, v134, s[0:1]
	v_exp_f32_e32 v134, v124
	v_cndmask_b32_e64 v140, v185, v131, s[0:1]
	v_lshlrev_b64 v[130:131], 13, v[142:143]
	v_lshl_add_u64 v[130:131], s[4:5], 0, v[130:131]
	v_lshl_add_u64 v[130:131], v[130:131], 0, v[166:167]
	v_lshl_add_u64 v[124:125], v[130:131], 0, v[156:157]
	v_add_f32_e32 v131, 1.0, v134
	v_lshlrev_b32_e32 v134, 16, v135
	v_and_b32_e32 v135, 0xffff0000, v135
	v_add_f32_e32 v130, 1.0, v132
	v_pk_mul_f32 v[134:135], v[128:129], v[134:135] op_sel_hi:[0,1]
	v_rcp_f32_e32 v130, v130
	v_rcp_f32_e32 v131, v131
	v_lshlrev_b32_e32 v132, 16, v133
	v_and_b32_e32 v133, 0xffff0000, v133
	v_pk_mul_f32 v[134:135], v[60:61], v[134:135]
	v_mov_b32_e32 v189, v157
	v_pk_fma_f32 v[134:135], v[120:121], v[134:135], v[132:133]
	v_lshlrev_b32_e32 v132, 16, v138
	v_and_b32_e32 v133, 0xffff0000, v138
	v_mov_b32_dpp v189, v187 row_ror:8 row_mask:0xf bank_mask:0xf
	v_pk_mul_f32 v[132:133], v[128:129], v[132:133] op_sel_hi:[0,1]
	v_cndmask_b32_e64 v141, v189, v141, s[0:1]
	v_lshlrev_b32_e32 v120, 16, v183
	v_and_b32_e32 v121, 0xffff0000, v183
	v_pk_mul_f32 v[132:133], v[56:57], v[132:133]
	v_mov_b32_e32 v142, v157
	v_pk_fma_f32 v[120:121], v[130:131], v[132:133], v[120:121]
	v_lshlrev_b32_e32 v132, 16, v141
	v_and_b32_e32 v133, 0xffff0000, v141
	v_pk_mul_f32 v[132:133], v[128:129], v[132:133] op_sel_hi:[0,1]
	v_lshlrev_b32_e32 v130, 16, v190
	v_and_b32_e32 v131, 0xffff0000, v190
	v_pk_mul_f32 v[132:133], v[62:63], v[132:133]
	v_mov_b32_e32 v143, v157
	v_pk_fma_f32 v[130:131], v[122:123], v[132:133], v[130:131]
	v_lshlrev_b32_e32 v132, 16, v139
	v_and_b32_e32 v133, 0xffff0000, v139
	v_pk_mul_f32 v[132:133], v[128:129], v[132:133] op_sel_hi:[0,1]
	v_lshlrev_b32_e32 v122, 16, v188
	v_and_b32_e32 v123, 0xffff0000, v188
	v_pk_mul_f32 v[132:133], v[58:59], v[132:133]
	v_mov_b32_e32 v141, v157
	v_pk_fma_f32 v[122:123], v[126:127], v[132:133], v[122:123]
	v_mov_b32_e32 v126, v157
	v_mov_b32_e32 v127, v157
	v_mov_b32_e32 v185, v157
; __device__ __forceinline__ float bflo(unsigned w) { return __uint_as_float(w << 16); }
; __device__ __forceinline__ float bfhi(unsigned w) { return __uint_as_float(w & 0xffff0000u); }
; __device__ __forceinline__ unsigned dpp_ror8(unsigned x) { return (unsigned)__builtin_amdgcn_update_dpp(0, (int)x, 0x128, 0xf, 0xf, false); }
;     __device__ __forceinline__ void operator()(const f32x4 (&acc)[2][2][4][2], const Unit& u, int wr, int wc, int fr, int fq) const {
;     ...
;                 float* orow = OUT + (size_t)(row - fr + (fr & 7)) * D + col0 + (lo ? 0 : 4);
; #pragma unroll
;                 for (int bj = 0; bj < 2; ++bj) { const u32x4 rw = rr[bj], ew = ee[bj];
;                     const float r[8] = {bflo(rw.x), bfhi(rw.x), bflo(rw.y), bfhi(rw.y), bflo(rw.z), bfhi(rw.z), bflo(rw.w), bfhi(rw.w)};
;                     const float e[8] = {bflo(ew.x), bfhi(ew.x), bflo(ew.y), bfhi(ew.y), bflo(ew.z), bfhi(ew.z), bflo(ew.w), bfhi(ew.w)};
;                     float o[8];
; #pragma unroll
;                     for (int j = 0; j < 8; ++j) { const float a = acc[ai][bj][m][j >> 2][j & 3]; const float gg = gv[bj][j >> 2][j & 3];
;                         o[j] = r[j] + e[j] * ri * gg * __builtin_amdgcn_rcpf(1.f + __builtin_amdgcn_exp2f(-a * LOG2E)); }
;                     f32x4 o1, o2;
; #pragma unroll
;                     for (int j = 0; j < 4; ++j) { const unsigned a = __float_as_uint(o[j]), b = __float_as_uint(o[4 + j]); const unsigned sa = dpp_ror8(a), sb = dpp_ror8(b);
;                         o1[j] = __uint_as_float(lo ? a : sb); o2[j] = __uint_as_float(lo ? sa : b); }
;                     *(f32x4*)(orow + 32 * bj) = o1; *(f32x4*)(orow + (size_t)8 * D + 32 * bj) = o2; } }
	v_mov_b32_dpp v126, v122 row_ror:8 row_mask:0xf bank_mask:0xf
	v_mov_b32_dpp v127, v123 row_ror:8 row_mask:0xf bank_mask:0xf
	v_mov_b32_dpp v142, v134 row_ror:8 row_mask:0xf bank_mask:0xf
	v_mov_b32_dpp v143, v135 row_ror:8 row_mask:0xf bank_mask:0xf
	v_mov_b32_e32 v138, v157
	v_mov_b32_e32 v183, v157
	v_mov_b32_dpp v141, v130 row_ror:8 row_mask:0xf bank_mask:0xf
	v_mov_b32_dpp v185, v131 row_ror:8 row_mask:0xf bank_mask:0xf
	v_cndmask_b32_e64 v133, v131, v127, s[0:1]
	v_cndmask_b32_e64 v132, v130, v126, s[0:1]
	v_lshlrev_b32_e32 v126, 16, v184
	v_and_b32_e32 v127, 0xffff0000, v184
	v_mov_b32_dpp v138, v120 row_ror:8 row_mask:0xf bank_mask:0xf
	v_mov_b32_dpp v183, v121 row_ror:8 row_mask:0xf bank_mask:0xf
	v_cndmask_b32_e64 v123, v185, v123, s[0:1]
	v_cndmask_b32_e64 v122, v141, v122, s[0:1]
	v_cndmask_b32_e64 v121, v143, v121, s[0:1]
	v_cndmask_b32_e64 v120, v142, v120, s[0:1]
	v_pk_mul_f32 v[126:127], v[128:129], v[126:127] op_sel_hi:[0,1]
	global_store_dwordx4 v[124:125], v[120:123], off
	v_pk_mul_f32 v[126:127], v[44:45], v[126:127]
	v_cndmask_b32_e64 v131, v135, v183, s[0:1]
	v_lshlrev_b32_e32 v122, 16, v136
	v_and_b32_e32 v123, 0xffff0000, v136
	v_pk_fma_f32 v[122:123], v[112:113], v[126:127], v[122:123]
	v_lshlrev_b32_e32 v126, 16, v173
	v_and_b32_e32 v127, 0xffff0000, v173
	v_pk_mul_f32 v[126:127], v[128:129], v[126:127] op_sel_hi:[0,1]
	v_lshlrev_b32_e32 v112, 16, v129
	v_and_b32_e32 v113, 0xffff0000, v129
	v_pk_mul_f32 v[126:127], v[40:41], v[126:127]
	v_mov_b32_e32 v129, v157
	v_pk_fma_f32 v[112:113], v[116:117], v[126:127], v[112:113]
	v_lshlrev_b32_e32 v126, 16, v172
	v_and_b32_e32 v127, 0xffff0000, v172
	v_mov_b32_dpp v129, v112 row_ror:8 row_mask:0xf bank_mask:0xf
	v_pk_mul_f32 v[126:127], v[128:129], v[126:127] op_sel_hi:[0,1]
	v_lshlrev_b32_e32 v116, 16, v137
	v_and_b32_e32 v117, 0xffff0000, v137
	v_pk_mul_f32 v[126:127], v[46:47], v[126:127]
	v_add_co_u32_e32 v120, vcc, s45, v124
	v_pk_fma_f32 v[116:117], v[114:115], v[126:127], v[116:117]
	v_lshlrev_b32_e32 v126, 16, v140
	v_and_b32_e32 v127, 0xffff0000, v140
	v_cndmask_b32_e64 v130, v134, v138, s[0:1]
	v_addc_co_u32_e32 v121, vcc, 0, v125, vcc
	v_pk_mul_f32 v[126:127], v[128:129], v[126:127] op_sel_hi:[0,1]
	global_store_dwordx4 v[120:121], v[130:133], off
	v_mov_b32_e32 v134, v157
	v_lshlrev_b32_e32 v114, 16, v171
	v_mov_b32_e32 v130, v157
	v_mov_b32_e32 v131, v157
	v_mov_b32_e32 v133, v157
	v_and_b32_e32 v115, 0xffff0000, v171
	v_pk_mul_f32 v[126:127], v[42:43], v[126:127]
	v_mov_b32_dpp v130, v122 row_ror:8 row_mask:0xf bank_mask:0xf
	v_mov_b32_dpp v131, v123 row_ror:8 row_mask:0xf bank_mask:0xf
	v_mov_b32_e32 v132, v157
	v_mov_b32_dpp v133, v116 row_ror:8 row_mask:0xf bank_mask:0xf
	v_mov_b32_dpp v134, v117 row_ror:8 row_mask:0xf bank_mask:0xf
	v_pk_fma_f32 v[114:115], v[118:119], v[126:127], v[114:115]
	v_mov_b32_e32 v118, v157
	v_mov_b32_e32 v119, v157
	v_mov_b32_dpp v132, v113 row_ror:8 row_mask:0xf bank_mask:0xf
	v_mov_b32_dpp v118, v114 row_ror:8 row_mask:0xf bank_mask:0xf
	v_mov_b32_dpp v119, v115 row_ror:8 row_mask:0xf bank_mask:0xf
	v_cndmask_b32_e64 v115, v134, v115, s[0:1]
	v_cndmask_b32_e64 v114, v133, v114, s[0:1]
	v_cndmask_b32_e64 v113, v131, v113, s[0:1]
	v_cndmask_b32_e64 v112, v130, v112, s[0:1]
	v_cndmask_b32_e64 v119, v117, v119, s[0:1]
	v_cndmask_b32_e64 v118, v116, v118, s[0:1]
	v_cndmask_b32_e64 v117, v123, v132, s[0:1]
	v_cndmask_b32_e64 v116, v122, v129, s[0:1]
	global_store_dwordx4 v[124:125], v[112:115], off offset:128
	global_store_dwordx4 v[120:121], v[116:119], off offset:128
	v_mov_b32_e32 v137, v157
	v_or_b32_e32 v112, 32, v170
	v_ashrrev_i32_e32 v113, 31, v112
	v_lshl_add_u64 v[114:115], v[112:113], 2, s[6:7]
	v_sub_u32_e32 v112, v112, v174
	v_add_u32_e32 v130, v112, v176
	v_ashrrev_i32_e32 v131, 31, v130
	v_lshlrev_b64 v[112:113], 12, v[130:131]
	v_lshl_add_u64 v[126:127], v[112:113], 0, s[16:17]
	v_lshl_add_u64 v[118:119], s[8:9], 0, v[126:127]
	s_waitcnt vmcnt(4)
	s_nop 0
	v_mov_b32_e32 v132, v228
	v_lshl_add_u64 v[114:115], s[8:9], 0, v[112:113]
	v_lshl_add_u64 v[118:119], v[118:119], 0, v[164:165]
	v_lshl_add_u64 v[112:113], s[10:11], 0, v[112:113]
	v_lshl_add_u64 v[114:115], v[114:115], 0, v[164:165]
	v_mov_b64_e32 v[118:119], v[232:233]
	v_mov_b64_e32 v[120:121], v[234:235]
	v_lshl_add_u64 v[112:113], v[112:113], 0, v[164:165]
	v_mov_b64_e32 v[114:115], v[236:237]
	v_mov_b64_e32 v[116:117], v[238:239]
	v_mov_b32_e32 v138, v157
	v_mov_b64_e32 v[122:123], v[240:241]
	v_mov_b64_e32 v[124:125], v[242:243]
	v_lshl_add_u64 v[112:113], s[10:11], 0, v[126:127]
	v_lshl_add_u64 v[112:113], v[112:113], 0, v[164:165]
	v_mov_b64_e32 v[126:127], v[244:245]
	v_mov_b64_e32 v[128:129], v[246:247]
	s_nop 1
	v_or_b32_e32 v216, 48, v170
	v_ashrrev_i32_e32 v217, 31, v216
	v_lshl_add_u64 v[218:219], v[216:217], 2, s[6:7]
	v_sub_u32_e32 v216, v216, v174
	v_add_u32_e32 v224, v216, v176
	v_ashrrev_i32_e32 v225, 31, v224
	v_lshlrev_b64 v[216:217], 12, v[224:225]
	v_lshl_add_u64 v[222:223], v[216:217], 0, s[16:17]
	v_lshl_add_u64 v[220:221], s[8:9], 0, v[222:223]
	global_load_dword v228, v[218:219], off
	v_lshl_add_u64 v[218:219], s[8:9], 0, v[216:217]
	v_lshl_add_u64 v[220:221], v[220:221], 0, v[164:165]
	v_lshl_add_u64 v[216:217], s[10:11], 0, v[216:217]
	v_lshl_add_u64 v[218:219], v[218:219], 0, v[164:165]
	global_load_dwordx4 v[232:235], v[220:221], off
	v_lshl_add_u64 v[216:217], v[216:217], 0, v[164:165]
	global_load_dwordx4 v[236:239], v[218:219], off
	global_load_dwordx4 v[240:243], v[216:217], off
	v_lshl_add_u64 v[216:217], s[10:11], 0, v[222:223]
	v_lshl_add_u64 v[216:217], v[216:217], 0, v[164:165]
	global_load_dwordx4 v[244:247], v[216:217], off
; __device__ __forceinline__ float bflo(unsigned w) { return __uint_as_float(w << 16); }
; __device__ __forceinline__ float bfhi(unsigned w) { return __uint_as_float(w & 0xffff0000u); }
; __device__ __forceinline__ unsigned dpp_ror8(unsigned x) { return (unsigned)__builtin_amdgcn_update_dpp(0, (int)x, 0x128, 0xf, 0xf, false); }
;     __device__ __forceinline__ void operator()(const f32x4 (&acc)[2][2][4][2], const Unit& u, int wr, int wc, int fr, int fq) const {
;     ...
;             for (int m = 0; m < 4; ++m) { const int row = row0 + ai * HALF + m * 16; const float ri = __builtin_amdgcn_rsqf(sse[row] * (1.f / D) + EPS);
;                 u32x4 rr[2], ee[2]; load_pair_lines(R, D, row, fr, col0, rr[0], rr[1], 32); load_pair_lines(E, D, row, fr, col0, ee[0], ee[1], 32);
;                 float* orow = OUT + (size_t)(row - fr + (fr & 7)) * D + col0 + (lo ? 0 : 4);
; #pragma unroll
;                 for (int bj = 0; bj < 2; ++bj) { const u32x4 rw = rr[bj], ew = ee[bj];
;                     const float r[8] = {bflo(rw.x), bfhi(rw.x), bflo(rw.y), bfhi(rw.y), bflo(rw.z), bfhi(rw.z), bflo(rw.w), bfhi(rw.w)};
;                     const float e[8] = {bflo(ew.x), bfhi(ew.x), bflo(ew.y), bfhi(ew.y), bflo(ew.z), bfhi(ew.z), bflo(ew.w), bfhi(ew.w)};
;                     float o[8];
; #pragma unroll
;                     for (int j = 0; j < 8; ++j) { const float a = acc[ai][bj][m][j >> 2][j & 3]; const float gg = gv[bj][j >> 2][j & 3];
;                         o[j] = r[j] + e[j] * ri * gg * __builtin_amdgcn_rcpf(1.f + __builtin_amdgcn_exp2f(-a * LOG2E)); }
;                     f32x4 o1, o2;
; #pragma unroll
;                     for (int j = 0; j < 4; ++j) { const unsigned a = __float_as_uint(o[j]), b = __float_as_uint(o[4 + j]); const unsigned sa = dpp_ror8(a), sb = dpp_ror8(b);
;                         o1[j] = __uint_as_float(lo ? a : sb); o2[j] = __uint_as_float(lo ? sa : b); }
;                     *(f32x4*)(orow + 32 * bj) = o1; *(f32x4*)(orow + (size_t)8 * D + 32 * bj) = o2; } }
	v_mov_b32_e32 v113, v157
	v_mov_b32_e32 v133, v157
	v_mov_b32_e32 v134, v157
	v_mov_b32_e32 v136, v157
	v_mov_b32_e32 v135, v157
	v_add_f32_e32 v105, 1.0, v105
	v_mul_f32_e32 v107, 0xbfb8aa3b, v107
	v_rcp_f32_e32 v105, v105
	v_exp_f32_e32 v106, v106
	v_exp_f32_e32 v107, v107
	v_mul_f32_e32 v110, 0xbfb8aa3b, v110
	v_mul_f32_e32 v111, 0xbfb8aa3b, v111
	v_exp_f32_e32 v110, v110
	v_exp_f32_e32 v111, v111
	v_add_f32_e32 v106, 1.0, v106
	v_add_f32_e32 v107, 1.0, v107
	v_rcp_f32_e32 v106, v106
	v_rcp_f32_e32 v107, v107
	v_add_f32_e32 v110, 1.0, v110
	v_add_f32_e32 v111, 1.0, v111
	v_mul_f32_e32 v96, 0xbfb8aa3b, v96
	v_mul_f32_e32 v97, 0xbfb8aa3b, v97
	v_rcp_f32_e32 v110, v110
	v_rcp_f32_e32 v111, v111
	v_exp_f32_e32 v96, v96
	v_exp_f32_e32 v97, v97
	v_mul_f32_e32 v100, 0xbfb8aa3b, v100
	v_mul_f32_e32 v101, 0xbfb8aa3b, v101
	v_exp_f32_e32 v100, v100
	v_exp_f32_e32 v101, v101
	v_add_f32_e32 v96, 1.0, v96
	v_add_f32_e32 v97, 1.0, v97
	v_rcp_f32_e32 v96, v96
	v_rcp_f32_e32 v97, v97
	v_mul_f32_e32 v98, 0xbfb8aa3b, v98
	v_mul_f32_e32 v99, 0xbfb8aa3b, v99
	v_add_f32_e32 v100, 1.0, v100
	v_add_f32_e32 v101, 1.0, v101
	v_exp_f32_e32 v98, v98
	v_exp_f32_e32 v99, v99
	v_rcp_f32_e32 v100, v100
	v_rcp_f32_e32 v101, v101
	v_mul_f32_e32 v102, 0xbfb8aa3b, v102
	v_mul_f32_e32 v103, 0xbfb8aa3b, v103
	v_exp_f32_e32 v102, v102
	v_exp_f32_e32 v103, v103
	v_add_f32_e32 v98, 1.0, v98
	v_add_f32_e32 v99, 1.0, v99
	v_rcp_f32_e32 v98, v98
	v_rcp_f32_e32 v99, v99
	v_add_f32_e32 v102, 1.0, v102
	v_add_f32_e32 v103, 1.0, v103
	v_rcp_f32_e32 v102, v102
	v_rcp_f32_e32 v103, v103
	v_mul_f32_e32 v88, 0xbfb8aa3b, v88
	v_mul_f32_e32 v89, 0xbfb8aa3b, v89
	v_mul_f32_e32 v92, 0xbfb8aa3b, v92
	v_exp_f32_e32 v88, v88
	v_exp_f32_e32 v89, v89
	v_mul_f32_e32 v90, 0xbfb8aa3b, v90
	v_mul_f32_e32 v91, 0xbfb8aa3b, v91
	v_add_f32_e32 v88, 1.0, v88
	v_add_f32_e32 v89, 1.0, v89
	v_rcp_f32_e32 v88, v88
	v_rcp_f32_e32 v89, v89
	v_exp_f32_e32 v90, v90
	v_exp_f32_e32 v91, v91
	s_waitcnt vmcnt(23)
	v_fmamk_f32 v112, v132, 0x3a000000, v182
	v_mov_b32_e32 v132, v157
	v_rsq_f32_e32 v112, v112
	v_mul_f32_e32 v94, 0xbfb8aa3b, v94
	v_mul_f32_e32 v95, 0xbfb8aa3b, v95
	v_mov_b32_dpp v137, v120 row_ror:8 row_mask:0xf bank_mask:0xf
	v_mov_b32_dpp v138, v121 row_ror:8 row_mask:0xf bank_mask:0xf
	v_mov_b32_dpp v113, v114 row_ror:8 row_mask:0xf bank_mask:0xf
	v_mov_b32_dpp v132, v115 row_ror:8 row_mask:0xf bank_mask:0xf
	v_mov_b32_dpp v133, v116 row_ror:8 row_mask:0xf bank_mask:0xf
	v_mov_b32_dpp v134, v117 row_ror:8 row_mask:0xf bank_mask:0xf
	v_mov_b32_dpp v136, v119 row_ror:8 row_mask:0xf bank_mask:0xf
	v_cndmask_b32_e64 v138, v138, v117, s[0:1]
	v_cndmask_b32_e64 v117, v137, v116, s[0:1]
	v_mov_b32_e32 v116, v157
	v_mov_b32_dpp v135, v118 row_ror:8 row_mask:0xf bank_mask:0xf
	v_cndmask_b32_e64 v136, v136, v115, s[0:1]
	v_cndmask_b32_e64 v132, v119, v132, s[0:1]
	v_cndmask_b32_e64 v121, v121, v134, s[0:1]
	v_cndmask_b32_e64 v113, v118, v113, s[0:1]
	v_mov_b32_e32 v115, v157
	v_mov_b32_dpp v116, v124 row_ror:8 row_mask:0xf bank_mask:0xf
	v_mov_b32_e32 v118, v157
	v_mov_b32_e32 v119, v157
	v_mov_b32_e32 v134, v157
	v_cndmask_b32_e64 v135, v135, v114, s[0:1]
	v_cndmask_b32_e64 v120, v120, v133, s[0:1]
	v_mov_b32_e32 v114, v157
	v_mov_b32_dpp v115, v123 row_ror:8 row_mask:0xf bank_mask:0xf
	v_mov_b32_dpp v118, v125 row_ror:8 row_mask:0xf bank_mask:0xf
	v_mov_b32_dpp v119, v126 row_ror:8 row_mask:0xf bank_mask:0xf
	v_mov_b32_e32 v133, v157
	v_mov_b32_dpp v134, v128 row_ror:8 row_mask:0xf bank_mask:0xf
	v_cndmask_b32_e64 v128, v128, v116, s[0:1]
	v_exp_f32_e32 v116, v108
	v_mul_f32_e32 v108, 0xbfb8aa3b, v109
	v_mov_b32_dpp v114, v122 row_ror:8 row_mask:0xf bank_mask:0xf
	v_mov_b32_dpp v133, v127 row_ror:8 row_mask:0xf bank_mask:0xf
	v_cndmask_b32_e64 v122, v119, v122, s[0:1]
	v_cndmask_b32_e64 v119, v134, v124, s[0:1]
	v_cndmask_b32_e64 v124, v127, v115, s[0:1]
	v_cndmask_b32_e64 v127, v129, v118, s[0:1]
	v_exp_f32_e32 v118, v108
	v_cndmask_b32_e64 v126, v126, v114, s[0:1]
	v_lshlrev_b64 v[114:115], 13, v[130:131]
	v_lshl_add_u64 v[114:115], s[4:5], 0, v[114:115]
	v_lshl_add_u64 v[114:115], v[114:115], 0, v[166:167]
	v_lshl_add_u64 v[108:109], v[114:115], 0, v[156:157]
	v_add_f32_e32 v115, 1.0, v118
	v_lshlrev_b32_e32 v118, 16, v119
	v_and_b32_e32 v119, 0xffff0000, v119
	v_add_f32_e32 v114, 1.0, v116
	v_pk_mul_f32 v[118:119], v[112:113], v[118:119] op_sel_hi:[0,1]
	v_rcp_f32_e32 v114, v114
	v_rcp_f32_e32 v115, v115
	v_lshlrev_b32_e32 v116, 16, v117
	v_and_b32_e32 v117, 0xffff0000, v117
	v_pk_mul_f32 v[118:119], v[60:61], v[118:119]
	v_mov_b32_e32 v137, v157
	v_pk_fma_f32 v[118:119], v[104:105], v[118:119], v[116:117]
	v_lshlrev_b32_e32 v116, 16, v122
	v_and_b32_e32 v117, 0xffff0000, v122
	v_mov_b32_dpp v137, v129 row_ror:8 row_mask:0xf bank_mask:0xf
	v_pk_mul_f32 v[116:117], v[112:113], v[116:117] op_sel_hi:[0,1]
	v_cndmask_b32_e64 v125, v137, v125, s[0:1]
	v_lshlrev_b32_e32 v104, 16, v135
	v_and_b32_e32 v105, 0xffff0000, v135
	v_pk_mul_f32 v[116:117], v[56:57], v[116:117]
	v_cndmask_b32_e64 v123, v133, v123, s[0:1]
	v_pk_fma_f32 v[104:105], v[114:115], v[116:117], v[104:105]
	v_lshlrev_b32_e32 v116, 16, v125
	v_and_b32_e32 v117, 0xffff0000, v125
	v_pk_mul_f32 v[116:117], v[112:113], v[116:117] op_sel_hi:[0,1]
	v_lshlrev_b32_e32 v114, 16, v138
	v_and_b32_e32 v115, 0xffff0000, v138
	v_pk_mul_f32 v[116:117], v[62:63], v[116:117]
	v_mov_b32_e32 v129, v157
	v_pk_fma_f32 v[114:115], v[106:107], v[116:117], v[114:115]
	v_lshlrev_b32_e32 v116, 16, v123
	v_and_b32_e32 v117, 0xffff0000, v123
	v_pk_mul_f32 v[116:117], v[112:113], v[116:117] op_sel_hi:[0,1]
	v_lshlrev_b32_e32 v106, 16, v136
	v_and_b32_e32 v107, 0xffff0000, v136
; __device__ __forceinline__ float bflo(unsigned w) { return __uint_as_float(w << 16); }
; __device__ __forceinline__ float bfhi(unsigned w) { return __uint_as_float(w & 0xffff0000u); }
; __device__ __forceinline__ unsigned dpp_ror8(unsigned x) { return (unsigned)__builtin_amdgcn_update_dpp(0, (int)x, 0x128, 0xf, 0xf, false); }
;     __device__ __forceinline__ void operator()(const f32x4 (&acc)[2][2][4][2], const Unit& u, int wr, int wc, int fr, int fq) const {
;     ...
;                 float* orow = OUT + (size_t)(row - fr + (fr & 7)) * D + col0 + (lo ? 0 : 4);
; #pragma unroll
;                 for (int bj = 0; bj < 2; ++bj) { const u32x4 rw = rr[bj], ew = ee[bj];
;                     const float r[8] = {bflo(rw.x), bfhi(rw.x), bflo(rw.y), bfhi(rw.y), bflo(rw.z), bfhi(rw.z), bflo(rw.w), bfhi(rw.w)};
;                     const float e[8] = {bflo(ew.x), bfhi(ew.x), bflo(ew.y), bfhi(ew.y), bflo(ew.z), bfhi(ew.z), bflo(ew.w), bfhi(ew.w)};
;                     float o[8];
; #pragma unroll
;                     for (int j = 0; j < 8; ++j) { const float a = acc[ai][bj][m][j >> 2][j & 3]; const float gg = gv[bj][j >> 2][j & 3];
;                         o[j] = r[j] + e[j] * ri * gg * __builtin_amdgcn_rcpf(1.f + __builtin_amdgcn_exp2f(-a * LOG2E)); }
;                     f32x4 o1, o2;
; #pragma unroll
;                     for (int j = 0; j < 4; ++j) { const unsigned a = __float_as_uint(o[j]), b = __float_as_uint(o[4 + j]); const unsigned sa = dpp_ror8(a), sb = dpp_ror8(b);
;                         o1[j] = __uint_as_float(lo ? a : sb); o2[j] = __uint_as_float(lo ? sa : b); }
;                     *(f32x4*)(orow + 32 * bj) = o1; *(f32x4*)(orow + (size_t)8 * D + 32 * bj) = o2; } }
	v_pk_mul_f32 v[116:117], v[58:59], v[116:117]
	v_mov_b32_e32 v130, v157
	v_pk_fma_f32 v[106:107], v[110:111], v[116:117], v[106:107]
	v_mov_b32_e32 v110, v157
	v_mov_b32_e32 v111, v157
	v_mov_b32_e32 v125, v157
	v_mov_b32_e32 v133, v157
	v_mov_b32_dpp v110, v106 row_ror:8 row_mask:0xf bank_mask:0xf
	v_mov_b32_dpp v111, v107 row_ror:8 row_mask:0xf bank_mask:0xf
	v_mov_b32_dpp v129, v118 row_ror:8 row_mask:0xf bank_mask:0xf
	v_mov_b32_dpp v130, v119 row_ror:8 row_mask:0xf bank_mask:0xf
	v_mov_b32_e32 v122, v157
	v_mov_b32_e32 v131, v157
	v_mov_b32_dpp v125, v114 row_ror:8 row_mask:0xf bank_mask:0xf
	v_mov_b32_dpp v133, v115 row_ror:8 row_mask:0xf bank_mask:0xf
	v_cndmask_b32_e64 v117, v115, v111, s[0:1]
	v_cndmask_b32_e64 v116, v114, v110, s[0:1]
	v_lshlrev_b32_e32 v110, 16, v128
	v_and_b32_e32 v111, 0xffff0000, v128
	v_mov_b32_dpp v122, v104 row_ror:8 row_mask:0xf bank_mask:0xf
	v_mov_b32_dpp v131, v105 row_ror:8 row_mask:0xf bank_mask:0xf
	v_cndmask_b32_e64 v107, v133, v107, s[0:1]
	v_cndmask_b32_e64 v106, v125, v106, s[0:1]
	v_cndmask_b32_e64 v105, v130, v105, s[0:1]
	v_cndmask_b32_e64 v104, v129, v104, s[0:1]
	v_pk_mul_f32 v[110:111], v[112:113], v[110:111] op_sel_hi:[0,1]
	global_store_dwordx4 v[108:109], v[104:107], off
	v_pk_mul_f32 v[110:111], v[44:45], v[110:111]
	v_cndmask_b32_e64 v115, v119, v131, s[0:1]
	v_lshlrev_b32_e32 v106, 16, v120
	v_and_b32_e32 v107, 0xffff0000, v120
	v_pk_fma_f32 v[106:107], v[96:97], v[110:111], v[106:107]
	v_lshlrev_b32_e32 v110, 16, v126
	v_and_b32_e32 v111, 0xffff0000, v126
	v_pk_mul_f32 v[110:111], v[112:113], v[110:111] op_sel_hi:[0,1]
	v_lshlrev_b32_e32 v96, 16, v113
	v_and_b32_e32 v97, 0xffff0000, v113
	v_pk_mul_f32 v[110:111], v[40:41], v[110:111]
	v_mov_b32_e32 v113, v157
	v_pk_fma_f32 v[96:97], v[100:101], v[110:111], v[96:97]
	v_lshlrev_b32_e32 v110, 16, v127
	v_and_b32_e32 v111, 0xffff0000, v127
	v_mov_b32_dpp v113, v96 row_ror:8 row_mask:0xf bank_mask:0xf
	v_pk_mul_f32 v[110:111], v[112:113], v[110:111] op_sel_hi:[0,1]
	v_lshlrev_b32_e32 v100, 16, v121
	v_and_b32_e32 v101, 0xffff0000, v121
	v_pk_mul_f32 v[110:111], v[46:47], v[110:111]
	v_add_co_u32_e32 v104, vcc, s45, v108
	v_pk_fma_f32 v[100:101], v[98:99], v[110:111], v[100:101]
	v_lshlrev_b32_e32 v110, 16, v124
	v_and_b32_e32 v111, 0xffff0000, v124
	v_cndmask_b32_e64 v114, v118, v122, s[0:1]
	v_addc_co_u32_e32 v105, vcc, 0, v109, vcc
	v_pk_mul_f32 v[110:111], v[112:113], v[110:111] op_sel_hi:[0,1]
	global_store_dwordx4 v[104:105], v[114:117], off
	v_mov_b32_e32 v118, v157
	v_lshlrev_b32_e32 v98, 16, v132
	v_mov_b32_e32 v114, v157
	v_mov_b32_e32 v115, v157
	v_mov_b32_e32 v117, v157
	v_and_b32_e32 v99, 0xffff0000, v132
	v_pk_mul_f32 v[110:111], v[42:43], v[110:111]
	v_mov_b32_dpp v114, v106 row_ror:8 row_mask:0xf bank_mask:0xf
	v_mov_b32_dpp v115, v107 row_ror:8 row_mask:0xf bank_mask:0xf
	v_mov_b32_e32 v116, v157
	v_mov_b32_dpp v117, v100 row_ror:8 row_mask:0xf bank_mask:0xf
	v_mov_b32_dpp v118, v101 row_ror:8 row_mask:0xf bank_mask:0xf
	v_pk_fma_f32 v[98:99], v[102:103], v[110:111], v[98:99]
	v_mov_b32_e32 v102, v157
	v_mov_b32_e32 v103, v157
	v_mov_b32_dpp v116, v97 row_ror:8 row_mask:0xf bank_mask:0xf
	v_mov_b32_dpp v102, v98 row_ror:8 row_mask:0xf bank_mask:0xf
	v_mov_b32_dpp v103, v99 row_ror:8 row_mask:0xf bank_mask:0xf
	v_cndmask_b32_e64 v99, v118, v99, s[0:1]
	v_cndmask_b32_e64 v98, v117, v98, s[0:1]
	v_cndmask_b32_e64 v97, v115, v97, s[0:1]
	v_cndmask_b32_e64 v96, v114, v96, s[0:1]
	v_cndmask_b32_e64 v103, v101, v103, s[0:1]
	v_cndmask_b32_e64 v102, v100, v102, s[0:1]
	v_cndmask_b32_e64 v101, v107, v116, s[0:1]
	v_cndmask_b32_e64 v100, v106, v113, s[0:1]
	global_store_dwordx4 v[108:109], v[96:99], off offset:128
	global_store_dwordx4 v[104:105], v[100:103], off offset:128
	v_mov_b32_e32 v121, v157
	v_or_b32_e32 v96, 48, v170
	v_ashrrev_i32_e32 v97, 31, v96
	v_lshl_add_u64 v[98:99], v[96:97], 2, s[6:7]
	v_sub_u32_e32 v96, v96, v174
	v_add_u32_e32 v114, v96, v176
	v_ashrrev_i32_e32 v115, 31, v114
	v_lshlrev_b64 v[96:97], 12, v[114:115]
	v_lshl_add_u64 v[110:111], v[96:97], 0, s[16:17]
	v_lshl_add_u64 v[102:103], s[8:9], 0, v[110:111]
	s_waitcnt vmcnt(4)
	s_nop 0
	v_mov_b32_e32 v116, v228
	v_lshl_add_u64 v[98:99], s[8:9], 0, v[96:97]
	v_lshl_add_u64 v[102:103], v[102:103], 0, v[164:165]
	v_lshl_add_u64 v[96:97], s[10:11], 0, v[96:97]
	v_lshl_add_u64 v[98:99], v[98:99], 0, v[164:165]
	v_mov_b64_e32 v[102:103], v[232:233]
	v_mov_b64_e32 v[104:105], v[234:235]
	v_lshl_add_u64 v[96:97], v[96:97], 0, v[164:165]
	v_mov_b64_e32 v[98:99], v[236:237]
	v_mov_b64_e32 v[100:101], v[238:239]
	v_mov_b32_e32 v122, v157
	v_mov_b64_e32 v[106:107], v[240:241]
	v_mov_b64_e32 v[108:109], v[242:243]
	v_lshl_add_u64 v[96:97], s[10:11], 0, v[110:111]
	v_lshl_add_u64 v[96:97], v[96:97], 0, v[164:165]
	v_mov_b64_e32 v[110:111], v[244:245]
	v_mov_b64_e32 v[112:113], v[246:247]
	s_nop 1
	global_load_dword v228, v[168:169], off offset:512
	v_sub_u32_e32 v217, v170, v174
	v_add_u32_e32 v217, v217, v176
	v_add_u32_e32 v226, 0x80, v217
	v_ashrrev_i32_e32 v227, 31, v226
	v_lshlrev_b64 v[222:223], 12, v[226:227]
	v_lshl_add_u64 v[224:225], v[222:223], 0, s[16:17]
	v_lshl_add_u64 v[218:219], s[8:9], 0, v[222:223]
	v_lshl_add_u64 v[220:221], s[8:9], 0, v[224:225]
	v_lshl_add_u64 v[218:219], v[218:219], 0, v[164:165]
	v_lshl_add_u64 v[220:221], v[220:221], 0, v[164:165]
	global_load_dwordx4 v[232:235], v[218:219], off
	v_lshl_add_u64 v[222:223], s[10:11], 0, v[222:223]
	global_load_dwordx4 v[236:239], v[220:221], off
	v_lshl_add_u64 v[222:223], v[222:223], 0, v[164:165]
	v_lshl_add_u64 v[224:225], s[10:11], 0, v[224:225]
	global_load_dwordx4 v[240:243], v[222:223], off
; __device__ __forceinline__ float bflo(unsigned w) { return __uint_as_float(w << 16); }
; __device__ __forceinline__ float bfhi(unsigned w) { return __uint_as_float(w & 0xffff0000u); }
; __device__ __forceinline__ unsigned dpp_ror8(unsigned x) { return (unsigned)__builtin_amdgcn_update_dpp(0, (int)x, 0x128, 0xf, 0xf, false); }
;     __device__ __forceinline__ void operator()(const f32x4 (&acc)[2][2][4][2], const Unit& u, int wr, int wc, int fr, int fq) const {
;     ...
;             for (int m = 0; m < 4; ++m) { const int row = row0 + ai * HALF + m * 16; const float ri = __builtin_amdgcn_rsqf(sse[row] * (1.f / D) + EPS);
;                 u32x4 rr[2], ee[2]; load_pair_lines(R, D, row, fr, col0, rr[0], rr[1], 32); load_pair_lines(E, D, row, fr, col0, ee[0], ee[1], 32);
;                 float* orow = OUT + (size_t)(row - fr + (fr & 7)) * D + col0 + (lo ? 0 : 4);
; #pragma unroll
;                 for (int bj = 0; bj < 2; ++bj) { const u32x4 rw = rr[bj], ew = ee[bj];
;                     const float r[8] = {bflo(rw.x), bfhi(rw.x), bflo(rw.y), bfhi(rw.y), bflo(rw.z), bfhi(rw.z), bflo(rw.w), bfhi(rw.w)};
;                     const float e[8] = {bflo(ew.x), bfhi(ew.x), bflo(ew.y), bfhi(ew.y), bflo(ew.z), bfhi(ew.z), bflo(ew.w), bfhi(ew.w)};
;                     float o[8];
; #pragma unroll
;                     for (int j = 0; j < 8; ++j) { const float a = acc[ai][bj][m][j >> 2][j & 3]; const float gg = gv[bj][j >> 2][j & 3];
;                         o[j] = r[j] + e[j] * ri * gg * __builtin_amdgcn_rcpf(1.f + __builtin_amdgcn_exp2f(-a * LOG2E)); }
;                     f32x4 o1, o2;
; #pragma unroll
;                     for (int j = 0; j < 4; ++j) { const unsigned a = __float_as_uint(o[j]), b = __float_as_uint(o[4 + j]); const unsigned sa = dpp_ror8(a), sb = dpp_ror8(b);
;                         o1[j] = __uint_as_float(lo ? a : sb); o2[j] = __uint_as_float(lo ? sa : b); }
;                     *(f32x4*)(orow + 32 * bj) = o1; *(f32x4*)(orow + (size_t)8 * D + 32 * bj) = o2; } }
	v_lshl_add_u64 v[224:225], v[224:225], 0, v[164:165]
	global_load_dwordx4 v[244:247], v[224:225], off
	v_mov_b32_e32 v97, v157
	v_mov_b32_e32 v117, v157
	v_mov_b32_e32 v118, v157
	v_mov_b32_e32 v120, v157
	v_mov_b32_e32 v119, v157
	v_exp_f32_e32 v94, v94
	v_exp_f32_e32 v95, v95
	v_add_f32_e32 v90, 1.0, v90
	v_add_f32_e32 v91, 1.0, v91
	v_rcp_f32_e32 v90, v90
	v_rcp_f32_e32 v91, v91
	v_add_f32_e32 v94, 1.0, v94
	v_add_f32_e32 v95, 1.0, v95
	v_mul_f32_e32 v80, 0xbfb8aa3b, v80
	v_mul_f32_e32 v81, 0xbfb8aa3b, v81
	v_rcp_f32_e32 v94, v94
	v_rcp_f32_e32 v95, v95
	v_exp_f32_e32 v80, v80
	v_exp_f32_e32 v81, v81
	v_mul_f32_e32 v84, 0xbfb8aa3b, v84
	v_mul_f32_e32 v85, 0xbfb8aa3b, v85
	v_exp_f32_e32 v84, v84
	v_exp_f32_e32 v85, v85
	v_add_f32_e32 v80, 1.0, v80
	v_add_f32_e32 v81, 1.0, v81
	v_rcp_f32_e32 v80, v80
	v_rcp_f32_e32 v81, v81
	v_mul_f32_e32 v82, 0xbfb8aa3b, v82
	v_mul_f32_e32 v83, 0xbfb8aa3b, v83
	v_add_f32_e32 v84, 1.0, v84
	v_add_f32_e32 v85, 1.0, v85
	v_exp_f32_e32 v82, v82
	v_exp_f32_e32 v83, v83
	v_rcp_f32_e32 v84, v84
	v_rcp_f32_e32 v85, v85
	v_mul_f32_e32 v86, 0xbfb8aa3b, v86
	v_mul_f32_e32 v87, 0xbfb8aa3b, v87
	v_exp_f32_e32 v86, v86
	v_exp_f32_e32 v87, v87
	v_add_f32_e32 v82, 1.0, v82
	v_add_f32_e32 v83, 1.0, v83
	v_rcp_f32_e32 v82, v82
	v_rcp_f32_e32 v83, v83
	v_add_f32_e32 v86, 1.0, v86
	v_add_f32_e32 v87, 1.0, v87
	v_rcp_f32_e32 v86, v86
	v_rcp_f32_e32 v87, v87
	v_mul_f32_e32 v72, 0xbfb8aa3b, v72
	v_mul_f32_e32 v73, 0xbfb8aa3b, v73
	v_mul_f32_e32 v76, 0xbfb8aa3b, v76
	v_exp_f32_e32 v72, v72
	v_exp_f32_e32 v73, v73
	v_mul_f32_e32 v74, 0xbfb8aa3b, v74
	v_mul_f32_e32 v75, 0xbfb8aa3b, v75
	v_add_f32_e32 v72, 1.0, v72
	v_add_f32_e32 v73, 1.0, v73
	v_rcp_f32_e32 v72, v72
	v_rcp_f32_e32 v73, v73
	v_exp_f32_e32 v74, v74
	v_exp_f32_e32 v75, v75
	v_mul_f32_e32 v78, 0xbfb8aa3b, v78
	v_mul_f32_e32 v79, 0xbfb8aa3b, v79
	v_exp_f32_e32 v78, v78
	v_exp_f32_e32 v79, v79
	v_add_f32_e32 v74, 1.0, v74
	v_add_f32_e32 v75, 1.0, v75
	v_rcp_f32_e32 v74, v74
	s_waitcnt vmcnt(32)
	v_fmamk_f32 v96, v116, 0x3a000000, v182
	v_mov_b32_e32 v116, v157
	v_rsq_f32_e32 v96, v96
	v_rcp_f32_e32 v75, v75
	v_add_f32_e32 v78, 1.0, v78
	v_mov_b32_dpp v121, v104 row_ror:8 row_mask:0xf bank_mask:0xf
	v_mov_b32_dpp v122, v105 row_ror:8 row_mask:0xf bank_mask:0xf
	v_mov_b32_dpp v97, v98 row_ror:8 row_mask:0xf bank_mask:0xf
	v_mov_b32_dpp v116, v99 row_ror:8 row_mask:0xf bank_mask:0xf
	v_mov_b32_dpp v117, v100 row_ror:8 row_mask:0xf bank_mask:0xf
	v_mov_b32_dpp v118, v101 row_ror:8 row_mask:0xf bank_mask:0xf
	v_mov_b32_dpp v120, v103 row_ror:8 row_mask:0xf bank_mask:0xf
	v_cndmask_b32_e64 v122, v122, v101, s[0:1]
	v_cndmask_b32_e64 v101, v121, v100, s[0:1]
	v_mov_b32_e32 v100, v157
	v_mov_b32_dpp v119, v102 row_ror:8 row_mask:0xf bank_mask:0xf
	v_cndmask_b32_e64 v120, v120, v99, s[0:1]
	v_cndmask_b32_e64 v116, v103, v116, s[0:1]
	v_cndmask_b32_e64 v105, v105, v118, s[0:1]
	v_cndmask_b32_e64 v97, v102, v97, s[0:1]
	v_mov_b32_e32 v99, v157
	v_mov_b32_dpp v100, v108 row_ror:8 row_mask:0xf bank_mask:0xf
	v_mov_b32_e32 v102, v157
	v_mov_b32_e32 v103, v157
	v_mov_b32_e32 v118, v157
	v_cndmask_b32_e64 v119, v119, v98, s[0:1]
	v_cndmask_b32_e64 v104, v104, v117, s[0:1]
	v_mov_b32_e32 v98, v157
	v_mov_b32_dpp v99, v107 row_ror:8 row_mask:0xf bank_mask:0xf
	v_mov_b32_dpp v102, v109 row_ror:8 row_mask:0xf bank_mask:0xf
	v_mov_b32_dpp v103, v110 row_ror:8 row_mask:0xf bank_mask:0xf
	v_mov_b32_e32 v117, v157
	v_mov_b32_dpp v118, v112 row_ror:8 row_mask:0xf bank_mask:0xf
	v_cndmask_b32_e64 v112, v112, v100, s[0:1]
	v_exp_f32_e32 v100, v92
	v_mul_f32_e32 v92, 0xbfb8aa3b, v93
	v_mov_b32_dpp v98, v106 row_ror:8 row_mask:0xf bank_mask:0xf
	v_mov_b32_dpp v117, v111 row_ror:8 row_mask:0xf bank_mask:0xf
	v_cndmask_b32_e64 v106, v103, v106, s[0:1]
	v_cndmask_b32_e64 v103, v118, v108, s[0:1]
	v_cndmask_b32_e64 v108, v111, v99, s[0:1]
	v_cndmask_b32_e64 v111, v113, v102, s[0:1]
	v_exp_f32_e32 v102, v92
	v_cndmask_b32_e64 v110, v110, v98, s[0:1]
	v_lshlrev_b64 v[98:99], 13, v[114:115]
	v_lshl_add_u64 v[98:99], s[4:5], 0, v[98:99]
	v_lshl_add_u64 v[98:99], v[98:99], 0, v[166:167]
	v_lshl_add_u64 v[92:93], v[98:99], 0, v[156:157]
	v_add_f32_e32 v99, 1.0, v102
	v_lshlrev_b32_e32 v102, 16, v103
	v_and_b32_e32 v103, 0xffff0000, v103
	v_add_f32_e32 v98, 1.0, v100
	v_pk_mul_f32 v[102:103], v[96:97], v[102:103] op_sel_hi:[0,1]
	v_rcp_f32_e32 v98, v98
	v_rcp_f32_e32 v99, v99
	v_lshlrev_b32_e32 v100, 16, v101
	v_and_b32_e32 v101, 0xffff0000, v101
	v_pk_mul_f32 v[102:103], v[60:61], v[102:103]
	v_mov_b32_e32 v121, v157
	v_pk_fma_f32 v[102:103], v[88:89], v[102:103], v[100:101]
	v_lshlrev_b32_e32 v100, 16, v106
	v_and_b32_e32 v101, 0xffff0000, v106
	v_mov_b32_dpp v121, v113 row_ror:8 row_mask:0xf bank_mask:0xf
	v_pk_mul_f32 v[100:101], v[96:97], v[100:101] op_sel_hi:[0,1]
	v_cndmask_b32_e64 v109, v121, v109, s[0:1]
	v_lshlrev_b32_e32 v88, 16, v119
	v_and_b32_e32 v89, 0xffff0000, v119
	v_pk_mul_f32 v[100:101], v[56:57], v[100:101]
	v_cndmask_b32_e64 v107, v117, v107, s[0:1]
	v_pk_fma_f32 v[88:89], v[98:99], v[100:101], v[88:89]
	v_lshlrev_b32_e32 v100, 16, v109
	v_and_b32_e32 v101, 0xffff0000, v109
	v_pk_mul_f32 v[100:101], v[96:97], v[100:101] op_sel_hi:[0,1]
	v_lshlrev_b32_e32 v98, 16, v122
	v_and_b32_e32 v99, 0xffff0000, v122
	v_pk_mul_f32 v[100:101], v[62:63], v[100:101]
	v_mov_b32_e32 v113, v157
	v_pk_fma_f32 v[98:99], v[90:91], v[100:101], v[98:99]
	v_lshlrev_b32_e32 v100, 16, v107
	v_and_b32_e32 v101, 0xffff0000, v107
	v_pk_mul_f32 v[100:101], v[96:97], v[100:101] op_sel_hi:[0,1]
	v_lshlrev_b32_e32 v90, 16, v120
	v_and_b32_e32 v91, 0xffff0000, v120
	v_pk_mul_f32 v[100:101], v[58:59], v[100:101]
; __device__ __forceinline__ float bflo(unsigned w) { return __uint_as_float(w << 16); }
; __device__ __forceinline__ float bfhi(unsigned w) { return __uint_as_float(w & 0xffff0000u); }
; __device__ __forceinline__ unsigned dpp_ror8(unsigned x) { return (unsigned)__builtin_amdgcn_update_dpp(0, (int)x, 0x128, 0xf, 0xf, false); }
;     __device__ __forceinline__ void operator()(const f32x4 (&acc)[2][2][4][2], const Unit& u, int wr, int wc, int fr, int fq) const {
;     ...
;                 float* orow = OUT + (size_t)(row - fr + (fr & 7)) * D + col0 + (lo ? 0 : 4);
; #pragma unroll
;                 for (int bj = 0; bj < 2; ++bj) { const u32x4 rw = rr[bj], ew = ee[bj];
;                     const float r[8] = {bflo(rw.x), bfhi(rw.x), bflo(rw.y), bfhi(rw.y), bflo(rw.z), bfhi(rw.z), bflo(rw.w), bfhi(rw.w)};
;                     const float e[8] = {bflo(ew.x), bfhi(ew.x), bflo(ew.y), bfhi(ew.y), bflo(ew.z), bfhi(ew.z), bflo(ew.w), bfhi(ew.w)};
;                     float o[8];
; #pragma unroll
;                     for (int j = 0; j < 8; ++j) { const float a = acc[ai][bj][m][j >> 2][j & 3]; const float gg = gv[bj][j >> 2][j & 3];
;                         o[j] = r[j] + e[j] * ri * gg * __builtin_amdgcn_rcpf(1.f + __builtin_amdgcn_exp2f(-a * LOG2E)); }
;                     f32x4 o1, o2;
; #pragma unroll
;                     for (int j = 0; j < 4; ++j) { const unsigned a = __float_as_uint(o[j]), b = __float_as_uint(o[4 + j]); const unsigned sa = dpp_ror8(a), sb = dpp_ror8(b);
;                         o1[j] = __uint_as_float(lo ? a : sb); o2[j] = __uint_as_float(lo ? sa : b); }
;                     *(f32x4*)(orow + 32 * bj) = o1; *(f32x4*)(orow + (size_t)8 * D + 32 * bj) = o2; } }
	v_mov_b32_e32 v114, v157
	v_pk_fma_f32 v[90:91], v[94:95], v[100:101], v[90:91]
	v_mov_b32_e32 v94, v157
	v_mov_b32_e32 v95, v157
	v_mov_b32_e32 v109, v157
	v_mov_b32_e32 v117, v157
	v_mov_b32_dpp v94, v90 row_ror:8 row_mask:0xf bank_mask:0xf
	v_mov_b32_dpp v95, v91 row_ror:8 row_mask:0xf bank_mask:0xf
	v_mov_b32_dpp v113, v102 row_ror:8 row_mask:0xf bank_mask:0xf
	v_mov_b32_dpp v114, v103 row_ror:8 row_mask:0xf bank_mask:0xf
	v_mov_b32_e32 v106, v157
	v_mov_b32_e32 v115, v157
	v_mov_b32_dpp v109, v98 row_ror:8 row_mask:0xf bank_mask:0xf
	v_mov_b32_dpp v117, v99 row_ror:8 row_mask:0xf bank_mask:0xf
	v_cndmask_b32_e64 v101, v99, v95, s[0:1]
	v_cndmask_b32_e64 v100, v98, v94, s[0:1]
	v_lshlrev_b32_e32 v94, 16, v112
	v_and_b32_e32 v95, 0xffff0000, v112
	v_mov_b32_dpp v106, v88 row_ror:8 row_mask:0xf bank_mask:0xf
	v_mov_b32_dpp v115, v89 row_ror:8 row_mask:0xf bank_mask:0xf
	v_cndmask_b32_e64 v91, v117, v91, s[0:1]
	v_cndmask_b32_e64 v90, v109, v90, s[0:1]
	v_cndmask_b32_e64 v89, v114, v89, s[0:1]
	v_cndmask_b32_e64 v88, v113, v88, s[0:1]
	v_pk_mul_f32 v[94:95], v[96:97], v[94:95] op_sel_hi:[0,1]
	global_store_dwordx4 v[92:93], v[88:91], off
	v_pk_mul_f32 v[94:95], v[44:45], v[94:95]
	v_cndmask_b32_e64 v99, v103, v115, s[0:1]
	v_lshlrev_b32_e32 v90, 16, v104
	v_and_b32_e32 v91, 0xffff0000, v104
	v_pk_fma_f32 v[90:91], v[80:81], v[94:95], v[90:91]
	v_lshlrev_b32_e32 v94, 16, v110
	v_and_b32_e32 v95, 0xffff0000, v110
	v_pk_mul_f32 v[94:95], v[96:97], v[94:95] op_sel_hi:[0,1]
	v_lshlrev_b32_e32 v80, 16, v97
	v_and_b32_e32 v81, 0xffff0000, v97
	v_pk_mul_f32 v[94:95], v[40:41], v[94:95]
	v_mov_b32_e32 v97, v157
	v_pk_fma_f32 v[80:81], v[84:85], v[94:95], v[80:81]
	v_lshlrev_b32_e32 v94, 16, v111
	v_and_b32_e32 v95, 0xffff0000, v111
	v_mov_b32_dpp v97, v80 row_ror:8 row_mask:0xf bank_mask:0xf
	v_pk_mul_f32 v[94:95], v[96:97], v[94:95] op_sel_hi:[0,1]
	v_lshlrev_b32_e32 v84, 16, v105
	v_and_b32_e32 v85, 0xffff0000, v105
	v_pk_mul_f32 v[94:95], v[46:47], v[94:95]
	v_add_co_u32_e32 v88, vcc, s45, v92
	v_pk_fma_f32 v[84:85], v[82:83], v[94:95], v[84:85]
	v_lshlrev_b32_e32 v94, 16, v108
	v_and_b32_e32 v95, 0xffff0000, v108
	v_cndmask_b32_e64 v98, v102, v106, s[0:1]
	v_addc_co_u32_e32 v89, vcc, 0, v93, vcc
	v_pk_mul_f32 v[94:95], v[96:97], v[94:95] op_sel_hi:[0,1]
	global_store_dwordx4 v[88:89], v[98:101], off
	v_mov_b32_e32 v102, v157
	v_lshlrev_b32_e32 v82, 16, v116
	v_mov_b32_e32 v98, v157
	v_mov_b32_e32 v99, v157
	v_mov_b32_e32 v101, v157
	v_and_b32_e32 v83, 0xffff0000, v116
	v_pk_mul_f32 v[94:95], v[42:43], v[94:95]
	v_mov_b32_dpp v98, v90 row_ror:8 row_mask:0xf bank_mask:0xf
	v_mov_b32_dpp v99, v91 row_ror:8 row_mask:0xf bank_mask:0xf
	v_mov_b32_e32 v100, v157
	v_mov_b32_dpp v101, v84 row_ror:8 row_mask:0xf bank_mask:0xf
	v_mov_b32_dpp v102, v85 row_ror:8 row_mask:0xf bank_mask:0xf
	v_pk_fma_f32 v[82:83], v[86:87], v[94:95], v[82:83]
	v_mov_b32_e32 v86, v157
	v_mov_b32_e32 v87, v157
	v_mov_b32_dpp v100, v81 row_ror:8 row_mask:0xf bank_mask:0xf
	v_mov_b32_dpp v86, v82 row_ror:8 row_mask:0xf bank_mask:0xf
	v_mov_b32_dpp v87, v83 row_ror:8 row_mask:0xf bank_mask:0xf
	v_cndmask_b32_e64 v83, v102, v83, s[0:1]
	v_cndmask_b32_e64 v82, v101, v82, s[0:1]
	v_cndmask_b32_e64 v81, v99, v81, s[0:1]
	v_cndmask_b32_e64 v80, v98, v80, s[0:1]
	v_cndmask_b32_e64 v87, v85, v87, s[0:1]
	v_cndmask_b32_e64 v86, v84, v86, s[0:1]
	v_cndmask_b32_e64 v85, v91, v100, s[0:1]
	v_cndmask_b32_e64 v84, v90, v97, s[0:1]
	global_store_dwordx4 v[92:93], v[80:83], off offset:128
	global_store_dwordx4 v[88:89], v[84:87], off offset:128
	s_waitcnt vmcnt(4)
	s_nop 0
	v_mov_b32_e32 v80, v228
	v_sub_u32_e32 v81, v170, v174
	v_add_u32_e32 v81, v81, v176
	v_add_u32_e32 v98, 0x80, v81
	v_ashrrev_i32_e32 v99, 31, v98
	v_lshlrev_b64 v[90:91], 12, v[98:99]
	v_lshl_add_u64 v[94:95], v[90:91], 0, s[16:17]
	v_lshl_add_u64 v[82:83], s[8:9], 0, v[90:91]
	v_lshl_add_u64 v[86:87], s[8:9], 0, v[94:95]
	v_lshl_add_u64 v[82:83], v[82:83], 0, v[164:165]
	v_lshl_add_u64 v[86:87], v[86:87], 0, v[164:165]
	v_mov_b64_e32 v[82:83], v[232:233]
	v_mov_b64_e32 v[84:85], v[234:235]
	v_lshl_add_u64 v[90:91], s[10:11], 0, v[90:91]
	v_mov_b64_e32 v[86:87], v[236:237]
	v_mov_b64_e32 v[88:89], v[238:239]
	v_lshl_add_u64 v[90:91], v[90:91], 0, v[164:165]
	v_lshl_add_u64 v[94:95], s[10:11], 0, v[94:95]
	v_mov_b64_e32 v[90:91], v[240:241]
	v_mov_b64_e32 v[92:93], v[242:243]
	v_lshl_add_u64 v[94:95], v[94:95], 0, v[164:165]
	v_mov_b64_e32 v[94:95], v[244:245]
	v_mov_b64_e32 v[96:97], v[246:247]
	s_nop 1
	v_add_u32_e32 v222, 0x90, v81
	v_ashrrev_i32_e32 v223, 31, v222
	global_load_dword v228, v[168:169], off offset:576
	v_lshlrev_b64 v[216:217], 12, v[222:223]
	v_lshl_add_u64 v[224:225], v[216:217], 0, s[16:17]
	v_lshl_add_u64 v[220:221], s[8:9], 0, v[224:225]
	v_lshl_add_u64 v[218:219], s[8:9], 0, v[216:217]
	v_lshl_add_u64 v[220:221], v[220:221], 0, v[164:165]
	v_lshl_add_u64 v[216:217], s[10:11], 0, v[216:217]
	v_lshl_add_u64 v[218:219], v[218:219], 0, v[164:165]
	global_load_dwordx4 v[232:235], v[220:221], off
	v_lshl_add_u64 v[216:217], v[216:217], 0, v[164:165]
	global_load_dwordx4 v[236:239], v[218:219], off
	global_load_dwordx4 v[240:243], v[216:217], off
	v_lshl_add_u64 v[216:217], s[10:11], 0, v[224:225]
	v_lshl_add_u64 v[216:217], v[216:217], 0, v[164:165]
	global_load_dwordx4 v[244:247], v[216:217], off
	v_mov_b32_e32 v106, v157
	v_mov_b32_e32 v107, v157
	v_mov_b32_e32 v100, v157
	v_mov_b32_e32 v101, v157
	v_mov_b32_e32 v102, v157
	v_mov_b32_e32 v103, v157
	v_mov_b32_e32 v105, v157
	v_mov_b32_e32 v104, v157
	v_add_f32_e32 v79, 1.0, v79
	v_mul_f32_e32 v64, 0xbfb8aa3b, v64
	v_mul_f32_e32 v65, 0xbfb8aa3b, v65
; __device__ __forceinline__ float bflo(unsigned w) { return __uint_as_float(w << 16); }
; __device__ __forceinline__ float bfhi(unsigned w) { return __uint_as_float(w & 0xffff0000u); }
; __device__ __forceinline__ unsigned dpp_ror8(unsigned x) { return (unsigned)__builtin_amdgcn_update_dpp(0, (int)x, 0x128, 0xf, 0xf, false); }
;     __device__ __forceinline__ void operator()(const f32x4 (&acc)[2][2][4][2], const Unit& u, int wr, int wc, int fr, int fq) const {
;     ...
;             for (int m = 0; m < 4; ++m) { const int row = row0 + ai * HALF + m * 16; const float ri = __builtin_amdgcn_rsqf(sse[row] * (1.f / D) + EPS);
;                 u32x4 rr[2], ee[2]; load_pair_lines(R, D, row, fr, col0, rr[0], rr[1], 32); load_pair_lines(E, D, row, fr, col0, ee[0], ee[1], 32);
;                 float* orow = OUT + (size_t)(row - fr + (fr & 7)) * D + col0 + (lo ? 0 : 4);
; #pragma unroll
;                 for (int bj = 0; bj < 2; ++bj) { const u32x4 rw = rr[bj], ew = ee[bj];
;                     const float r[8] = {bflo(rw.x), bfhi(rw.x), bflo(rw.y), bfhi(rw.y), bflo(rw.z), bfhi(rw.z), bflo(rw.w), bfhi(rw.w)};
;                     const float e[8] = {bflo(ew.x), bfhi(ew.x), bflo(ew.y), bfhi(ew.y), bflo(ew.z), bfhi(ew.z), bflo(ew.w), bfhi(ew.w)};
;                     float o[8];
; #pragma unroll
;                     for (int j = 0; j < 8; ++j) { const float a = acc[ai][bj][m][j >> 2][j & 3]; const float gg = gv[bj][j >> 2][j & 3];
;                         o[j] = r[j] + e[j] * ri * gg * __builtin_amdgcn_rcpf(1.f + __builtin_amdgcn_exp2f(-a * LOG2E)); }
;                     f32x4 o1, o2;
; #pragma unroll
;                     for (int j = 0; j < 4; ++j) { const unsigned a = __float_as_uint(o[j]), b = __float_as_uint(o[4 + j]); const unsigned sa = dpp_ror8(a), sb = dpp_ror8(b);
;                         o1[j] = __uint_as_float(lo ? a : sb); o2[j] = __uint_as_float(lo ? sa : b); }
;                     *(f32x4*)(orow + 32 * bj) = o1; *(f32x4*)(orow + (size_t)8 * D + 32 * bj) = o2; } }
	v_rcp_f32_e32 v78, v78
	v_rcp_f32_e32 v79, v79
	v_exp_f32_e32 v64, v64
	v_exp_f32_e32 v65, v65
	v_mul_f32_e32 v68, 0xbfb8aa3b, v68
	v_mul_f32_e32 v69, 0xbfb8aa3b, v69
	v_exp_f32_e32 v68, v68
	v_exp_f32_e32 v69, v69
	v_add_f32_e32 v64, 1.0, v64
	v_add_f32_e32 v65, 1.0, v65
	v_rcp_f32_e32 v64, v64
	v_mul_f32_e32 v66, 0xbfb8aa3b, v66
	v_mul_f32_e32 v67, 0xbfb8aa3b, v67
	v_rcp_f32_e32 v65, v65
	v_exp_f32_e32 v66, v66
	v_exp_f32_e32 v67, v67
	v_add_f32_e32 v68, 1.0, v68
	v_add_f32_e32 v69, 1.0, v69
	v_rcp_f32_e32 v68, v68
	v_mul_f32_e32 v70, 0xbfb8aa3b, v70
	v_mul_f32_e32 v71, 0xbfb8aa3b, v71
	v_rcp_f32_e32 v69, v69
	v_exp_f32_e32 v70, v70
	v_exp_f32_e32 v71, v71
	v_add_f32_e32 v66, 1.0, v66
	v_add_f32_e32 v67, 1.0, v67
	v_rcp_f32_e32 v66, v66
	v_rcp_f32_e32 v67, v67
	v_add_f32_e32 v70, 1.0, v70
	v_add_f32_e32 v71, 1.0, v71
	v_rcp_f32_e32 v70, v70
	v_rcp_f32_e32 v71, v71
	v_mul_f32_e32 v48, 0xbfb8aa3b, v48
	v_mul_f32_e32 v49, 0xbfb8aa3b, v49
	v_mul_f32_e32 v52, 0xbfb8aa3b, v52
	v_exp_f32_e32 v48, v48
	v_exp_f32_e32 v49, v49
	v_mul_f32_e32 v50, 0xbfb8aa3b, v50
	v_mul_f32_e32 v51, 0xbfb8aa3b, v51
	v_add_f32_e32 v48, 1.0, v48
	v_add_f32_e32 v49, 1.0, v49
	v_rcp_f32_e32 v48, v48
	v_rcp_f32_e32 v49, v49
	v_exp_f32_e32 v50, v50
	v_exp_f32_e32 v51, v51
	v_mul_f32_e32 v54, 0xbfb8aa3b, v54
	v_mul_f32_e32 v55, 0xbfb8aa3b, v55
	v_exp_f32_e32 v54, v54
	v_exp_f32_e32 v55, v55
	v_add_f32_e32 v50, 1.0, v50
	s_waitcnt vmcnt(41)
	v_fmamk_f32 v80, v80, 0x3a000000, v182
	v_rsq_f32_e32 v80, v80
	v_add_f32_e32 v51, 1.0, v51
	v_rcp_f32_e32 v50, v50
	v_rcp_f32_e32 v51, v51
	v_add_f32_e32 v54, 1.0, v54
	v_add_f32_e32 v55, 1.0, v55
	v_mul_f32_e32 v32, 0xbfb8aa3b, v32
	v_mul_f32_e32 v33, 0xbfb8aa3b, v33
	v_rcp_f32_e32 v54, v54
	v_rcp_f32_e32 v55, v55
	v_mov_b32_dpp v100, v82 row_ror:8 row_mask:0xf bank_mask:0xf
	v_mov_b32_dpp v101, v83 row_ror:8 row_mask:0xf bank_mask:0xf
	v_mov_b32_dpp v106, v88 row_ror:8 row_mask:0xf bank_mask:0xf
	v_mov_b32_dpp v107, v89 row_ror:8 row_mask:0xf bank_mask:0xf
	v_mov_b32_dpp v102, v84 row_ror:8 row_mask:0xf bank_mask:0xf
	v_mov_b32_dpp v103, v85 row_ror:8 row_mask:0xf bank_mask:0xf
	v_mov_b32_dpp v105, v87 row_ror:8 row_mask:0xf bank_mask:0xf
	v_cndmask_b32_e64 v107, v107, v85, s[0:1]
	v_cndmask_b32_e64 v85, v106, v84, s[0:1]
	v_mov_b32_e32 v84, v157
	v_mov_b32_dpp v104, v86 row_ror:8 row_mask:0xf bank_mask:0xf
	v_cndmask_b32_e64 v105, v105, v83, s[0:1]
	v_cndmask_b32_e64 v101, v87, v101, s[0:1]
	v_cndmask_b32_e64 v89, v89, v103, s[0:1]
	v_cndmask_b32_e64 v100, v86, v100, s[0:1]
	v_mov_b32_e32 v83, v157
	v_mov_b32_dpp v84, v92 row_ror:8 row_mask:0xf bank_mask:0xf
	v_mov_b32_e32 v86, v157
	v_mov_b32_e32 v87, v157
	v_mov_b32_e32 v103, v157
	v_cndmask_b32_e64 v104, v104, v82, s[0:1]
	v_cndmask_b32_e64 v88, v88, v102, s[0:1]
	v_mov_b32_e32 v82, v157
	v_mov_b32_dpp v83, v91 row_ror:8 row_mask:0xf bank_mask:0xf
	v_mov_b32_dpp v86, v93 row_ror:8 row_mask:0xf bank_mask:0xf
	v_mov_b32_dpp v87, v94 row_ror:8 row_mask:0xf bank_mask:0xf
	v_mov_b32_e32 v102, v157
	v_mov_b32_dpp v103, v96 row_ror:8 row_mask:0xf bank_mask:0xf
	v_cndmask_b32_e64 v96, v96, v84, s[0:1]
	v_exp_f32_e32 v84, v76
	v_mul_f32_e32 v76, 0xbfb8aa3b, v77
	v_mov_b32_dpp v82, v90 row_ror:8 row_mask:0xf bank_mask:0xf
	v_mov_b32_dpp v102, v95 row_ror:8 row_mask:0xf bank_mask:0xf
	v_cndmask_b32_e64 v90, v87, v90, s[0:1]
	v_cndmask_b32_e64 v87, v103, v92, s[0:1]
	v_cndmask_b32_e64 v92, v95, v83, s[0:1]
	v_cndmask_b32_e64 v95, v97, v86, s[0:1]
	v_exp_f32_e32 v86, v76
	v_cndmask_b32_e64 v94, v94, v82, s[0:1]
	v_lshlrev_b64 v[82:83], 13, v[98:99]
	v_lshl_add_u64 v[82:83], s[4:5], 0, v[82:83]
	v_lshl_add_u64 v[82:83], v[82:83], 0, v[166:167]
	v_lshl_add_u64 v[76:77], v[82:83], 0, v[156:157]
	v_add_f32_e32 v83, 1.0, v86
	v_lshlrev_b32_e32 v86, 16, v87
	v_and_b32_e32 v87, 0xffff0000, v87
	v_add_f32_e32 v82, 1.0, v84
	v_pk_mul_f32 v[86:87], v[80:81], v[86:87] op_sel_hi:[0,1]
	v_rcp_f32_e32 v82, v82
	v_rcp_f32_e32 v83, v83
	v_lshlrev_b32_e32 v84, 16, v85
	v_and_b32_e32 v85, 0xffff0000, v85
	v_pk_mul_f32 v[86:87], v[60:61], v[86:87]
	v_mov_b32_e32 v106, v157
	v_pk_fma_f32 v[86:87], v[72:73], v[86:87], v[84:85]
	v_lshlrev_b32_e32 v84, 16, v90
	v_and_b32_e32 v85, 0xffff0000, v90
	v_mov_b32_dpp v106, v97 row_ror:8 row_mask:0xf bank_mask:0xf
	v_pk_mul_f32 v[84:85], v[80:81], v[84:85] op_sel_hi:[0,1]
	v_cndmask_b32_e64 v93, v106, v93, s[0:1]
	v_lshlrev_b32_e32 v72, 16, v104
	v_and_b32_e32 v73, 0xffff0000, v104
	v_pk_mul_f32 v[84:85], v[56:57], v[84:85]
	v_cndmask_b32_e64 v91, v102, v91, s[0:1]
	v_pk_fma_f32 v[72:73], v[82:83], v[84:85], v[72:73]
	v_lshlrev_b32_e32 v84, 16, v93
	v_and_b32_e32 v85, 0xffff0000, v93
	v_pk_mul_f32 v[84:85], v[80:81], v[84:85] op_sel_hi:[0,1]
	v_lshlrev_b32_e32 v82, 16, v107
	v_and_b32_e32 v83, 0xffff0000, v107
	v_pk_mul_f32 v[84:85], v[62:63], v[84:85]
	v_mov_b32_e32 v97, v157
	v_pk_fma_f32 v[82:83], v[74:75], v[84:85], v[82:83]
	v_lshlrev_b32_e32 v84, 16, v91
	v_and_b32_e32 v85, 0xffff0000, v91
	v_pk_mul_f32 v[84:85], v[80:81], v[84:85] op_sel_hi:[0,1]
	v_lshlrev_b32_e32 v74, 16, v105
	v_and_b32_e32 v75, 0xffff0000, v105
	v_pk_mul_f32 v[84:85], v[58:59], v[84:85]
	v_mov_b32_e32 v98, v157
	v_pk_fma_f32 v[74:75], v[78:79], v[84:85], v[74:75]
	v_mov_b32_e32 v78, v157
	v_mov_b32_e32 v79, v157
	v_mov_b32_e32 v93, v157
	v_mov_b32_e32 v102, v157
	v_mov_b32_dpp v78, v74 row_ror:8 row_mask:0xf bank_mask:0xf
	v_mov_b32_dpp v79, v75 row_ror:8 row_mask:0xf bank_mask:0xf
	v_mov_b32_dpp v97, v86 row_ror:8 row_mask:0xf bank_mask:0xf
	v_mov_b32_dpp v98, v87 row_ror:8 row_mask:0xf bank_mask:0xf
	v_mov_b32_e32 v90, v157
	v_mov_b32_e32 v99, v157
	v_mov_b32_dpp v93, v82 row_ror:8 row_mask:0xf bank_mask:0xf
; __device__ __forceinline__ float bflo(unsigned w) { return __uint_as_float(w << 16); }
; __device__ __forceinline__ float bfhi(unsigned w) { return __uint_as_float(w & 0xffff0000u); }
; __device__ __forceinline__ unsigned dpp_ror8(unsigned x) { return (unsigned)__builtin_amdgcn_update_dpp(0, (int)x, 0x128, 0xf, 0xf, false); }
;     __device__ __forceinline__ void operator()(const f32x4 (&acc)[2][2][4][2], const Unit& u, int wr, int wc, int fr, int fq) const {
;     ...
;                 float* orow = OUT + (size_t)(row - fr + (fr & 7)) * D + col0 + (lo ? 0 : 4);
; #pragma unroll
;                 for (int bj = 0; bj < 2; ++bj) { const u32x4 rw = rr[bj], ew = ee[bj];
;                     const float r[8] = {bflo(rw.x), bfhi(rw.x), bflo(rw.y), bfhi(rw.y), bflo(rw.z), bfhi(rw.z), bflo(rw.w), bfhi(rw.w)};
;                     const float e[8] = {bflo(ew.x), bfhi(ew.x), bflo(ew.y), bfhi(ew.y), bflo(ew.z), bfhi(ew.z), bflo(ew.w), bfhi(ew.w)};
;                     float o[8];
; #pragma unroll
;                     for (int j = 0; j < 8; ++j) { const float a = acc[ai][bj][m][j >> 2][j & 3]; const float gg = gv[bj][j >> 2][j & 3];
;                         o[j] = r[j] + e[j] * ri * gg * __builtin_amdgcn_rcpf(1.f + __builtin_amdgcn_exp2f(-a * LOG2E)); }
;                     f32x4 o1, o2;
; #pragma unroll
;                     for (int j = 0; j < 4; ++j) { const unsigned a = __float_as_uint(o[j]), b = __float_as_uint(o[4 + j]); const unsigned sa = dpp_ror8(a), sb = dpp_ror8(b);
;                         o1[j] = __uint_as_float(lo ? a : sb); o2[j] = __uint_as_float(lo ? sa : b); }
;                     *(f32x4*)(orow + 32 * bj) = o1; *(f32x4*)(orow + (size_t)8 * D + 32 * bj) = o2; } }
	v_mov_b32_dpp v102, v83 row_ror:8 row_mask:0xf bank_mask:0xf
	v_cndmask_b32_e64 v85, v83, v79, s[0:1]
	v_cndmask_b32_e64 v84, v82, v78, s[0:1]
	v_lshlrev_b32_e32 v78, 16, v96
	v_and_b32_e32 v79, 0xffff0000, v96
	v_mov_b32_dpp v90, v72 row_ror:8 row_mask:0xf bank_mask:0xf
	v_mov_b32_dpp v99, v73 row_ror:8 row_mask:0xf bank_mask:0xf
	v_cndmask_b32_e64 v75, v102, v75, s[0:1]
	v_cndmask_b32_e64 v74, v93, v74, s[0:1]
	v_cndmask_b32_e64 v73, v98, v73, s[0:1]
	v_cndmask_b32_e64 v72, v97, v72, s[0:1]
	v_pk_mul_f32 v[78:79], v[80:81], v[78:79] op_sel_hi:[0,1]
	global_store_dwordx4 v[76:77], v[72:75], off
	v_pk_mul_f32 v[78:79], v[44:45], v[78:79]
	v_cndmask_b32_e64 v83, v87, v99, s[0:1]
	v_lshlrev_b32_e32 v74, 16, v88
	v_and_b32_e32 v75, 0xffff0000, v88
	v_pk_fma_f32 v[74:75], v[64:65], v[78:79], v[74:75]
	v_lshlrev_b32_e32 v78, 16, v94
	v_and_b32_e32 v79, 0xffff0000, v94
	v_pk_mul_f32 v[78:79], v[80:81], v[78:79] op_sel_hi:[0,1]
	v_lshlrev_b32_e32 v64, 16, v100
	v_and_b32_e32 v65, 0xffff0000, v100
	v_pk_mul_f32 v[78:79], v[40:41], v[78:79]
	v_add_co_u32_e32 v72, vcc, s45, v76
	v_pk_fma_f32 v[64:65], v[68:69], v[78:79], v[64:65]
	v_lshlrev_b32_e32 v78, 16, v95
	v_and_b32_e32 v79, 0xffff0000, v95
	v_pk_mul_f32 v[78:79], v[80:81], v[78:79] op_sel_hi:[0,1]
	v_lshlrev_b32_e32 v68, 16, v89
	v_and_b32_e32 v69, 0xffff0000, v89
	v_pk_mul_f32 v[78:79], v[46:47], v[78:79]
	v_cndmask_b32_e64 v82, v86, v90, s[0:1]
	v_pk_fma_f32 v[68:69], v[66:67], v[78:79], v[68:69]
	v_lshlrev_b32_e32 v78, 16, v92
	v_and_b32_e32 v79, 0xffff0000, v92
	v_addc_co_u32_e32 v73, vcc, 0, v77, vcc
	v_pk_mul_f32 v[78:79], v[80:81], v[78:79] op_sel_hi:[0,1]
	global_store_dwordx4 v[72:73], v[82:85], off
	v_mov_b32_e32 v86, v157
	v_mov_b32_e32 v87, v157
	v_mov_b32_e32 v82, v157
	v_mov_b32_e32 v83, v157
	v_lshlrev_b32_e32 v66, 16, v101
	v_and_b32_e32 v67, 0xffff0000, v101
	v_pk_mul_f32 v[78:79], v[42:43], v[78:79]
	v_mov_b32_dpp v82, v74 row_ror:8 row_mask:0xf bank_mask:0xf
	v_mov_b32_dpp v83, v75 row_ror:8 row_mask:0xf bank_mask:0xf
	v_mov_b32_e32 v84, v157
	v_mov_b32_e32 v85, v157
	v_mov_b32_dpp v86, v68 row_ror:8 row_mask:0xf bank_mask:0xf
	v_mov_b32_dpp v87, v69 row_ror:8 row_mask:0xf bank_mask:0xf
	v_pk_fma_f32 v[66:67], v[70:71], v[78:79], v[66:67]
	v_mov_b32_e32 v70, v157
	v_mov_b32_e32 v71, v157
	v_add_u32_e32 v78, 0x90, v81
	v_mov_b32_dpp v84, v64 row_ror:8 row_mask:0xf bank_mask:0xf
	v_mov_b32_dpp v85, v65 row_ror:8 row_mask:0xf bank_mask:0xf
	v_mov_b32_dpp v70, v66 row_ror:8 row_mask:0xf bank_mask:0xf
	v_mov_b32_dpp v71, v67 row_ror:8 row_mask:0xf bank_mask:0xf
	v_cndmask_b32_e64 v67, v87, v67, s[0:1]
	v_cndmask_b32_e64 v66, v86, v66, s[0:1]
	v_cndmask_b32_e64 v65, v83, v65, s[0:1]
	v_cndmask_b32_e64 v64, v82, v64, s[0:1]
	v_ashrrev_i32_e32 v79, 31, v78
	v_cndmask_b32_e64 v71, v69, v71, s[0:1]
	v_cndmask_b32_e64 v70, v68, v70, s[0:1]
	v_cndmask_b32_e64 v69, v75, v85, s[0:1]
	v_cndmask_b32_e64 v68, v74, v84, s[0:1]
	global_store_dwordx4 v[76:77], v[64:67], off offset:128
	global_store_dwordx4 v[72:73], v[68:71], off offset:128
	s_waitcnt vmcnt(4)
	s_nop 0
	v_mov_b32_e32 v80, v228
	v_lshlrev_b64 v[64:65], 12, v[78:79]
	v_lshl_add_u64 v[82:83], v[64:65], 0, s[16:17]
	v_lshl_add_u64 v[70:71], s[8:9], 0, v[82:83]
	v_lshl_add_u64 v[66:67], s[8:9], 0, v[64:65]
	v_lshl_add_u64 v[70:71], v[70:71], 0, v[164:165]
	v_lshl_add_u64 v[64:65], s[10:11], 0, v[64:65]
	v_lshl_add_u64 v[66:67], v[66:67], 0, v[164:165]
	v_mov_b64_e32 v[70:71], v[232:233]
	v_mov_b64_e32 v[72:73], v[234:235]
	v_lshl_add_u64 v[64:65], v[64:65], 0, v[164:165]
	v_mov_b64_e32 v[66:67], v[236:237]
	v_mov_b64_e32 v[68:69], v[238:239]
	v_mov_b32_e32 v90, v157
	v_mov_b64_e32 v[74:75], v[240:241]
	v_mov_b64_e32 v[76:77], v[242:243]
	v_lshl_add_u64 v[64:65], s[10:11], 0, v[82:83]
	v_lshl_add_u64 v[64:65], v[64:65], 0, v[164:165]
	v_mov_b64_e32 v[82:83], v[244:245]
	v_mov_b64_e32 v[84:85], v[246:247]
	s_nop 1
	global_load_dword v228, v[168:169], off offset:640
	v_add_u32_e32 v220, 0xa0, v81
	v_ashrrev_i32_e32 v221, 31, v220
	v_lshlrev_b64 v[216:217], 12, v[220:221]
	v_lshl_add_u64 v[224:225], v[216:217], 0, s[16:17]
	v_lshl_add_u64 v[222:223], s[8:9], 0, v[224:225]
	v_lshl_add_u64 v[218:219], s[8:9], 0, v[216:217]
	v_lshl_add_u64 v[222:223], v[222:223], 0, v[164:165]
	v_lshl_add_u64 v[216:217], s[10:11], 0, v[216:217]
	v_lshl_add_u64 v[218:219], v[218:219], 0, v[164:165]
	global_load_dwordx4 v[232:235], v[222:223], off
	v_lshl_add_u64 v[216:217], v[216:217], 0, v[164:165]
	global_load_dwordx4 v[236:239], v[218:219], off
	global_load_dwordx4 v[240:243], v[216:217], off
	v_lshl_add_u64 v[216:217], s[10:11], 0, v[224:225]
	v_lshl_add_u64 v[216:217], v[216:217], 0, v[164:165]
	global_load_dwordx4 v[244:247], v[216:217], off
	v_mov_b32_e32 v91, v157
	v_mov_b32_e32 v65, v157
	v_mov_b32_e32 v86, v157
	v_mov_b32_e32 v87, v157
	v_mov_b32_e32 v89, v157
	v_mov_b32_e32 v88, v157
	v_exp_f32_e32 v32, v32
	v_exp_f32_e32 v33, v33
	v_mul_f32_e32 v36, 0xbfb8aa3b, v36
	v_mul_f32_e32 v37, 0xbfb8aa3b, v37
	v_exp_f32_e32 v36, v36
	v_exp_f32_e32 v37, v37
	v_add_f32_e32 v32, 1.0, v32
	v_add_f32_e32 v33, 1.0, v33
	v_rcp_f32_e32 v32, v32
	v_rcp_f32_e32 v33, v33
	v_mul_f32_e32 v34, 0xbfb8aa3b, v34
	v_mul_f32_e32 v35, 0xbfb8aa3b, v35
	v_add_f32_e32 v36, 1.0, v36
	v_add_f32_e32 v37, 1.0, v37
	v_exp_f32_e32 v34, v34
	v_exp_f32_e32 v35, v35
	v_rcp_f32_e32 v36, v36
	v_rcp_f32_e32 v37, v37
	v_mul_f32_e32 v38, 0xbfb8aa3b, v38
	v_mul_f32_e32 v39, 0xbfb8aa3b, v39
	v_exp_f32_e32 v38, v38
	v_exp_f32_e32 v39, v39
	v_add_f32_e32 v34, 1.0, v34
	v_add_f32_e32 v35, 1.0, v35
	v_rcp_f32_e32 v34, v34
	v_rcp_f32_e32 v35, v35
	v_add_f32_e32 v38, 1.0, v38
	v_add_f32_e32 v39, 1.0, v39
	v_rcp_f32_e32 v38, v38
	v_rcp_f32_e32 v39, v39
	v_mul_f32_e32 v24, 0xbfb8aa3b, v24
	v_mul_f32_e32 v25, 0xbfb8aa3b, v25
	v_mul_f32_e32 v28, 0xbfb8aa3b, v28
	v_exp_f32_e32 v24, v24
	v_exp_f32_e32 v25, v25
	v_mul_f32_e32 v26, 0xbfb8aa3b, v26
	v_mul_f32_e32 v27, 0xbfb8aa3b, v27
	v_add_f32_e32 v24, 1.0, v24
	v_add_f32_e32 v25, 1.0, v25
	v_rcp_f32_e32 v24, v24
	v_rcp_f32_e32 v25, v25
	v_exp_f32_e32 v26, v26
	v_exp_f32_e32 v27, v27
	v_mul_f32_e32 v30, 0xbfb8aa3b, v30
	v_mul_f32_e32 v31, 0xbfb8aa3b, v31
	v_exp_f32_e32 v30, v30
	v_exp_f32_e32 v31, v31
	v_add_f32_e32 v26, 1.0, v26
	v_add_f32_e32 v27, 1.0, v27
	v_rcp_f32_e32 v26, v26
	v_rcp_f32_e32 v27, v27
	v_add_f32_e32 v30, 1.0, v30
	v_add_f32_e32 v31, 1.0, v31
	v_mul_f32_e32 v16, 0xbfb8aa3b, v16
	v_mul_f32_e32 v17, 0xbfb8aa3b, v17
	v_rcp_f32_e32 v30, v30
	v_rcp_f32_e32 v31, v31
	v_exp_f32_e32 v16, v16
	s_waitcnt vmcnt(50)
; __device__ __forceinline__ float bflo(unsigned w) { return __uint_as_float(w << 16); }
; __device__ __forceinline__ float bfhi(unsigned w) { return __uint_as_float(w & 0xffff0000u); }
; __device__ __forceinline__ unsigned dpp_ror8(unsigned x) { return (unsigned)__builtin_amdgcn_update_dpp(0, (int)x, 0x128, 0xf, 0xf, false); }
;     __device__ __forceinline__ void operator()(const f32x4 (&acc)[2][2][4][2], const Unit& u, int wr, int wc, int fr, int fq) const {
;     ...
;             for (int m = 0; m < 4; ++m) { const int row = row0 + ai * HALF + m * 16; const float ri = __builtin_amdgcn_rsqf(sse[row] * (1.f / D) + EPS);
;                 u32x4 rr[2], ee[2]; load_pair_lines(R, D, row, fr, col0, rr[0], rr[1], 32); load_pair_lines(E, D, row, fr, col0, ee[0], ee[1], 32);
;                 float* orow = OUT + (size_t)(row - fr + (fr & 7)) * D + col0 + (lo ? 0 : 4);
; #pragma unroll
;                 for (int bj = 0; bj < 2; ++bj) { const u32x4 rw = rr[bj], ew = ee[bj];
;                     const float r[8] = {bflo(rw.x), bfhi(rw.x), bflo(rw.y), bfhi(rw.y), bflo(rw.z), bfhi(rw.z), bflo(rw.w), bfhi(rw.w)};
;                     const float e[8] = {bflo(ew.x), bfhi(ew.x), bflo(ew.y), bfhi(ew.y), bflo(ew.z), bfhi(ew.z), bflo(ew.w), bfhi(ew.w)};
;                     float o[8];
; #pragma unroll
;                     for (int j = 0; j < 8; ++j) { const float a = acc[ai][bj][m][j >> 2][j & 3]; const float gg = gv[bj][j >> 2][j & 3];
;                         o[j] = r[j] + e[j] * ri * gg * __builtin_amdgcn_rcpf(1.f + __builtin_amdgcn_exp2f(-a * LOG2E)); }
;                     f32x4 o1, o2;
; #pragma unroll
;                     for (int j = 0; j < 4; ++j) { const unsigned a = __float_as_uint(o[j]), b = __float_as_uint(o[4 + j]); const unsigned sa = dpp_ror8(a), sb = dpp_ror8(b);
;                         o1[j] = __uint_as_float(lo ? a : sb); o2[j] = __uint_as_float(lo ? sa : b); }
;                     *(f32x4*)(orow + 32 * bj) = o1; *(f32x4*)(orow + (size_t)8 * D + 32 * bj) = o2; } }
	v_fmamk_f32 v64, v80, 0x3a000000, v182
	v_mov_b32_e32 v80, v157
	v_rsq_f32_e32 v64, v64
	v_exp_f32_e32 v17, v17
	v_mul_f32_e32 v20, 0xbfb8aa3b, v20
	v_mul_f32_e32 v21, 0xbfb8aa3b, v21
	v_exp_f32_e32 v20, v20
	v_exp_f32_e32 v21, v21
	v_mov_b32_dpp v90, v72 row_ror:8 row_mask:0xf bank_mask:0xf
	v_mov_b32_dpp v91, v73 row_ror:8 row_mask:0xf bank_mask:0xf
	v_mov_b32_dpp v65, v66 row_ror:8 row_mask:0xf bank_mask:0xf
	v_mov_b32_dpp v80, v67 row_ror:8 row_mask:0xf bank_mask:0xf
	v_mov_b32_dpp v86, v68 row_ror:8 row_mask:0xf bank_mask:0xf
	v_mov_b32_dpp v87, v69 row_ror:8 row_mask:0xf bank_mask:0xf
	v_mov_b32_dpp v89, v71 row_ror:8 row_mask:0xf bank_mask:0xf
	v_cndmask_b32_e64 v91, v91, v69, s[0:1]
	v_cndmask_b32_e64 v69, v90, v68, s[0:1]
	v_mov_b32_e32 v68, v157
	v_mov_b32_dpp v88, v70 row_ror:8 row_mask:0xf bank_mask:0xf
	v_cndmask_b32_e64 v89, v89, v67, s[0:1]
	v_cndmask_b32_e64 v80, v71, v80, s[0:1]
	v_cndmask_b32_e64 v73, v73, v87, s[0:1]
	v_cndmask_b32_e64 v65, v70, v65, s[0:1]
	v_mov_b32_e32 v67, v157
	v_mov_b32_dpp v68, v76 row_ror:8 row_mask:0xf bank_mask:0xf
	v_mov_b32_e32 v70, v157
	v_mov_b32_e32 v71, v157
	v_mov_b32_e32 v87, v157
	v_cndmask_b32_e64 v88, v88, v66, s[0:1]
	v_cndmask_b32_e64 v72, v72, v86, s[0:1]
	v_mov_b32_e32 v66, v157
	v_mov_b32_dpp v67, v75 row_ror:8 row_mask:0xf bank_mask:0xf
	v_mov_b32_dpp v70, v77 row_ror:8 row_mask:0xf bank_mask:0xf
	v_mov_b32_dpp v71, v82 row_ror:8 row_mask:0xf bank_mask:0xf
	v_mov_b32_e32 v86, v157
	v_mov_b32_dpp v87, v84 row_ror:8 row_mask:0xf bank_mask:0xf
	v_cndmask_b32_e64 v84, v84, v68, s[0:1]
	v_exp_f32_e32 v68, v52
	v_mul_f32_e32 v52, 0xbfb8aa3b, v53
	v_mov_b32_dpp v66, v74 row_ror:8 row_mask:0xf bank_mask:0xf
	v_mov_b32_dpp v86, v83 row_ror:8 row_mask:0xf bank_mask:0xf
	v_cndmask_b32_e64 v74, v71, v74, s[0:1]
	v_cndmask_b32_e64 v71, v87, v76, s[0:1]
	v_cndmask_b32_e64 v76, v83, v67, s[0:1]
	v_cndmask_b32_e64 v83, v85, v70, s[0:1]
	v_exp_f32_e32 v70, v52
	v_cndmask_b32_e64 v82, v82, v66, s[0:1]
	v_lshlrev_b64 v[66:67], 13, v[78:79]
	v_lshl_add_u64 v[66:67], s[4:5], 0, v[66:67]
	v_lshl_add_u64 v[66:67], v[66:67], 0, v[166:167]
	v_lshl_add_u64 v[52:53], v[66:67], 0, v[156:157]
	v_add_f32_e32 v67, 1.0, v70
	v_lshlrev_b32_e32 v70, 16, v71
	v_and_b32_e32 v71, 0xffff0000, v71
	v_add_f32_e32 v66, 1.0, v68
	v_pk_mul_f32 v[70:71], v[64:65], v[70:71] op_sel_hi:[0,1]
	v_rcp_f32_e32 v66, v66
	v_rcp_f32_e32 v67, v67
	v_lshlrev_b32_e32 v68, 16, v69
	v_and_b32_e32 v69, 0xffff0000, v69
	v_pk_mul_f32 v[70:71], v[60:61], v[70:71]
	v_mov_b32_e32 v90, v157
	v_pk_fma_f32 v[70:71], v[48:49], v[70:71], v[68:69]
	v_lshlrev_b32_e32 v68, 16, v74
	v_and_b32_e32 v69, 0xffff0000, v74
	v_mov_b32_dpp v90, v85 row_ror:8 row_mask:0xf bank_mask:0xf
	v_pk_mul_f32 v[68:69], v[64:65], v[68:69] op_sel_hi:[0,1]
	v_cndmask_b32_e64 v77, v90, v77, s[0:1]
	v_lshlrev_b32_e32 v48, 16, v88
	v_and_b32_e32 v49, 0xffff0000, v88
	v_pk_mul_f32 v[68:69], v[56:57], v[68:69]
	v_cndmask_b32_e64 v75, v86, v75, s[0:1]
	v_pk_fma_f32 v[48:49], v[66:67], v[68:69], v[48:49]
	v_lshlrev_b32_e32 v68, 16, v77
	v_and_b32_e32 v69, 0xffff0000, v77
	v_pk_mul_f32 v[68:69], v[64:65], v[68:69] op_sel_hi:[0,1]
	v_lshlrev_b32_e32 v66, 16, v91
	v_and_b32_e32 v67, 0xffff0000, v91
	v_pk_mul_f32 v[68:69], v[62:63], v[68:69]
	v_mov_b32_e32 v78, v157
	v_pk_fma_f32 v[66:67], v[50:51], v[68:69], v[66:67]
	v_lshlrev_b32_e32 v68, 16, v75
	v_and_b32_e32 v69, 0xffff0000, v75
	v_pk_mul_f32 v[68:69], v[64:65], v[68:69] op_sel_hi:[0,1]
	v_lshlrev_b32_e32 v50, 16, v89
	v_and_b32_e32 v51, 0xffff0000, v89
	v_pk_mul_f32 v[68:69], v[58:59], v[68:69]
	v_mov_b32_e32 v79, v157
	v_pk_fma_f32 v[50:51], v[54:55], v[68:69], v[50:51]
	v_mov_b32_e32 v54, v157
	v_mov_b32_e32 v55, v157
	v_mov_b32_e32 v77, v157
	v_mov_b32_e32 v86, v157
	v_mov_b32_dpp v54, v50 row_ror:8 row_mask:0xf bank_mask:0xf
	v_mov_b32_dpp v55, v51 row_ror:8 row_mask:0xf bank_mask:0xf
	v_mov_b32_dpp v78, v70 row_ror:8 row_mask:0xf bank_mask:0xf
	v_mov_b32_dpp v79, v71 row_ror:8 row_mask:0xf bank_mask:0xf
	v_mov_b32_e32 v74, v157
	v_mov_b32_e32 v85, v157
	v_mov_b32_dpp v77, v66 row_ror:8 row_mask:0xf bank_mask:0xf
	v_mov_b32_dpp v86, v67 row_ror:8 row_mask:0xf bank_mask:0xf
	v_cndmask_b32_e64 v69, v67, v55, s[0:1]
	v_cndmask_b32_e64 v68, v66, v54, s[0:1]
	v_lshlrev_b32_e32 v54, 16, v84
	v_and_b32_e32 v55, 0xffff0000, v84
	v_mov_b32_dpp v74, v48 row_ror:8 row_mask:0xf bank_mask:0xf
	v_mov_b32_dpp v85, v49 row_ror:8 row_mask:0xf bank_mask:0xf
	v_cndmask_b32_e64 v51, v86, v51, s[0:1]
	v_cndmask_b32_e64 v50, v77, v50, s[0:1]
	v_cndmask_b32_e64 v49, v79, v49, s[0:1]
	v_cndmask_b32_e64 v48, v78, v48, s[0:1]
	v_pk_mul_f32 v[54:55], v[64:65], v[54:55] op_sel_hi:[0,1]
	global_store_dwordx4 v[52:53], v[48:51], off
	v_pk_mul_f32 v[54:55], v[44:45], v[54:55]
	v_cndmask_b32_e64 v67, v71, v85, s[0:1]
	v_lshlrev_b32_e32 v50, 16, v72
	v_and_b32_e32 v51, 0xffff0000, v72
	v_pk_fma_f32 v[50:51], v[32:33], v[54:55], v[50:51]
	v_lshlrev_b32_e32 v54, 16, v82
	v_and_b32_e32 v55, 0xffff0000, v82
	v_pk_mul_f32 v[54:55], v[64:65], v[54:55] op_sel_hi:[0,1]
	v_lshlrev_b32_e32 v32, 16, v65
	v_and_b32_e32 v33, 0xffff0000, v65
	v_pk_mul_f32 v[54:55], v[40:41], v[54:55]
	v_mov_b32_e32 v65, v157
	v_pk_fma_f32 v[32:33], v[36:37], v[54:55], v[32:33]
	v_lshlrev_b32_e32 v54, 16, v83
	v_and_b32_e32 v55, 0xffff0000, v83
	v_mov_b32_dpp v65, v32 row_ror:8 row_mask:0xf bank_mask:0xf
	v_pk_mul_f32 v[54:55], v[64:65], v[54:55] op_sel_hi:[0,1]
	v_lshlrev_b32_e32 v36, 16, v73
	v_and_b32_e32 v37, 0xffff0000, v73
	v_pk_mul_f32 v[54:55], v[46:47], v[54:55]
	v_add_co_u32_e32 v48, vcc, s45, v52
	v_pk_fma_f32 v[36:37], v[34:35], v[54:55], v[36:37]
	v_lshlrev_b32_e32 v54, 16, v76
; __device__ __forceinline__ float bflo(unsigned w) { return __uint_as_float(w << 16); }
; __device__ __forceinline__ float bfhi(unsigned w) { return __uint_as_float(w & 0xffff0000u); }
; __device__ __forceinline__ unsigned dpp_ror8(unsigned x) { return (unsigned)__builtin_amdgcn_update_dpp(0, (int)x, 0x128, 0xf, 0xf, false); }
;     __device__ __forceinline__ void operator()(const f32x4 (&acc)[2][2][4][2], const Unit& u, int wr, int wc, int fr, int fq) const {
;     ...
;                 float* orow = OUT + (size_t)(row - fr + (fr & 7)) * D + col0 + (lo ? 0 : 4);
; #pragma unroll
;                 for (int bj = 0; bj < 2; ++bj) { const u32x4 rw = rr[bj], ew = ee[bj];
;                     const float r[8] = {bflo(rw.x), bfhi(rw.x), bflo(rw.y), bfhi(rw.y), bflo(rw.z), bfhi(rw.z), bflo(rw.w), bfhi(rw.w)};
;                     const float e[8] = {bflo(ew.x), bfhi(ew.x), bflo(ew.y), bfhi(ew.y), bflo(ew.z), bfhi(ew.z), bflo(ew.w), bfhi(ew.w)};
;                     float o[8];
; #pragma unroll
;                     for (int j = 0; j < 8; ++j) { const float a = acc[ai][bj][m][j >> 2][j & 3]; const float gg = gv[bj][j >> 2][j & 3];
;                         o[j] = r[j] + e[j] * ri * gg * __builtin_amdgcn_rcpf(1.f + __builtin_amdgcn_exp2f(-a * LOG2E)); }
;                     f32x4 o1, o2;
; #pragma unroll
;                     for (int j = 0; j < 4; ++j) { const unsigned a = __float_as_uint(o[j]), b = __float_as_uint(o[4 + j]); const unsigned sa = dpp_ror8(a), sb = dpp_ror8(b);
;                         o1[j] = __uint_as_float(lo ? a : sb); o2[j] = __uint_as_float(lo ? sa : b); }
;                     *(f32x4*)(orow + 32 * bj) = o1; *(f32x4*)(orow + (size_t)8 * D + 32 * bj) = o2; } }
	v_and_b32_e32 v55, 0xffff0000, v76
	v_pk_mul_f32 v[54:55], v[64:65], v[54:55] op_sel_hi:[0,1]
	v_cndmask_b32_e64 v66, v70, v74, s[0:1]
	v_addc_co_u32_e32 v49, vcc, 0, v53, vcc
	v_lshlrev_b32_e32 v34, 16, v80
	v_and_b32_e32 v35, 0xffff0000, v80
	v_pk_mul_f32 v[54:55], v[42:43], v[54:55]
	global_store_dwordx4 v[48:49], v[66:69], off
	v_mov_b32_e32 v70, v157
	v_pk_fma_f32 v[34:35], v[38:39], v[54:55], v[34:35]
	v_mov_b32_e32 v66, v157
	v_mov_b32_e32 v67, v157
	v_mov_b32_e32 v69, v157
	v_mov_b32_e32 v38, v157
	v_mov_b32_dpp v66, v50 row_ror:8 row_mask:0xf bank_mask:0xf
	v_mov_b32_dpp v67, v51 row_ror:8 row_mask:0xf bank_mask:0xf
	v_mov_b32_e32 v68, v157
	v_mov_b32_dpp v69, v36 row_ror:8 row_mask:0xf bank_mask:0xf
	v_mov_b32_dpp v70, v37 row_ror:8 row_mask:0xf bank_mask:0xf
	v_mov_b32_dpp v38, v34 row_ror:8 row_mask:0xf bank_mask:0xf
	v_mov_b32_e32 v39, v157
	v_mov_b32_dpp v68, v33 row_ror:8 row_mask:0xf bank_mask:0xf
	v_cndmask_b32_e64 v34, v69, v34, s[0:1]
	v_mov_b32_dpp v39, v35 row_ror:8 row_mask:0xf bank_mask:0xf
	v_cndmask_b32_e64 v35, v70, v35, s[0:1]
	v_cndmask_b32_e64 v33, v67, v33, s[0:1]
	v_cndmask_b32_e64 v32, v66, v32, s[0:1]
	v_cndmask_b32_e64 v38, v36, v38, s[0:1]
	v_cndmask_b32_e64 v39, v37, v39, s[0:1]
	v_cndmask_b32_e64 v37, v51, v68, s[0:1]
	v_cndmask_b32_e64 v36, v50, v65, s[0:1]
	global_store_dwordx4 v[52:53], v[32:35], off offset:128
	global_store_dwordx4 v[48:49], v[36:39], off offset:128
	s_waitcnt vmcnt(4)
	s_nop 0
	v_mov_b32_e32 v68, v228
	v_mov_b32_e32 v73, v157
	v_add_u32_e32 v38, 0xa0, v81
	v_ashrrev_i32_e32 v39, 31, v38
	v_lshlrev_b64 v[32:33], 12, v[38:39]
	v_lshl_add_u64 v[64:65], v[32:33], 0, s[16:17]
	v_lshl_add_u64 v[48:49], s[8:9], 0, v[64:65]
	v_lshl_add_u64 v[34:35], s[8:9], 0, v[32:33]
	v_lshl_add_u64 v[48:49], v[48:49], 0, v[164:165]
	v_lshl_add_u64 v[32:33], s[10:11], 0, v[32:33]
	v_lshl_add_u64 v[34:35], v[34:35], 0, v[164:165]
	v_mov_b64_e32 v[48:49], v[232:233]
	v_mov_b64_e32 v[50:51], v[234:235]
	v_lshl_add_u64 v[32:33], v[32:33], 0, v[164:165]
	v_mov_b64_e32 v[34:35], v[236:237]
	v_mov_b64_e32 v[36:37], v[238:239]
	v_mov_b32_e32 v74, v157
	v_mov_b64_e32 v[52:53], v[240:241]
	v_mov_b64_e32 v[54:55], v[242:243]
	v_lshl_add_u64 v[32:33], s[10:11], 0, v[64:65]
	v_lshl_add_u64 v[32:33], v[32:33], 0, v[164:165]
	v_mov_b64_e32 v[64:65], v[244:245]
	v_mov_b64_e32 v[66:67], v[246:247]
	s_nop 1
	v_add_u32_e32 v224, 0xb0, v81
	v_ashrrev_i32_e32 v225, 31, v224
	global_load_dword v228, v[168:169], off offset:704
	v_lshlrev_b64 v[216:217], 12, v[224:225]
	v_lshl_add_u64 v[222:223], v[216:217], 0, s[16:17]
	v_lshl_add_u64 v[220:221], s[8:9], 0, v[222:223]
	v_lshl_add_u64 v[218:219], s[8:9], 0, v[216:217]
	v_lshl_add_u64 v[220:221], v[220:221], 0, v[164:165]
	v_lshl_add_u64 v[216:217], s[10:11], 0, v[216:217]
	v_lshl_add_u64 v[218:219], v[218:219], 0, v[164:165]
	global_load_dwordx4 v[232:235], v[220:221], off
	v_lshl_add_u64 v[216:217], v[216:217], 0, v[164:165]
	global_load_dwordx4 v[236:239], v[218:219], off
	global_load_dwordx4 v[240:243], v[216:217], off
	v_lshl_add_u64 v[216:217], s[10:11], 0, v[222:223]
	v_lshl_add_u64 v[216:217], v[216:217], 0, v[164:165]
	global_load_dwordx4 v[244:247], v[216:217], off
	v_mov_b32_e32 v69, v157
	v_mov_b32_e32 v70, v157
	v_mov_b32_e32 v71, v157
	v_mov_b32_e32 v72, v157
	v_mov_b32_e32 v33, v157
	v_add_f32_e32 v16, 1.0, v16
	v_add_f32_e32 v17, 1.0, v17
	v_rcp_f32_e32 v16, v16
	v_rcp_f32_e32 v17, v17
	v_mul_f32_e32 v18, 0xbfb8aa3b, v18
	v_mul_f32_e32 v19, 0xbfb8aa3b, v19
	v_add_f32_e32 v20, 1.0, v20
	v_add_f32_e32 v21, 1.0, v21
	v_exp_f32_e32 v18, v18
	v_exp_f32_e32 v19, v19
	v_rcp_f32_e32 v20, v20
	v_rcp_f32_e32 v21, v21
	v_mul_f32_e32 v22, 0xbfb8aa3b, v22
	v_mul_f32_e32 v23, 0xbfb8aa3b, v23
	v_exp_f32_e32 v22, v22
	v_exp_f32_e32 v23, v23
	v_add_f32_e32 v18, 1.0, v18
	v_add_f32_e32 v19, 1.0, v19
	v_rcp_f32_e32 v18, v18
	v_rcp_f32_e32 v19, v19
	v_add_f32_e32 v22, 1.0, v22
	v_add_f32_e32 v23, 1.0, v23
	v_rcp_f32_e32 v22, v22
	v_rcp_f32_e32 v23, v23
	v_mul_f32_e32 v8, 0xbfb8aa3b, v8
	v_mul_f32_e32 v9, 0xbfb8aa3b, v9
	v_mul_f32_e32 v12, 0xbfb8aa3b, v12
	v_exp_f32_e32 v8, v8
	v_exp_f32_e32 v9, v9
	v_mul_f32_e32 v10, 0xbfb8aa3b, v10
	v_mul_f32_e32 v11, 0xbfb8aa3b, v11
	v_add_f32_e32 v8, 1.0, v8
	v_add_f32_e32 v9, 1.0, v9
	v_rcp_f32_e32 v8, v8
	v_rcp_f32_e32 v9, v9
	v_exp_f32_e32 v10, v10
	v_exp_f32_e32 v11, v11
	v_mul_f32_e32 v14, 0xbfb8aa3b, v14
	v_mul_f32_e32 v15, 0xbfb8aa3b, v15
	v_exp_f32_e32 v14, v14
	v_exp_f32_e32 v15, v15
	v_add_f32_e32 v10, 1.0, v10
	v_add_f32_e32 v11, 1.0, v11
	v_rcp_f32_e32 v10, v10
	v_rcp_f32_e32 v11, v11
	v_add_f32_e32 v14, 1.0, v14
	v_add_f32_e32 v15, 1.0, v15
	v_mul_f32_e32 v0, 0xbfb8aa3b, v0
	v_mul_f32_e32 v1, 0xbfb8aa3b, v1
	v_rcp_f32_e32 v14, v14
	v_rcp_f32_e32 v15, v15
	v_exp_f32_e32 v0, v0
	v_exp_f32_e32 v1, v1
	v_mul_f32_e32 v4, 0xbfb8aa3b, v4
	v_mul_f32_e32 v5, 0xbfb8aa3b, v5
	v_exp_f32_e32 v4, v4
	s_waitcnt vmcnt(59)
; __device__ __forceinline__ float bflo(unsigned w) { return __uint_as_float(w << 16); }
; __device__ __forceinline__ float bfhi(unsigned w) { return __uint_as_float(w & 0xffff0000u); }
; __device__ __forceinline__ unsigned dpp_ror8(unsigned x) { return (unsigned)__builtin_amdgcn_update_dpp(0, (int)x, 0x128, 0xf, 0xf, false); }
;     const bool lo = fr < 8;
;     const int r1 = row - fr + (fr & 7), cb = col0 + (lo ? 0 : boff);
;     const u32x4 l1 = *(const u32x4*)(P + (size_t)r1 * ld + cb), l2 = *(const u32x4*)(P + (size_t)(r1 + 8) * ld + cb);
;     const u32x4 s1 = {dpp_ror8(l1.x), dpp_ror8(l1.y), dpp_ror8(l1.z), dpp_ror8(l1.w)}, s2 = {dpp_ror8(l2.x), dpp_ror8(l2.y), dpp_ror8(l2.z), dpp_ror8(l2.w)};
;     wA = lo ? l1 : s2; wB = lo ? s1 : l2;
; }
;     __device__ __forceinline__ void operator()(const f32x4 (&acc)[2][2][4][2], const Unit& u, int wr, int wc, int fr, int fq) const {
;     ...
;             for (int m = 0; m < 4; ++m) { const int row = row0 + ai * HALF + m * 16; const float ri = __builtin_amdgcn_rsqf(sse[row] * (1.f / D) + EPS);
;                 u32x4 rr[2], ee[2]; load_pair_lines(R, D, row, fr, col0, rr[0], rr[1], 32); load_pair_lines(E, D, row, fr, col0, ee[0], ee[1], 32);
;                 float* orow = OUT + (size_t)(row - fr + (fr & 7)) * D + col0 + (lo ? 0 : 4);
; #pragma unroll
;                 for (int bj = 0; bj < 2; ++bj) { const u32x4 rw = rr[bj], ew = ee[bj];
;                     const float r[8] = {bflo(rw.x), bfhi(rw.x), bflo(rw.y), bfhi(rw.y), bflo(rw.z), bfhi(rw.z), bflo(rw.w), bfhi(rw.w)};
;                     const float e[8] = {bflo(ew.x), bfhi(ew.x), bflo(ew.y), bfhi(ew.y), bflo(ew.z), bfhi(ew.z), bflo(ew.w), bfhi(ew.w)};
;                     float o[8];
; #pragma unroll
;                     for (int j = 0; j < 8; ++j) { const float a = acc[ai][bj][m][j >> 2][j & 3]; const float gg = gv[bj][j >> 2][j & 3];
;                         o[j] = r[j] + e[j] * ri * gg * __builtin_amdgcn_rcpf(1.f + __builtin_amdgcn_exp2f(-a * LOG2E)); }
;                     f32x4 o1, o2;
; #pragma unroll
;                     for (int j = 0; j < 4; ++j) { const unsigned a = __float_as_uint(o[j]), b = __float_as_uint(o[4 + j]); const unsigned sa = dpp_ror8(a), sb = dpp_ror8(b);
;                         o1[j] = __uint_as_float(lo ? a : sb); o2[j] = __uint_as_float(lo ? sa : b); }
	v_fmamk_f32 v32, v68, 0x3a000000, v182
	v_mov_b32_e32 v68, v157
	v_rsq_f32_e32 v32, v32
	v_exp_f32_e32 v5, v5
	v_add_f32_e32 v0, 1.0, v0
	v_add_f32_e32 v1, 1.0, v1
	v_rcp_f32_e32 v0, v0
	v_rcp_f32_e32 v1, v1
	v_mul_f32_e32 v2, 0xbfb8aa3b, v2
	v_mul_f32_e32 v3, 0xbfb8aa3b, v3
	v_add_f32_e32 v4, 1.0, v4
	v_mov_b32_dpp v73, v50 row_ror:8 row_mask:0xf bank_mask:0xf
	v_mov_b32_dpp v74, v51 row_ror:8 row_mask:0xf bank_mask:0xf
	v_mov_b32_dpp v69, v36 row_ror:8 row_mask:0xf bank_mask:0xf
	v_mov_b32_dpp v70, v37 row_ror:8 row_mask:0xf bank_mask:0xf
	v_mov_b32_dpp v71, v48 row_ror:8 row_mask:0xf bank_mask:0xf
	v_mov_b32_dpp v72, v49 row_ror:8 row_mask:0xf bank_mask:0xf
	v_cndmask_b32_e64 v74, v74, v37, s[0:1]
	v_cndmask_b32_e64 v37, v73, v36, s[0:1]
	v_mov_b32_e32 v36, v157
	v_mov_b32_dpp v33, v34 row_ror:8 row_mask:0xf bank_mask:0xf
	v_mov_b32_dpp v68, v35 row_ror:8 row_mask:0xf bank_mask:0xf
	v_cndmask_b32_e64 v72, v72, v35, s[0:1]
	v_cndmask_b32_e64 v71, v71, v34, s[0:1]
	v_cndmask_b32_e64 v51, v51, v70, s[0:1]
	v_mov_b32_e32 v34, v157
	v_mov_b32_e32 v35, v157
	v_mov_b32_dpp v36, v54 row_ror:8 row_mask:0xf bank_mask:0xf
	v_mov_b32_e32 v70, v157
	v_cndmask_b32_e64 v49, v49, v68, s[0:1]
	v_cndmask_b32_e64 v33, v48, v33, s[0:1]
	v_cndmask_b32_e64 v48, v50, v69, s[0:1]
	v_mov_b32_dpp v34, v52 row_ror:8 row_mask:0xf bank_mask:0xf
	v_mov_b32_dpp v35, v53 row_ror:8 row_mask:0xf bank_mask:0xf
	v_mov_b32_e32 v68, v157
	v_mov_b32_e32 v69, v157
	v_mov_b32_dpp v70, v66 row_ror:8 row_mask:0xf bank_mask:0xf
	v_cndmask_b32_e64 v66, v66, v36, s[0:1]
	v_exp_f32_e32 v36, v28
	v_mul_f32_e32 v28, 0xbfb8aa3b, v29
	v_mov_b32_dpp v68, v64 row_ror:8 row_mask:0xf bank_mask:0xf
	v_mov_b32_dpp v69, v65 row_ror:8 row_mask:0xf bank_mask:0xf
	v_cndmask_b32_e64 v65, v65, v35, s[0:1]
	v_cndmask_b32_e64 v64, v64, v34, s[0:1]
	v_lshlrev_b64 v[34:35], 13, v[38:39]
	v_exp_f32_e32 v38, v28
	v_lshl_add_u64 v[34:35], s[4:5], 0, v[34:35]
	v_cndmask_b32_e64 v54, v70, v54, s[0:1]
	v_lshl_add_u64 v[34:35], v[34:35], 0, v[166:167]
	v_lshl_add_u64 v[28:29], v[34:35], 0, v[156:157]
	v_add_f32_e32 v35, 1.0, v38
	v_lshlrev_b32_e32 v38, 16, v54
	v_and_b32_e32 v39, 0xffff0000, v54
	v_add_f32_e32 v34, 1.0, v36
	v_pk_mul_f32 v[38:39], v[32:33], v[38:39] op_sel_hi:[0,1]
	v_cndmask_b32_e64 v52, v68, v52, s[0:1]
	v_rcp_f32_e32 v34, v34
	v_rcp_f32_e32 v35, v35
	v_lshlrev_b32_e32 v36, 16, v37
	v_and_b32_e32 v37, 0xffff0000, v37
	v_pk_mul_f32 v[38:39], v[60:61], v[38:39]
	v_mov_b32_e32 v73, v157
	v_pk_fma_f32 v[38:39], v[24:25], v[38:39], v[36:37]
	v_lshlrev_b32_e32 v36, 16, v52
	v_and_b32_e32 v37, 0xffff0000, v52
	v_mov_b32_e32 v50, v157
	v_mov_b32_dpp v73, v67 row_ror:8 row_mask:0xf bank_mask:0xf
	v_pk_mul_f32 v[36:37], v[32:33], v[36:37] op_sel_hi:[0,1]
	v_mov_b32_dpp v50, v55 row_ror:8 row_mask:0xf bank_mask:0xf
	v_cndmask_b32_e64 v55, v73, v55, s[0:1]
	v_lshlrev_b32_e32 v24, 16, v71
	v_and_b32_e32 v25, 0xffff0000, v71
	v_pk_mul_f32 v[36:37], v[56:57], v[36:37]
	v_cndmask_b32_e64 v53, v69, v53, s[0:1]
	v_pk_fma_f32 v[24:25], v[34:35], v[36:37], v[24:25]
	v_lshlrev_b32_e32 v36, 16, v55
	v_and_b32_e32 v37, 0xffff0000, v55
	v_pk_mul_f32 v[36:37], v[32:33], v[36:37] op_sel_hi:[0,1]
	v_lshlrev_b32_e32 v34, 16, v74
	v_and_b32_e32 v35, 0xffff0000, v74
	v_pk_mul_f32 v[36:37], v[62:63], v[36:37]
	v_cndmask_b32_e64 v50, v67, v50, s[0:1]
	v_pk_fma_f32 v[34:35], v[26:27], v[36:37], v[34:35]
	v_lshlrev_b32_e32 v36, 16, v53
	v_and_b32_e32 v37, 0xffff0000, v53
	v_pk_mul_f32 v[36:37], v[32:33], v[36:37] op_sel_hi:[0,1]
	v_lshlrev_b32_e32 v26, 16, v72
	v_and_b32_e32 v27, 0xffff0000, v72
	v_pk_mul_f32 v[36:37], v[58:59], v[36:37]
	v_mov_b32_e32 v54, v157
	v_pk_fma_f32 v[26:27], v[30:31], v[36:37], v[26:27]
	v_mov_b32_e32 v30, v157
	v_mov_b32_e32 v31, v157
	v_mov_b32_e32 v67, v157
	v_mov_b32_e32 v55, v157
	v_mov_b32_e32 v69, v157
	v_mov_b32_dpp v30, v26 row_ror:8 row_mask:0xf bank_mask:0xf
	v_mov_b32_dpp v31, v27 row_ror:8 row_mask:0xf bank_mask:0xf
	v_mov_b32_dpp v54, v38 row_ror:8 row_mask:0xf bank_mask:0xf
	v_mov_b32_dpp v67, v39 row_ror:8 row_mask:0xf bank_mask:0xf
	v_mov_b32_e32 v52, v157
	v_mov_b32_e32 v68, v157
	v_mov_b32_dpp v55, v34 row_ror:8 row_mask:0xf bank_mask:0xf
	v_mov_b32_dpp v69, v35 row_ror:8 row_mask:0xf bank_mask:0xf
	v_cndmask_b32_e64 v37, v35, v31, s[0:1]
	v_cndmask_b32_e64 v36, v34, v30, s[0:1]
	v_lshlrev_b32_e32 v30, 16, v66
	v_and_b32_e32 v31, 0xffff0000, v66
	v_mov_b32_dpp v52, v24 row_ror:8 row_mask:0xf bank_mask:0xf
	v_mov_b32_dpp v68, v25 row_ror:8 row_mask:0xf bank_mask:0xf
	v_cndmask_b32_e64 v27, v69, v27, s[0:1]
	v_cndmask_b32_e64 v26, v55, v26, s[0:1]
	v_cndmask_b32_e64 v25, v67, v25, s[0:1]
	v_cndmask_b32_e64 v24, v54, v24, s[0:1]
	v_pk_mul_f32 v[30:31], v[32:33], v[30:31] op_sel_hi:[0,1]
	global_store_dwordx4 v[28:29], v[24:27], off
	v_pk_mul_f32 v[30:31], v[44:45], v[30:31]
	v_cndmask_b32_e64 v35, v39, v68, s[0:1]
	v_lshlrev_b32_e32 v26, 16, v48
	v_and_b32_e32 v27, 0xffff0000, v48
	v_pk_fma_f32 v[26:27], v[16:17], v[30:31], v[26:27]
	v_lshlrev_b32_e32 v30, 16, v64
	v_and_b32_e32 v31, 0xffff0000, v64
	v_pk_mul_f32 v[30:31], v[32:33], v[30:31] op_sel_hi:[0,1]
	v_lshlrev_b32_e32 v16, 16, v33
	v_and_b32_e32 v17, 0xffff0000, v33
	v_pk_mul_f32 v[30:31], v[40:41], v[30:31]
	v_mov_b32_e32 v33, v157
	v_pk_fma_f32 v[16:17], v[20:21], v[30:31], v[16:17]
	v_lshlrev_b32_e32 v30, 16, v50
	v_and_b32_e32 v31, 0xffff0000, v50
	v_mov_b32_dpp v33, v16 row_ror:8 row_mask:0xf bank_mask:0xf
	v_pk_mul_f32 v[30:31], v[32:33], v[30:31] op_sel_hi:[0,1]
	v_add_co_u32_e32 v24, vcc, s45, v28
	v_lshlrev_b32_e32 v20, 16, v51
	v_and_b32_e32 v21, 0xffff0000, v51
	v_pk_mul_f32 v[30:31], v[46:47], v[30:31]
; __device__ __forceinline__ float bflo(unsigned w) { return __uint_as_float(w << 16); }
; __device__ __forceinline__ float bfhi(unsigned w) { return __uint_as_float(w & 0xffff0000u); }
; __device__ __forceinline__ unsigned dpp_ror8(unsigned x) { return (unsigned)__builtin_amdgcn_update_dpp(0, (int)x, 0x128, 0xf, 0xf, false); }
;     __device__ __forceinline__ void operator()(const f32x4 (&acc)[2][2][4][2], const Unit& u, int wr, int wc, int fr, int fq) const {
;     ...
;             for (int m = 0; m < 4; ++m) { const int row = row0 + ai * HALF + m * 16; const float ri = __builtin_amdgcn_rsqf(sse[row] * (1.f / D) + EPS);
;                 u32x4 rr[2], ee[2]; load_pair_lines(R, D, row, fr, col0, rr[0], rr[1], 32); load_pair_lines(E, D, row, fr, col0, ee[0], ee[1], 32);
;                 float* orow = OUT + (size_t)(row - fr + (fr & 7)) * D + col0 + (lo ? 0 : 4);
; #pragma unroll
;                 for (int bj = 0; bj < 2; ++bj) { const u32x4 rw = rr[bj], ew = ee[bj];
;                     const float r[8] = {bflo(rw.x), bfhi(rw.x), bflo(rw.y), bfhi(rw.y), bflo(rw.z), bfhi(rw.z), bflo(rw.w), bfhi(rw.w)};
;                     const float e[8] = {bflo(ew.x), bfhi(ew.x), bflo(ew.y), bfhi(ew.y), bflo(ew.z), bfhi(ew.z), bflo(ew.w), bfhi(ew.w)};
;                     float o[8];
; #pragma unroll
;                     for (int j = 0; j < 8; ++j) { const float a = acc[ai][bj][m][j >> 2][j & 3]; const float gg = gv[bj][j >> 2][j & 3];
;                         o[j] = r[j] + e[j] * ri * gg * __builtin_amdgcn_rcpf(1.f + __builtin_amdgcn_exp2f(-a * LOG2E)); }
;                     f32x4 o1, o2;
; #pragma unroll
;                     for (int j = 0; j < 4; ++j) { const unsigned a = __float_as_uint(o[j]), b = __float_as_uint(o[4 + j]); const unsigned sa = dpp_ror8(a), sb = dpp_ror8(b);
;                         o1[j] = __uint_as_float(lo ? a : sb); o2[j] = __uint_as_float(lo ? sa : b); }
;                     *(f32x4*)(orow + 32 * bj) = o1; *(f32x4*)(orow + (size_t)8 * D + 32 * bj) = o2; } }
	v_cndmask_b32_e64 v34, v38, v52, s[0:1]
	v_addc_co_u32_e32 v25, vcc, 0, v29, vcc
	v_pk_fma_f32 v[20:21], v[18:19], v[30:31], v[20:21]
	v_lshlrev_b32_e32 v30, 16, v65
	v_and_b32_e32 v31, 0xffff0000, v65
	global_store_dwordx4 v[24:25], v[34:37], off
	v_pk_mul_f32 v[30:31], v[32:33], v[30:31] op_sel_hi:[0,1]
	v_mov_b32_e32 v38, v157
	v_mov_b32_e32 v34, v157
	v_mov_b32_e32 v35, v157
	v_mov_b32_e32 v37, v157
	v_mov_b32_dpp v34, v26 row_ror:8 row_mask:0xf bank_mask:0xf
	v_lshlrev_b32_e32 v18, 16, v49
	v_and_b32_e32 v19, 0xffff0000, v49
	v_pk_mul_f32 v[30:31], v[42:43], v[30:31]
	v_mov_b32_dpp v35, v27 row_ror:8 row_mask:0xf bank_mask:0xf
	v_mov_b32_e32 v36, v157
	v_mov_b32_dpp v37, v20 row_ror:8 row_mask:0xf bank_mask:0xf
	v_mov_b32_dpp v38, v21 row_ror:8 row_mask:0xf bank_mask:0xf
	v_pk_fma_f32 v[18:19], v[22:23], v[30:31], v[18:19]
	v_mov_b32_e32 v22, v157
	v_mov_b32_e32 v23, v157
	v_cndmask_b32_e64 v16, v34, v16, s[0:1]
	v_add_u32_e32 v34, 0xb0, v81
	v_mov_b32_dpp v36, v17 row_ror:8 row_mask:0xf bank_mask:0xf
	v_mov_b32_dpp v22, v18 row_ror:8 row_mask:0xf bank_mask:0xf
	v_mov_b32_dpp v23, v19 row_ror:8 row_mask:0xf bank_mask:0xf
	v_cndmask_b32_e64 v19, v38, v19, s[0:1]
	v_cndmask_b32_e64 v18, v37, v18, s[0:1]
	v_cndmask_b32_e64 v17, v35, v17, s[0:1]
	v_ashrrev_i32_e32 v35, 31, v34
	v_cndmask_b32_e64 v23, v21, v23, s[0:1]
	v_cndmask_b32_e64 v22, v20, v22, s[0:1]
	v_cndmask_b32_e64 v21, v27, v36, s[0:1]
	v_cndmask_b32_e64 v20, v26, v33, s[0:1]
	global_store_dwordx4 v[28:29], v[16:19], off offset:128
	global_store_dwordx4 v[24:25], v[20:23], off offset:128
	s_waitcnt vmcnt(4)
	s_nop 0
	v_mov_b32_e32 v36, v228
	v_lshlrev_b64 v[16:17], 12, v[34:35]
	v_lshl_add_u64 v[30:31], v[16:17], 0, s[16:17]
	v_lshl_add_u64 v[22:23], s[8:9], 0, v[30:31]
	v_lshl_add_u64 v[18:19], s[8:9], 0, v[16:17]
	v_lshl_add_u64 v[22:23], v[22:23], 0, v[164:165]
	v_lshl_add_u64 v[16:17], s[10:11], 0, v[16:17]
	v_lshl_add_u64 v[18:19], v[18:19], 0, v[164:165]
	v_mov_b64_e32 v[22:23], v[232:233]
	v_mov_b64_e32 v[24:25], v[234:235]
	v_lshl_add_u64 v[16:17], v[16:17], 0, v[164:165]
	v_mov_b64_e32 v[18:19], v[236:237]
	v_mov_b64_e32 v[20:21], v[238:239]
	v_mov_b32_e32 v49, v157
	v_mov_b64_e32 v[26:27], v[240:241]
	v_mov_b64_e32 v[28:29], v[242:243]
	v_lshl_add_u64 v[16:17], s[10:11], 0, v[30:31]
	v_lshl_add_u64 v[16:17], v[16:17], 0, v[164:165]
	v_mov_b64_e32 v[30:31], v[244:245]
	v_mov_b64_e32 v[32:33], v[246:247]
	s_nop 1
	v_mov_b32_e32 v50, v157
	v_mov_b32_e32 v17, v157
	v_mov_b32_e32 v37, v157
	v_mov_b32_e32 v38, v157
	v_mov_b32_e32 v48, v157
	v_mov_b32_e32 v39, v157
	v_add_f32_e32 v5, 1.0, v5
	v_exp_f32_e32 v2, v2
	v_exp_f32_e32 v3, v3
	v_rcp_f32_e32 v4, v4
	v_rcp_f32_e32 v5, v5
	v_mul_f32_e32 v6, 0xbfb8aa3b, v6
	v_mul_f32_e32 v7, 0xbfb8aa3b, v7
	v_exp_f32_e32 v6, v6
	v_exp_f32_e32 v7, v7
	v_add_f32_e32 v2, 1.0, v2
	v_add_f32_e32 v3, 1.0, v3
	v_rcp_f32_e32 v2, v2
	v_rcp_f32_e32 v3, v3
	v_add_f32_e32 v6, 1.0, v6
	v_add_f32_e32 v7, 1.0, v7
	v_rcp_f32_e32 v6, v6
	v_rcp_f32_e32 v7, v7
	s_mov_b32 s53, s18
	s_mov_b32 s30, s22
	s_mov_b64 s[36:37], s[28:29]
	s_mov_b64 s[34:35], s[24:25]
	s_waitcnt vmcnt(63)
; __device__ __forceinline__ unsigned dpp_ror8(unsigned x) { return (unsigned)__builtin_amdgcn_update_dpp(0, (int)x, 0x128, 0xf, 0xf, false); }
; #define PG8_WAIT_V(n) asm volatile("s_waitcnt vmcnt(" #n ")" ::: "memory")
; #define PG8_BAR __builtin_amdgcn_s_barrier()
;     __device__ __forceinline__ void operator()(const f32x4 (&acc)[2][2][4][2], const Unit& u, int wr, int wc, int fr, int fq) const {
;     ...
;                     for (int j = 0; j < 8; ++j) { const float a = acc[ai][bj][m][j >> 2][j & 3]; const float gg = gv[bj][j >> 2][j & 3];
;                         o[j] = r[j] + e[j] * ri * gg * __builtin_amdgcn_rcpf(1.f + __builtin_amdgcn_exp2f(-a * LOG2E)); }
;                     f32x4 o1, o2;
; #pragma unroll
;                     for (int j = 0; j < 4; ++j) { const unsigned a = __float_as_uint(o[j]), b = __float_as_uint(o[4 + j]); const unsigned sa = dpp_ror8(a), sb = dpp_ror8(b);
;                         o1[j] = __uint_as_float(lo ? a : sb); o2[j] = __uint_as_float(lo ? sa : b); }
;                     *(f32x4*)(orow + 32 * bj) = o1; *(f32x4*)(orow + (size_t)8 * D + 32 * bj) = o2; } }
; template <class Epi>
; __device__ __forceinline__ void gemm_phase(LAS unsigned char* lds, const Gemm g, const StaticOrder& S, const Epi& E) {
;     ...
;         if (!has_next) break;
; #pragma unroll
;         for (int a = 0; a < 2; ++a)
; #pragma unroll
;             for (int b = 0; b < 2; ++b)
; #pragma unroll
;                 for (int m = 0; m < 4; ++m)
; #pragma unroll
;                     for (int n = 0; n < 2; ++n) acc[a][b][m][n] = (f32x4){0.f, 0.f, 0.f, 0.f};
;         cur = nxt; cA = nA; cB = nB; ++ui;
;     }
;     PG8_WAIT_V(0);
;     if (wr == 0) PG8_BAR;
;     PG8_BAR;
	v_fmamk_f32 v16, v36, 0x3a000000, v182
	v_mov_b32_e32 v36, v157
	v_rsq_f32_e32 v16, v16
	v_mov_b32_dpp v49, v24 row_ror:8 row_mask:0xf bank_mask:0xf
	v_mov_b32_dpp v50, v25 row_ror:8 row_mask:0xf bank_mask:0xf
	v_mov_b32_dpp v17, v18 row_ror:8 row_mask:0xf bank_mask:0xf
	v_mov_b32_dpp v36, v19 row_ror:8 row_mask:0xf bank_mask:0xf
	v_mov_b32_dpp v37, v20 row_ror:8 row_mask:0xf bank_mask:0xf
	v_mov_b32_dpp v38, v21 row_ror:8 row_mask:0xf bank_mask:0xf
	v_mov_b32_dpp v48, v23 row_ror:8 row_mask:0xf bank_mask:0xf
	v_cndmask_b32_e64 v50, v50, v21, s[0:1]
	v_cndmask_b32_e64 v21, v49, v20, s[0:1]
	v_mov_b32_e32 v20, v157
	v_mov_b32_dpp v39, v22 row_ror:8 row_mask:0xf bank_mask:0xf
	v_cndmask_b32_e64 v48, v48, v19, s[0:1]
	v_cndmask_b32_e64 v36, v23, v36, s[0:1]
	v_cndmask_b32_e64 v25, v25, v38, s[0:1]
	v_cndmask_b32_e64 v17, v22, v17, s[0:1]
	v_mov_b32_e32 v19, v157
	v_mov_b32_dpp v20, v28 row_ror:8 row_mask:0xf bank_mask:0xf
	v_mov_b32_e32 v22, v157
	v_mov_b32_e32 v23, v157
	v_mov_b32_e32 v38, v157
	v_cndmask_b32_e64 v39, v39, v18, s[0:1]
	v_cndmask_b32_e64 v24, v24, v37, s[0:1]
	v_mov_b32_e32 v18, v157
	v_mov_b32_dpp v19, v27 row_ror:8 row_mask:0xf bank_mask:0xf
	v_mov_b32_dpp v22, v29 row_ror:8 row_mask:0xf bank_mask:0xf
	v_mov_b32_dpp v23, v30 row_ror:8 row_mask:0xf bank_mask:0xf
	v_mov_b32_e32 v37, v157
	v_mov_b32_dpp v38, v32 row_ror:8 row_mask:0xf bank_mask:0xf
	v_cndmask_b32_e64 v32, v32, v20, s[0:1]
	v_exp_f32_e32 v20, v12
	v_mul_f32_e32 v12, 0xbfb8aa3b, v13
	v_mov_b32_dpp v18, v26 row_ror:8 row_mask:0xf bank_mask:0xf
	v_mov_b32_dpp v37, v31 row_ror:8 row_mask:0xf bank_mask:0xf
	v_cndmask_b32_e64 v26, v23, v26, s[0:1]
	v_cndmask_b32_e64 v23, v38, v28, s[0:1]
	v_cndmask_b32_e64 v28, v31, v19, s[0:1]
	v_cndmask_b32_e64 v31, v33, v22, s[0:1]
	v_exp_f32_e32 v22, v12
	v_cndmask_b32_e64 v30, v30, v18, s[0:1]
	v_lshlrev_b64 v[18:19], 13, v[34:35]
	v_lshl_add_u64 v[18:19], s[4:5], 0, v[18:19]
	v_lshl_add_u64 v[18:19], v[18:19], 0, v[166:167]
	v_lshl_add_u64 v[12:13], v[18:19], 0, v[156:157]
	v_add_f32_e32 v19, 1.0, v22
	v_lshlrev_b32_e32 v22, 16, v23
	v_and_b32_e32 v23, 0xffff0000, v23
	v_add_f32_e32 v18, 1.0, v20
	v_pk_mul_f32 v[22:23], v[16:17], v[22:23] op_sel_hi:[0,1]
	v_rcp_f32_e32 v18, v18
	v_rcp_f32_e32 v19, v19
	v_lshlrev_b32_e32 v20, 16, v21
	v_and_b32_e32 v21, 0xffff0000, v21
	v_pk_mul_f32 v[22:23], v[60:61], v[22:23]
	v_mov_b32_e32 v49, v157
	v_pk_fma_f32 v[22:23], v[8:9], v[22:23], v[20:21]
	v_lshlrev_b32_e32 v20, 16, v26
	v_and_b32_e32 v21, 0xffff0000, v26
	v_mov_b32_dpp v49, v33 row_ror:8 row_mask:0xf bank_mask:0xf
	v_pk_mul_f32 v[20:21], v[16:17], v[20:21] op_sel_hi:[0,1]
	v_cndmask_b32_e64 v29, v49, v29, s[0:1]
	v_lshlrev_b32_e32 v8, 16, v39
	v_and_b32_e32 v9, 0xffff0000, v39
	v_pk_mul_f32 v[20:21], v[56:57], v[20:21]
	v_cndmask_b32_e64 v27, v37, v27, s[0:1]
	v_pk_fma_f32 v[8:9], v[18:19], v[20:21], v[8:9]
	v_lshlrev_b32_e32 v20, 16, v29
	v_and_b32_e32 v21, 0xffff0000, v29
	v_pk_mul_f32 v[20:21], v[16:17], v[20:21] op_sel_hi:[0,1]
	v_lshlrev_b32_e32 v18, 16, v50
	v_and_b32_e32 v19, 0xffff0000, v50
	v_pk_mul_f32 v[20:21], v[62:63], v[20:21]
	v_mov_b32_e32 v33, v157
	v_pk_fma_f32 v[18:19], v[10:11], v[20:21], v[18:19]
	v_lshlrev_b32_e32 v20, 16, v27
	v_and_b32_e32 v21, 0xffff0000, v27
	v_pk_mul_f32 v[20:21], v[16:17], v[20:21] op_sel_hi:[0,1]
	v_lshlrev_b32_e32 v10, 16, v48
	v_and_b32_e32 v11, 0xffff0000, v48
	v_pk_mul_f32 v[20:21], v[58:59], v[20:21]
	v_mov_b32_e32 v34, v157
	v_pk_fma_f32 v[10:11], v[14:15], v[20:21], v[10:11]
	v_mov_b32_e32 v14, v157
	v_mov_b32_e32 v15, v157
	v_mov_b32_e32 v29, v157
	v_mov_b32_e32 v37, v157
	v_mov_b32_dpp v14, v10 row_ror:8 row_mask:0xf bank_mask:0xf
	v_mov_b32_dpp v15, v11 row_ror:8 row_mask:0xf bank_mask:0xf
	v_mov_b32_dpp v33, v22 row_ror:8 row_mask:0xf bank_mask:0xf
	v_mov_b32_dpp v34, v23 row_ror:8 row_mask:0xf bank_mask:0xf
	v_mov_b32_e32 v26, v157
	v_mov_b32_e32 v35, v157
	v_mov_b32_dpp v29, v18 row_ror:8 row_mask:0xf bank_mask:0xf
	v_mov_b32_dpp v37, v19 row_ror:8 row_mask:0xf bank_mask:0xf
	v_cndmask_b32_e64 v21, v19, v15, s[0:1]
	v_cndmask_b32_e64 v20, v18, v14, s[0:1]
	v_lshlrev_b32_e32 v14, 16, v32
	v_and_b32_e32 v15, 0xffff0000, v32
	v_mov_b32_dpp v26, v8 row_ror:8 row_mask:0xf bank_mask:0xf
	v_mov_b32_dpp v35, v9 row_ror:8 row_mask:0xf bank_mask:0xf
	v_cndmask_b32_e64 v11, v37, v11, s[0:1]
	v_cndmask_b32_e64 v10, v29, v10, s[0:1]
	v_cndmask_b32_e64 v9, v34, v9, s[0:1]
	v_cndmask_b32_e64 v8, v33, v8, s[0:1]
	v_pk_mul_f32 v[14:15], v[16:17], v[14:15] op_sel_hi:[0,1]
	global_store_dwordx4 v[12:13], v[8:11], off
	v_pk_mul_f32 v[14:15], v[44:45], v[14:15]
	v_cndmask_b32_e64 v19, v23, v35, s[0:1]
	v_lshlrev_b32_e32 v10, 16, v24
	v_and_b32_e32 v11, 0xffff0000, v24
	v_pk_fma_f32 v[10:11], v[0:1], v[14:15], v[10:11]
	v_lshlrev_b32_e32 v14, 16, v30
	v_and_b32_e32 v15, 0xffff0000, v30
	v_pk_mul_f32 v[14:15], v[16:17], v[14:15] op_sel_hi:[0,1]
	v_lshlrev_b32_e32 v0, 16, v17
	v_and_b32_e32 v1, 0xffff0000, v17
	v_pk_mul_f32 v[14:15], v[40:41], v[14:15]
	v_mov_b32_e32 v17, v157
	v_pk_fma_f32 v[0:1], v[4:5], v[14:15], v[0:1]
	v_lshlrev_b32_e32 v14, 16, v31
	v_and_b32_e32 v15, 0xffff0000, v31
	v_mov_b32_dpp v17, v0 row_ror:8 row_mask:0xf bank_mask:0xf
	v_pk_mul_f32 v[14:15], v[16:17], v[14:15] op_sel_hi:[0,1]
	v_lshlrev_b32_e32 v4, 16, v25
	v_and_b32_e32 v5, 0xffff0000, v25
	v_pk_mul_f32 v[14:15], v[46:47], v[14:15]
	v_add_co_u32_e32 v8, vcc, s45, v12
	v_pk_fma_f32 v[4:5], v[2:3], v[14:15], v[4:5]
	v_lshlrev_b32_e32 v14, 16, v28
	v_and_b32_e32 v15, 0xffff0000, v28
	v_cndmask_b32_e64 v18, v22, v26, s[0:1]
	v_addc_co_u32_e32 v9, vcc, 0, v13, vcc
	v_pk_mul_f32 v[14:15], v[16:17], v[14:15] op_sel_hi:[0,1]
	global_store_dwordx4 v[8:9], v[18:21], off
	v_mov_b32_e32 v22, v157
	v_lshlrev_b32_e32 v2, 16, v36
	v_mov_b32_e32 v18, v157
	v_mov_b32_e32 v19, v157
	v_mov_b32_e32 v21, v157
	v_and_b32_e32 v3, 0xffff0000, v36
	v_pk_mul_f32 v[14:15], v[42:43], v[14:15]
	v_mov_b32_dpp v18, v10 row_ror:8 row_mask:0xf bank_mask:0xf
	v_mov_b32_dpp v19, v11 row_ror:8 row_mask:0xf bank_mask:0xf
	v_mov_b32_e32 v20, v157
	v_mov_b32_dpp v21, v4 row_ror:8 row_mask:0xf bank_mask:0xf
	v_mov_b32_dpp v22, v5 row_ror:8 row_mask:0xf bank_mask:0xf
	v_pk_fma_f32 v[2:3], v[6:7], v[14:15], v[2:3]
	v_mov_b32_e32 v6, v157
	v_mov_b32_e32 v7, v157
	v_mov_b32_dpp v20, v1 row_ror:8 row_mask:0xf bank_mask:0xf
	v_mov_b32_dpp v6, v2 row_ror:8 row_mask:0xf bank_mask:0xf
	v_mov_b32_dpp v7, v3 row_ror:8 row_mask:0xf bank_mask:0xf
	v_cndmask_b32_e64 v3, v22, v3, s[0:1]
	v_cndmask_b32_e64 v2, v21, v2, s[0:1]
	v_cndmask_b32_e64 v1, v19, v1, s[0:1]
	v_cndmask_b32_e64 v0, v18, v0, s[0:1]
	s_and_b64 vcc, exec, s[26:27]
	v_cndmask_b32_e64 v7, v5, v7, s[0:1]
	v_cndmask_b32_e64 v6, v4, v6, s[0:1]
	v_cndmask_b32_e64 v5, v11, v20, s[0:1]
	v_cndmask_b32_e64 v4, v10, v17, s[0:1]
	global_store_dwordx4 v[12:13], v[0:3], off offset:128
	global_store_dwordx4 v[8:9], v[4:7], off offset:128
	s_cbranch_vccz .LBB0_1595
	s_waitcnt vmcnt(0)
	s_cmpk_gt_u32 s3, 0xff
	s_cbranch_scc1 .LBB0_1607
	s_barrier
